# v22: two stagger groups around the N=1024 tiles (copy+mini-GEMM before vs after the tile) and hand-written de-serialised residual epilogue (16 X loads in flight per half instead of 16 dependent round
# speedup vs baseline: 1.1848x; 1.0156x over previous
.LBB0_221:
	s_or_b64 exec, exec, s[4:5]
	v_mov_b32_e32 v8, v174
	s_cmpk_lt_i32 s2, 0x104
	s_barrier
	s_and_b32 s80, s33, 64
	s_cmp_eq_u32 s80, 0
	s_cbranch_scc1 .Lpre1_skip
	v_lshrrev_b32_e32 v21, 6, v174
	v_and_b32_e32 v22, 63, v174
	v_lshlrev_b32_e32 v22, 4, v22
	v_readfirstlane_b32 s80, v21
	v_add_u32_e32 v23, 0x1000, v22
	v_readfirstlane_b32 s92, v235
	v_readfirstlane_b32 s93, v236
	v_readfirstlane_b32 s94, v237
	v_readfirstlane_b32 s95, v238
	v_readfirstlane_b32 s98, v239
	v_readfirstlane_b32 s99, v240
	s_lshr_b32 s100, s33, 7
	s_lshl_b32 s100, s100, 3
	s_lshr_b32 s101, s33, 3
	s_and_b32 s101, s101, 7
	s_add_i32 s100, s100, s101
	s_lshl_b32 s100, s100, 3
	s_add_i32 s80, s80, s100
	s_add_i32 s80, s80, 0x1f40
	s_movk_i32 s100, 0x400
.Lcpy1p_loop:
	s_add_i32 s101, s80, s100
	s_cmp_lt_u32 s101, 0x3df4
	s_cbranch_scc0 .Lcpy1p_tail
	s_mul_hi_u32 s81, s80, 0x2ad5802b
	s_lshr_b32 s81, s81, 8
	s_mul_i32 s82, s81, 0x5fa
	s_sub_i32 s82, s80, s82
	s_lshl_b32 s82, s82, 13
	s_and_b32 s83, s81, 31
	s_mul_i32 s83, s83, 0xc00000
	s_add_i32 s82, s82, s83
	s_cmp_lt_u32 s81, 32
	s_cselect_b32 s84, s92, s94
	s_cselect_b32 s85, s93, s95
	s_mov_b32 s83, 0x1f210000
	s_cselect_b32 s83, 0x7210000, s83
	s_add_u32 s84, s84, s82
	s_addc_u32 s85, s85, 0
	s_add_u32 s84, s84, 0xc000
	s_addc_u32 s85, s85, 0
	s_add_u32 s83, s83, s82
	s_add_u32 s86, s98, s83
	s_addc_u32 s87, s99, 0
	s_mul_hi_u32 s81, s101, 0x2ad5802b
	s_lshr_b32 s81, s81, 8
	s_mul_i32 s82, s81, 0x5fa
	s_sub_i32 s82, s101, s82
	s_lshl_b32 s82, s82, 13
	s_and_b32 s83, s81, 31
	s_mul_i32 s83, s83, 0xc00000
	s_add_i32 s82, s82, s83
	s_cmp_lt_u32 s81, 32
	s_cselect_b32 s88, s92, s94
	s_cselect_b32 s89, s93, s95
	s_mov_b32 s83, 0x1f210000
	s_cselect_b32 s83, 0x7210000, s83
	s_add_u32 s88, s88, s82
	s_addc_u32 s89, s89, 0
	s_add_u32 s88, s88, 0xc000
	s_addc_u32 s89, s89, 0
	s_add_u32 s83, s83, s82
	s_add_u32 s90, s98, s83
	s_addc_u32 s91, s99, 0
	global_load_dwordx4 v[64:67], v22, s[84:85] nt
	global_load_dwordx4 v[68:71], v22, s[84:85] offset:1024 nt
	global_load_dwordx4 v[72:75], v22, s[84:85] offset:2048 nt
	global_load_dwordx4 v[76:79], v22, s[84:85] offset:3072 nt
	global_load_dwordx4 v[80:83], v23, s[84:85] nt
	global_load_dwordx4 v[84:87], v23, s[84:85] offset:1024 nt
	global_load_dwordx4 v[88:91], v23, s[84:85] offset:2048 nt
	global_load_dwordx4 v[92:95], v23, s[84:85] offset:3072 nt
	global_load_dwordx4 v[96:99], v22, s[88:89] nt
	global_load_dwordx4 v[100:103], v22, s[88:89] offset:1024 nt
	global_load_dwordx4 v[104:107], v22, s[88:89] offset:2048 nt
	global_load_dwordx4 v[108:111], v22, s[88:89] offset:3072 nt
	global_load_dwordx4 v[112:115], v23, s[88:89] nt
	global_load_dwordx4 v[116:119], v23, s[88:89] offset:1024 nt
	global_load_dwordx4 v[120:123], v23, s[88:89] offset:2048 nt
	global_load_dwordx4 v[124:127], v23, s[88:89] offset:3072 nt
	s_waitcnt vmcnt(15)
	global_store_dwordx4 v22, v[64:67], s[86:87] nt
	s_waitcnt vmcnt(15)
	global_store_dwordx4 v22, v[68:71], s[86:87] offset:1024 nt
	s_waitcnt vmcnt(15)
	global_store_dwordx4 v22, v[72:75], s[86:87] offset:2048 nt
	s_waitcnt vmcnt(15)
	global_store_dwordx4 v22, v[76:79], s[86:87] offset:3072 nt
	s_waitcnt vmcnt(15)
	global_store_dwordx4 v23, v[80:83], s[86:87] nt
	s_waitcnt vmcnt(15)
	global_store_dwordx4 v23, v[84:87], s[86:87] offset:1024 nt
	s_waitcnt vmcnt(15)
	global_store_dwordx4 v23, v[88:91], s[86:87] offset:2048 nt
	s_waitcnt vmcnt(15)
	global_store_dwordx4 v23, v[92:95], s[86:87] offset:3072 nt
	s_waitcnt vmcnt(15)
	global_store_dwordx4 v22, v[96:99], s[90:91] nt
	s_waitcnt vmcnt(15)
	global_store_dwordx4 v22, v[100:103], s[90:91] offset:1024 nt
	s_waitcnt vmcnt(15)
	global_store_dwordx4 v22, v[104:107], s[90:91] offset:2048 nt
	s_waitcnt vmcnt(15)
	global_store_dwordx4 v22, v[108:111], s[90:91] offset:3072 nt
	s_waitcnt vmcnt(15)
	global_store_dwordx4 v23, v[112:115], s[90:91] nt
	s_waitcnt vmcnt(15)
	global_store_dwordx4 v23, v[116:119], s[90:91] offset:1024 nt
	s_waitcnt vmcnt(15)
	global_store_dwordx4 v23, v[120:123], s[90:91] offset:2048 nt
	s_waitcnt vmcnt(15)
	global_store_dwordx4 v23, v[124:127], s[90:91] offset:3072 nt
	s_add_i32 s80, s101, s100
	s_branch .Lcpy1p_loop
.Lcpy1p_tail:
	s_cmp_lt_u32 s80, 0x3df4
	s_cbranch_scc0 .Lcpy1p_end
	s_mul_hi_u32 s81, s80, 0x2ad5802b
	s_lshr_b32 s81, s81, 8
	s_mul_i32 s82, s81, 0x5fa
	s_sub_i32 s82, s80, s82
	s_lshl_b32 s82, s82, 13
	s_and_b32 s83, s81, 31
	s_mul_i32 s83, s83, 0xc00000
	s_add_i32 s82, s82, s83
	s_cmp_lt_u32 s81, 32
	s_cselect_b32 s84, s92, s94
	s_cselect_b32 s85, s93, s95
	s_mov_b32 s83, 0x1f210000
	s_cselect_b32 s83, 0x7210000, s83
	s_add_u32 s84, s84, s82
	s_addc_u32 s85, s85, 0
	s_add_u32 s84, s84, 0xc000
	s_addc_u32 s85, s85, 0
	s_add_u32 s83, s83, s82
	s_add_u32 s86, s98, s83
	s_addc_u32 s87, s99, 0
	global_load_dwordx4 v[64:67], v22, s[84:85] nt
	global_load_dwordx4 v[68:71], v22, s[84:85] offset:1024 nt
	global_load_dwordx4 v[72:75], v22, s[84:85] offset:2048 nt
	global_load_dwordx4 v[76:79], v22, s[84:85] offset:3072 nt
	global_load_dwordx4 v[80:83], v23, s[84:85] nt
	global_load_dwordx4 v[84:87], v23, s[84:85] offset:1024 nt
	global_load_dwordx4 v[88:91], v23, s[84:85] offset:2048 nt
	global_load_dwordx4 v[92:95], v23, s[84:85] offset:3072 nt
	s_waitcnt vmcnt(7)
	global_store_dwordx4 v22, v[64:67], s[86:87] nt
	s_waitcnt vmcnt(7)
	global_store_dwordx4 v22, v[68:71], s[86:87] offset:1024 nt
	s_waitcnt vmcnt(7)
	global_store_dwordx4 v22, v[72:75], s[86:87] offset:2048 nt
	s_waitcnt vmcnt(7)
	global_store_dwordx4 v22, v[76:79], s[86:87] offset:3072 nt
	s_waitcnt vmcnt(7)
	global_store_dwordx4 v23, v[80:83], s[86:87] nt
	s_waitcnt vmcnt(7)
	global_store_dwordx4 v23, v[84:87], s[86:87] offset:1024 nt
	s_waitcnt vmcnt(7)
	global_store_dwordx4 v23, v[88:91], s[86:87] offset:2048 nt
	s_waitcnt vmcnt(7)
	global_store_dwordx4 v23, v[92:95], s[86:87] offset:3072 nt
.Lcpy1p_end:
	v_and_b32_e32 v160, 15, v174
	v_bfe_u32 v161, v174, 4, 2
	v_lshrrev_b32_e32 v162, 6, v174
	v_and_b32_e32 v136, 63, v174
	v_readfirstlane_b32 s80, v162
	s_lshr_b32 s81, s33, 8
	s_lshr_b32 s82, s33, 3
	s_and_b32 s82, s82, 31
	s_mul_i32 s83, s80, 704
	v_lshlrev_b32_e32 v164, 4, v161
	v_mov_b32_e32 v167, 0
	s_lshl_b32 s84, s82, 5
	v_add_u32_e32 v165, s84, v160
	v_mul_u32_u24_e32 v166, 0x1600, v165
	v_add3_u32 v166, v166, v164, s83
	s_add_u32 s86, s74, 0x2c00000
	s_addc_u32 s87, s75, 0
	s_mov_b32 s88, 0x16000
	s_mov_b32 s89, 0
	v_lshl_add_u64 v[152:153], s[86:87], 0, v[166:167]
	v_lshl_add_u64 v[154:155], v[152:153], 0, s[88:89]
	s_lshl_b32 s84, s81, 5
	v_add_u32_e32 v165, s84, v160
	v_mul_u32_u24_e32 v166, 0x1600, v165
	v_add3_u32 v166, v166, v164, s83
	s_add_u32 s90, s74, 0x10980000
	s_addc_u32 s91, s75, 0
	v_lshl_add_u64 v[156:157], s[90:91], 0, v[166:167]
	v_lshl_add_u64 v[158:159], v[156:157], 0, s[88:89]
	v_mov_b32_e32 v128, 0
	v_mov_b32_e32 v129, 0
	v_mov_b32_e32 v130, 0
	v_mov_b32_e32 v131, 0
	v_mov_b32_e32 v132, 0
	v_mov_b32_e32 v133, 0
	v_mov_b32_e32 v134, 0
	v_mov_b32_e32 v135, 0
	v_mov_b32_e32 v144, 0
	v_mov_b32_e32 v145, 0
	v_mov_b32_e32 v146, 0
	v_mov_b32_e32 v147, 0
	v_mov_b32_e32 v148, 0
	v_mov_b32_e32 v149, 0
	v_mov_b32_e32 v150, 0
	v_mov_b32_e32 v151, 0
	global_load_dwordx4 v[0:3], v[152:153], off
	global_load_dwordx4 v[4:7], v[154:155], off
	global_load_dwordx4 v[8:11], v[156:157], off
	global_load_dwordx4 v[12:15], v[158:159], off
	global_load_dwordx4 v[16:19], v[152:153], off offset:64
	global_load_dwordx4 v[20:23], v[154:155], off offset:64
	global_load_dwordx4 v[24:27], v[156:157], off offset:64
	global_load_dwordx4 v[28:31], v[158:159], off offset:64
	global_load_dwordx4 v[32:35], v[152:153], off offset:128
	global_load_dwordx4 v[36:39], v[154:155], off offset:128
	global_load_dwordx4 v[40:43], v[156:157], off offset:128
	global_load_dwordx4 v[44:47], v[158:159], off offset:128
	global_load_dwordx4 v[48:51], v[152:153], off offset:192
	global_load_dwordx4 v[52:55], v[154:155], off offset:192
	global_load_dwordx4 v[56:59], v[156:157], off offset:192
	global_load_dwordx4 v[60:63], v[158:159], off offset:192
	global_load_dwordx4 v[64:67], v[152:153], off offset:256
	global_load_dwordx4 v[68:71], v[154:155], off offset:256
	global_load_dwordx4 v[72:75], v[156:157], off offset:256
	global_load_dwordx4 v[76:79], v[158:159], off offset:256
	global_load_dwordx4 v[80:83], v[152:153], off offset:320
	global_load_dwordx4 v[84:87], v[154:155], off offset:320
	global_load_dwordx4 v[88:91], v[156:157], off offset:320
	global_load_dwordx4 v[92:95], v[158:159], off offset:320
	global_load_dwordx4 v[96:99], v[152:153], off offset:384
	global_load_dwordx4 v[100:103], v[154:155], off offset:384
	global_load_dwordx4 v[104:107], v[156:157], off offset:384
	global_load_dwordx4 v[108:111], v[158:159], off offset:384
	global_load_dwordx4 v[112:115], v[152:153], off offset:448
	global_load_dwordx4 v[116:119], v[154:155], off offset:448
	global_load_dwordx4 v[120:123], v[156:157], off offset:448
	global_load_dwordx4 v[124:127], v[158:159], off offset:448
	s_waitcnt vmcnt(16)
	v_mfma_f32_16x16x32_bf16 v[128:131], v[0:3], v[8:11], v[128:131]
	v_mfma_f32_16x16x32_bf16 v[132:135], v[4:7], v[8:11], v[132:135]
	v_mfma_f32_16x16x32_bf16 v[144:147], v[0:3], v[12:15], v[144:147]
	v_mfma_f32_16x16x32_bf16 v[148:151], v[4:7], v[12:15], v[148:151]
	v_mfma_f32_16x16x32_bf16 v[128:131], v[16:19], v[24:27], v[128:131]
	v_mfma_f32_16x16x32_bf16 v[132:135], v[20:23], v[24:27], v[132:135]
	v_mfma_f32_16x16x32_bf16 v[144:147], v[16:19], v[28:31], v[144:147]
	v_mfma_f32_16x16x32_bf16 v[148:151], v[20:23], v[28:31], v[148:151]
	v_mfma_f32_16x16x32_bf16 v[128:131], v[32:35], v[40:43], v[128:131]
	v_mfma_f32_16x16x32_bf16 v[132:135], v[36:39], v[40:43], v[132:135]
	v_mfma_f32_16x16x32_bf16 v[144:147], v[32:35], v[44:47], v[144:147]
	v_mfma_f32_16x16x32_bf16 v[148:151], v[36:39], v[44:47], v[148:151]
	v_mfma_f32_16x16x32_bf16 v[128:131], v[48:51], v[56:59], v[128:131]
	v_mfma_f32_16x16x32_bf16 v[132:135], v[52:55], v[56:59], v[132:135]
	v_mfma_f32_16x16x32_bf16 v[144:147], v[48:51], v[60:63], v[144:147]
	v_mfma_f32_16x16x32_bf16 v[148:151], v[52:55], v[60:63], v[148:151]
	global_load_dwordx4 v[0:3], v[152:153], off offset:512
	global_load_dwordx4 v[4:7], v[154:155], off offset:512
	global_load_dwordx4 v[8:11], v[156:157], off offset:512
	global_load_dwordx4 v[12:15], v[158:159], off offset:512
	global_load_dwordx4 v[16:19], v[152:153], off offset:576
	global_load_dwordx4 v[20:23], v[154:155], off offset:576
	global_load_dwordx4 v[24:27], v[156:157], off offset:576
	global_load_dwordx4 v[28:31], v[158:159], off offset:576
	global_load_dwordx4 v[32:35], v[152:153], off offset:640
	global_load_dwordx4 v[36:39], v[154:155], off offset:640
	global_load_dwordx4 v[40:43], v[156:157], off offset:640
	global_load_dwordx4 v[44:47], v[158:159], off offset:640
	s_waitcnt vmcnt(12)
	v_mfma_f32_16x16x32_bf16 v[128:131], v[64:67], v[72:75], v[128:131]
	v_mfma_f32_16x16x32_bf16 v[132:135], v[68:71], v[72:75], v[132:135]
	v_mfma_f32_16x16x32_bf16 v[144:147], v[64:67], v[76:79], v[144:147]
	v_mfma_f32_16x16x32_bf16 v[148:151], v[68:71], v[76:79], v[148:151]
	v_mfma_f32_16x16x32_bf16 v[128:131], v[80:83], v[88:91], v[128:131]
	v_mfma_f32_16x16x32_bf16 v[132:135], v[84:87], v[88:91], v[132:135]
	v_mfma_f32_16x16x32_bf16 v[144:147], v[80:83], v[92:95], v[144:147]
	v_mfma_f32_16x16x32_bf16 v[148:151], v[84:87], v[92:95], v[148:151]
	v_mfma_f32_16x16x32_bf16 v[128:131], v[96:99], v[104:107], v[128:131]
	v_mfma_f32_16x16x32_bf16 v[132:135], v[100:103], v[104:107], v[132:135]
	v_mfma_f32_16x16x32_bf16 v[144:147], v[96:99], v[108:111], v[144:147]
	v_mfma_f32_16x16x32_bf16 v[148:151], v[100:103], v[108:111], v[148:151]
	v_mfma_f32_16x16x32_bf16 v[128:131], v[112:115], v[120:123], v[128:131]
	v_mfma_f32_16x16x32_bf16 v[132:135], v[116:119], v[120:123], v[132:135]
	v_mfma_f32_16x16x32_bf16 v[144:147], v[112:115], v[124:127], v[144:147]
	v_mfma_f32_16x16x32_bf16 v[148:151], v[116:119], v[124:127], v[148:151]
	s_waitcnt vmcnt(0)
	v_mfma_f32_16x16x32_bf16 v[128:131], v[0:3], v[8:11], v[128:131]
	v_mfma_f32_16x16x32_bf16 v[132:135], v[4:7], v[8:11], v[132:135]
	v_mfma_f32_16x16x32_bf16 v[144:147], v[0:3], v[12:15], v[144:147]
	v_mfma_f32_16x16x32_bf16 v[148:151], v[4:7], v[12:15], v[148:151]
	v_mfma_f32_16x16x32_bf16 v[128:131], v[16:19], v[24:27], v[128:131]
	v_mfma_f32_16x16x32_bf16 v[132:135], v[20:23], v[24:27], v[132:135]
	v_mfma_f32_16x16x32_bf16 v[144:147], v[16:19], v[28:31], v[144:147]
	v_mfma_f32_16x16x32_bf16 v[148:151], v[20:23], v[28:31], v[148:151]
	v_mfma_f32_16x16x32_bf16 v[128:131], v[32:35], v[40:43], v[128:131]
	v_mfma_f32_16x16x32_bf16 v[132:135], v[36:39], v[40:43], v[132:135]
	v_mfma_f32_16x16x32_bf16 v[144:147], v[32:35], v[44:47], v[144:147]
	v_mfma_f32_16x16x32_bf16 v[148:151], v[36:39], v[44:47], v[148:151]
	s_nop 7
	s_nop 7
	v_lshlrev_b32_e32 v170, 12, v162
	v_lshl_add_u32 v170, v136, 4, v170
	ds_write_b128 v170, v[128:131]
	ds_write_b128 v170, v[132:135] offset:1024
	ds_write_b128 v170, v[144:147] offset:2048
	ds_write_b128 v170, v[148:151] offset:3072
	s_waitcnt lgkmcnt(0)
	s_barrier
	s_cmp_ge_u32 s80, 4
	s_cbranch_scc1 .Lmg1p_end
	s_lshl_b32 s84, s80, 10
	v_lshlrev_b32_e32 v171, 4, v136
	v_add_u32_e32 v171, s84, v171
	ds_read_b128 v[0:3], v171
	ds_read_b128 v[4:7], v171 offset:4096
	ds_read_b128 v[8:11], v171 offset:8192
	ds_read_b128 v[12:15], v171 offset:12288
	ds_read_b128 v[16:19], v171 offset:16384
	ds_read_b128 v[20:23], v171 offset:20480
	ds_read_b128 v[24:27], v171 offset:24576
	ds_read_b128 v[28:31], v171 offset:28672
	s_lshr_b32 s84, s80, 1
	s_lshl_b32 s84, s84, 4
	s_lshl_b32 s85, s81, 5
	s_add_i32 s84, s84, s85
	s_addk_i32 s84, 0x4000
	s_and_b32 s85, s80, 1
	s_lshl_b32 s85, s85, 4
	s_lshl_b32 s83, s82, 5
	s_add_i32 s85, s85, s83
	v_add_u32_e32 v165, s84, v160
	v_lshl_add_u32 v164, v161, 2, s85
	v_lshlrev_b32_e32 v166, 12, v165
	v_lshl_add_u32 v166, v164, 2, v166
	v_mov_b32_e32 v167, 0
	s_add_u32 s86, s74, 0x5000000
	s_addc_u32 s87, s75, 0
	v_lshl_add_u64 v[168:169], s[86:87], 0, v[166:167]
	global_load_dwordx4 v[32:35], v[168:169], off
	v_lshrrev_b32_e32 v172, 1, v166
	v_mov_b32_e32 v173, 0
	s_add_u32 s86, s74, 0x9100000
	s_addc_u32 s87, s75, 0
	v_lshl_add_u64 v[172:173], s[86:87], 0, v[172:173]
	v_lshlrev_b32_e32 v166, 2, v165
	s_add_u32 s86, s74, 0x12b70400
	s_addc_u32 s87, s75, 0
	v_lshl_add_u64 v[166:167], s[86:87], 0, v[166:167]
	s_waitcnt lgkmcnt(0)
	v_add_f32_e32 v0, v0, v4
	v_add_f32_e32 v1, v1, v5
	v_add_f32_e32 v2, v2, v6
	v_add_f32_e32 v3, v3, v7
	v_add_f32_e32 v0, v0, v8
	v_add_f32_e32 v1, v1, v9
	v_add_f32_e32 v2, v2, v10
	v_add_f32_e32 v3, v3, v11
	v_add_f32_e32 v0, v0, v12
	v_add_f32_e32 v1, v1, v13
	v_add_f32_e32 v2, v2, v14
	v_add_f32_e32 v3, v3, v15
	v_add_f32_e32 v0, v0, v16
	v_add_f32_e32 v1, v1, v17
	v_add_f32_e32 v2, v2, v18
	v_add_f32_e32 v3, v3, v19
	v_add_f32_e32 v0, v0, v20
	v_add_f32_e32 v1, v1, v21
	v_add_f32_e32 v2, v2, v22
	v_add_f32_e32 v3, v3, v23
	v_add_f32_e32 v0, v0, v24
	v_add_f32_e32 v1, v1, v25
	v_add_f32_e32 v2, v2, v26
	v_add_f32_e32 v3, v3, v27
	v_add_f32_e32 v0, v0, v28
	v_add_f32_e32 v1, v1, v29
	v_add_f32_e32 v2, v2, v30
	v_add_f32_e32 v3, v3, v31
	s_waitcnt vmcnt(0)
	v_fma_f32 v32, v0, 0.5, v32
	v_fma_f32 v33, v1, 0.5, v33
	v_fma_f32 v34, v2, 0.5, v34
	v_fma_f32 v35, v3, 0.5, v35
	global_store_dwordx4 v[168:169], v[32:35], off
	v_cvt_pk_bf16_f32 v36, v32, v33
	v_cvt_pk_bf16_f32 v37, v34, v35
	v_mul_f32_e32 v38, v32, v32
	v_fmac_f32_e32 v38, v33, v33
	v_fmac_f32_e32 v38, v34, v34
	v_fmac_f32_e32 v38, v35, v35
	v_xor_b32_e32 v39, 16, v136
	v_lshlrev_b32_e32 v39, 2, v39
	ds_bpermute_b32 v40, v39, v38
	v_xor_b32_e32 v41, 32, v136
	v_lshlrev_b32_e32 v41, 2, v41
	s_waitcnt lgkmcnt(0)
	v_add_f32_e32 v38, v38, v40
	ds_bpermute_b32 v40, v41, v38
	s_waitcnt lgkmcnt(0)
	v_add_f32_e32 v38, v38, v40
	v_cmp_gt_u32_e64 s[82:83], 16, v136
	s_nop 1
	s_and_saveexec_b64 s[84:85], s[82:83]
	global_atomic_add_f32 v[166:167], v38, off
	s_mov_b64 exec, s[84:85]
.Lmg1p_end:
	s_barrier
.Lpre1_skip:
	v_mov_b32_e32 v8, v174
	s_cmpk_lt_i32 s2, 0x104
	s_cselect_b64 s[6:7], -1, 0
	s_cmpk_gt_i32 s2, 0x103
	v_readfirstlane_b32 s46, v8
	s_cbranch_scc1 .LBB0_227
	s_ashr_i32 s4, s2, 31
	s_lshr_b32 s4, s4, 29
	s_add_i32 s8, s2, s4
	s_and_b32 s4, s8, -8
	s_sub_i32 s9, s2, s4
	s_cmp_gt_i32 s9, -1
	s_cbranch_scc0 .LBB0_224
	s_lshl_b32 s4, s9, 5
	s_or_b32 s10, s4, 0
	s_cbranch_execz .LBB0_225
	s_branch .LBB0_226

.LBB0_243:
	ds_read_b128 v[144:147], v151
	ds_read_b128 v[156:159], v151 offset:1024
	ds_read_b128 v[160:163], v151 offset:2048
	ds_read_b128 v[164:167], v151 offset:3072
	s_add_u32 s30, s28, 0x100
	s_addc_u32 s31, s29, 0
	s_cmp_eq_u32 s82, 40
	s_cselect_b32 s37, s11, s31
	s_cselect_b32 s36, s10, s30
	s_cselect_b32 s35, s13, s81
	s_cselect_b32 s34, s12, s80
	v_lshl_add_u64 v[172:173], s[28:29], 0, v[136:137]
	s_add_i32 m0, s52, 0xc000
	ds_read_b128 v[168:171], v152
	ds_read_b128 v[176:179], v152 offset:1024
	ds_read_b128 v[180:183], v152 offset:2048
	ds_read_b128 v[184:187], v152 offset:3072
	ds_read_b128 v[188:191], v152 offset:4096
	ds_read_b128 v[192:195], v152 offset:5120
	ds_read_b128 v[196:199], v152 offset:6144
	ds_read_b128 v[200:203], v152 offset:7168
	global_load_lds_dwordx4 v[172:173], off
	v_lshl_add_u64 v[172:173], s[28:29], 0, v[138:139]
	s_add_i32 m0, s52, 0xe000
	s_nop 0
	global_load_lds_dwordx4 v[172:173], off
	s_waitcnt lgkmcnt(8)
	s_barrier
	s_waitcnt lgkmcnt(0)
	s_setprio 1
	s_waitcnt lgkmcnt(0)
	v_mfma_f32_16x16x32_bf16 v[124:127], v[144:147], v[168:171], v[124:127]
	v_mfma_f32_16x16x32_bf16 v[120:123], v[160:163], v[168:171], v[120:123]
	v_mfma_f32_16x16x32_bf16 v[108:111], v[144:147], v[180:183], v[108:111]
	v_mfma_f32_16x16x32_bf16 v[104:107], v[160:163], v[180:183], v[104:107]
	v_mfma_f32_16x16x32_bf16 v[92:95], v[144:147], v[188:191], v[92:95]
	v_mfma_f32_16x16x32_bf16 v[88:91], v[160:163], v[188:191], v[88:91]
	v_mfma_f32_16x16x32_bf16 v[76:79], v[144:147], v[196:199], v[76:79]
	v_mfma_f32_16x16x32_bf16 v[72:75], v[160:163], v[196:199], v[72:75]
	v_mfma_f32_16x16x32_bf16 v[124:127], v[156:159], v[176:179], v[124:127]
	v_mfma_f32_16x16x32_bf16 v[120:123], v[164:167], v[176:179], v[120:123]
	v_mfma_f32_16x16x32_bf16 v[108:111], v[156:159], v[184:187], v[108:111]
	v_mfma_f32_16x16x32_bf16 v[104:107], v[164:167], v[184:187], v[104:107]
	v_mfma_f32_16x16x32_bf16 v[92:95], v[156:159], v[192:195], v[92:95]
	v_mfma_f32_16x16x32_bf16 v[88:91], v[164:167], v[192:195], v[88:91]
	v_mfma_f32_16x16x32_bf16 v[76:79], v[156:159], v[200:203], v[76:79]
	v_mfma_f32_16x16x32_bf16 v[72:75], v[164:167], v[200:203], v[72:75]
	s_setprio 0
	s_barrier
	s_add_i32 s28, s65, s47
	v_lshl_add_u64 v[172:173], s[34:35], 0, v[130:131]
	s_mov_b32 m0, s28
	ds_read_b128 v[204:207], v153
	ds_read_b128 v[208:211], v153 offset:1024
	ds_read_b128 v[212:215], v153 offset:2048
	ds_read_b128 v[216:219], v153 offset:3072
	global_load_lds_dwordx4 v[172:173], off
	v_lshl_add_u64 v[220:221], s[34:35], 0, v[134:135]
	s_add_i32 m0, s28, 0x2000
	s_nop 0
	global_load_lds_dwordx4 v[220:221], off
	s_barrier
	s_waitcnt lgkmcnt(0)
	s_setprio 1
	s_waitcnt lgkmcnt(0)
	v_mfma_f32_16x16x32_bf16 v[116:119], v[204:207], v[168:171], v[116:119]
	v_mfma_f32_16x16x32_bf16 v[112:115], v[212:215], v[168:171], v[112:115]
	v_mfma_f32_16x16x32_bf16 v[100:103], v[204:207], v[180:183], v[100:103]
	v_mfma_f32_16x16x32_bf16 v[96:99], v[212:215], v[180:183], v[96:99]
	v_mfma_f32_16x16x32_bf16 v[84:87], v[204:207], v[188:191], v[84:87]
	v_mfma_f32_16x16x32_bf16 v[80:83], v[212:215], v[188:191], v[80:83]
	v_mfma_f32_16x16x32_bf16 v[68:71], v[204:207], v[196:199], v[68:71]
	v_mfma_f32_16x16x32_bf16 v[64:67], v[212:215], v[196:199], v[64:67]
	v_mfma_f32_16x16x32_bf16 v[116:119], v[208:211], v[176:179], v[116:119]
	v_mfma_f32_16x16x32_bf16 v[112:115], v[216:219], v[176:179], v[112:115]
	v_mfma_f32_16x16x32_bf16 v[100:103], v[208:211], v[184:187], v[100:103]
	v_mfma_f32_16x16x32_bf16 v[96:99], v[216:219], v[184:187], v[96:99]
	v_mfma_f32_16x16x32_bf16 v[84:87], v[208:211], v[192:195], v[84:87]
	v_mfma_f32_16x16x32_bf16 v[80:83], v[216:219], v[192:195], v[80:83]
	v_mfma_f32_16x16x32_bf16 v[68:71], v[208:211], v[200:203], v[68:71]
	v_mfma_f32_16x16x32_bf16 v[64:67], v[216:219], v[200:203], v[64:67]
	s_setprio 0
	s_mov_b32 m0, s52
	v_lshl_add_u64 v[222:223], s[36:37], 0, v[128:129]
	s_barrier
	ds_read_b128 v[168:171], v152 offset:16384
	ds_read_b128 v[176:179], v152 offset:17408
	ds_read_b128 v[180:183], v152 offset:18432
	ds_read_b128 v[184:187], v152 offset:19456
	ds_read_b128 v[188:191], v152 offset:20480
	ds_read_b128 v[192:195], v152 offset:21504
	ds_read_b128 v[196:199], v152 offset:22528
	ds_read_b128 v[200:203], v152 offset:23552
	global_load_lds_dwordx4 v[222:223], off
	v_lshl_add_u64 v[224:225], s[36:37], 0, v[132:133]
	s_mov_b32 m0, s53
	s_nop 0
	global_load_lds_dwordx4 v[224:225], off
	s_barrier
	s_waitcnt lgkmcnt(0)
	s_setprio 1
	s_waitcnt lgkmcnt(0)
	v_mfma_f32_16x16x32_bf16 v[60:63], v[144:147], v[168:171], v[60:63]
	v_mfma_f32_16x16x32_bf16 v[56:59], v[160:163], v[168:171], v[56:59]
	v_mfma_f32_16x16x32_bf16 v[44:47], v[144:147], v[180:183], v[44:47]
	v_mfma_f32_16x16x32_bf16 v[40:43], v[160:163], v[180:183], v[40:43]
	v_mfma_f32_16x16x32_bf16 v[28:31], v[144:147], v[188:191], v[28:31]
	v_mfma_f32_16x16x32_bf16 v[24:27], v[160:163], v[188:191], v[24:27]
	v_mfma_f32_16x16x32_bf16 v[12:15], v[144:147], v[196:199], v[12:15]
	v_mfma_f32_16x16x32_bf16 v[8:11], v[160:163], v[196:199], v[8:11]
	v_mfma_f32_16x16x32_bf16 v[60:63], v[156:159], v[176:179], v[60:63]
	v_mfma_f32_16x16x32_bf16 v[56:59], v[164:167], v[176:179], v[56:59]
	v_mfma_f32_16x16x32_bf16 v[44:47], v[156:159], v[184:187], v[44:47]
	v_mfma_f32_16x16x32_bf16 v[40:43], v[164:167], v[184:187], v[40:43]
	v_mfma_f32_16x16x32_bf16 v[28:31], v[156:159], v[192:195], v[28:31]
	v_mfma_f32_16x16x32_bf16 v[24:27], v[164:167], v[192:195], v[24:27]
	v_mfma_f32_16x16x32_bf16 v[12:15], v[156:159], v[200:203], v[12:15]
	v_mfma_f32_16x16x32_bf16 v[8:11], v[164:167], v[200:203], v[8:11]
	s_setprio 0
	s_barrier
	s_add_u32 s28, s34, 0xb0000
	s_addc_u32 s29, s35, 0
	s_add_i32 s83, s66, s47
	v_lshl_add_u64 v[144:145], s[28:29], 0, v[130:131]
	s_mov_b32 m0, s83
	s_nop 0
	global_load_lds_dwordx4 v[144:145], off
	v_lshl_add_u64 v[144:145], s[28:29], 0, v[134:135]
	s_add_i32 m0, s83, 0x2000
	s_nop 0
	global_load_lds_dwordx4 v[144:145], off
	s_waitcnt vmcnt(6)
	s_barrier
	s_setprio 1
	v_mfma_f32_16x16x32_bf16 v[52:55], v[204:207], v[168:171], v[52:55]
	v_mfma_f32_16x16x32_bf16 v[48:51], v[212:215], v[168:171], v[48:51]
	v_mfma_f32_16x16x32_bf16 v[36:39], v[204:207], v[180:183], v[36:39]
	v_mfma_f32_16x16x32_bf16 v[32:35], v[212:215], v[180:183], v[32:35]
	v_mfma_f32_16x16x32_bf16 v[20:23], v[204:207], v[188:191], v[20:23]
	v_mfma_f32_16x16x32_bf16 v[16:19], v[212:215], v[188:191], v[16:19]
	v_mfma_f32_16x16x32_bf16 v[4:7], v[204:207], v[196:199], v[4:7]
	v_mfma_f32_16x16x32_bf16 v[0:3], v[212:215], v[196:199], v[0:3]
	v_mfma_f32_16x16x32_bf16 v[52:55], v[208:211], v[176:179], v[52:55]
	v_mfma_f32_16x16x32_bf16 v[48:51], v[216:219], v[176:179], v[48:51]
	v_mfma_f32_16x16x32_bf16 v[36:39], v[208:211], v[184:187], v[36:39]
	v_mfma_f32_16x16x32_bf16 v[32:35], v[216:219], v[184:187], v[32:35]
	v_mfma_f32_16x16x32_bf16 v[20:23], v[208:211], v[192:195], v[20:23]
	v_mfma_f32_16x16x32_bf16 v[16:19], v[216:219], v[192:195], v[16:19]
	v_mfma_f32_16x16x32_bf16 v[4:7], v[208:211], v[200:203], v[4:7]
	v_mfma_f32_16x16x32_bf16 v[0:3], v[216:219], v[200:203], v[0:3]
	s_setprio 0
	s_add_i32 s83, 0, 0x18000
	v_add_u32_e32 v155, s83, v149
	s_barrier
	ds_read_b128 v[144:147], v155
	ds_read_b128 v[156:159], v155 offset:1024
	ds_read_b128 v[160:163], v155 offset:2048
	ds_read_b128 v[164:167], v155 offset:3072
	s_add_u32 s28, s36, 0xb0000
	s_addc_u32 s29, s37, 0
	s_mov_b32 m0, s54
	v_lshl_add_u64 v[204:205], s[28:29], 0, v[128:129]
	ds_read_b128 v[168:171], v152 offset:32768
	ds_read_b128 v[176:179], v152 offset:33792
	ds_read_b128 v[180:183], v152 offset:34816
	ds_read_b128 v[184:187], v152 offset:35840
	ds_read_b128 v[188:191], v152 offset:36864
	ds_read_b128 v[192:195], v152 offset:37888
	ds_read_b128 v[196:199], v152 offset:38912
	ds_read_b128 v[200:203], v152 offset:39936
	global_load_lds_dwordx4 v[204:205], off
	v_lshl_add_u64 v[204:205], s[28:29], 0, v[132:133]
	s_mov_b32 m0, s55
	s_nop 0
	global_load_lds_dwordx4 v[204:205], off
	s_waitcnt lgkmcnt(8)
	s_barrier
	s_waitcnt lgkmcnt(0)
	s_setprio 1
	s_waitcnt lgkmcnt(0)
	v_mfma_f32_16x16x32_bf16 v[124:127], v[144:147], v[168:171], v[124:127]
	v_mfma_f32_16x16x32_bf16 v[120:123], v[160:163], v[168:171], v[120:123]
	v_mfma_f32_16x16x32_bf16 v[108:111], v[144:147], v[180:183], v[108:111]
	v_mfma_f32_16x16x32_bf16 v[104:107], v[160:163], v[180:183], v[104:107]
	v_mfma_f32_16x16x32_bf16 v[92:95], v[144:147], v[188:191], v[92:95]
	v_mfma_f32_16x16x32_bf16 v[88:91], v[160:163], v[188:191], v[88:91]
	v_mfma_f32_16x16x32_bf16 v[76:79], v[144:147], v[196:199], v[76:79]
	v_mfma_f32_16x16x32_bf16 v[72:75], v[160:163], v[196:199], v[72:75]
	v_mfma_f32_16x16x32_bf16 v[124:127], v[156:159], v[176:179], v[124:127]
	v_mfma_f32_16x16x32_bf16 v[120:123], v[164:167], v[176:179], v[120:123]
	v_mfma_f32_16x16x32_bf16 v[108:111], v[156:159], v[184:187], v[108:111]
	v_mfma_f32_16x16x32_bf16 v[104:107], v[164:167], v[184:187], v[104:107]
	v_mfma_f32_16x16x32_bf16 v[92:95], v[156:159], v[192:195], v[92:95]
	v_mfma_f32_16x16x32_bf16 v[88:91], v[164:167], v[192:195], v[88:91]
	v_mfma_f32_16x16x32_bf16 v[76:79], v[156:159], v[200:203], v[76:79]
	v_mfma_f32_16x16x32_bf16 v[72:75], v[164:167], v[200:203], v[72:75]
	s_setprio 0
	s_barrier
	s_add_i32 s36, 0, 0x1c000
	s_add_i32 s28, s83, s47
	v_add_u32_e32 v155, s36, v149
	v_lshl_add_u64 v[172:173], v[172:173], 0, s[24:25]
	s_mov_b32 m0, s28
	ds_read_b128 v[204:207], v155
	ds_read_b128 v[208:211], v155 offset:1024
	ds_read_b128 v[212:215], v155 offset:2048
	ds_read_b128 v[216:219], v155 offset:3072
	global_load_lds_dwordx4 v[172:173], off
	v_lshl_add_u64 v[172:173], v[220:221], 0, s[24:25]
	s_add_i32 m0, s28, 0x2000
	s_nop 0
	global_load_lds_dwordx4 v[172:173], off
	s_barrier
	s_waitcnt lgkmcnt(0)
	s_setprio 1
	s_waitcnt lgkmcnt(0)
	v_mfma_f32_16x16x32_bf16 v[116:119], v[204:207], v[168:171], v[116:119]
	v_mfma_f32_16x16x32_bf16 v[112:115], v[212:215], v[168:171], v[112:115]
	v_mfma_f32_16x16x32_bf16 v[100:103], v[204:207], v[180:183], v[100:103]
	v_mfma_f32_16x16x32_bf16 v[96:99], v[212:215], v[180:183], v[96:99]
	v_mfma_f32_16x16x32_bf16 v[84:87], v[204:207], v[188:191], v[84:87]
	v_mfma_f32_16x16x32_bf16 v[80:83], v[212:215], v[188:191], v[80:83]
	v_mfma_f32_16x16x32_bf16 v[68:71], v[204:207], v[196:199], v[68:71]
	v_mfma_f32_16x16x32_bf16 v[64:67], v[212:215], v[196:199], v[64:67]
	v_mfma_f32_16x16x32_bf16 v[116:119], v[208:211], v[176:179], v[116:119]
	v_mfma_f32_16x16x32_bf16 v[112:115], v[216:219], v[176:179], v[112:115]
	v_mfma_f32_16x16x32_bf16 v[100:103], v[208:211], v[184:187], v[100:103]
	v_mfma_f32_16x16x32_bf16 v[96:99], v[216:219], v[184:187], v[96:99]
	v_mfma_f32_16x16x32_bf16 v[84:87], v[208:211], v[192:195], v[84:87]
	v_mfma_f32_16x16x32_bf16 v[80:83], v[216:219], v[192:195], v[80:83]
	v_mfma_f32_16x16x32_bf16 v[68:71], v[208:211], v[200:203], v[68:71]
	v_mfma_f32_16x16x32_bf16 v[64:67], v[216:219], v[200:203], v[64:67]
	s_setprio 0
	s_mov_b32 m0, s57
	v_lshl_add_u64 v[172:173], v[222:223], 0, s[24:25]
	s_barrier
	ds_read_b128 v[168:171], v152 offset:49152
	ds_read_b128 v[176:179], v152 offset:50176
	ds_read_b128 v[180:183], v152 offset:51200
	ds_read_b128 v[184:187], v152 offset:52224
	ds_read_b128 v[188:191], v152 offset:53248
	ds_read_b128 v[192:195], v152 offset:54272
	ds_read_b128 v[196:199], v152 offset:55296
	ds_read_b128 v[200:203], v152 offset:56320
	global_load_lds_dwordx4 v[172:173], off
	v_lshl_add_u64 v[172:173], v[224:225], 0, s[24:25]
	s_mov_b32 m0, s62
	s_nop 0
	global_load_lds_dwordx4 v[172:173], off
	s_barrier
	s_waitcnt lgkmcnt(0)
	s_setprio 1
	s_waitcnt lgkmcnt(0)
	v_mfma_f32_16x16x32_bf16 v[60:63], v[144:147], v[168:171], v[60:63]
	v_mfma_f32_16x16x32_bf16 v[56:59], v[160:163], v[168:171], v[56:59]
	v_mfma_f32_16x16x32_bf16 v[44:47], v[144:147], v[180:183], v[44:47]
	v_mfma_f32_16x16x32_bf16 v[40:43], v[160:163], v[180:183], v[40:43]
	v_mfma_f32_16x16x32_bf16 v[28:31], v[144:147], v[188:191], v[28:31]
	v_mfma_f32_16x16x32_bf16 v[24:27], v[160:163], v[188:191], v[24:27]
	v_mfma_f32_16x16x32_bf16 v[12:15], v[144:147], v[196:199], v[12:15]
	v_mfma_f32_16x16x32_bf16 v[8:11], v[160:163], v[196:199], v[8:11]
	v_mfma_f32_16x16x32_bf16 v[60:63], v[156:159], v[176:179], v[60:63]
	v_mfma_f32_16x16x32_bf16 v[56:59], v[164:167], v[176:179], v[56:59]
	v_mfma_f32_16x16x32_bf16 v[44:47], v[156:159], v[184:187], v[44:47]
	v_mfma_f32_16x16x32_bf16 v[40:43], v[164:167], v[184:187], v[40:43]
	v_mfma_f32_16x16x32_bf16 v[28:31], v[156:159], v[192:195], v[28:31]
	v_mfma_f32_16x16x32_bf16 v[24:27], v[164:167], v[192:195], v[24:27]
	v_mfma_f32_16x16x32_bf16 v[12:15], v[156:159], v[200:203], v[12:15]
	v_mfma_f32_16x16x32_bf16 v[8:11], v[164:167], v[200:203], v[8:11]
	s_setprio 0
	s_barrier
	s_add_u32 s28, s34, 0xb0080
	s_addc_u32 s29, s35, 0
	s_add_i32 s34, s36, s47
	v_lshl_add_u64 v[144:145], s[28:29], 0, v[130:131]
	s_mov_b32 m0, s34
	s_nop 0
	global_load_lds_dwordx4 v[144:145], off
	v_lshl_add_u64 v[144:145], s[28:29], 0, v[134:135]
	s_add_i32 m0, s34, 0x2000
	s_nop 0
	global_load_lds_dwordx4 v[144:145], off
	s_waitcnt vmcnt(6)
	s_barrier
	s_setprio 1
	v_mfma_f32_16x16x32_bf16 v[52:55], v[204:207], v[168:171], v[52:55]
	v_mfma_f32_16x16x32_bf16 v[48:51], v[212:215], v[168:171], v[48:51]
	v_mfma_f32_16x16x32_bf16 v[36:39], v[204:207], v[180:183], v[36:39]
	v_mfma_f32_16x16x32_bf16 v[32:35], v[212:215], v[180:183], v[32:35]
	v_mfma_f32_16x16x32_bf16 v[20:23], v[204:207], v[188:191], v[20:23]
	v_mfma_f32_16x16x32_bf16 v[16:19], v[212:215], v[188:191], v[16:19]
	v_mfma_f32_16x16x32_bf16 v[4:7], v[204:207], v[196:199], v[4:7]
	v_mfma_f32_16x16x32_bf16 v[0:3], v[212:215], v[196:199], v[0:3]
	v_mfma_f32_16x16x32_bf16 v[52:55], v[208:211], v[176:179], v[52:55]
	v_mfma_f32_16x16x32_bf16 v[48:51], v[216:219], v[176:179], v[48:51]
	v_mfma_f32_16x16x32_bf16 v[36:39], v[208:211], v[184:187], v[36:39]
	v_mfma_f32_16x16x32_bf16 v[32:35], v[216:219], v[184:187], v[32:35]
	v_mfma_f32_16x16x32_bf16 v[20:23], v[208:211], v[192:195], v[20:23]
	v_mfma_f32_16x16x32_bf16 v[16:19], v[216:219], v[192:195], v[16:19]
	v_mfma_f32_16x16x32_bf16 v[4:7], v[208:211], v[200:203], v[4:7]
	v_mfma_f32_16x16x32_bf16 v[0:3], v[216:219], v[200:203], v[0:3]
	s_setprio 0
	s_add_i32 s82, s82, 2
	s_add_u32 s80, s80, 0x100
	s_addc_u32 s81, s81, 0
	s_cmp_gt_u32 s82, 41
	s_mov_b64 s[28:29], s[30:31]
	s_barrier
	s_cbranch_scc0 .LBB0_243
	s_nop 7
	s_nop 7
	v_and_b32_e32 v160, 15, v174
	v_bfe_u32 v161, v174, 4, 2
	v_lshrrev_b32_e32 v162, 6, v174
	v_lshrrev_b32_e32 v163, 2, v162
	v_and_b32_e32 v164, 3, v162
	v_and_b32_e32 v170, 63, v174
	s_lshr_b32 s80, s33, 3
	s_and_b32 s81, s80, 7
	s_lshl_b32 s81, s81, 3
	s_lshr_b32 s82, s80, 3
	s_and_b32 s82, s82, 7
	s_add_i32 s81, s81, s82
	s_lshr_b32 s82, s80, 6
	v_lshl_add_u32 v165, v163, 6, v160
	s_lshl_b32 s83, s81, 8
	v_add_u32_e32 v165, s83, v165
	v_lshlrev_b32_e32 v166, 3, v161
	v_lshl_add_u32 v166, v164, 5, v166
	s_lshl_b32 s83, s82, 8
	v_add_u32_e32 v166, s83, v166
	v_lshlrev_b32_e32 v168, 12, v165
	v_lshl_add_u32 v168, v166, 2, v168
	v_mov_b32_e32 v169, 0
	s_add_u32 s84, s74, 0x5000000
	s_addc_u32 s85, s75, 0
	v_lshl_add_u64 v[210:211], s[84:85], 0, v[168:169]
	v_lshrrev_b32_e32 v168, 1, v168
	s_add_u32 s84, s74, 0x9100000
	s_addc_u32 s85, s75, 0
	v_lshl_add_u64 v[212:213], s[84:85], 0, v[168:169]
	v_lshlrev_b32_e32 v168, 2, v165
	s_add_u32 s84, s74, 0x12b70400
	s_addc_u32 s85, s75, 0
	v_lshl_add_u64 v[214:215], s[84:85], 0, v[168:169]
	v_xor_b32_e32 v171, 16, v170
	v_lshlrev_b32_e32 v171, 2, v171
	v_xor_b32_e32 v172, 32, v170
	v_lshlrev_b32_e32 v172, 2, v172
	v_cmp_eq_u32_e64 s[86:87], 0, v161
	s_mov_b32 s85, 0
	s_mov_b32 s89, 0
	s_mov_b32 s84, 0x0
	v_lshl_add_u64 v[216:217], s[84:85], 0, v[210:211]
	global_load_dwordx4 v[128:131], v[216:217], off
	global_load_dwordx4 v[132:135], v[216:217], off offset:16
	global_load_dwordx4 v[136:139], v[216:217], off offset:512
	global_load_dwordx4 v[140:143], v[216:217], off offset:528
	s_mov_b32 s84, 0x10000
	v_lshl_add_u64 v[216:217], s[84:85], 0, v[210:211]
	global_load_dwordx4 v[144:147], v[216:217], off
	global_load_dwordx4 v[148:151], v[216:217], off offset:16
	global_load_dwordx4 v[152:155], v[216:217], off offset:512
	global_load_dwordx4 v[156:159], v[216:217], off offset:528
	s_mov_b32 s84, 0x20000
	v_lshl_add_u64 v[216:217], s[84:85], 0, v[210:211]
	global_load_dwordx4 v[178:181], v[216:217], off
	global_load_dwordx4 v[182:185], v[216:217], off offset:16
	global_load_dwordx4 v[186:189], v[216:217], off offset:512
	global_load_dwordx4 v[190:193], v[216:217], off offset:528
	s_mov_b32 s84, 0x30000
	v_lshl_add_u64 v[216:217], s[84:85], 0, v[210:211]
	global_load_dwordx4 v[194:197], v[216:217], off
	global_load_dwordx4 v[198:201], v[216:217], off offset:16
	global_load_dwordx4 v[202:205], v[216:217], off offset:512
	global_load_dwordx4 v[206:209], v[216:217], off offset:528
	s_waitcnt vmcnt(0)
	s_mov_b32 s84, 0x0
	v_lshl_add_u64 v[216:217], s[84:85], 0, v[210:211]
	v_pk_fma_f32 v[128:129], v[124:125], 0.5, v[128:129] op_sel_hi:[1,0,1]
	v_pk_fma_f32 v[130:131], v[126:127], 0.5, v[130:131] op_sel_hi:[1,0,1]
	v_pk_fma_f32 v[132:133], v[120:121], 0.5, v[132:133] op_sel_hi:[1,0,1]
	v_pk_fma_f32 v[134:135], v[122:123], 0.5, v[134:135] op_sel_hi:[1,0,1]
	global_store_dwordx4 v[216:217], v[128:131], off
	global_store_dwordx4 v[216:217], v[132:135], off offset:16
	v_mul_f32_e32 v220, v128, v128
	v_fmac_f32_e32 v220, v129, v129
	v_fmac_f32_e32 v220, v130, v130
	v_fmac_f32_e32 v220, v131, v131
	v_fmac_f32_e32 v220, v132, v132
	v_fmac_f32_e32 v220, v133, v133
	v_fmac_f32_e32 v220, v134, v134
	v_fmac_f32_e32 v220, v135, v135
	v_pk_fma_f32 v[136:137], v[116:117], 0.5, v[136:137] op_sel_hi:[1,0,1]
	v_pk_fma_f32 v[138:139], v[118:119], 0.5, v[138:139] op_sel_hi:[1,0,1]
	v_pk_fma_f32 v[140:141], v[112:113], 0.5, v[140:141] op_sel_hi:[1,0,1]
	v_pk_fma_f32 v[142:143], v[114:115], 0.5, v[142:143] op_sel_hi:[1,0,1]
	global_store_dwordx4 v[216:217], v[136:139], off offset:512
	global_store_dwordx4 v[216:217], v[140:143], off offset:528
	v_fmac_f32_e32 v220, v136, v136
	v_fmac_f32_e32 v220, v137, v137
	v_fmac_f32_e32 v220, v138, v138
	v_fmac_f32_e32 v220, v139, v139
	v_fmac_f32_e32 v220, v140, v140
	v_fmac_f32_e32 v220, v141, v141
	v_fmac_f32_e32 v220, v142, v142
	v_fmac_f32_e32 v220, v143, v143
	s_mov_b32 s84, 0x10000
	v_lshl_add_u64 v[216:217], s[84:85], 0, v[210:211]
	v_pk_fma_f32 v[144:145], v[108:109], 0.5, v[144:145] op_sel_hi:[1,0,1]
	v_pk_fma_f32 v[146:147], v[110:111], 0.5, v[146:147] op_sel_hi:[1,0,1]
	v_pk_fma_f32 v[148:149], v[104:105], 0.5, v[148:149] op_sel_hi:[1,0,1]
	v_pk_fma_f32 v[150:151], v[106:107], 0.5, v[150:151] op_sel_hi:[1,0,1]
	global_store_dwordx4 v[216:217], v[144:147], off
	global_store_dwordx4 v[216:217], v[148:151], off offset:16
	v_mul_f32_e32 v221, v144, v144
	v_fmac_f32_e32 v221, v145, v145
	v_fmac_f32_e32 v221, v146, v146
	v_fmac_f32_e32 v221, v147, v147
	v_fmac_f32_e32 v221, v148, v148
	v_fmac_f32_e32 v221, v149, v149
	v_fmac_f32_e32 v221, v150, v150
	v_fmac_f32_e32 v221, v151, v151
	v_pk_fma_f32 v[152:153], v[100:101], 0.5, v[152:153] op_sel_hi:[1,0,1]
	v_pk_fma_f32 v[154:155], v[102:103], 0.5, v[154:155] op_sel_hi:[1,0,1]
	v_pk_fma_f32 v[156:157], v[96:97], 0.5, v[156:157] op_sel_hi:[1,0,1]
	v_pk_fma_f32 v[158:159], v[98:99], 0.5, v[158:159] op_sel_hi:[1,0,1]
	global_store_dwordx4 v[216:217], v[152:155], off offset:512
	global_store_dwordx4 v[216:217], v[156:159], off offset:528
	v_fmac_f32_e32 v221, v152, v152
	v_fmac_f32_e32 v221, v153, v153
	v_fmac_f32_e32 v221, v154, v154
	v_fmac_f32_e32 v221, v155, v155
	v_fmac_f32_e32 v221, v156, v156
	v_fmac_f32_e32 v221, v157, v157
	v_fmac_f32_e32 v221, v158, v158
	v_fmac_f32_e32 v221, v159, v159
	s_mov_b32 s84, 0x20000
	v_lshl_add_u64 v[216:217], s[84:85], 0, v[210:211]
	v_pk_fma_f32 v[178:179], v[92:93], 0.5, v[178:179] op_sel_hi:[1,0,1]
	v_pk_fma_f32 v[180:181], v[94:95], 0.5, v[180:181] op_sel_hi:[1,0,1]
	v_pk_fma_f32 v[182:183], v[88:89], 0.5, v[182:183] op_sel_hi:[1,0,1]
	v_pk_fma_f32 v[184:185], v[90:91], 0.5, v[184:185] op_sel_hi:[1,0,1]
	global_store_dwordx4 v[216:217], v[178:181], off
	global_store_dwordx4 v[216:217], v[182:185], off offset:16
	v_mul_f32_e32 v222, v178, v178
	v_fmac_f32_e32 v222, v179, v179
	v_fmac_f32_e32 v222, v180, v180
	v_fmac_f32_e32 v222, v181, v181
	v_fmac_f32_e32 v222, v182, v182
	v_fmac_f32_e32 v222, v183, v183
	v_fmac_f32_e32 v222, v184, v184
	v_fmac_f32_e32 v222, v185, v185
	v_pk_fma_f32 v[186:187], v[84:85], 0.5, v[186:187] op_sel_hi:[1,0,1]
	v_pk_fma_f32 v[188:189], v[86:87], 0.5, v[188:189] op_sel_hi:[1,0,1]
	v_pk_fma_f32 v[190:191], v[80:81], 0.5, v[190:191] op_sel_hi:[1,0,1]
	v_pk_fma_f32 v[192:193], v[82:83], 0.5, v[192:193] op_sel_hi:[1,0,1]
	global_store_dwordx4 v[216:217], v[186:189], off offset:512
	global_store_dwordx4 v[216:217], v[190:193], off offset:528
	v_fmac_f32_e32 v222, v186, v186
	v_fmac_f32_e32 v222, v187, v187
	v_fmac_f32_e32 v222, v188, v188
	v_fmac_f32_e32 v222, v189, v189
	v_fmac_f32_e32 v222, v190, v190
	v_fmac_f32_e32 v222, v191, v191
	v_fmac_f32_e32 v222, v192, v192
	v_fmac_f32_e32 v222, v193, v193
	s_mov_b32 s84, 0x30000
	v_lshl_add_u64 v[216:217], s[84:85], 0, v[210:211]
	v_pk_fma_f32 v[194:195], v[76:77], 0.5, v[194:195] op_sel_hi:[1,0,1]
	v_pk_fma_f32 v[196:197], v[78:79], 0.5, v[196:197] op_sel_hi:[1,0,1]
	v_pk_fma_f32 v[198:199], v[72:73], 0.5, v[198:199] op_sel_hi:[1,0,1]
	v_pk_fma_f32 v[200:201], v[74:75], 0.5, v[200:201] op_sel_hi:[1,0,1]
	global_store_dwordx4 v[216:217], v[194:197], off
	global_store_dwordx4 v[216:217], v[198:201], off offset:16
	v_mul_f32_e32 v223, v194, v194
	v_fmac_f32_e32 v223, v195, v195
	v_fmac_f32_e32 v223, v196, v196
	v_fmac_f32_e32 v223, v197, v197
	v_fmac_f32_e32 v223, v198, v198
	v_fmac_f32_e32 v223, v199, v199
	v_fmac_f32_e32 v223, v200, v200
	v_fmac_f32_e32 v223, v201, v201
	v_pk_fma_f32 v[202:203], v[68:69], 0.5, v[202:203] op_sel_hi:[1,0,1]
	v_pk_fma_f32 v[204:205], v[70:71], 0.5, v[204:205] op_sel_hi:[1,0,1]
	v_pk_fma_f32 v[206:207], v[64:65], 0.5, v[206:207] op_sel_hi:[1,0,1]
	v_pk_fma_f32 v[208:209], v[66:67], 0.5, v[208:209] op_sel_hi:[1,0,1]
	global_store_dwordx4 v[216:217], v[202:205], off offset:512
	global_store_dwordx4 v[216:217], v[206:209], off offset:528
	v_fmac_f32_e32 v223, v202, v202
	v_fmac_f32_e32 v223, v203, v203
	v_fmac_f32_e32 v223, v204, v204
	v_fmac_f32_e32 v223, v205, v205
	v_fmac_f32_e32 v223, v206, v206
	v_fmac_f32_e32 v223, v207, v207
	v_fmac_f32_e32 v223, v208, v208
	v_fmac_f32_e32 v223, v209, v209
	ds_bpermute_b32 v224, v171, v220
	ds_bpermute_b32 v225, v171, v221
	ds_bpermute_b32 v226, v171, v222
	ds_bpermute_b32 v227, v171, v223
	s_waitcnt lgkmcnt(0)
	v_add_f32_e32 v220, v220, v224
	v_add_f32_e32 v221, v221, v225
	v_add_f32_e32 v222, v222, v226
	v_add_f32_e32 v223, v223, v227
	ds_bpermute_b32 v224, v172, v220
	ds_bpermute_b32 v225, v172, v221
	ds_bpermute_b32 v226, v172, v222
	ds_bpermute_b32 v227, v172, v223
	s_waitcnt lgkmcnt(0)
	v_add_f32_e32 v220, v220, v224
	v_add_f32_e32 v221, v221, v225
	v_add_f32_e32 v222, v222, v226
	v_add_f32_e32 v223, v223, v227
	s_and_saveexec_b64 s[90:91], s[86:87]
	global_atomic_add_f32 v[214:215], v220, off
	global_atomic_add_f32 v[214:215], v221, off offset:64
	global_atomic_add_f32 v[214:215], v222, off offset:128
	global_atomic_add_f32 v[214:215], v223, off offset:192
	s_mov_b64 exec, s[90:91]
	s_mov_b32 s84, 0x80000
	v_lshl_add_u64 v[216:217], s[84:85], 0, v[210:211]
	global_load_dwordx4 v[128:131], v[216:217], off
	global_load_dwordx4 v[132:135], v[216:217], off offset:16
	global_load_dwordx4 v[136:139], v[216:217], off offset:512
	global_load_dwordx4 v[140:143], v[216:217], off offset:528
	s_mov_b32 s84, 0x90000
	v_lshl_add_u64 v[216:217], s[84:85], 0, v[210:211]
	global_load_dwordx4 v[144:147], v[216:217], off
	global_load_dwordx4 v[148:151], v[216:217], off offset:16
	global_load_dwordx4 v[152:155], v[216:217], off offset:512
	global_load_dwordx4 v[156:159], v[216:217], off offset:528
	s_mov_b32 s84, 0xa0000
	v_lshl_add_u64 v[216:217], s[84:85], 0, v[210:211]
	global_load_dwordx4 v[178:181], v[216:217], off
	global_load_dwordx4 v[182:185], v[216:217], off offset:16
	global_load_dwordx4 v[186:189], v[216:217], off offset:512
	global_load_dwordx4 v[190:193], v[216:217], off offset:528
	s_mov_b32 s84, 0xb0000
	v_lshl_add_u64 v[216:217], s[84:85], 0, v[210:211]
	global_load_dwordx4 v[194:197], v[216:217], off
	global_load_dwordx4 v[198:201], v[216:217], off offset:16
	global_load_dwordx4 v[202:205], v[216:217], off offset:512
	global_load_dwordx4 v[206:209], v[216:217], off offset:528
	s_waitcnt vmcnt(0)
	s_mov_b32 s84, 0x80000
	v_lshl_add_u64 v[216:217], s[84:85], 0, v[210:211]
	v_pk_fma_f32 v[128:129], v[60:61], 0.5, v[128:129] op_sel_hi:[1,0,1]
	v_pk_fma_f32 v[130:131], v[62:63], 0.5, v[130:131] op_sel_hi:[1,0,1]
	v_pk_fma_f32 v[132:133], v[56:57], 0.5, v[132:133] op_sel_hi:[1,0,1]
	v_pk_fma_f32 v[134:135], v[58:59], 0.5, v[134:135] op_sel_hi:[1,0,1]
	global_store_dwordx4 v[216:217], v[128:131], off
	global_store_dwordx4 v[216:217], v[132:135], off offset:16
	v_mul_f32_e32 v220, v128, v128
	v_fmac_f32_e32 v220, v129, v129
	v_fmac_f32_e32 v220, v130, v130
	v_fmac_f32_e32 v220, v131, v131
	v_fmac_f32_e32 v220, v132, v132
	v_fmac_f32_e32 v220, v133, v133
	v_fmac_f32_e32 v220, v134, v134
	v_fmac_f32_e32 v220, v135, v135
	v_pk_fma_f32 v[136:137], v[52:53], 0.5, v[136:137] op_sel_hi:[1,0,1]
	v_pk_fma_f32 v[138:139], v[54:55], 0.5, v[138:139] op_sel_hi:[1,0,1]
	v_pk_fma_f32 v[140:141], v[48:49], 0.5, v[140:141] op_sel_hi:[1,0,1]
	v_pk_fma_f32 v[142:143], v[50:51], 0.5, v[142:143] op_sel_hi:[1,0,1]
	global_store_dwordx4 v[216:217], v[136:139], off offset:512
	global_store_dwordx4 v[216:217], v[140:143], off offset:528
	v_fmac_f32_e32 v220, v136, v136
	v_fmac_f32_e32 v220, v137, v137
	v_fmac_f32_e32 v220, v138, v138
	v_fmac_f32_e32 v220, v139, v139
	v_fmac_f32_e32 v220, v140, v140
	v_fmac_f32_e32 v220, v141, v141
	v_fmac_f32_e32 v220, v142, v142
	v_fmac_f32_e32 v220, v143, v143
	s_mov_b32 s84, 0x90000
	v_lshl_add_u64 v[216:217], s[84:85], 0, v[210:211]
	v_pk_fma_f32 v[144:145], v[44:45], 0.5, v[144:145] op_sel_hi:[1,0,1]
	v_pk_fma_f32 v[146:147], v[46:47], 0.5, v[146:147] op_sel_hi:[1,0,1]
	v_pk_fma_f32 v[148:149], v[40:41], 0.5, v[148:149] op_sel_hi:[1,0,1]
	v_pk_fma_f32 v[150:151], v[42:43], 0.5, v[150:151] op_sel_hi:[1,0,1]
	global_store_dwordx4 v[216:217], v[144:147], off
	global_store_dwordx4 v[216:217], v[148:151], off offset:16
	v_mul_f32_e32 v221, v144, v144
	v_fmac_f32_e32 v221, v145, v145
	v_fmac_f32_e32 v221, v146, v146
	v_fmac_f32_e32 v221, v147, v147
	v_fmac_f32_e32 v221, v148, v148
	v_fmac_f32_e32 v221, v149, v149
	v_fmac_f32_e32 v221, v150, v150
	v_fmac_f32_e32 v221, v151, v151
	v_pk_fma_f32 v[152:153], v[36:37], 0.5, v[152:153] op_sel_hi:[1,0,1]
	v_pk_fma_f32 v[154:155], v[38:39], 0.5, v[154:155] op_sel_hi:[1,0,1]
	v_pk_fma_f32 v[156:157], v[32:33], 0.5, v[156:157] op_sel_hi:[1,0,1]
	v_pk_fma_f32 v[158:159], v[34:35], 0.5, v[158:159] op_sel_hi:[1,0,1]
	global_store_dwordx4 v[216:217], v[152:155], off offset:512
	global_store_dwordx4 v[216:217], v[156:159], off offset:528
	v_fmac_f32_e32 v221, v152, v152
	v_fmac_f32_e32 v221, v153, v153
	v_fmac_f32_e32 v221, v154, v154
	v_fmac_f32_e32 v221, v155, v155
	v_fmac_f32_e32 v221, v156, v156
	v_fmac_f32_e32 v221, v157, v157
	v_fmac_f32_e32 v221, v158, v158
	v_fmac_f32_e32 v221, v159, v159
	s_mov_b32 s84, 0xa0000
	v_lshl_add_u64 v[216:217], s[84:85], 0, v[210:211]
	v_pk_fma_f32 v[178:179], v[28:29], 0.5, v[178:179] op_sel_hi:[1,0,1]
	v_pk_fma_f32 v[180:181], v[30:31], 0.5, v[180:181] op_sel_hi:[1,0,1]
	v_pk_fma_f32 v[182:183], v[24:25], 0.5, v[182:183] op_sel_hi:[1,0,1]
	v_pk_fma_f32 v[184:185], v[26:27], 0.5, v[184:185] op_sel_hi:[1,0,1]
	global_store_dwordx4 v[216:217], v[178:181], off
	global_store_dwordx4 v[216:217], v[182:185], off offset:16
	v_mul_f32_e32 v222, v178, v178
	v_fmac_f32_e32 v222, v179, v179
	v_fmac_f32_e32 v222, v180, v180
	v_fmac_f32_e32 v222, v181, v181
	v_fmac_f32_e32 v222, v182, v182
	v_fmac_f32_e32 v222, v183, v183
	v_fmac_f32_e32 v222, v184, v184
	v_fmac_f32_e32 v222, v185, v185
	v_pk_fma_f32 v[186:187], v[20:21], 0.5, v[186:187] op_sel_hi:[1,0,1]
	v_pk_fma_f32 v[188:189], v[22:23], 0.5, v[188:189] op_sel_hi:[1,0,1]
	v_pk_fma_f32 v[190:191], v[16:17], 0.5, v[190:191] op_sel_hi:[1,0,1]
	v_pk_fma_f32 v[192:193], v[18:19], 0.5, v[192:193] op_sel_hi:[1,0,1]
	global_store_dwordx4 v[216:217], v[186:189], off offset:512
	global_store_dwordx4 v[216:217], v[190:193], off offset:528
	v_fmac_f32_e32 v222, v186, v186
	v_fmac_f32_e32 v222, v187, v187
	v_fmac_f32_e32 v222, v188, v188
	v_fmac_f32_e32 v222, v189, v189
	v_fmac_f32_e32 v222, v190, v190
	v_fmac_f32_e32 v222, v191, v191
	v_fmac_f32_e32 v222, v192, v192
	v_fmac_f32_e32 v222, v193, v193
	s_mov_b32 s84, 0xb0000
	v_lshl_add_u64 v[216:217], s[84:85], 0, v[210:211]
	v_pk_fma_f32 v[194:195], v[12:13], 0.5, v[194:195] op_sel_hi:[1,0,1]
	v_pk_fma_f32 v[196:197], v[14:15], 0.5, v[196:197] op_sel_hi:[1,0,1]
	v_pk_fma_f32 v[198:199], v[8:9], 0.5, v[198:199] op_sel_hi:[1,0,1]
	v_pk_fma_f32 v[200:201], v[10:11], 0.5, v[200:201] op_sel_hi:[1,0,1]
	global_store_dwordx4 v[216:217], v[194:197], off
	global_store_dwordx4 v[216:217], v[198:201], off offset:16
	v_mul_f32_e32 v223, v194, v194
	v_fmac_f32_e32 v223, v195, v195
	v_fmac_f32_e32 v223, v196, v196
	v_fmac_f32_e32 v223, v197, v197
	v_fmac_f32_e32 v223, v198, v198
	v_fmac_f32_e32 v223, v199, v199
	v_fmac_f32_e32 v223, v200, v200
	v_fmac_f32_e32 v223, v201, v201
	v_pk_fma_f32 v[202:203], v[4:5], 0.5, v[202:203] op_sel_hi:[1,0,1]
	v_pk_fma_f32 v[204:205], v[6:7], 0.5, v[204:205] op_sel_hi:[1,0,1]
	v_pk_fma_f32 v[206:207], v[0:1], 0.5, v[206:207] op_sel_hi:[1,0,1]
	v_pk_fma_f32 v[208:209], v[2:3], 0.5, v[208:209] op_sel_hi:[1,0,1]
	global_store_dwordx4 v[216:217], v[202:205], off offset:512
	global_store_dwordx4 v[216:217], v[206:209], off offset:528
	v_fmac_f32_e32 v223, v202, v202
	v_fmac_f32_e32 v223, v203, v203
	v_fmac_f32_e32 v223, v204, v204
	v_fmac_f32_e32 v223, v205, v205
	v_fmac_f32_e32 v223, v206, v206
	v_fmac_f32_e32 v223, v207, v207
	v_fmac_f32_e32 v223, v208, v208
	v_fmac_f32_e32 v223, v209, v209
	ds_bpermute_b32 v224, v171, v220
	ds_bpermute_b32 v225, v171, v221
	ds_bpermute_b32 v226, v171, v222
	ds_bpermute_b32 v227, v171, v223
	s_waitcnt lgkmcnt(0)
	v_add_f32_e32 v220, v220, v224
	v_add_f32_e32 v221, v221, v225
	v_add_f32_e32 v222, v222, v226
	v_add_f32_e32 v223, v223, v227
	ds_bpermute_b32 v224, v172, v220
	ds_bpermute_b32 v225, v172, v221
	ds_bpermute_b32 v226, v172, v222
	ds_bpermute_b32 v227, v172, v223
	s_waitcnt lgkmcnt(0)
	v_add_f32_e32 v220, v220, v224
	v_add_f32_e32 v221, v221, v225
	v_add_f32_e32 v222, v222, v226
	v_add_f32_e32 v223, v223, v227
	s_and_saveexec_b64 s[90:91], s[86:87]
	global_atomic_add_f32 v[214:215], v220, off offset:512
	global_atomic_add_f32 v[214:215], v221, off offset:576
	global_atomic_add_f32 v[214:215], v222, off offset:640
	global_atomic_add_f32 v[214:215], v223, off offset:704
	s_mov_b64 exec, s[90:91]

.LBB0_263:
	s_and_b32 s80, s33, 64
	s_cmp_lg_u32 s80, 0
	s_cbranch_scc1 .Lpost1_skip
	v_and_b32_e32 v160, 15, v174
	v_bfe_u32 v161, v174, 4, 2
	v_lshrrev_b32_e32 v162, 6, v174
	v_and_b32_e32 v136, 63, v174
	v_readfirstlane_b32 s80, v162
	s_lshr_b32 s81, s33, 8
	s_lshr_b32 s82, s33, 3
	s_and_b32 s82, s82, 31
	s_mul_i32 s83, s80, 704
	v_lshlrev_b32_e32 v164, 4, v161
	v_mov_b32_e32 v167, 0
	s_lshl_b32 s84, s82, 5
	v_add_u32_e32 v165, s84, v160
	v_mul_u32_u24_e32 v166, 0x1600, v165
	v_add3_u32 v166, v166, v164, s83
	s_add_u32 s86, s74, 0x2c00000
	s_addc_u32 s87, s75, 0
	s_mov_b32 s88, 0x16000
	s_mov_b32 s89, 0
	v_lshl_add_u64 v[152:153], s[86:87], 0, v[166:167]
	v_lshl_add_u64 v[154:155], v[152:153], 0, s[88:89]
	s_lshl_b32 s84, s81, 5
	v_add_u32_e32 v165, s84, v160
	v_mul_u32_u24_e32 v166, 0x1600, v165
	v_add3_u32 v166, v166, v164, s83
	s_add_u32 s90, s74, 0x10980000
	s_addc_u32 s91, s75, 0
	v_lshl_add_u64 v[156:157], s[90:91], 0, v[166:167]
	v_lshl_add_u64 v[158:159], v[156:157], 0, s[88:89]
	v_mov_b32_e32 v128, 0
	v_mov_b32_e32 v129, 0
	v_mov_b32_e32 v130, 0
	v_mov_b32_e32 v131, 0
	v_mov_b32_e32 v132, 0
	v_mov_b32_e32 v133, 0
	v_mov_b32_e32 v134, 0
	v_mov_b32_e32 v135, 0
	v_mov_b32_e32 v144, 0
	v_mov_b32_e32 v145, 0
	v_mov_b32_e32 v146, 0
	v_mov_b32_e32 v147, 0
	v_mov_b32_e32 v148, 0
	v_mov_b32_e32 v149, 0
	v_mov_b32_e32 v150, 0
	v_mov_b32_e32 v151, 0
	global_load_dwordx4 v[0:3], v[152:153], off
	global_load_dwordx4 v[4:7], v[154:155], off
	global_load_dwordx4 v[8:11], v[156:157], off
	global_load_dwordx4 v[12:15], v[158:159], off
	global_load_dwordx4 v[16:19], v[152:153], off offset:64
	global_load_dwordx4 v[20:23], v[154:155], off offset:64
	global_load_dwordx4 v[24:27], v[156:157], off offset:64
	global_load_dwordx4 v[28:31], v[158:159], off offset:64
	global_load_dwordx4 v[32:35], v[152:153], off offset:128
	global_load_dwordx4 v[36:39], v[154:155], off offset:128
	global_load_dwordx4 v[40:43], v[156:157], off offset:128
	global_load_dwordx4 v[44:47], v[158:159], off offset:128
	global_load_dwordx4 v[48:51], v[152:153], off offset:192
	global_load_dwordx4 v[52:55], v[154:155], off offset:192
	global_load_dwordx4 v[56:59], v[156:157], off offset:192
	global_load_dwordx4 v[60:63], v[158:159], off offset:192
	global_load_dwordx4 v[64:67], v[152:153], off offset:256
	global_load_dwordx4 v[68:71], v[154:155], off offset:256
	global_load_dwordx4 v[72:75], v[156:157], off offset:256
	global_load_dwordx4 v[76:79], v[158:159], off offset:256
	global_load_dwordx4 v[80:83], v[152:153], off offset:320
	global_load_dwordx4 v[84:87], v[154:155], off offset:320
	global_load_dwordx4 v[88:91], v[156:157], off offset:320
	global_load_dwordx4 v[92:95], v[158:159], off offset:320
	global_load_dwordx4 v[96:99], v[152:153], off offset:384
	global_load_dwordx4 v[100:103], v[154:155], off offset:384
	global_load_dwordx4 v[104:107], v[156:157], off offset:384
	global_load_dwordx4 v[108:111], v[158:159], off offset:384
	global_load_dwordx4 v[112:115], v[152:153], off offset:448
	global_load_dwordx4 v[116:119], v[154:155], off offset:448
	global_load_dwordx4 v[120:123], v[156:157], off offset:448
	global_load_dwordx4 v[124:127], v[158:159], off offset:448
	s_waitcnt vmcnt(16)
	v_mfma_f32_16x16x32_bf16 v[128:131], v[0:3], v[8:11], v[128:131]
	v_mfma_f32_16x16x32_bf16 v[132:135], v[4:7], v[8:11], v[132:135]
	v_mfma_f32_16x16x32_bf16 v[144:147], v[0:3], v[12:15], v[144:147]
	v_mfma_f32_16x16x32_bf16 v[148:151], v[4:7], v[12:15], v[148:151]
	v_mfma_f32_16x16x32_bf16 v[128:131], v[16:19], v[24:27], v[128:131]
	v_mfma_f32_16x16x32_bf16 v[132:135], v[20:23], v[24:27], v[132:135]
	v_mfma_f32_16x16x32_bf16 v[144:147], v[16:19], v[28:31], v[144:147]
	v_mfma_f32_16x16x32_bf16 v[148:151], v[20:23], v[28:31], v[148:151]
	v_mfma_f32_16x16x32_bf16 v[128:131], v[32:35], v[40:43], v[128:131]
	v_mfma_f32_16x16x32_bf16 v[132:135], v[36:39], v[40:43], v[132:135]
	v_mfma_f32_16x16x32_bf16 v[144:147], v[32:35], v[44:47], v[144:147]
	v_mfma_f32_16x16x32_bf16 v[148:151], v[36:39], v[44:47], v[148:151]
	v_mfma_f32_16x16x32_bf16 v[128:131], v[48:51], v[56:59], v[128:131]
	v_mfma_f32_16x16x32_bf16 v[132:135], v[52:55], v[56:59], v[132:135]
	v_mfma_f32_16x16x32_bf16 v[144:147], v[48:51], v[60:63], v[144:147]
	v_mfma_f32_16x16x32_bf16 v[148:151], v[52:55], v[60:63], v[148:151]
	global_load_dwordx4 v[0:3], v[152:153], off offset:512
	global_load_dwordx4 v[4:7], v[154:155], off offset:512
	global_load_dwordx4 v[8:11], v[156:157], off offset:512
	global_load_dwordx4 v[12:15], v[158:159], off offset:512
	global_load_dwordx4 v[16:19], v[152:153], off offset:576
	global_load_dwordx4 v[20:23], v[154:155], off offset:576
	global_load_dwordx4 v[24:27], v[156:157], off offset:576
	global_load_dwordx4 v[28:31], v[158:159], off offset:576
	global_load_dwordx4 v[32:35], v[152:153], off offset:640
	global_load_dwordx4 v[36:39], v[154:155], off offset:640
	global_load_dwordx4 v[40:43], v[156:157], off offset:640
	global_load_dwordx4 v[44:47], v[158:159], off offset:640
	s_waitcnt vmcnt(12)
	v_mfma_f32_16x16x32_bf16 v[128:131], v[64:67], v[72:75], v[128:131]
	v_mfma_f32_16x16x32_bf16 v[132:135], v[68:71], v[72:75], v[132:135]
	v_mfma_f32_16x16x32_bf16 v[144:147], v[64:67], v[76:79], v[144:147]
	v_mfma_f32_16x16x32_bf16 v[148:151], v[68:71], v[76:79], v[148:151]
	v_mfma_f32_16x16x32_bf16 v[128:131], v[80:83], v[88:91], v[128:131]
	v_mfma_f32_16x16x32_bf16 v[132:135], v[84:87], v[88:91], v[132:135]
	v_mfma_f32_16x16x32_bf16 v[144:147], v[80:83], v[92:95], v[144:147]
	v_mfma_f32_16x16x32_bf16 v[148:151], v[84:87], v[92:95], v[148:151]
	v_mfma_f32_16x16x32_bf16 v[128:131], v[96:99], v[104:107], v[128:131]
	v_mfma_f32_16x16x32_bf16 v[132:135], v[100:103], v[104:107], v[132:135]
	v_mfma_f32_16x16x32_bf16 v[144:147], v[96:99], v[108:111], v[144:147]
	v_mfma_f32_16x16x32_bf16 v[148:151], v[100:103], v[108:111], v[148:151]
	v_mfma_f32_16x16x32_bf16 v[128:131], v[112:115], v[120:123], v[128:131]
	v_mfma_f32_16x16x32_bf16 v[132:135], v[116:119], v[120:123], v[132:135]
	v_mfma_f32_16x16x32_bf16 v[144:147], v[112:115], v[124:127], v[144:147]
	v_mfma_f32_16x16x32_bf16 v[148:151], v[116:119], v[124:127], v[148:151]
	s_waitcnt vmcnt(0)
	v_mfma_f32_16x16x32_bf16 v[128:131], v[0:3], v[8:11], v[128:131]
	v_mfma_f32_16x16x32_bf16 v[132:135], v[4:7], v[8:11], v[132:135]
	v_mfma_f32_16x16x32_bf16 v[144:147], v[0:3], v[12:15], v[144:147]
	v_mfma_f32_16x16x32_bf16 v[148:151], v[4:7], v[12:15], v[148:151]
	v_mfma_f32_16x16x32_bf16 v[128:131], v[16:19], v[24:27], v[128:131]
	v_mfma_f32_16x16x32_bf16 v[132:135], v[20:23], v[24:27], v[132:135]
	v_mfma_f32_16x16x32_bf16 v[144:147], v[16:19], v[28:31], v[144:147]
	v_mfma_f32_16x16x32_bf16 v[148:151], v[20:23], v[28:31], v[148:151]
	v_mfma_f32_16x16x32_bf16 v[128:131], v[32:35], v[40:43], v[128:131]
	v_mfma_f32_16x16x32_bf16 v[132:135], v[36:39], v[40:43], v[132:135]
	v_mfma_f32_16x16x32_bf16 v[144:147], v[32:35], v[44:47], v[144:147]
	v_mfma_f32_16x16x32_bf16 v[148:151], v[36:39], v[44:47], v[148:151]
	s_nop 7
	s_nop 7
	v_lshlrev_b32_e32 v170, 12, v162
	v_lshl_add_u32 v170, v136, 4, v170
	ds_write_b128 v170, v[128:131]
	ds_write_b128 v170, v[132:135] offset:1024
	ds_write_b128 v170, v[144:147] offset:2048
	ds_write_b128 v170, v[148:151] offset:3072
	s_waitcnt lgkmcnt(0)
	s_barrier
	s_cmp_ge_u32 s80, 4
	s_cbranch_scc1 .Lmg1_end
	s_lshl_b32 s84, s80, 10
	v_lshlrev_b32_e32 v171, 4, v136
	v_add_u32_e32 v171, s84, v171
	ds_read_b128 v[0:3], v171
	ds_read_b128 v[4:7], v171 offset:4096
	ds_read_b128 v[8:11], v171 offset:8192
	ds_read_b128 v[12:15], v171 offset:12288
	ds_read_b128 v[16:19], v171 offset:16384
	ds_read_b128 v[20:23], v171 offset:20480
	ds_read_b128 v[24:27], v171 offset:24576
	ds_read_b128 v[28:31], v171 offset:28672
	s_lshr_b32 s84, s80, 1
	s_lshl_b32 s84, s84, 4
	s_lshl_b32 s85, s81, 5
	s_add_i32 s84, s84, s85
	s_addk_i32 s84, 0x4000
	s_and_b32 s85, s80, 1
	s_lshl_b32 s85, s85, 4
	s_lshl_b32 s83, s82, 5
	s_add_i32 s85, s85, s83
	v_add_u32_e32 v165, s84, v160
	v_lshl_add_u32 v164, v161, 2, s85
	v_lshlrev_b32_e32 v166, 12, v165
	v_lshl_add_u32 v166, v164, 2, v166
	v_mov_b32_e32 v167, 0
	s_add_u32 s86, s74, 0x5000000
	s_addc_u32 s87, s75, 0
	v_lshl_add_u64 v[168:169], s[86:87], 0, v[166:167]
	global_load_dwordx4 v[32:35], v[168:169], off
	v_lshrrev_b32_e32 v172, 1, v166
	v_mov_b32_e32 v173, 0
	s_add_u32 s86, s74, 0x9100000
	s_addc_u32 s87, s75, 0
	v_lshl_add_u64 v[172:173], s[86:87], 0, v[172:173]
	v_lshlrev_b32_e32 v166, 2, v165
	s_add_u32 s86, s74, 0x12b70400
	s_addc_u32 s87, s75, 0
	v_lshl_add_u64 v[166:167], s[86:87], 0, v[166:167]
	s_waitcnt lgkmcnt(0)
	v_add_f32_e32 v0, v0, v4
	v_add_f32_e32 v1, v1, v5
	v_add_f32_e32 v2, v2, v6
	v_add_f32_e32 v3, v3, v7
	v_add_f32_e32 v0, v0, v8
	v_add_f32_e32 v1, v1, v9
	v_add_f32_e32 v2, v2, v10
	v_add_f32_e32 v3, v3, v11
	v_add_f32_e32 v0, v0, v12
	v_add_f32_e32 v1, v1, v13
	v_add_f32_e32 v2, v2, v14
	v_add_f32_e32 v3, v3, v15
	v_add_f32_e32 v0, v0, v16
	v_add_f32_e32 v1, v1, v17
	v_add_f32_e32 v2, v2, v18
	v_add_f32_e32 v3, v3, v19
	v_add_f32_e32 v0, v0, v20
	v_add_f32_e32 v1, v1, v21
	v_add_f32_e32 v2, v2, v22
	v_add_f32_e32 v3, v3, v23
	v_add_f32_e32 v0, v0, v24
	v_add_f32_e32 v1, v1, v25
	v_add_f32_e32 v2, v2, v26
	v_add_f32_e32 v3, v3, v27
	v_add_f32_e32 v0, v0, v28
	v_add_f32_e32 v1, v1, v29
	v_add_f32_e32 v2, v2, v30
	v_add_f32_e32 v3, v3, v31
	s_waitcnt vmcnt(0)
	v_fma_f32 v32, v0, 0.5, v32
	v_fma_f32 v33, v1, 0.5, v33
	v_fma_f32 v34, v2, 0.5, v34
	v_fma_f32 v35, v3, 0.5, v35
	global_store_dwordx4 v[168:169], v[32:35], off
	v_cvt_pk_bf16_f32 v36, v32, v33
	v_cvt_pk_bf16_f32 v37, v34, v35
	v_mul_f32_e32 v38, v32, v32
	v_fmac_f32_e32 v38, v33, v33
	v_fmac_f32_e32 v38, v34, v34
	v_fmac_f32_e32 v38, v35, v35
	v_xor_b32_e32 v39, 16, v136
	v_lshlrev_b32_e32 v39, 2, v39
	ds_bpermute_b32 v40, v39, v38
	v_xor_b32_e32 v41, 32, v136
	v_lshlrev_b32_e32 v41, 2, v41
	s_waitcnt lgkmcnt(0)
	v_add_f32_e32 v38, v38, v40
	ds_bpermute_b32 v40, v41, v38
	s_waitcnt lgkmcnt(0)
	v_add_f32_e32 v38, v38, v40
	v_cmp_gt_u32_e64 s[82:83], 16, v136
	s_nop 1
	s_and_saveexec_b64 s[84:85], s[82:83]
	global_atomic_add_f32 v[166:167], v38, off
	s_mov_b64 exec, s[84:85]
.Lmg1_end:
	v_lshrrev_b32_e32 v21, 6, v174
	v_and_b32_e32 v22, 63, v174
	v_lshlrev_b32_e32 v22, 4, v22
	v_readfirstlane_b32 s80, v21
	v_add_u32_e32 v23, 0x1000, v22
	v_readfirstlane_b32 s92, v235
	v_readfirstlane_b32 s93, v236
	v_readfirstlane_b32 s94, v237
	v_readfirstlane_b32 s95, v238
	v_readfirstlane_b32 s98, v239
	v_readfirstlane_b32 s99, v240
	s_lshr_b32 s100, s33, 7
	s_lshl_b32 s100, s100, 3
	s_lshr_b32 s101, s33, 3
	s_and_b32 s101, s101, 7
	s_add_i32 s100, s100, s101
	s_lshl_b32 s100, s100, 3
	s_add_i32 s80, s80, s100
	s_add_i32 s80, s80, 0x3df4
	s_movk_i32 s100, 0x400

.Lcpy1_end:
.Lpost1_skip:
	v_cvt_f32_u32_e32 v176, s78
	s_waitcnt vmcnt(0)
	s_waitcnt lgkmcnt(0)
	s_barrier
	s_and_saveexec_b64 s[6:7], s[0:1]
	s_cbranch_execz .LBB0_283
	v_rcp_iflag_f32_e32 v0, v176
	s_sub_i32 s4, 0, s78
	s_mov_b64 s[8:9], exec
	buffer_wbl2 sc1
	s_waitcnt vmcnt(0)
	v_mul_f32_e32 v0, 0x4f7ffffe, v0
	v_cvt_u32_f32_e32 v0, v0
	s_waitcnt vmcnt(0)
	v_mbcnt_lo_u32_b32 v1, s8, 0
	s_lshl_b32 s5, s78, 1
	v_readfirstlane_b32 s10, v0
	s_mul_i32 s4, s4, s10
	s_mul_hi_u32 s4, s10, s4
	s_add_i32 s10, s10, s4
	v_mbcnt_hi_u32_b32 v0, s9, v1
	s_mul_hi_u32 s4, s5, s10
	v_cmp_eq_u32_e32 vcc, 0, v0
	s_and_saveexec_b64 s[10:11], vcc
	s_cbranch_execz .LBB0_266
	s_bcnt1_i32_b64 s8, s[8:9]
	v_mov_b32_e32 v1, 0
	v_mov_b32_e32 v2, s8
	global_atomic_add v1, v1, v2, s[96:97] sc0

.LBB0_472:
	s_or_b64 exec, exec, s[8:9]
	v_readlane_b32 s4, v234, 2
	v_mov_b32_e32 v8, v174
	v_readlane_b32 s5, v234, 3
	s_barrier
	s_and_b32 s80, s33, 64
	s_cmp_eq_u32 s80, 0
	s_cbranch_scc1 .Lpre2_skip
	v_lshrrev_b32_e32 v21, 6, v174
	v_and_b32_e32 v22, 63, v174
	v_lshlrev_b32_e32 v22, 4, v22
	v_readfirstlane_b32 s80, v21
	v_add_u32_e32 v23, 0x1000, v22
	v_readfirstlane_b32 s92, v235
	v_readfirstlane_b32 s93, v236
	v_readfirstlane_b32 s94, v237
	v_readfirstlane_b32 s95, v238
	v_readfirstlane_b32 s98, v239
	v_readfirstlane_b32 s99, v240
	s_lshr_b32 s100, s33, 7
	s_lshl_b32 s100, s100, 3
	s_lshr_b32 s101, s33, 3
	s_and_b32 s101, s101, 7
	s_add_i32 s100, s100, s101
	s_lshl_b32 s100, s100, 3
	s_add_i32 s80, s80, s100
	s_add_i32 s80, s80, 0x9650
	s_movk_i32 s100, 0x400
.Lcpy2p_loop:
	s_add_i32 s101, s80, s100
	s_cmp_lt_u32 s101, 0xb504
	s_cbranch_scc0 .Lcpy2p_tail
	s_mul_hi_u32 s81, s80, 0x2ad5802b
	s_lshr_b32 s81, s81, 8
	s_mul_i32 s82, s81, 0x5fa
	s_sub_i32 s82, s80, s82
	s_lshl_b32 s82, s82, 13
	s_and_b32 s83, s81, 31
	s_mul_i32 s83, s83, 0xc00000
	s_add_i32 s82, s82, s83
	s_cmp_lt_u32 s81, 32
	s_cselect_b32 s84, s92, s94
	s_cselect_b32 s85, s93, s95
	s_mov_b32 s83, 0x1f210000
	s_cselect_b32 s83, 0x7210000, s83
	s_add_u32 s84, s84, s82
	s_addc_u32 s85, s85, 0
	s_add_u32 s84, s84, 0xc000
	s_addc_u32 s85, s85, 0
	s_add_u32 s83, s83, s82
	s_add_u32 s86, s98, s83
	s_addc_u32 s87, s99, 0
	s_mul_hi_u32 s81, s101, 0x2ad5802b
	s_lshr_b32 s81, s81, 8
	s_mul_i32 s82, s81, 0x5fa
	s_sub_i32 s82, s101, s82
	s_lshl_b32 s82, s82, 13
	s_and_b32 s83, s81, 31
	s_mul_i32 s83, s83, 0xc00000
	s_add_i32 s82, s82, s83
	s_cmp_lt_u32 s81, 32
	s_cselect_b32 s88, s92, s94
	s_cselect_b32 s89, s93, s95
	s_mov_b32 s83, 0x1f210000
	s_cselect_b32 s83, 0x7210000, s83
	s_add_u32 s88, s88, s82
	s_addc_u32 s89, s89, 0
	s_add_u32 s88, s88, 0xc000
	s_addc_u32 s89, s89, 0
	s_add_u32 s83, s83, s82
	s_add_u32 s90, s98, s83
	s_addc_u32 s91, s99, 0
	global_load_dwordx4 v[64:67], v22, s[84:85] nt
	global_load_dwordx4 v[68:71], v22, s[84:85] offset:1024 nt
	global_load_dwordx4 v[72:75], v22, s[84:85] offset:2048 nt
	global_load_dwordx4 v[76:79], v22, s[84:85] offset:3072 nt
	global_load_dwordx4 v[80:83], v23, s[84:85] nt
	global_load_dwordx4 v[84:87], v23, s[84:85] offset:1024 nt
	global_load_dwordx4 v[88:91], v23, s[84:85] offset:2048 nt
	global_load_dwordx4 v[92:95], v23, s[84:85] offset:3072 nt
	global_load_dwordx4 v[96:99], v22, s[88:89] nt
	global_load_dwordx4 v[100:103], v22, s[88:89] offset:1024 nt
	global_load_dwordx4 v[104:107], v22, s[88:89] offset:2048 nt
	global_load_dwordx4 v[108:111], v22, s[88:89] offset:3072 nt
	global_load_dwordx4 v[112:115], v23, s[88:89] nt
	global_load_dwordx4 v[116:119], v23, s[88:89] offset:1024 nt
	global_load_dwordx4 v[120:123], v23, s[88:89] offset:2048 nt
	global_load_dwordx4 v[124:127], v23, s[88:89] offset:3072 nt
	s_waitcnt vmcnt(15)
	global_store_dwordx4 v22, v[64:67], s[86:87] nt
	s_waitcnt vmcnt(15)
	global_store_dwordx4 v22, v[68:71], s[86:87] offset:1024 nt
	s_waitcnt vmcnt(15)
	global_store_dwordx4 v22, v[72:75], s[86:87] offset:2048 nt
	s_waitcnt vmcnt(15)
	global_store_dwordx4 v22, v[76:79], s[86:87] offset:3072 nt
	s_waitcnt vmcnt(15)
	global_store_dwordx4 v23, v[80:83], s[86:87] nt
	s_waitcnt vmcnt(15)
	global_store_dwordx4 v23, v[84:87], s[86:87] offset:1024 nt
	s_waitcnt vmcnt(15)
	global_store_dwordx4 v23, v[88:91], s[86:87] offset:2048 nt
	s_waitcnt vmcnt(15)
	global_store_dwordx4 v23, v[92:95], s[86:87] offset:3072 nt
	s_waitcnt vmcnt(15)
	global_store_dwordx4 v22, v[96:99], s[90:91] nt
	s_waitcnt vmcnt(15)
	global_store_dwordx4 v22, v[100:103], s[90:91] offset:1024 nt
	s_waitcnt vmcnt(15)
	global_store_dwordx4 v22, v[104:107], s[90:91] offset:2048 nt
	s_waitcnt vmcnt(15)
	global_store_dwordx4 v22, v[108:111], s[90:91] offset:3072 nt
	s_waitcnt vmcnt(15)
	global_store_dwordx4 v23, v[112:115], s[90:91] nt
	s_waitcnt vmcnt(15)
	global_store_dwordx4 v23, v[116:119], s[90:91] offset:1024 nt
	s_waitcnt vmcnt(15)
	global_store_dwordx4 v23, v[120:123], s[90:91] offset:2048 nt
	s_waitcnt vmcnt(15)
	global_store_dwordx4 v23, v[124:127], s[90:91] offset:3072 nt
	s_add_i32 s80, s101, s100
	s_branch .Lcpy2p_loop
.Lcpy2p_tail:
	s_cmp_lt_u32 s80, 0xb504
	s_cbranch_scc0 .Lcpy2p_end
	s_mul_hi_u32 s81, s80, 0x2ad5802b
	s_lshr_b32 s81, s81, 8
	s_mul_i32 s82, s81, 0x5fa
	s_sub_i32 s82, s80, s82
	s_lshl_b32 s82, s82, 13
	s_and_b32 s83, s81, 31
	s_mul_i32 s83, s83, 0xc00000
	s_add_i32 s82, s82, s83
	s_cmp_lt_u32 s81, 32
	s_cselect_b32 s84, s92, s94
	s_cselect_b32 s85, s93, s95
	s_mov_b32 s83, 0x1f210000
	s_cselect_b32 s83, 0x7210000, s83
	s_add_u32 s84, s84, s82
	s_addc_u32 s85, s85, 0
	s_add_u32 s84, s84, 0xc000
	s_addc_u32 s85, s85, 0
	s_add_u32 s83, s83, s82
	s_add_u32 s86, s98, s83
	s_addc_u32 s87, s99, 0
	global_load_dwordx4 v[64:67], v22, s[84:85] nt
	global_load_dwordx4 v[68:71], v22, s[84:85] offset:1024 nt
	global_load_dwordx4 v[72:75], v22, s[84:85] offset:2048 nt
	global_load_dwordx4 v[76:79], v22, s[84:85] offset:3072 nt
	global_load_dwordx4 v[80:83], v23, s[84:85] nt
	global_load_dwordx4 v[84:87], v23, s[84:85] offset:1024 nt
	global_load_dwordx4 v[88:91], v23, s[84:85] offset:2048 nt
	global_load_dwordx4 v[92:95], v23, s[84:85] offset:3072 nt
	s_waitcnt vmcnt(7)
	global_store_dwordx4 v22, v[64:67], s[86:87] nt
	s_waitcnt vmcnt(7)
	global_store_dwordx4 v22, v[68:71], s[86:87] offset:1024 nt
	s_waitcnt vmcnt(7)
	global_store_dwordx4 v22, v[72:75], s[86:87] offset:2048 nt
	s_waitcnt vmcnt(7)
	global_store_dwordx4 v22, v[76:79], s[86:87] offset:3072 nt
	s_waitcnt vmcnt(7)
	global_store_dwordx4 v23, v[80:83], s[86:87] nt
	s_waitcnt vmcnt(7)
	global_store_dwordx4 v23, v[84:87], s[86:87] offset:1024 nt
	s_waitcnt vmcnt(7)
	global_store_dwordx4 v23, v[88:91], s[86:87] offset:2048 nt
	s_waitcnt vmcnt(7)
	global_store_dwordx4 v23, v[92:95], s[86:87] offset:3072 nt
.Lcpy2p_end:
	v_and_b32_e32 v160, 15, v174
	v_bfe_u32 v161, v174, 4, 2
	v_lshrrev_b32_e32 v162, 6, v174
	v_and_b32_e32 v136, 63, v174
	v_readfirstlane_b32 s80, v162
	s_lshr_b32 s81, s33, 8
	s_lshr_b32 s82, s33, 3
	s_and_b32 s82, s82, 31
	s_mul_i32 s83, s80, 704
	v_lshlrev_b32_e32 v164, 4, v161
	v_mov_b32_e32 v167, 0
	s_lshl_b32 s84, s82, 5
	v_add_u32_e32 v165, s84, v160
	v_mul_u32_u24_e32 v166, 0x1600, v165
	v_add3_u32 v166, v166, v164, s83
	s_add_u32 s86, s74, 0x3700000
	s_addc_u32 s87, s75, 0
	s_mov_b32 s88, 0x16000
	s_mov_b32 s89, 0
	v_lshl_add_u64 v[152:153], s[86:87], 0, v[166:167]
	v_lshl_add_u64 v[154:155], v[152:153], 0, s[88:89]
	s_lshl_b32 s84, s81, 5
	v_add_u32_e32 v165, s84, v160
	v_mul_u32_u24_e32 v166, 0x1600, v165
	v_add3_u32 v166, v166, v164, s83
	s_add_u32 s90, s74, 0x10980000
	s_addc_u32 s91, s75, 0
	v_lshl_add_u64 v[156:157], s[90:91], 0, v[166:167]
	v_lshl_add_u64 v[158:159], v[156:157], 0, s[88:89]
	v_mov_b32_e32 v128, 0
	v_mov_b32_e32 v129, 0
	v_mov_b32_e32 v130, 0
	v_mov_b32_e32 v131, 0
	v_mov_b32_e32 v132, 0
	v_mov_b32_e32 v133, 0
	v_mov_b32_e32 v134, 0
	v_mov_b32_e32 v135, 0
	v_mov_b32_e32 v144, 0
	v_mov_b32_e32 v145, 0
	v_mov_b32_e32 v146, 0
	v_mov_b32_e32 v147, 0
	v_mov_b32_e32 v148, 0
	v_mov_b32_e32 v149, 0
	v_mov_b32_e32 v150, 0
	v_mov_b32_e32 v151, 0
	global_load_dwordx4 v[0:3], v[152:153], off
	global_load_dwordx4 v[4:7], v[154:155], off
	global_load_dwordx4 v[8:11], v[156:157], off
	global_load_dwordx4 v[12:15], v[158:159], off
	global_load_dwordx4 v[16:19], v[152:153], off offset:64
	global_load_dwordx4 v[20:23], v[154:155], off offset:64
	global_load_dwordx4 v[24:27], v[156:157], off offset:64
	global_load_dwordx4 v[28:31], v[158:159], off offset:64
	global_load_dwordx4 v[32:35], v[152:153], off offset:128
	global_load_dwordx4 v[36:39], v[154:155], off offset:128
	global_load_dwordx4 v[40:43], v[156:157], off offset:128
	global_load_dwordx4 v[44:47], v[158:159], off offset:128
	global_load_dwordx4 v[48:51], v[152:153], off offset:192
	global_load_dwordx4 v[52:55], v[154:155], off offset:192
	global_load_dwordx4 v[56:59], v[156:157], off offset:192
	global_load_dwordx4 v[60:63], v[158:159], off offset:192
	global_load_dwordx4 v[64:67], v[152:153], off offset:256
	global_load_dwordx4 v[68:71], v[154:155], off offset:256
	global_load_dwordx4 v[72:75], v[156:157], off offset:256
	global_load_dwordx4 v[76:79], v[158:159], off offset:256
	global_load_dwordx4 v[80:83], v[152:153], off offset:320
	global_load_dwordx4 v[84:87], v[154:155], off offset:320
	global_load_dwordx4 v[88:91], v[156:157], off offset:320
	global_load_dwordx4 v[92:95], v[158:159], off offset:320
	global_load_dwordx4 v[96:99], v[152:153], off offset:384
	global_load_dwordx4 v[100:103], v[154:155], off offset:384
	global_load_dwordx4 v[104:107], v[156:157], off offset:384
	global_load_dwordx4 v[108:111], v[158:159], off offset:384
	global_load_dwordx4 v[112:115], v[152:153], off offset:448
	global_load_dwordx4 v[116:119], v[154:155], off offset:448
	global_load_dwordx4 v[120:123], v[156:157], off offset:448
	global_load_dwordx4 v[124:127], v[158:159], off offset:448
	s_waitcnt vmcnt(16)
	v_mfma_f32_16x16x32_bf16 v[128:131], v[0:3], v[8:11], v[128:131]
	v_mfma_f32_16x16x32_bf16 v[132:135], v[4:7], v[8:11], v[132:135]
	v_mfma_f32_16x16x32_bf16 v[144:147], v[0:3], v[12:15], v[144:147]
	v_mfma_f32_16x16x32_bf16 v[148:151], v[4:7], v[12:15], v[148:151]
	v_mfma_f32_16x16x32_bf16 v[128:131], v[16:19], v[24:27], v[128:131]
	v_mfma_f32_16x16x32_bf16 v[132:135], v[20:23], v[24:27], v[132:135]
	v_mfma_f32_16x16x32_bf16 v[144:147], v[16:19], v[28:31], v[144:147]
	v_mfma_f32_16x16x32_bf16 v[148:151], v[20:23], v[28:31], v[148:151]
	v_mfma_f32_16x16x32_bf16 v[128:131], v[32:35], v[40:43], v[128:131]
	v_mfma_f32_16x16x32_bf16 v[132:135], v[36:39], v[40:43], v[132:135]
	v_mfma_f32_16x16x32_bf16 v[144:147], v[32:35], v[44:47], v[144:147]
	v_mfma_f32_16x16x32_bf16 v[148:151], v[36:39], v[44:47], v[148:151]
	v_mfma_f32_16x16x32_bf16 v[128:131], v[48:51], v[56:59], v[128:131]
	v_mfma_f32_16x16x32_bf16 v[132:135], v[52:55], v[56:59], v[132:135]
	v_mfma_f32_16x16x32_bf16 v[144:147], v[48:51], v[60:63], v[144:147]
	v_mfma_f32_16x16x32_bf16 v[148:151], v[52:55], v[60:63], v[148:151]
	global_load_dwordx4 v[0:3], v[152:153], off offset:512
	global_load_dwordx4 v[4:7], v[154:155], off offset:512
	global_load_dwordx4 v[8:11], v[156:157], off offset:512
	global_load_dwordx4 v[12:15], v[158:159], off offset:512
	global_load_dwordx4 v[16:19], v[152:153], off offset:576
	global_load_dwordx4 v[20:23], v[154:155], off offset:576
	global_load_dwordx4 v[24:27], v[156:157], off offset:576
	global_load_dwordx4 v[28:31], v[158:159], off offset:576
	global_load_dwordx4 v[32:35], v[152:153], off offset:640
	global_load_dwordx4 v[36:39], v[154:155], off offset:640
	global_load_dwordx4 v[40:43], v[156:157], off offset:640
	global_load_dwordx4 v[44:47], v[158:159], off offset:640
	s_waitcnt vmcnt(12)
	v_mfma_f32_16x16x32_bf16 v[128:131], v[64:67], v[72:75], v[128:131]
	v_mfma_f32_16x16x32_bf16 v[132:135], v[68:71], v[72:75], v[132:135]
	v_mfma_f32_16x16x32_bf16 v[144:147], v[64:67], v[76:79], v[144:147]
	v_mfma_f32_16x16x32_bf16 v[148:151], v[68:71], v[76:79], v[148:151]
	v_mfma_f32_16x16x32_bf16 v[128:131], v[80:83], v[88:91], v[128:131]
	v_mfma_f32_16x16x32_bf16 v[132:135], v[84:87], v[88:91], v[132:135]
	v_mfma_f32_16x16x32_bf16 v[144:147], v[80:83], v[92:95], v[144:147]
	v_mfma_f32_16x16x32_bf16 v[148:151], v[84:87], v[92:95], v[148:151]
	v_mfma_f32_16x16x32_bf16 v[128:131], v[96:99], v[104:107], v[128:131]
	v_mfma_f32_16x16x32_bf16 v[132:135], v[100:103], v[104:107], v[132:135]
	v_mfma_f32_16x16x32_bf16 v[144:147], v[96:99], v[108:111], v[144:147]
	v_mfma_f32_16x16x32_bf16 v[148:151], v[100:103], v[108:111], v[148:151]
	v_mfma_f32_16x16x32_bf16 v[128:131], v[112:115], v[120:123], v[128:131]
	v_mfma_f32_16x16x32_bf16 v[132:135], v[116:119], v[120:123], v[132:135]
	v_mfma_f32_16x16x32_bf16 v[144:147], v[112:115], v[124:127], v[144:147]
	v_mfma_f32_16x16x32_bf16 v[148:151], v[116:119], v[124:127], v[148:151]
	s_waitcnt vmcnt(0)
	v_mfma_f32_16x16x32_bf16 v[128:131], v[0:3], v[8:11], v[128:131]
	v_mfma_f32_16x16x32_bf16 v[132:135], v[4:7], v[8:11], v[132:135]
	v_mfma_f32_16x16x32_bf16 v[144:147], v[0:3], v[12:15], v[144:147]
	v_mfma_f32_16x16x32_bf16 v[148:151], v[4:7], v[12:15], v[148:151]
	v_mfma_f32_16x16x32_bf16 v[128:131], v[16:19], v[24:27], v[128:131]
	v_mfma_f32_16x16x32_bf16 v[132:135], v[20:23], v[24:27], v[132:135]
	v_mfma_f32_16x16x32_bf16 v[144:147], v[16:19], v[28:31], v[144:147]
	v_mfma_f32_16x16x32_bf16 v[148:151], v[20:23], v[28:31], v[148:151]
	v_mfma_f32_16x16x32_bf16 v[128:131], v[32:35], v[40:43], v[128:131]
	v_mfma_f32_16x16x32_bf16 v[132:135], v[36:39], v[40:43], v[132:135]
	v_mfma_f32_16x16x32_bf16 v[144:147], v[32:35], v[44:47], v[144:147]
	v_mfma_f32_16x16x32_bf16 v[148:151], v[36:39], v[44:47], v[148:151]
	s_nop 7
	s_nop 7
	v_lshlrev_b32_e32 v170, 12, v162
	v_lshl_add_u32 v170, v136, 4, v170
	ds_write_b128 v170, v[128:131]
	ds_write_b128 v170, v[132:135] offset:1024
	ds_write_b128 v170, v[144:147] offset:2048
	ds_write_b128 v170, v[148:151] offset:3072
	s_waitcnt lgkmcnt(0)
	s_barrier
	s_cmp_ge_u32 s80, 4
	s_cbranch_scc1 .Lmg2p_end
	s_lshl_b32 s84, s80, 10
	v_lshlrev_b32_e32 v171, 4, v136
	v_add_u32_e32 v171, s84, v171
	ds_read_b128 v[0:3], v171
	ds_read_b128 v[4:7], v171 offset:4096
	ds_read_b128 v[8:11], v171 offset:8192
	ds_read_b128 v[12:15], v171 offset:12288
	ds_read_b128 v[16:19], v171 offset:16384
	ds_read_b128 v[20:23], v171 offset:20480
	ds_read_b128 v[24:27], v171 offset:24576
	ds_read_b128 v[28:31], v171 offset:28672
	s_lshr_b32 s84, s80, 1
	s_lshl_b32 s84, s84, 4
	s_lshl_b32 s85, s81, 5
	s_add_i32 s84, s84, s85
	s_addk_i32 s84, 0x4000
	s_and_b32 s85, s80, 1
	s_lshl_b32 s85, s85, 4
	s_lshl_b32 s83, s82, 5
	s_add_i32 s85, s85, s83
	v_add_u32_e32 v165, s84, v160
	v_lshl_add_u32 v164, v161, 2, s85
	v_lshlrev_b32_e32 v166, 12, v165
	v_lshl_add_u32 v166, v164, 2, v166
	v_mov_b32_e32 v167, 0
	s_add_u32 s86, s74, 0x5000000
	s_addc_u32 s87, s75, 0
	v_lshl_add_u64 v[168:169], s[86:87], 0, v[166:167]
	global_load_dwordx4 v[32:35], v[168:169], off
	v_lshrrev_b32_e32 v172, 1, v166
	v_mov_b32_e32 v173, 0
	s_add_u32 s86, s74, 0x9100000
	s_addc_u32 s87, s75, 0
	v_lshl_add_u64 v[172:173], s[86:87], 0, v[172:173]
	v_lshlrev_b32_e32 v166, 2, v165
	s_add_u32 s86, s74, 0x12b90c00
	s_addc_u32 s87, s75, 0
	v_lshl_add_u64 v[166:167], s[86:87], 0, v[166:167]
	s_waitcnt lgkmcnt(0)
	v_add_f32_e32 v0, v0, v4
	v_add_f32_e32 v1, v1, v5
	v_add_f32_e32 v2, v2, v6
	v_add_f32_e32 v3, v3, v7
	v_add_f32_e32 v0, v0, v8
	v_add_f32_e32 v1, v1, v9
	v_add_f32_e32 v2, v2, v10
	v_add_f32_e32 v3, v3, v11
	v_add_f32_e32 v0, v0, v12
	v_add_f32_e32 v1, v1, v13
	v_add_f32_e32 v2, v2, v14
	v_add_f32_e32 v3, v3, v15
	v_add_f32_e32 v0, v0, v16
	v_add_f32_e32 v1, v1, v17
	v_add_f32_e32 v2, v2, v18
	v_add_f32_e32 v3, v3, v19
	v_add_f32_e32 v0, v0, v20
	v_add_f32_e32 v1, v1, v21
	v_add_f32_e32 v2, v2, v22
	v_add_f32_e32 v3, v3, v23
	v_add_f32_e32 v0, v0, v24
	v_add_f32_e32 v1, v1, v25
	v_add_f32_e32 v2, v2, v26
	v_add_f32_e32 v3, v3, v27
	v_add_f32_e32 v0, v0, v28
	v_add_f32_e32 v1, v1, v29
	v_add_f32_e32 v2, v2, v30
	v_add_f32_e32 v3, v3, v31
	s_waitcnt vmcnt(0)
	v_fma_f32 v32, v0, 0.5, v32
	v_fma_f32 v33, v1, 0.5, v33
	v_fma_f32 v34, v2, 0.5, v34
	v_fma_f32 v35, v3, 0.5, v35
	global_store_dwordx4 v[168:169], v[32:35], off
	v_cvt_pk_bf16_f32 v36, v32, v33
	v_cvt_pk_bf16_f32 v37, v34, v35
	global_store_dwordx2 v[172:173], v[36:37], off
	v_mul_f32_e32 v38, v32, v32
	v_fmac_f32_e32 v38, v33, v33
	v_fmac_f32_e32 v38, v34, v34
	v_fmac_f32_e32 v38, v35, v35
	v_xor_b32_e32 v39, 16, v136
	v_lshlrev_b32_e32 v39, 2, v39
	ds_bpermute_b32 v40, v39, v38
	v_xor_b32_e32 v41, 32, v136
	v_lshlrev_b32_e32 v41, 2, v41
	s_waitcnt lgkmcnt(0)
	v_add_f32_e32 v38, v38, v40
	ds_bpermute_b32 v40, v41, v38
	s_waitcnt lgkmcnt(0)
	v_add_f32_e32 v38, v38, v40
	v_cmp_gt_u32_e64 s[82:83], 16, v136
	s_nop 1
	s_and_saveexec_b64 s[84:85], s[82:83]
	global_atomic_add_f32 v[166:167], v38, off
	s_mov_b64 exec, s[84:85]
.Lmg2p_end:
	s_barrier
.Lpre2_skip:
	v_mov_b32_e32 v8, v174
	s_and_b64 vcc, exec, s[4:5]
	v_readfirstlane_b32 s4, v8
	s_cbranch_vccnz .LBB0_478
	s_ashr_i32 s5, s2, 31
	s_lshr_b32 s5, s5, 29
	s_add_i32 s5, s2, s5
	s_and_b32 s6, s5, -8
	s_sub_i32 s6, s2, s6
	s_cmp_gt_i32 s6, -1
	s_cbranch_scc0 .LBB0_475
	s_lshl_b32 s7, s6, 5
	s_or_b32 s7, s7, 0
	s_cbranch_execz .LBB0_476
	s_branch .LBB0_477

.LBB0_494:
	ds_read_b128 v[144:147], v151
	ds_read_b128 v[156:159], v151 offset:1024
	ds_read_b128 v[160:163], v151 offset:2048
	ds_read_b128 v[164:167], v151 offset:3072
	s_add_u32 s22, s20, 0x100
	s_addc_u32 s23, s21, 0
	s_cmp_eq_u32 s59, 40
	s_cselect_b32 s29, s13, s23
	s_cselect_b32 s28, s12, s22
	s_cselect_b32 s27, s15, s58
	s_cselect_b32 s26, s14, s57
	v_lshl_add_u64 v[172:173], s[20:21], 0, v[136:137]
	s_add_i32 m0, s30, 0xc000
	ds_read_b128 v[168:171], v152
	ds_read_b128 v[178:181], v152 offset:1024
	ds_read_b128 v[182:185], v152 offset:2048
	ds_read_b128 v[186:189], v152 offset:3072
	ds_read_b128 v[190:193], v152 offset:4096
	ds_read_b128 v[194:197], v152 offset:5120
	ds_read_b128 v[198:201], v152 offset:6144
	ds_read_b128 v[202:205], v152 offset:7168
	global_load_lds_dwordx4 v[172:173], off
	v_lshl_add_u64 v[172:173], s[20:21], 0, v[138:139]
	s_add_i32 m0, s30, 0xe000
	s_nop 0
	global_load_lds_dwordx4 v[172:173], off
	s_waitcnt lgkmcnt(8)
	s_barrier
	s_waitcnt lgkmcnt(0)
	s_setprio 1
	s_waitcnt lgkmcnt(0)
	v_mfma_f32_16x16x32_bf16 v[124:127], v[144:147], v[168:171], v[124:127]
	v_mfma_f32_16x16x32_bf16 v[120:123], v[160:163], v[168:171], v[120:123]
	v_mfma_f32_16x16x32_bf16 v[108:111], v[144:147], v[182:185], v[108:111]
	v_mfma_f32_16x16x32_bf16 v[104:107], v[160:163], v[182:185], v[104:107]
	v_mfma_f32_16x16x32_bf16 v[92:95], v[144:147], v[190:193], v[92:95]
	v_mfma_f32_16x16x32_bf16 v[88:91], v[160:163], v[190:193], v[88:91]
	v_mfma_f32_16x16x32_bf16 v[76:79], v[144:147], v[198:201], v[76:79]
	v_mfma_f32_16x16x32_bf16 v[72:75], v[160:163], v[198:201], v[72:75]
	v_mfma_f32_16x16x32_bf16 v[124:127], v[156:159], v[178:181], v[124:127]
	v_mfma_f32_16x16x32_bf16 v[120:123], v[164:167], v[178:181], v[120:123]
	v_mfma_f32_16x16x32_bf16 v[108:111], v[156:159], v[186:189], v[108:111]
	v_mfma_f32_16x16x32_bf16 v[104:107], v[164:167], v[186:189], v[104:107]
	v_mfma_f32_16x16x32_bf16 v[92:95], v[156:159], v[194:197], v[92:95]
	v_mfma_f32_16x16x32_bf16 v[88:91], v[164:167], v[194:197], v[88:91]
	v_mfma_f32_16x16x32_bf16 v[76:79], v[156:159], v[202:205], v[76:79]
	v_mfma_f32_16x16x32_bf16 v[72:75], v[164:167], v[202:205], v[72:75]
	s_setprio 0
	s_barrier
	s_add_i32 s20, s47, s7
	v_lshl_add_u64 v[172:173], s[26:27], 0, v[130:131]
	s_mov_b32 m0, s20
	ds_read_b128 v[206:209], v153
	ds_read_b128 v[210:213], v153 offset:1024
	ds_read_b128 v[214:217], v153 offset:2048
	ds_read_b128 v[218:221], v153 offset:3072
	global_load_lds_dwordx4 v[172:173], off
	v_lshl_add_u64 v[222:223], s[26:27], 0, v[134:135]
	s_add_i32 m0, s20, 0x2000
	s_nop 0
	global_load_lds_dwordx4 v[222:223], off
	s_barrier
	s_waitcnt lgkmcnt(0)
	s_setprio 1
	s_waitcnt lgkmcnt(0)
	v_mfma_f32_16x16x32_bf16 v[116:119], v[206:209], v[168:171], v[116:119]
	v_mfma_f32_16x16x32_bf16 v[112:115], v[214:217], v[168:171], v[112:115]
	v_mfma_f32_16x16x32_bf16 v[100:103], v[206:209], v[182:185], v[100:103]
	v_mfma_f32_16x16x32_bf16 v[96:99], v[214:217], v[182:185], v[96:99]
	v_mfma_f32_16x16x32_bf16 v[84:87], v[206:209], v[190:193], v[84:87]
	v_mfma_f32_16x16x32_bf16 v[80:83], v[214:217], v[190:193], v[80:83]
	v_mfma_f32_16x16x32_bf16 v[68:71], v[206:209], v[198:201], v[68:71]
	v_mfma_f32_16x16x32_bf16 v[64:67], v[214:217], v[198:201], v[64:67]
	v_mfma_f32_16x16x32_bf16 v[116:119], v[210:213], v[178:181], v[116:119]
	v_mfma_f32_16x16x32_bf16 v[112:115], v[218:221], v[178:181], v[112:115]
	v_mfma_f32_16x16x32_bf16 v[100:103], v[210:213], v[186:189], v[100:103]
	v_mfma_f32_16x16x32_bf16 v[96:99], v[218:221], v[186:189], v[96:99]
	v_mfma_f32_16x16x32_bf16 v[84:87], v[210:213], v[194:197], v[84:87]
	v_mfma_f32_16x16x32_bf16 v[80:83], v[218:221], v[194:197], v[80:83]
	v_mfma_f32_16x16x32_bf16 v[68:71], v[210:213], v[202:205], v[68:71]
	v_mfma_f32_16x16x32_bf16 v[64:67], v[218:221], v[202:205], v[64:67]
	s_setprio 0
	s_mov_b32 m0, s30
	v_lshl_add_u64 v[224:225], s[28:29], 0, v[128:129]
	s_barrier
	ds_read_b128 v[168:171], v152 offset:16384
	ds_read_b128 v[178:181], v152 offset:17408
	ds_read_b128 v[182:185], v152 offset:18432
	ds_read_b128 v[186:189], v152 offset:19456
	ds_read_b128 v[190:193], v152 offset:20480
	ds_read_b128 v[194:197], v152 offset:21504
	ds_read_b128 v[198:201], v152 offset:22528
	ds_read_b128 v[202:205], v152 offset:23552
	global_load_lds_dwordx4 v[224:225], off
	v_lshl_add_u64 v[226:227], s[28:29], 0, v[132:133]
	s_mov_b32 m0, s31
	s_nop 0
	global_load_lds_dwordx4 v[226:227], off
	s_barrier
	s_waitcnt lgkmcnt(0)
	s_setprio 1
	s_waitcnt lgkmcnt(0)
	v_mfma_f32_16x16x32_bf16 v[60:63], v[144:147], v[168:171], v[60:63]
	v_mfma_f32_16x16x32_bf16 v[56:59], v[160:163], v[168:171], v[56:59]
	v_mfma_f32_16x16x32_bf16 v[44:47], v[144:147], v[182:185], v[44:47]
	v_mfma_f32_16x16x32_bf16 v[40:43], v[160:163], v[182:185], v[40:43]
	v_mfma_f32_16x16x32_bf16 v[28:31], v[144:147], v[190:193], v[28:31]
	v_mfma_f32_16x16x32_bf16 v[24:27], v[160:163], v[190:193], v[24:27]
	v_mfma_f32_16x16x32_bf16 v[12:15], v[144:147], v[198:201], v[12:15]
	v_mfma_f32_16x16x32_bf16 v[8:11], v[160:163], v[198:201], v[8:11]
	v_mfma_f32_16x16x32_bf16 v[60:63], v[156:159], v[178:181], v[60:63]
	v_mfma_f32_16x16x32_bf16 v[56:59], v[164:167], v[178:181], v[56:59]
	v_mfma_f32_16x16x32_bf16 v[44:47], v[156:159], v[186:189], v[44:47]
	v_mfma_f32_16x16x32_bf16 v[40:43], v[164:167], v[186:189], v[40:43]
	v_mfma_f32_16x16x32_bf16 v[28:31], v[156:159], v[194:197], v[28:31]
	v_mfma_f32_16x16x32_bf16 v[24:27], v[164:167], v[194:197], v[24:27]
	v_mfma_f32_16x16x32_bf16 v[12:15], v[156:159], v[202:205], v[12:15]
	v_mfma_f32_16x16x32_bf16 v[8:11], v[164:167], v[202:205], v[8:11]
	s_setprio 0
	s_barrier
	s_add_u32 s20, s26, 0xb0000
	s_addc_u32 s21, s27, 0
	s_add_i32 s62, s52, s7
	v_lshl_add_u64 v[144:145], s[20:21], 0, v[130:131]
	s_mov_b32 m0, s62
	s_nop 0
	global_load_lds_dwordx4 v[144:145], off
	v_lshl_add_u64 v[144:145], s[20:21], 0, v[134:135]
	s_add_i32 m0, s62, 0x2000
	s_nop 0
	global_load_lds_dwordx4 v[144:145], off
	s_waitcnt vmcnt(6)
	s_barrier
	s_setprio 1
	v_mfma_f32_16x16x32_bf16 v[52:55], v[206:209], v[168:171], v[52:55]
	v_mfma_f32_16x16x32_bf16 v[48:51], v[214:217], v[168:171], v[48:51]
	v_mfma_f32_16x16x32_bf16 v[36:39], v[206:209], v[182:185], v[36:39]
	v_mfma_f32_16x16x32_bf16 v[32:35], v[214:217], v[182:185], v[32:35]
	v_mfma_f32_16x16x32_bf16 v[20:23], v[206:209], v[190:193], v[20:23]
	v_mfma_f32_16x16x32_bf16 v[16:19], v[214:217], v[190:193], v[16:19]
	v_mfma_f32_16x16x32_bf16 v[4:7], v[206:209], v[198:201], v[4:7]
	v_mfma_f32_16x16x32_bf16 v[0:3], v[214:217], v[198:201], v[0:3]
	v_mfma_f32_16x16x32_bf16 v[52:55], v[210:213], v[178:181], v[52:55]
	v_mfma_f32_16x16x32_bf16 v[48:51], v[218:221], v[178:181], v[48:51]
	v_mfma_f32_16x16x32_bf16 v[36:39], v[210:213], v[186:189], v[36:39]
	v_mfma_f32_16x16x32_bf16 v[32:35], v[218:221], v[186:189], v[32:35]
	v_mfma_f32_16x16x32_bf16 v[20:23], v[210:213], v[194:197], v[20:23]
	v_mfma_f32_16x16x32_bf16 v[16:19], v[218:221], v[194:197], v[16:19]
	v_mfma_f32_16x16x32_bf16 v[4:7], v[210:213], v[202:205], v[4:7]
	v_mfma_f32_16x16x32_bf16 v[0:3], v[218:221], v[202:205], v[0:3]
	s_setprio 0
	s_add_i32 s62, 0, 0x18000
	v_add_u32_e32 v155, s62, v149
	s_barrier
	ds_read_b128 v[144:147], v155
	ds_read_b128 v[156:159], v155 offset:1024
	ds_read_b128 v[160:163], v155 offset:2048
	ds_read_b128 v[164:167], v155 offset:3072
	s_add_u32 s20, s28, 0xb0000
	s_addc_u32 s21, s29, 0
	s_mov_b32 m0, s34
	v_lshl_add_u64 v[206:207], s[20:21], 0, v[128:129]
	ds_read_b128 v[168:171], v152 offset:32768
	ds_read_b128 v[178:181], v152 offset:33792
	ds_read_b128 v[182:185], v152 offset:34816
	ds_read_b128 v[186:189], v152 offset:35840
	ds_read_b128 v[190:193], v152 offset:36864
	ds_read_b128 v[194:197], v152 offset:37888
	ds_read_b128 v[198:201], v152 offset:38912
	ds_read_b128 v[202:205], v152 offset:39936
	global_load_lds_dwordx4 v[206:207], off
	v_lshl_add_u64 v[206:207], s[20:21], 0, v[132:133]
	s_mov_b32 m0, s35
	s_nop 0
	global_load_lds_dwordx4 v[206:207], off
	s_waitcnt lgkmcnt(8)
	s_barrier
	s_waitcnt lgkmcnt(0)
	s_setprio 1
	s_waitcnt lgkmcnt(0)
	v_mfma_f32_16x16x32_bf16 v[124:127], v[144:147], v[168:171], v[124:127]
	v_mfma_f32_16x16x32_bf16 v[120:123], v[160:163], v[168:171], v[120:123]
	v_mfma_f32_16x16x32_bf16 v[108:111], v[144:147], v[182:185], v[108:111]
	v_mfma_f32_16x16x32_bf16 v[104:107], v[160:163], v[182:185], v[104:107]
	v_mfma_f32_16x16x32_bf16 v[92:95], v[144:147], v[190:193], v[92:95]
	v_mfma_f32_16x16x32_bf16 v[88:91], v[160:163], v[190:193], v[88:91]
	v_mfma_f32_16x16x32_bf16 v[76:79], v[144:147], v[198:201], v[76:79]
	v_mfma_f32_16x16x32_bf16 v[72:75], v[160:163], v[198:201], v[72:75]
	v_mfma_f32_16x16x32_bf16 v[124:127], v[156:159], v[178:181], v[124:127]
	v_mfma_f32_16x16x32_bf16 v[120:123], v[164:167], v[178:181], v[120:123]
	v_mfma_f32_16x16x32_bf16 v[108:111], v[156:159], v[186:189], v[108:111]
	v_mfma_f32_16x16x32_bf16 v[104:107], v[164:167], v[186:189], v[104:107]
	v_mfma_f32_16x16x32_bf16 v[92:95], v[156:159], v[194:197], v[92:95]
	v_mfma_f32_16x16x32_bf16 v[88:91], v[164:167], v[194:197], v[88:91]
	v_mfma_f32_16x16x32_bf16 v[76:79], v[156:159], v[202:205], v[76:79]
	v_mfma_f32_16x16x32_bf16 v[72:75], v[164:167], v[202:205], v[72:75]
	s_setprio 0
	s_barrier
	s_add_i32 s28, 0, 0x1c000
	s_add_i32 s20, s62, s7
	v_add_u32_e32 v155, s28, v149
	v_lshl_add_u64 v[172:173], v[172:173], 0, s[16:17]
	s_mov_b32 m0, s20
	ds_read_b128 v[206:209], v155
	ds_read_b128 v[210:213], v155 offset:1024
	ds_read_b128 v[214:217], v155 offset:2048
	ds_read_b128 v[218:221], v155 offset:3072
	global_load_lds_dwordx4 v[172:173], off
	v_lshl_add_u64 v[172:173], v[222:223], 0, s[16:17]
	s_add_i32 m0, s20, 0x2000
	s_nop 0
	global_load_lds_dwordx4 v[172:173], off
	s_barrier
	s_waitcnt lgkmcnt(0)
	s_setprio 1
	s_waitcnt lgkmcnt(0)
	v_mfma_f32_16x16x32_bf16 v[116:119], v[206:209], v[168:171], v[116:119]
	v_mfma_f32_16x16x32_bf16 v[112:115], v[214:217], v[168:171], v[112:115]
	v_mfma_f32_16x16x32_bf16 v[100:103], v[206:209], v[182:185], v[100:103]
	v_mfma_f32_16x16x32_bf16 v[96:99], v[214:217], v[182:185], v[96:99]
	v_mfma_f32_16x16x32_bf16 v[84:87], v[206:209], v[190:193], v[84:87]
	v_mfma_f32_16x16x32_bf16 v[80:83], v[214:217], v[190:193], v[80:83]
	v_mfma_f32_16x16x32_bf16 v[68:71], v[206:209], v[198:201], v[68:71]
	v_mfma_f32_16x16x32_bf16 v[64:67], v[214:217], v[198:201], v[64:67]
	v_mfma_f32_16x16x32_bf16 v[116:119], v[210:213], v[178:181], v[116:119]
	v_mfma_f32_16x16x32_bf16 v[112:115], v[218:221], v[178:181], v[112:115]
	v_mfma_f32_16x16x32_bf16 v[100:103], v[210:213], v[186:189], v[100:103]
	v_mfma_f32_16x16x32_bf16 v[96:99], v[218:221], v[186:189], v[96:99]
	v_mfma_f32_16x16x32_bf16 v[84:87], v[210:213], v[194:197], v[84:87]
	v_mfma_f32_16x16x32_bf16 v[80:83], v[218:221], v[194:197], v[80:83]
	v_mfma_f32_16x16x32_bf16 v[68:71], v[210:213], v[202:205], v[68:71]
	v_mfma_f32_16x16x32_bf16 v[64:67], v[218:221], v[202:205], v[64:67]
	s_setprio 0
	s_mov_b32 m0, s37
	v_lshl_add_u64 v[172:173], v[224:225], 0, s[16:17]
	s_barrier
	ds_read_b128 v[168:171], v152 offset:49152
	ds_read_b128 v[178:181], v152 offset:50176
	ds_read_b128 v[182:185], v152 offset:51200
	ds_read_b128 v[186:189], v152 offset:52224
	ds_read_b128 v[190:193], v152 offset:53248
	ds_read_b128 v[194:197], v152 offset:54272
	ds_read_b128 v[198:201], v152 offset:55296
	ds_read_b128 v[202:205], v152 offset:56320
	global_load_lds_dwordx4 v[172:173], off
	v_lshl_add_u64 v[172:173], v[226:227], 0, s[16:17]
	s_mov_b32 m0, s42
	s_nop 0
	global_load_lds_dwordx4 v[172:173], off
	s_barrier
	s_waitcnt lgkmcnt(0)
	s_setprio 1
	s_waitcnt lgkmcnt(0)
	v_mfma_f32_16x16x32_bf16 v[60:63], v[144:147], v[168:171], v[60:63]
	v_mfma_f32_16x16x32_bf16 v[56:59], v[160:163], v[168:171], v[56:59]
	v_mfma_f32_16x16x32_bf16 v[44:47], v[144:147], v[182:185], v[44:47]
	v_mfma_f32_16x16x32_bf16 v[40:43], v[160:163], v[182:185], v[40:43]
	v_mfma_f32_16x16x32_bf16 v[28:31], v[144:147], v[190:193], v[28:31]
	v_mfma_f32_16x16x32_bf16 v[24:27], v[160:163], v[190:193], v[24:27]
	v_mfma_f32_16x16x32_bf16 v[12:15], v[144:147], v[198:201], v[12:15]
	v_mfma_f32_16x16x32_bf16 v[8:11], v[160:163], v[198:201], v[8:11]
	v_mfma_f32_16x16x32_bf16 v[60:63], v[156:159], v[178:181], v[60:63]
	v_mfma_f32_16x16x32_bf16 v[56:59], v[164:167], v[178:181], v[56:59]
	v_mfma_f32_16x16x32_bf16 v[44:47], v[156:159], v[186:189], v[44:47]
	v_mfma_f32_16x16x32_bf16 v[40:43], v[164:167], v[186:189], v[40:43]
	v_mfma_f32_16x16x32_bf16 v[28:31], v[156:159], v[194:197], v[28:31]
	v_mfma_f32_16x16x32_bf16 v[24:27], v[164:167], v[194:197], v[24:27]
	v_mfma_f32_16x16x32_bf16 v[12:15], v[156:159], v[202:205], v[12:15]
	v_mfma_f32_16x16x32_bf16 v[8:11], v[164:167], v[202:205], v[8:11]
	s_setprio 0
	s_barrier
	s_add_u32 s20, s26, 0xb0080
	s_addc_u32 s21, s27, 0
	s_add_i32 s26, s28, s7
	v_lshl_add_u64 v[144:145], s[20:21], 0, v[130:131]
	s_mov_b32 m0, s26
	s_nop 0
	global_load_lds_dwordx4 v[144:145], off
	v_lshl_add_u64 v[144:145], s[20:21], 0, v[134:135]
	s_add_i32 m0, s26, 0x2000
	s_nop 0
	global_load_lds_dwordx4 v[144:145], off
	s_waitcnt vmcnt(6)
	s_barrier
	s_setprio 1
	v_mfma_f32_16x16x32_bf16 v[52:55], v[206:209], v[168:171], v[52:55]
	v_mfma_f32_16x16x32_bf16 v[48:51], v[214:217], v[168:171], v[48:51]
	v_mfma_f32_16x16x32_bf16 v[36:39], v[206:209], v[182:185], v[36:39]
	v_mfma_f32_16x16x32_bf16 v[32:35], v[214:217], v[182:185], v[32:35]
	v_mfma_f32_16x16x32_bf16 v[20:23], v[206:209], v[190:193], v[20:23]
	v_mfma_f32_16x16x32_bf16 v[16:19], v[214:217], v[190:193], v[16:19]
	v_mfma_f32_16x16x32_bf16 v[4:7], v[206:209], v[198:201], v[4:7]
	v_mfma_f32_16x16x32_bf16 v[0:3], v[214:217], v[198:201], v[0:3]
	v_mfma_f32_16x16x32_bf16 v[52:55], v[210:213], v[178:181], v[52:55]
	v_mfma_f32_16x16x32_bf16 v[48:51], v[218:221], v[178:181], v[48:51]
	v_mfma_f32_16x16x32_bf16 v[36:39], v[210:213], v[186:189], v[36:39]
	v_mfma_f32_16x16x32_bf16 v[32:35], v[218:221], v[186:189], v[32:35]
	v_mfma_f32_16x16x32_bf16 v[20:23], v[210:213], v[194:197], v[20:23]
	v_mfma_f32_16x16x32_bf16 v[16:19], v[218:221], v[194:197], v[16:19]
	v_mfma_f32_16x16x32_bf16 v[4:7], v[210:213], v[202:205], v[4:7]
	v_mfma_f32_16x16x32_bf16 v[0:3], v[218:221], v[202:205], v[0:3]
	s_setprio 0
	s_add_i32 s59, s59, 2
	s_add_u32 s57, s57, 0x100
	s_addc_u32 s58, s58, 0
	s_cmp_gt_u32 s59, 41
	s_mov_b64 s[20:21], s[22:23]
	s_barrier
	s_cbranch_scc0 .LBB0_494
	s_nop 7
	s_nop 7
	v_and_b32_e32 v160, 15, v174
	v_bfe_u32 v161, v174, 4, 2
	v_lshrrev_b32_e32 v162, 6, v174
	v_lshrrev_b32_e32 v163, 2, v162
	v_and_b32_e32 v164, 3, v162
	v_and_b32_e32 v170, 63, v174
	s_lshr_b32 s80, s33, 3
	s_and_b32 s81, s80, 7
	s_lshl_b32 s81, s81, 3
	s_lshr_b32 s82, s80, 3
	s_and_b32 s82, s82, 7
	s_add_i32 s81, s81, s82
	s_lshr_b32 s82, s80, 6
	v_lshl_add_u32 v165, v163, 6, v160
	s_lshl_b32 s83, s81, 8
	v_add_u32_e32 v165, s83, v165
	v_lshlrev_b32_e32 v166, 3, v161
	v_lshl_add_u32 v166, v164, 5, v166
	s_lshl_b32 s83, s82, 8
	v_add_u32_e32 v166, s83, v166
	v_lshlrev_b32_e32 v168, 12, v165
	v_lshl_add_u32 v168, v166, 2, v168
	v_mov_b32_e32 v169, 0
	s_add_u32 s84, s74, 0x5000000
	s_addc_u32 s85, s75, 0
	v_lshl_add_u64 v[210:211], s[84:85], 0, v[168:169]
	v_lshrrev_b32_e32 v168, 1, v168
	s_add_u32 s84, s74, 0x9100000
	s_addc_u32 s85, s75, 0
	v_lshl_add_u64 v[212:213], s[84:85], 0, v[168:169]
	v_lshlrev_b32_e32 v168, 2, v165
	s_add_u32 s84, s74, 0x12b90c00
	s_addc_u32 s85, s75, 0
	v_lshl_add_u64 v[214:215], s[84:85], 0, v[168:169]
	v_xor_b32_e32 v171, 16, v170
	v_lshlrev_b32_e32 v171, 2, v171
	v_xor_b32_e32 v172, 32, v170
	v_lshlrev_b32_e32 v172, 2, v172
	v_cmp_eq_u32_e64 s[86:87], 0, v161
	s_mov_b32 s85, 0
	s_mov_b32 s89, 0
	s_mov_b32 s84, 0x0
	v_lshl_add_u64 v[216:217], s[84:85], 0, v[210:211]
	global_load_dwordx4 v[128:131], v[216:217], off
	global_load_dwordx4 v[132:135], v[216:217], off offset:16
	global_load_dwordx4 v[136:139], v[216:217], off offset:512
	global_load_dwordx4 v[140:143], v[216:217], off offset:528
	s_mov_b32 s84, 0x10000
	v_lshl_add_u64 v[216:217], s[84:85], 0, v[210:211]
	global_load_dwordx4 v[144:147], v[216:217], off
	global_load_dwordx4 v[148:151], v[216:217], off offset:16
	global_load_dwordx4 v[152:155], v[216:217], off offset:512
	global_load_dwordx4 v[156:159], v[216:217], off offset:528
	s_mov_b32 s84, 0x20000
	v_lshl_add_u64 v[216:217], s[84:85], 0, v[210:211]
	global_load_dwordx4 v[178:181], v[216:217], off
	global_load_dwordx4 v[182:185], v[216:217], off offset:16
	global_load_dwordx4 v[186:189], v[216:217], off offset:512
	global_load_dwordx4 v[190:193], v[216:217], off offset:528
	s_mov_b32 s84, 0x30000
	v_lshl_add_u64 v[216:217], s[84:85], 0, v[210:211]
	global_load_dwordx4 v[194:197], v[216:217], off
	global_load_dwordx4 v[198:201], v[216:217], off offset:16
	global_load_dwordx4 v[202:205], v[216:217], off offset:512
	global_load_dwordx4 v[206:209], v[216:217], off offset:528
	s_waitcnt vmcnt(0)
	s_mov_b32 s84, 0x0
	v_lshl_add_u64 v[216:217], s[84:85], 0, v[210:211]
	s_mov_b32 s88, 0x0
	v_lshl_add_u64 v[218:219], s[88:89], 0, v[212:213]
	v_pk_fma_f32 v[128:129], v[124:125], 0.5, v[128:129] op_sel_hi:[1,0,1]
	v_pk_fma_f32 v[130:131], v[126:127], 0.5, v[130:131] op_sel_hi:[1,0,1]
	v_pk_fma_f32 v[132:133], v[120:121], 0.5, v[132:133] op_sel_hi:[1,0,1]
	v_pk_fma_f32 v[134:135], v[122:123], 0.5, v[134:135] op_sel_hi:[1,0,1]
	global_store_dwordx4 v[216:217], v[128:131], off
	global_store_dwordx4 v[216:217], v[132:135], off offset:16
	v_cvt_pk_bf16_f32 v224, v128, v129
	v_cvt_pk_bf16_f32 v225, v130, v131
	v_cvt_pk_bf16_f32 v226, v132, v133
	v_cvt_pk_bf16_f32 v227, v134, v135
	global_store_dwordx4 v[218:219], v[224:227], off
	v_mul_f32_e32 v220, v128, v128
	v_fmac_f32_e32 v220, v129, v129
	v_fmac_f32_e32 v220, v130, v130
	v_fmac_f32_e32 v220, v131, v131
	v_fmac_f32_e32 v220, v132, v132
	v_fmac_f32_e32 v220, v133, v133
	v_fmac_f32_e32 v220, v134, v134
	v_fmac_f32_e32 v220, v135, v135
	v_pk_fma_f32 v[136:137], v[116:117], 0.5, v[136:137] op_sel_hi:[1,0,1]
	v_pk_fma_f32 v[138:139], v[118:119], 0.5, v[138:139] op_sel_hi:[1,0,1]
	v_pk_fma_f32 v[140:141], v[112:113], 0.5, v[140:141] op_sel_hi:[1,0,1]
	v_pk_fma_f32 v[142:143], v[114:115], 0.5, v[142:143] op_sel_hi:[1,0,1]
	global_store_dwordx4 v[216:217], v[136:139], off offset:512
	global_store_dwordx4 v[216:217], v[140:143], off offset:528
	v_cvt_pk_bf16_f32 v228, v136, v137
	v_cvt_pk_bf16_f32 v229, v138, v139
	v_cvt_pk_bf16_f32 v230, v140, v141
	v_cvt_pk_bf16_f32 v231, v142, v143
	global_store_dwordx4 v[218:219], v[228:231], off offset:256
	v_fmac_f32_e32 v220, v136, v136
	v_fmac_f32_e32 v220, v137, v137
	v_fmac_f32_e32 v220, v138, v138
	v_fmac_f32_e32 v220, v139, v139
	v_fmac_f32_e32 v220, v140, v140
	v_fmac_f32_e32 v220, v141, v141
	v_fmac_f32_e32 v220, v142, v142
	v_fmac_f32_e32 v220, v143, v143
	s_mov_b32 s84, 0x10000
	v_lshl_add_u64 v[216:217], s[84:85], 0, v[210:211]
	s_mov_b32 s88, 0x8000
	v_lshl_add_u64 v[218:219], s[88:89], 0, v[212:213]
	v_pk_fma_f32 v[144:145], v[108:109], 0.5, v[144:145] op_sel_hi:[1,0,1]
	v_pk_fma_f32 v[146:147], v[110:111], 0.5, v[146:147] op_sel_hi:[1,0,1]
	v_pk_fma_f32 v[148:149], v[104:105], 0.5, v[148:149] op_sel_hi:[1,0,1]
	v_pk_fma_f32 v[150:151], v[106:107], 0.5, v[150:151] op_sel_hi:[1,0,1]
	global_store_dwordx4 v[216:217], v[144:147], off
	global_store_dwordx4 v[216:217], v[148:151], off offset:16
	v_cvt_pk_bf16_f32 v224, v144, v145
	v_cvt_pk_bf16_f32 v225, v146, v147
	v_cvt_pk_bf16_f32 v226, v148, v149
	v_cvt_pk_bf16_f32 v227, v150, v151
	global_store_dwordx4 v[218:219], v[224:227], off
	v_mul_f32_e32 v221, v144, v144
	v_fmac_f32_e32 v221, v145, v145
	v_fmac_f32_e32 v221, v146, v146
	v_fmac_f32_e32 v221, v147, v147
	v_fmac_f32_e32 v221, v148, v148
	v_fmac_f32_e32 v221, v149, v149
	v_fmac_f32_e32 v221, v150, v150
	v_fmac_f32_e32 v221, v151, v151
	v_pk_fma_f32 v[152:153], v[100:101], 0.5, v[152:153] op_sel_hi:[1,0,1]
	v_pk_fma_f32 v[154:155], v[102:103], 0.5, v[154:155] op_sel_hi:[1,0,1]
	v_pk_fma_f32 v[156:157], v[96:97], 0.5, v[156:157] op_sel_hi:[1,0,1]
	v_pk_fma_f32 v[158:159], v[98:99], 0.5, v[158:159] op_sel_hi:[1,0,1]
	global_store_dwordx4 v[216:217], v[152:155], off offset:512
	global_store_dwordx4 v[216:217], v[156:159], off offset:528
	v_cvt_pk_bf16_f32 v228, v152, v153
	v_cvt_pk_bf16_f32 v229, v154, v155
	v_cvt_pk_bf16_f32 v230, v156, v157
	v_cvt_pk_bf16_f32 v231, v158, v159
	global_store_dwordx4 v[218:219], v[228:231], off offset:256
	v_fmac_f32_e32 v221, v152, v152
	v_fmac_f32_e32 v221, v153, v153
	v_fmac_f32_e32 v221, v154, v154
	v_fmac_f32_e32 v221, v155, v155
	v_fmac_f32_e32 v221, v156, v156
	v_fmac_f32_e32 v221, v157, v157
	v_fmac_f32_e32 v221, v158, v158
	v_fmac_f32_e32 v221, v159, v159
	s_mov_b32 s84, 0x20000
	v_lshl_add_u64 v[216:217], s[84:85], 0, v[210:211]
	s_mov_b32 s88, 0x10000
	v_lshl_add_u64 v[218:219], s[88:89], 0, v[212:213]
	v_pk_fma_f32 v[178:179], v[92:93], 0.5, v[178:179] op_sel_hi:[1,0,1]
	v_pk_fma_f32 v[180:181], v[94:95], 0.5, v[180:181] op_sel_hi:[1,0,1]
	v_pk_fma_f32 v[182:183], v[88:89], 0.5, v[182:183] op_sel_hi:[1,0,1]
	v_pk_fma_f32 v[184:185], v[90:91], 0.5, v[184:185] op_sel_hi:[1,0,1]
	global_store_dwordx4 v[216:217], v[178:181], off
	global_store_dwordx4 v[216:217], v[182:185], off offset:16
	v_cvt_pk_bf16_f32 v224, v178, v179
	v_cvt_pk_bf16_f32 v225, v180, v181
	v_cvt_pk_bf16_f32 v226, v182, v183
	v_cvt_pk_bf16_f32 v227, v184, v185
	global_store_dwordx4 v[218:219], v[224:227], off
	v_mul_f32_e32 v222, v178, v178
	v_fmac_f32_e32 v222, v179, v179
	v_fmac_f32_e32 v222, v180, v180
	v_fmac_f32_e32 v222, v181, v181
	v_fmac_f32_e32 v222, v182, v182
	v_fmac_f32_e32 v222, v183, v183
	v_fmac_f32_e32 v222, v184, v184
	v_fmac_f32_e32 v222, v185, v185
	v_pk_fma_f32 v[186:187], v[84:85], 0.5, v[186:187] op_sel_hi:[1,0,1]
	v_pk_fma_f32 v[188:189], v[86:87], 0.5, v[188:189] op_sel_hi:[1,0,1]
	v_pk_fma_f32 v[190:191], v[80:81], 0.5, v[190:191] op_sel_hi:[1,0,1]
	v_pk_fma_f32 v[192:193], v[82:83], 0.5, v[192:193] op_sel_hi:[1,0,1]
	global_store_dwordx4 v[216:217], v[186:189], off offset:512
	global_store_dwordx4 v[216:217], v[190:193], off offset:528
	v_cvt_pk_bf16_f32 v228, v186, v187
	v_cvt_pk_bf16_f32 v229, v188, v189
	v_cvt_pk_bf16_f32 v230, v190, v191
	v_cvt_pk_bf16_f32 v231, v192, v193
	global_store_dwordx4 v[218:219], v[228:231], off offset:256
	v_fmac_f32_e32 v222, v186, v186
	v_fmac_f32_e32 v222, v187, v187
	v_fmac_f32_e32 v222, v188, v188
	v_fmac_f32_e32 v222, v189, v189
	v_fmac_f32_e32 v222, v190, v190
	v_fmac_f32_e32 v222, v191, v191
	v_fmac_f32_e32 v222, v192, v192
	v_fmac_f32_e32 v222, v193, v193
	s_mov_b32 s84, 0x30000
	v_lshl_add_u64 v[216:217], s[84:85], 0, v[210:211]
	s_mov_b32 s88, 0x18000
	v_lshl_add_u64 v[218:219], s[88:89], 0, v[212:213]
	v_pk_fma_f32 v[194:195], v[76:77], 0.5, v[194:195] op_sel_hi:[1,0,1]
	v_pk_fma_f32 v[196:197], v[78:79], 0.5, v[196:197] op_sel_hi:[1,0,1]
	v_pk_fma_f32 v[198:199], v[72:73], 0.5, v[198:199] op_sel_hi:[1,0,1]
	v_pk_fma_f32 v[200:201], v[74:75], 0.5, v[200:201] op_sel_hi:[1,0,1]
	global_store_dwordx4 v[216:217], v[194:197], off
	global_store_dwordx4 v[216:217], v[198:201], off offset:16
	v_cvt_pk_bf16_f32 v224, v194, v195
	v_cvt_pk_bf16_f32 v225, v196, v197
	v_cvt_pk_bf16_f32 v226, v198, v199
	v_cvt_pk_bf16_f32 v227, v200, v201
	global_store_dwordx4 v[218:219], v[224:227], off
	v_mul_f32_e32 v223, v194, v194
	v_fmac_f32_e32 v223, v195, v195
	v_fmac_f32_e32 v223, v196, v196
	v_fmac_f32_e32 v223, v197, v197
	v_fmac_f32_e32 v223, v198, v198
	v_fmac_f32_e32 v223, v199, v199
	v_fmac_f32_e32 v223, v200, v200
	v_fmac_f32_e32 v223, v201, v201
	v_pk_fma_f32 v[202:203], v[68:69], 0.5, v[202:203] op_sel_hi:[1,0,1]
	v_pk_fma_f32 v[204:205], v[70:71], 0.5, v[204:205] op_sel_hi:[1,0,1]
	v_pk_fma_f32 v[206:207], v[64:65], 0.5, v[206:207] op_sel_hi:[1,0,1]
	v_pk_fma_f32 v[208:209], v[66:67], 0.5, v[208:209] op_sel_hi:[1,0,1]
	global_store_dwordx4 v[216:217], v[202:205], off offset:512
	global_store_dwordx4 v[216:217], v[206:209], off offset:528
	v_cvt_pk_bf16_f32 v228, v202, v203
	v_cvt_pk_bf16_f32 v229, v204, v205
	v_cvt_pk_bf16_f32 v230, v206, v207
	v_cvt_pk_bf16_f32 v231, v208, v209
	global_store_dwordx4 v[218:219], v[228:231], off offset:256
	v_fmac_f32_e32 v223, v202, v202
	v_fmac_f32_e32 v223, v203, v203
	v_fmac_f32_e32 v223, v204, v204
	v_fmac_f32_e32 v223, v205, v205
	v_fmac_f32_e32 v223, v206, v206
	v_fmac_f32_e32 v223, v207, v207
	v_fmac_f32_e32 v223, v208, v208
	v_fmac_f32_e32 v223, v209, v209
	ds_bpermute_b32 v224, v171, v220
	ds_bpermute_b32 v225, v171, v221
	ds_bpermute_b32 v226, v171, v222
	ds_bpermute_b32 v227, v171, v223
	s_waitcnt lgkmcnt(0)
	v_add_f32_e32 v220, v220, v224
	v_add_f32_e32 v221, v221, v225
	v_add_f32_e32 v222, v222, v226
	v_add_f32_e32 v223, v223, v227
	ds_bpermute_b32 v224, v172, v220
	ds_bpermute_b32 v225, v172, v221
	ds_bpermute_b32 v226, v172, v222
	ds_bpermute_b32 v227, v172, v223
	s_waitcnt lgkmcnt(0)
	v_add_f32_e32 v220, v220, v224
	v_add_f32_e32 v221, v221, v225
	v_add_f32_e32 v222, v222, v226
	v_add_f32_e32 v223, v223, v227
	s_and_saveexec_b64 s[90:91], s[86:87]
	global_atomic_add_f32 v[214:215], v220, off
	global_atomic_add_f32 v[214:215], v221, off offset:64
	global_atomic_add_f32 v[214:215], v222, off offset:128
	global_atomic_add_f32 v[214:215], v223, off offset:192
	s_mov_b64 exec, s[90:91]
	s_mov_b32 s84, 0x80000
	v_lshl_add_u64 v[216:217], s[84:85], 0, v[210:211]
	global_load_dwordx4 v[128:131], v[216:217], off
	global_load_dwordx4 v[132:135], v[216:217], off offset:16
	global_load_dwordx4 v[136:139], v[216:217], off offset:512
	global_load_dwordx4 v[140:143], v[216:217], off offset:528
	s_mov_b32 s84, 0x90000
	v_lshl_add_u64 v[216:217], s[84:85], 0, v[210:211]
	global_load_dwordx4 v[144:147], v[216:217], off
	global_load_dwordx4 v[148:151], v[216:217], off offset:16
	global_load_dwordx4 v[152:155], v[216:217], off offset:512
	global_load_dwordx4 v[156:159], v[216:217], off offset:528
	s_mov_b32 s84, 0xa0000
	v_lshl_add_u64 v[216:217], s[84:85], 0, v[210:211]
	global_load_dwordx4 v[178:181], v[216:217], off
	global_load_dwordx4 v[182:185], v[216:217], off offset:16
	global_load_dwordx4 v[186:189], v[216:217], off offset:512
	global_load_dwordx4 v[190:193], v[216:217], off offset:528
	s_mov_b32 s84, 0xb0000
	v_lshl_add_u64 v[216:217], s[84:85], 0, v[210:211]
	global_load_dwordx4 v[194:197], v[216:217], off
	global_load_dwordx4 v[198:201], v[216:217], off offset:16
	global_load_dwordx4 v[202:205], v[216:217], off offset:512
	global_load_dwordx4 v[206:209], v[216:217], off offset:528
	s_waitcnt vmcnt(0)
	s_mov_b32 s84, 0x80000
	v_lshl_add_u64 v[216:217], s[84:85], 0, v[210:211]
	s_mov_b32 s88, 0x40000
	v_lshl_add_u64 v[218:219], s[88:89], 0, v[212:213]
	v_pk_fma_f32 v[128:129], v[60:61], 0.5, v[128:129] op_sel_hi:[1,0,1]
	v_pk_fma_f32 v[130:131], v[62:63], 0.5, v[130:131] op_sel_hi:[1,0,1]
	v_pk_fma_f32 v[132:133], v[56:57], 0.5, v[132:133] op_sel_hi:[1,0,1]
	v_pk_fma_f32 v[134:135], v[58:59], 0.5, v[134:135] op_sel_hi:[1,0,1]
	global_store_dwordx4 v[216:217], v[128:131], off
	global_store_dwordx4 v[216:217], v[132:135], off offset:16
	v_cvt_pk_bf16_f32 v224, v128, v129
	v_cvt_pk_bf16_f32 v225, v130, v131
	v_cvt_pk_bf16_f32 v226, v132, v133
	v_cvt_pk_bf16_f32 v227, v134, v135
	global_store_dwordx4 v[218:219], v[224:227], off
	v_mul_f32_e32 v220, v128, v128
	v_fmac_f32_e32 v220, v129, v129
	v_fmac_f32_e32 v220, v130, v130
	v_fmac_f32_e32 v220, v131, v131
	v_fmac_f32_e32 v220, v132, v132
	v_fmac_f32_e32 v220, v133, v133
	v_fmac_f32_e32 v220, v134, v134
	v_fmac_f32_e32 v220, v135, v135
	v_pk_fma_f32 v[136:137], v[52:53], 0.5, v[136:137] op_sel_hi:[1,0,1]
	v_pk_fma_f32 v[138:139], v[54:55], 0.5, v[138:139] op_sel_hi:[1,0,1]
	v_pk_fma_f32 v[140:141], v[48:49], 0.5, v[140:141] op_sel_hi:[1,0,1]
	v_pk_fma_f32 v[142:143], v[50:51], 0.5, v[142:143] op_sel_hi:[1,0,1]
	global_store_dwordx4 v[216:217], v[136:139], off offset:512
	global_store_dwordx4 v[216:217], v[140:143], off offset:528
	v_cvt_pk_bf16_f32 v228, v136, v137
	v_cvt_pk_bf16_f32 v229, v138, v139
	v_cvt_pk_bf16_f32 v230, v140, v141
	v_cvt_pk_bf16_f32 v231, v142, v143
	global_store_dwordx4 v[218:219], v[228:231], off offset:256
	v_fmac_f32_e32 v220, v136, v136
	v_fmac_f32_e32 v220, v137, v137
	v_fmac_f32_e32 v220, v138, v138
	v_fmac_f32_e32 v220, v139, v139
	v_fmac_f32_e32 v220, v140, v140
	v_fmac_f32_e32 v220, v141, v141
	v_fmac_f32_e32 v220, v142, v142
	v_fmac_f32_e32 v220, v143, v143
	s_mov_b32 s84, 0x90000
	v_lshl_add_u64 v[216:217], s[84:85], 0, v[210:211]
	s_mov_b32 s88, 0x48000
	v_lshl_add_u64 v[218:219], s[88:89], 0, v[212:213]
	v_pk_fma_f32 v[144:145], v[44:45], 0.5, v[144:145] op_sel_hi:[1,0,1]
	v_pk_fma_f32 v[146:147], v[46:47], 0.5, v[146:147] op_sel_hi:[1,0,1]
	v_pk_fma_f32 v[148:149], v[40:41], 0.5, v[148:149] op_sel_hi:[1,0,1]
	v_pk_fma_f32 v[150:151], v[42:43], 0.5, v[150:151] op_sel_hi:[1,0,1]
	global_store_dwordx4 v[216:217], v[144:147], off
	global_store_dwordx4 v[216:217], v[148:151], off offset:16
	v_cvt_pk_bf16_f32 v224, v144, v145
	v_cvt_pk_bf16_f32 v225, v146, v147
	v_cvt_pk_bf16_f32 v226, v148, v149
	v_cvt_pk_bf16_f32 v227, v150, v151
	global_store_dwordx4 v[218:219], v[224:227], off
	v_mul_f32_e32 v221, v144, v144
	v_fmac_f32_e32 v221, v145, v145
	v_fmac_f32_e32 v221, v146, v146
	v_fmac_f32_e32 v221, v147, v147
	v_fmac_f32_e32 v221, v148, v148
	v_fmac_f32_e32 v221, v149, v149
	v_fmac_f32_e32 v221, v150, v150
	v_fmac_f32_e32 v221, v151, v151
	v_pk_fma_f32 v[152:153], v[36:37], 0.5, v[152:153] op_sel_hi:[1,0,1]
	v_pk_fma_f32 v[154:155], v[38:39], 0.5, v[154:155] op_sel_hi:[1,0,1]
	v_pk_fma_f32 v[156:157], v[32:33], 0.5, v[156:157] op_sel_hi:[1,0,1]
	v_pk_fma_f32 v[158:159], v[34:35], 0.5, v[158:159] op_sel_hi:[1,0,1]
	global_store_dwordx4 v[216:217], v[152:155], off offset:512
	global_store_dwordx4 v[216:217], v[156:159], off offset:528
	v_cvt_pk_bf16_f32 v228, v152, v153
	v_cvt_pk_bf16_f32 v229, v154, v155
	v_cvt_pk_bf16_f32 v230, v156, v157
	v_cvt_pk_bf16_f32 v231, v158, v159
	global_store_dwordx4 v[218:219], v[228:231], off offset:256
	v_fmac_f32_e32 v221, v152, v152
	v_fmac_f32_e32 v221, v153, v153
	v_fmac_f32_e32 v221, v154, v154
	v_fmac_f32_e32 v221, v155, v155
	v_fmac_f32_e32 v221, v156, v156
	v_fmac_f32_e32 v221, v157, v157
	v_fmac_f32_e32 v221, v158, v158
	v_fmac_f32_e32 v221, v159, v159
	s_mov_b32 s84, 0xa0000
	v_lshl_add_u64 v[216:217], s[84:85], 0, v[210:211]
	s_mov_b32 s88, 0x50000
	v_lshl_add_u64 v[218:219], s[88:89], 0, v[212:213]
	v_pk_fma_f32 v[178:179], v[28:29], 0.5, v[178:179] op_sel_hi:[1,0,1]
	v_pk_fma_f32 v[180:181], v[30:31], 0.5, v[180:181] op_sel_hi:[1,0,1]
	v_pk_fma_f32 v[182:183], v[24:25], 0.5, v[182:183] op_sel_hi:[1,0,1]
	v_pk_fma_f32 v[184:185], v[26:27], 0.5, v[184:185] op_sel_hi:[1,0,1]
	global_store_dwordx4 v[216:217], v[178:181], off
	global_store_dwordx4 v[216:217], v[182:185], off offset:16
	v_cvt_pk_bf16_f32 v224, v178, v179
	v_cvt_pk_bf16_f32 v225, v180, v181
	v_cvt_pk_bf16_f32 v226, v182, v183
	v_cvt_pk_bf16_f32 v227, v184, v185
	global_store_dwordx4 v[218:219], v[224:227], off
	v_mul_f32_e32 v222, v178, v178
	v_fmac_f32_e32 v222, v179, v179
	v_fmac_f32_e32 v222, v180, v180
	v_fmac_f32_e32 v222, v181, v181
	v_fmac_f32_e32 v222, v182, v182
	v_fmac_f32_e32 v222, v183, v183
	v_fmac_f32_e32 v222, v184, v184
	v_fmac_f32_e32 v222, v185, v185
	v_pk_fma_f32 v[186:187], v[20:21], 0.5, v[186:187] op_sel_hi:[1,0,1]
	v_pk_fma_f32 v[188:189], v[22:23], 0.5, v[188:189] op_sel_hi:[1,0,1]
	v_pk_fma_f32 v[190:191], v[16:17], 0.5, v[190:191] op_sel_hi:[1,0,1]
	v_pk_fma_f32 v[192:193], v[18:19], 0.5, v[192:193] op_sel_hi:[1,0,1]
	global_store_dwordx4 v[216:217], v[186:189], off offset:512
	global_store_dwordx4 v[216:217], v[190:193], off offset:528
	v_cvt_pk_bf16_f32 v228, v186, v187
	v_cvt_pk_bf16_f32 v229, v188, v189
	v_cvt_pk_bf16_f32 v230, v190, v191
	v_cvt_pk_bf16_f32 v231, v192, v193
	global_store_dwordx4 v[218:219], v[228:231], off offset:256
	v_fmac_f32_e32 v222, v186, v186
	v_fmac_f32_e32 v222, v187, v187
	v_fmac_f32_e32 v222, v188, v188
	v_fmac_f32_e32 v222, v189, v189
	v_fmac_f32_e32 v222, v190, v190
	v_fmac_f32_e32 v222, v191, v191
	v_fmac_f32_e32 v222, v192, v192
	v_fmac_f32_e32 v222, v193, v193
	s_mov_b32 s84, 0xb0000
	v_lshl_add_u64 v[216:217], s[84:85], 0, v[210:211]
	s_mov_b32 s88, 0x58000
	v_lshl_add_u64 v[218:219], s[88:89], 0, v[212:213]
	v_pk_fma_f32 v[194:195], v[12:13], 0.5, v[194:195] op_sel_hi:[1,0,1]
	v_pk_fma_f32 v[196:197], v[14:15], 0.5, v[196:197] op_sel_hi:[1,0,1]
	v_pk_fma_f32 v[198:199], v[8:9], 0.5, v[198:199] op_sel_hi:[1,0,1]
	v_pk_fma_f32 v[200:201], v[10:11], 0.5, v[200:201] op_sel_hi:[1,0,1]
	global_store_dwordx4 v[216:217], v[194:197], off
	global_store_dwordx4 v[216:217], v[198:201], off offset:16
	v_cvt_pk_bf16_f32 v224, v194, v195
	v_cvt_pk_bf16_f32 v225, v196, v197
	v_cvt_pk_bf16_f32 v226, v198, v199
	v_cvt_pk_bf16_f32 v227, v200, v201
	global_store_dwordx4 v[218:219], v[224:227], off
	v_mul_f32_e32 v223, v194, v194
	v_fmac_f32_e32 v223, v195, v195
	v_fmac_f32_e32 v223, v196, v196
	v_fmac_f32_e32 v223, v197, v197
	v_fmac_f32_e32 v223, v198, v198
	v_fmac_f32_e32 v223, v199, v199
	v_fmac_f32_e32 v223, v200, v200
	v_fmac_f32_e32 v223, v201, v201
	v_pk_fma_f32 v[202:203], v[4:5], 0.5, v[202:203] op_sel_hi:[1,0,1]
	v_pk_fma_f32 v[204:205], v[6:7], 0.5, v[204:205] op_sel_hi:[1,0,1]
	v_pk_fma_f32 v[206:207], v[0:1], 0.5, v[206:207] op_sel_hi:[1,0,1]
	v_pk_fma_f32 v[208:209], v[2:3], 0.5, v[208:209] op_sel_hi:[1,0,1]
	global_store_dwordx4 v[216:217], v[202:205], off offset:512
	global_store_dwordx4 v[216:217], v[206:209], off offset:528
	v_cvt_pk_bf16_f32 v228, v202, v203
	v_cvt_pk_bf16_f32 v229, v204, v205
	v_cvt_pk_bf16_f32 v230, v206, v207
	v_cvt_pk_bf16_f32 v231, v208, v209
	global_store_dwordx4 v[218:219], v[228:231], off offset:256
	v_fmac_f32_e32 v223, v202, v202
	v_fmac_f32_e32 v223, v203, v203
	v_fmac_f32_e32 v223, v204, v204
	v_fmac_f32_e32 v223, v205, v205
	v_fmac_f32_e32 v223, v206, v206
	v_fmac_f32_e32 v223, v207, v207
	v_fmac_f32_e32 v223, v208, v208
	v_fmac_f32_e32 v223, v209, v209
	ds_bpermute_b32 v224, v171, v220
	ds_bpermute_b32 v225, v171, v221
	ds_bpermute_b32 v226, v171, v222
	ds_bpermute_b32 v227, v171, v223
	s_waitcnt lgkmcnt(0)
	v_add_f32_e32 v220, v220, v224
	v_add_f32_e32 v221, v221, v225
	v_add_f32_e32 v222, v222, v226
	v_add_f32_e32 v223, v223, v227
	ds_bpermute_b32 v224, v172, v220
	ds_bpermute_b32 v225, v172, v221
	ds_bpermute_b32 v226, v172, v222
	ds_bpermute_b32 v227, v172, v223
	s_waitcnt lgkmcnt(0)
	v_add_f32_e32 v220, v220, v224
	v_add_f32_e32 v221, v221, v225
	v_add_f32_e32 v222, v222, v226
	v_add_f32_e32 v223, v223, v227
	s_and_saveexec_b64 s[90:91], s[86:87]
	global_atomic_add_f32 v[214:215], v220, off offset:512
	global_atomic_add_f32 v[214:215], v221, off offset:576
	global_atomic_add_f32 v[214:215], v222, off offset:640
	global_atomic_add_f32 v[214:215], v223, off offset:704
	s_mov_b64 exec, s[90:91]

.LBB0_514:
	s_and_b32 s80, s33, 64
	s_cmp_lg_u32 s80, 0
	s_cbranch_scc1 .Lpost2_skip
	v_and_b32_e32 v160, 15, v174
	v_bfe_u32 v161, v174, 4, 2
	v_lshrrev_b32_e32 v162, 6, v174
	v_and_b32_e32 v136, 63, v174
	v_readfirstlane_b32 s80, v162
	s_lshr_b32 s81, s33, 8
	s_lshr_b32 s82, s33, 3
	s_and_b32 s82, s82, 31
	s_mul_i32 s83, s80, 704
	v_lshlrev_b32_e32 v164, 4, v161
	v_mov_b32_e32 v167, 0
	s_lshl_b32 s84, s82, 5
	v_add_u32_e32 v165, s84, v160
	v_mul_u32_u24_e32 v166, 0x1600, v165
	v_add3_u32 v166, v166, v164, s83
	s_add_u32 s86, s74, 0x3700000
	s_addc_u32 s87, s75, 0
	s_mov_b32 s88, 0x16000
	s_mov_b32 s89, 0
	v_lshl_add_u64 v[152:153], s[86:87], 0, v[166:167]
	v_lshl_add_u64 v[154:155], v[152:153], 0, s[88:89]
	s_lshl_b32 s84, s81, 5
	v_add_u32_e32 v165, s84, v160
	v_mul_u32_u24_e32 v166, 0x1600, v165
	v_add3_u32 v166, v166, v164, s83
	s_add_u32 s90, s74, 0x10980000
	s_addc_u32 s91, s75, 0
	v_lshl_add_u64 v[156:157], s[90:91], 0, v[166:167]
	v_lshl_add_u64 v[158:159], v[156:157], 0, s[88:89]
	v_mov_b32_e32 v128, 0
	v_mov_b32_e32 v129, 0
	v_mov_b32_e32 v130, 0
	v_mov_b32_e32 v131, 0
	v_mov_b32_e32 v132, 0
	v_mov_b32_e32 v133, 0
	v_mov_b32_e32 v134, 0
	v_mov_b32_e32 v135, 0
	v_mov_b32_e32 v144, 0
	v_mov_b32_e32 v145, 0
	v_mov_b32_e32 v146, 0
	v_mov_b32_e32 v147, 0
	v_mov_b32_e32 v148, 0
	v_mov_b32_e32 v149, 0
	v_mov_b32_e32 v150, 0
	v_mov_b32_e32 v151, 0
	global_load_dwordx4 v[0:3], v[152:153], off
	global_load_dwordx4 v[4:7], v[154:155], off
	global_load_dwordx4 v[8:11], v[156:157], off
	global_load_dwordx4 v[12:15], v[158:159], off
	global_load_dwordx4 v[16:19], v[152:153], off offset:64
	global_load_dwordx4 v[20:23], v[154:155], off offset:64
	global_load_dwordx4 v[24:27], v[156:157], off offset:64
	global_load_dwordx4 v[28:31], v[158:159], off offset:64
	global_load_dwordx4 v[32:35], v[152:153], off offset:128
	global_load_dwordx4 v[36:39], v[154:155], off offset:128
	global_load_dwordx4 v[40:43], v[156:157], off offset:128
	global_load_dwordx4 v[44:47], v[158:159], off offset:128
	global_load_dwordx4 v[48:51], v[152:153], off offset:192
	global_load_dwordx4 v[52:55], v[154:155], off offset:192
	global_load_dwordx4 v[56:59], v[156:157], off offset:192
	global_load_dwordx4 v[60:63], v[158:159], off offset:192
	global_load_dwordx4 v[64:67], v[152:153], off offset:256
	global_load_dwordx4 v[68:71], v[154:155], off offset:256
	global_load_dwordx4 v[72:75], v[156:157], off offset:256
	global_load_dwordx4 v[76:79], v[158:159], off offset:256
	global_load_dwordx4 v[80:83], v[152:153], off offset:320
	global_load_dwordx4 v[84:87], v[154:155], off offset:320
	global_load_dwordx4 v[88:91], v[156:157], off offset:320
	global_load_dwordx4 v[92:95], v[158:159], off offset:320
	global_load_dwordx4 v[96:99], v[152:153], off offset:384
	global_load_dwordx4 v[100:103], v[154:155], off offset:384
	global_load_dwordx4 v[104:107], v[156:157], off offset:384
	global_load_dwordx4 v[108:111], v[158:159], off offset:384
	global_load_dwordx4 v[112:115], v[152:153], off offset:448
	global_load_dwordx4 v[116:119], v[154:155], off offset:448
	global_load_dwordx4 v[120:123], v[156:157], off offset:448
	global_load_dwordx4 v[124:127], v[158:159], off offset:448
	s_waitcnt vmcnt(16)
	v_mfma_f32_16x16x32_bf16 v[128:131], v[0:3], v[8:11], v[128:131]
	v_mfma_f32_16x16x32_bf16 v[132:135], v[4:7], v[8:11], v[132:135]
	v_mfma_f32_16x16x32_bf16 v[144:147], v[0:3], v[12:15], v[144:147]
	v_mfma_f32_16x16x32_bf16 v[148:151], v[4:7], v[12:15], v[148:151]
	v_mfma_f32_16x16x32_bf16 v[128:131], v[16:19], v[24:27], v[128:131]
	v_mfma_f32_16x16x32_bf16 v[132:135], v[20:23], v[24:27], v[132:135]
	v_mfma_f32_16x16x32_bf16 v[144:147], v[16:19], v[28:31], v[144:147]
	v_mfma_f32_16x16x32_bf16 v[148:151], v[20:23], v[28:31], v[148:151]
	v_mfma_f32_16x16x32_bf16 v[128:131], v[32:35], v[40:43], v[128:131]
	v_mfma_f32_16x16x32_bf16 v[132:135], v[36:39], v[40:43], v[132:135]
	v_mfma_f32_16x16x32_bf16 v[144:147], v[32:35], v[44:47], v[144:147]
	v_mfma_f32_16x16x32_bf16 v[148:151], v[36:39], v[44:47], v[148:151]
	v_mfma_f32_16x16x32_bf16 v[128:131], v[48:51], v[56:59], v[128:131]
	v_mfma_f32_16x16x32_bf16 v[132:135], v[52:55], v[56:59], v[132:135]
	v_mfma_f32_16x16x32_bf16 v[144:147], v[48:51], v[60:63], v[144:147]
	v_mfma_f32_16x16x32_bf16 v[148:151], v[52:55], v[60:63], v[148:151]
	global_load_dwordx4 v[0:3], v[152:153], off offset:512
	global_load_dwordx4 v[4:7], v[154:155], off offset:512
	global_load_dwordx4 v[8:11], v[156:157], off offset:512
	global_load_dwordx4 v[12:15], v[158:159], off offset:512
	global_load_dwordx4 v[16:19], v[152:153], off offset:576
	global_load_dwordx4 v[20:23], v[154:155], off offset:576
	global_load_dwordx4 v[24:27], v[156:157], off offset:576
	global_load_dwordx4 v[28:31], v[158:159], off offset:576
	global_load_dwordx4 v[32:35], v[152:153], off offset:640
	global_load_dwordx4 v[36:39], v[154:155], off offset:640
	global_load_dwordx4 v[40:43], v[156:157], off offset:640
	global_load_dwordx4 v[44:47], v[158:159], off offset:640
	s_waitcnt vmcnt(12)
	v_mfma_f32_16x16x32_bf16 v[128:131], v[64:67], v[72:75], v[128:131]
	v_mfma_f32_16x16x32_bf16 v[132:135], v[68:71], v[72:75], v[132:135]
	v_mfma_f32_16x16x32_bf16 v[144:147], v[64:67], v[76:79], v[144:147]
	v_mfma_f32_16x16x32_bf16 v[148:151], v[68:71], v[76:79], v[148:151]
	v_mfma_f32_16x16x32_bf16 v[128:131], v[80:83], v[88:91], v[128:131]
	v_mfma_f32_16x16x32_bf16 v[132:135], v[84:87], v[88:91], v[132:135]
	v_mfma_f32_16x16x32_bf16 v[144:147], v[80:83], v[92:95], v[144:147]
	v_mfma_f32_16x16x32_bf16 v[148:151], v[84:87], v[92:95], v[148:151]
	v_mfma_f32_16x16x32_bf16 v[128:131], v[96:99], v[104:107], v[128:131]
	v_mfma_f32_16x16x32_bf16 v[132:135], v[100:103], v[104:107], v[132:135]
	v_mfma_f32_16x16x32_bf16 v[144:147], v[96:99], v[108:111], v[144:147]
	v_mfma_f32_16x16x32_bf16 v[148:151], v[100:103], v[108:111], v[148:151]
	v_mfma_f32_16x16x32_bf16 v[128:131], v[112:115], v[120:123], v[128:131]
	v_mfma_f32_16x16x32_bf16 v[132:135], v[116:119], v[120:123], v[132:135]
	v_mfma_f32_16x16x32_bf16 v[144:147], v[112:115], v[124:127], v[144:147]
	v_mfma_f32_16x16x32_bf16 v[148:151], v[116:119], v[124:127], v[148:151]
	s_waitcnt vmcnt(0)
	v_mfma_f32_16x16x32_bf16 v[128:131], v[0:3], v[8:11], v[128:131]
	v_mfma_f32_16x16x32_bf16 v[132:135], v[4:7], v[8:11], v[132:135]
	v_mfma_f32_16x16x32_bf16 v[144:147], v[0:3], v[12:15], v[144:147]
	v_mfma_f32_16x16x32_bf16 v[148:151], v[4:7], v[12:15], v[148:151]
	v_mfma_f32_16x16x32_bf16 v[128:131], v[16:19], v[24:27], v[128:131]
	v_mfma_f32_16x16x32_bf16 v[132:135], v[20:23], v[24:27], v[132:135]
	v_mfma_f32_16x16x32_bf16 v[144:147], v[16:19], v[28:31], v[144:147]
	v_mfma_f32_16x16x32_bf16 v[148:151], v[20:23], v[28:31], v[148:151]
	v_mfma_f32_16x16x32_bf16 v[128:131], v[32:35], v[40:43], v[128:131]
	v_mfma_f32_16x16x32_bf16 v[132:135], v[36:39], v[40:43], v[132:135]
	v_mfma_f32_16x16x32_bf16 v[144:147], v[32:35], v[44:47], v[144:147]
	v_mfma_f32_16x16x32_bf16 v[148:151], v[36:39], v[44:47], v[148:151]
	s_nop 7
	s_nop 7
	v_lshlrev_b32_e32 v170, 12, v162
	v_lshl_add_u32 v170, v136, 4, v170
	ds_write_b128 v170, v[128:131]
	ds_write_b128 v170, v[132:135] offset:1024
	ds_write_b128 v170, v[144:147] offset:2048
	ds_write_b128 v170, v[148:151] offset:3072
	s_waitcnt lgkmcnt(0)
	s_barrier
	s_cmp_ge_u32 s80, 4
	s_cbranch_scc1 .Lmg2_end
	s_lshl_b32 s84, s80, 10
	v_lshlrev_b32_e32 v171, 4, v136
	v_add_u32_e32 v171, s84, v171
	ds_read_b128 v[0:3], v171
	ds_read_b128 v[4:7], v171 offset:4096
	ds_read_b128 v[8:11], v171 offset:8192
	ds_read_b128 v[12:15], v171 offset:12288
	ds_read_b128 v[16:19], v171 offset:16384
	ds_read_b128 v[20:23], v171 offset:20480
	ds_read_b128 v[24:27], v171 offset:24576
	ds_read_b128 v[28:31], v171 offset:28672
	s_lshr_b32 s84, s80, 1
	s_lshl_b32 s84, s84, 4
	s_lshl_b32 s85, s81, 5
	s_add_i32 s84, s84, s85
	s_addk_i32 s84, 0x4000
	s_and_b32 s85, s80, 1
	s_lshl_b32 s85, s85, 4
	s_lshl_b32 s83, s82, 5
	s_add_i32 s85, s85, s83
	v_add_u32_e32 v165, s84, v160
	v_lshl_add_u32 v164, v161, 2, s85
	v_lshlrev_b32_e32 v166, 12, v165
	v_lshl_add_u32 v166, v164, 2, v166
	v_mov_b32_e32 v167, 0
	s_add_u32 s86, s74, 0x5000000
	s_addc_u32 s87, s75, 0
	v_lshl_add_u64 v[168:169], s[86:87], 0, v[166:167]
	global_load_dwordx4 v[32:35], v[168:169], off
	v_lshrrev_b32_e32 v172, 1, v166
	v_mov_b32_e32 v173, 0
	s_add_u32 s86, s74, 0x9100000
	s_addc_u32 s87, s75, 0
	v_lshl_add_u64 v[172:173], s[86:87], 0, v[172:173]
	v_lshlrev_b32_e32 v166, 2, v165
	s_add_u32 s86, s74, 0x12b90c00
	s_addc_u32 s87, s75, 0
	v_lshl_add_u64 v[166:167], s[86:87], 0, v[166:167]
	s_waitcnt lgkmcnt(0)
	v_add_f32_e32 v0, v0, v4
	v_add_f32_e32 v1, v1, v5
	v_add_f32_e32 v2, v2, v6
	v_add_f32_e32 v3, v3, v7
	v_add_f32_e32 v0, v0, v8
	v_add_f32_e32 v1, v1, v9
	v_add_f32_e32 v2, v2, v10
	v_add_f32_e32 v3, v3, v11
	v_add_f32_e32 v0, v0, v12
	v_add_f32_e32 v1, v1, v13
	v_add_f32_e32 v2, v2, v14
	v_add_f32_e32 v3, v3, v15
	v_add_f32_e32 v0, v0, v16
	v_add_f32_e32 v1, v1, v17
	v_add_f32_e32 v2, v2, v18
	v_add_f32_e32 v3, v3, v19
	v_add_f32_e32 v0, v0, v20
	v_add_f32_e32 v1, v1, v21
	v_add_f32_e32 v2, v2, v22
	v_add_f32_e32 v3, v3, v23
	v_add_f32_e32 v0, v0, v24
	v_add_f32_e32 v1, v1, v25
	v_add_f32_e32 v2, v2, v26
	v_add_f32_e32 v3, v3, v27
	v_add_f32_e32 v0, v0, v28
	v_add_f32_e32 v1, v1, v29
	v_add_f32_e32 v2, v2, v30
	v_add_f32_e32 v3, v3, v31
	s_waitcnt vmcnt(0)
	v_fma_f32 v32, v0, 0.5, v32
	v_fma_f32 v33, v1, 0.5, v33
	v_fma_f32 v34, v2, 0.5, v34
	v_fma_f32 v35, v3, 0.5, v35
	global_store_dwordx4 v[168:169], v[32:35], off
	v_cvt_pk_bf16_f32 v36, v32, v33
	v_cvt_pk_bf16_f32 v37, v34, v35
	global_store_dwordx2 v[172:173], v[36:37], off
	v_mul_f32_e32 v38, v32, v32
	v_fmac_f32_e32 v38, v33, v33
	v_fmac_f32_e32 v38, v34, v34
	v_fmac_f32_e32 v38, v35, v35
	v_xor_b32_e32 v39, 16, v136
	v_lshlrev_b32_e32 v39, 2, v39
	ds_bpermute_b32 v40, v39, v38
	v_xor_b32_e32 v41, 32, v136
	v_lshlrev_b32_e32 v41, 2, v41
	s_waitcnt lgkmcnt(0)
	v_add_f32_e32 v38, v38, v40
	ds_bpermute_b32 v40, v41, v38
	s_waitcnt lgkmcnt(0)
	v_add_f32_e32 v38, v38, v40
	v_cmp_gt_u32_e64 s[82:83], 16, v136
	s_nop 1
	s_and_saveexec_b64 s[84:85], s[82:83]
	global_atomic_add_f32 v[166:167], v38, off
	s_mov_b64 exec, s[84:85]
.Lmg2_end:
	v_lshrrev_b32_e32 v21, 6, v174
	v_and_b32_e32 v22, 63, v174
	v_lshlrev_b32_e32 v22, 4, v22
	v_readfirstlane_b32 s80, v21
	v_add_u32_e32 v23, 0x1000, v22
	v_readfirstlane_b32 s92, v235
	v_readfirstlane_b32 s93, v236
	v_readfirstlane_b32 s94, v237
	v_readfirstlane_b32 s95, v238
	v_readfirstlane_b32 s98, v239
	v_readfirstlane_b32 s99, v240
	s_lshr_b32 s100, s33, 7
	s_lshl_b32 s100, s100, 3
	s_lshr_b32 s101, s33, 3
	s_and_b32 s101, s101, 7
	s_add_i32 s100, s100, s101
	s_lshl_b32 s100, s100, 3
	s_add_i32 s80, s80, s100
	s_add_i32 s80, s80, 0xb504
	s_movk_i32 s100, 0x400

.Lcpy2_end:
.Lpost2_skip:
	s_waitcnt vmcnt(0)
	s_waitcnt lgkmcnt(0)
	s_barrier
	s_and_saveexec_b64 s[8:9], s[0:1]
	s_cbranch_execz .LBB0_534
	v_rcp_iflag_f32_e32 v0, v176
	s_sub_i32 s4, 0, s78
	s_mov_b64 s[10:11], exec
	buffer_wbl2 sc1
	s_waitcnt vmcnt(0)
	v_mul_f32_e32 v0, 0x4f7ffffe, v0
	v_cvt_u32_f32_e32 v0, v0
	s_waitcnt vmcnt(0)
	v_mbcnt_lo_u32_b32 v1, s10, 0
	s_mul_i32 s5, s78, 7
	v_readfirstlane_b32 s6, v0
	s_mul_i32 s4, s4, s6
	s_mul_hi_u32 s4, s6, s4
	s_add_i32 s6, s6, s4
	v_mbcnt_hi_u32_b32 v0, s11, v1
	s_mul_hi_u32 s4, s5, s6
	v_cmp_eq_u32_e32 vcc, 0, v0
	s_and_saveexec_b64 s[12:13], vcc
	s_cbranch_execz .LBB0_517
	s_bcnt1_i32_b64 s6, s[10:11]
	v_mov_b32_e32 v1, 0
	v_mov_b32_e32 v2, s6
	global_atomic_add v1, v1, v2, s[96:97] sc0

.LBB0_980:
	s_or_b64 exec, exec, s[8:9]
	v_readlane_b32 s4, v234, 2
	v_mov_b32_e32 v8, v174
	v_readlane_b32 s5, v234, 3
	s_barrier
	s_and_b32 s80, s33, 64
	s_cmp_eq_u32 s80, 0
	s_cbranch_scc1 .Lpre3_skip
	v_lshrrev_b32_e32 v21, 6, v174
	v_and_b32_e32 v22, 63, v174
	v_lshlrev_b32_e32 v22, 4, v22
	v_readfirstlane_b32 s80, v21
	v_add_u32_e32 v23, 0x1000, v22
	v_readfirstlane_b32 s92, v235
	v_readfirstlane_b32 s93, v236
	v_readfirstlane_b32 s94, v237
	v_readfirstlane_b32 s95, v238
	v_readfirstlane_b32 s98, v239
	v_readfirstlane_b32 s99, v240
	s_lshr_b32 s100, s33, 7
	s_lshl_b32 s100, s100, 3
	s_lshr_b32 s101, s33, 3
	s_and_b32 s101, s101, 7
	s_add_i32 s100, s100, s101
	s_lshl_b32 s100, s100, 3
	s_add_i32 s80, s80, s100
	s_add_i32 s80, s80, 0xda98
	s_movk_i32 s100, 0x400
.Lcpy3p_loop:
	s_add_i32 s101, s80, s100
	s_cmp_lt_u32 s101, 0xf94c
	s_cbranch_scc0 .Lcpy3p_tail
	s_mul_hi_u32 s81, s80, 0x2ad5802b
	s_lshr_b32 s81, s81, 8
	s_mul_i32 s82, s81, 0x5fa
	s_sub_i32 s82, s80, s82
	s_lshl_b32 s82, s82, 13
	s_and_b32 s83, s81, 31
	s_mul_i32 s83, s83, 0xc00000
	s_add_i32 s82, s82, s83
	s_cmp_lt_u32 s81, 32
	s_cselect_b32 s84, s92, s94
	s_cselect_b32 s85, s93, s95
	s_mov_b32 s83, 0x1f210000
	s_cselect_b32 s83, 0x7210000, s83
	s_add_u32 s84, s84, s82
	s_addc_u32 s85, s85, 0
	s_add_u32 s84, s84, 0xc000
	s_addc_u32 s85, s85, 0
	s_add_u32 s83, s83, s82
	s_add_u32 s86, s98, s83
	s_addc_u32 s87, s99, 0
	s_mul_hi_u32 s81, s101, 0x2ad5802b
	s_lshr_b32 s81, s81, 8
	s_mul_i32 s82, s81, 0x5fa
	s_sub_i32 s82, s101, s82
	s_lshl_b32 s82, s82, 13
	s_and_b32 s83, s81, 31
	s_mul_i32 s83, s83, 0xc00000
	s_add_i32 s82, s82, s83
	s_cmp_lt_u32 s81, 32
	s_cselect_b32 s88, s92, s94
	s_cselect_b32 s89, s93, s95
	s_mov_b32 s83, 0x1f210000
	s_cselect_b32 s83, 0x7210000, s83
	s_add_u32 s88, s88, s82
	s_addc_u32 s89, s89, 0
	s_add_u32 s88, s88, 0xc000
	s_addc_u32 s89, s89, 0
	s_add_u32 s83, s83, s82
	s_add_u32 s90, s98, s83
	s_addc_u32 s91, s99, 0
	global_load_dwordx4 v[64:67], v22, s[84:85] nt
	global_load_dwordx4 v[68:71], v22, s[84:85] offset:1024 nt
	global_load_dwordx4 v[72:75], v22, s[84:85] offset:2048 nt
	global_load_dwordx4 v[76:79], v22, s[84:85] offset:3072 nt
	global_load_dwordx4 v[80:83], v23, s[84:85] nt
	global_load_dwordx4 v[84:87], v23, s[84:85] offset:1024 nt
	global_load_dwordx4 v[88:91], v23, s[84:85] offset:2048 nt
	global_load_dwordx4 v[92:95], v23, s[84:85] offset:3072 nt
	global_load_dwordx4 v[96:99], v22, s[88:89] nt
	global_load_dwordx4 v[100:103], v22, s[88:89] offset:1024 nt
	global_load_dwordx4 v[104:107], v22, s[88:89] offset:2048 nt
	global_load_dwordx4 v[108:111], v22, s[88:89] offset:3072 nt
	global_load_dwordx4 v[112:115], v23, s[88:89] nt
	global_load_dwordx4 v[116:119], v23, s[88:89] offset:1024 nt
	global_load_dwordx4 v[120:123], v23, s[88:89] offset:2048 nt
	global_load_dwordx4 v[124:127], v23, s[88:89] offset:3072 nt
	s_waitcnt vmcnt(15)
	global_store_dwordx4 v22, v[64:67], s[86:87] nt
	s_waitcnt vmcnt(15)
	global_store_dwordx4 v22, v[68:71], s[86:87] offset:1024 nt
	s_waitcnt vmcnt(15)
	global_store_dwordx4 v22, v[72:75], s[86:87] offset:2048 nt
	s_waitcnt vmcnt(15)
	global_store_dwordx4 v22, v[76:79], s[86:87] offset:3072 nt
	s_waitcnt vmcnt(15)
	global_store_dwordx4 v23, v[80:83], s[86:87] nt
	s_waitcnt vmcnt(15)
	global_store_dwordx4 v23, v[84:87], s[86:87] offset:1024 nt
	s_waitcnt vmcnt(15)
	global_store_dwordx4 v23, v[88:91], s[86:87] offset:2048 nt
	s_waitcnt vmcnt(15)
	global_store_dwordx4 v23, v[92:95], s[86:87] offset:3072 nt
	s_waitcnt vmcnt(15)
	global_store_dwordx4 v22, v[96:99], s[90:91] nt
	s_waitcnt vmcnt(15)
	global_store_dwordx4 v22, v[100:103], s[90:91] offset:1024 nt
	s_waitcnt vmcnt(15)
	global_store_dwordx4 v22, v[104:107], s[90:91] offset:2048 nt
	s_waitcnt vmcnt(15)
	global_store_dwordx4 v22, v[108:111], s[90:91] offset:3072 nt
	s_waitcnt vmcnt(15)
	global_store_dwordx4 v23, v[112:115], s[90:91] nt
	s_waitcnt vmcnt(15)
	global_store_dwordx4 v23, v[116:119], s[90:91] offset:1024 nt
	s_waitcnt vmcnt(15)
	global_store_dwordx4 v23, v[120:123], s[90:91] offset:2048 nt
	s_waitcnt vmcnt(15)
	global_store_dwordx4 v23, v[124:127], s[90:91] offset:3072 nt
	s_add_i32 s80, s101, s100
	s_branch .Lcpy3p_loop
.Lcpy3p_tail:
	s_cmp_lt_u32 s80, 0xf94c
	s_cbranch_scc0 .Lcpy3p_end
	s_mul_hi_u32 s81, s80, 0x2ad5802b
	s_lshr_b32 s81, s81, 8
	s_mul_i32 s82, s81, 0x5fa
	s_sub_i32 s82, s80, s82
	s_lshl_b32 s82, s82, 13
	s_and_b32 s83, s81, 31
	s_mul_i32 s83, s83, 0xc00000
	s_add_i32 s82, s82, s83
	s_cmp_lt_u32 s81, 32
	s_cselect_b32 s84, s92, s94
	s_cselect_b32 s85, s93, s95
	s_mov_b32 s83, 0x1f210000
	s_cselect_b32 s83, 0x7210000, s83
	s_add_u32 s84, s84, s82
	s_addc_u32 s85, s85, 0
	s_add_u32 s84, s84, 0xc000
	s_addc_u32 s85, s85, 0
	s_add_u32 s83, s83, s82
	s_add_u32 s86, s98, s83
	s_addc_u32 s87, s99, 0
	global_load_dwordx4 v[64:67], v22, s[84:85] nt
	global_load_dwordx4 v[68:71], v22, s[84:85] offset:1024 nt
	global_load_dwordx4 v[72:75], v22, s[84:85] offset:2048 nt
	global_load_dwordx4 v[76:79], v22, s[84:85] offset:3072 nt
	global_load_dwordx4 v[80:83], v23, s[84:85] nt
	global_load_dwordx4 v[84:87], v23, s[84:85] offset:1024 nt
	global_load_dwordx4 v[88:91], v23, s[84:85] offset:2048 nt
	global_load_dwordx4 v[92:95], v23, s[84:85] offset:3072 nt
	s_waitcnt vmcnt(7)
	global_store_dwordx4 v22, v[64:67], s[86:87] nt
	s_waitcnt vmcnt(7)
	global_store_dwordx4 v22, v[68:71], s[86:87] offset:1024 nt
	s_waitcnt vmcnt(7)
	global_store_dwordx4 v22, v[72:75], s[86:87] offset:2048 nt
	s_waitcnt vmcnt(7)
	global_store_dwordx4 v22, v[76:79], s[86:87] offset:3072 nt
	s_waitcnt vmcnt(7)
	global_store_dwordx4 v23, v[80:83], s[86:87] nt
	s_waitcnt vmcnt(7)
	global_store_dwordx4 v23, v[84:87], s[86:87] offset:1024 nt
	s_waitcnt vmcnt(7)
	global_store_dwordx4 v23, v[88:91], s[86:87] offset:2048 nt
	s_waitcnt vmcnt(7)
	global_store_dwordx4 v23, v[92:95], s[86:87] offset:3072 nt
.Lcpy3p_end:
	v_and_b32_e32 v160, 15, v174
	v_bfe_u32 v161, v174, 4, 2
	v_lshrrev_b32_e32 v162, 6, v174
	v_and_b32_e32 v136, 63, v174
	v_readfirstlane_b32 s80, v162
	s_lshr_b32 s81, s33, 8
	s_lshr_b32 s82, s33, 3
	s_and_b32 s82, s82, 31
	s_mul_i32 s83, s80, 704
	v_lshlrev_b32_e32 v164, 4, v161
	v_mov_b32_e32 v167, 0
	s_lshl_b32 s84, s82, 5
	v_add_u32_e32 v165, s84, v160
	v_mul_u32_u24_e32 v166, 0x1600, v165
	v_add3_u32 v166, v166, v164, s83
	s_add_u32 s86, s74, 0x3180000
	s_addc_u32 s87, s75, 0
	s_mov_b32 s88, 0x16000
	s_mov_b32 s89, 0
	v_lshl_add_u64 v[152:153], s[86:87], 0, v[166:167]
	v_lshl_add_u64 v[154:155], v[152:153], 0, s[88:89]
	s_lshl_b32 s84, s81, 5
	v_add_u32_e32 v165, s84, v160
	v_mul_u32_u24_e32 v166, 0x1600, v165
	v_add3_u32 v166, v166, v164, s83
	s_add_u32 s90, s74, 0x10980000
	s_addc_u32 s91, s75, 0
	v_lshl_add_u64 v[156:157], s[90:91], 0, v[166:167]
	v_lshl_add_u64 v[158:159], v[156:157], 0, s[88:89]
	v_mov_b32_e32 v128, 0
	v_mov_b32_e32 v129, 0
	v_mov_b32_e32 v130, 0
	v_mov_b32_e32 v131, 0
	v_mov_b32_e32 v132, 0
	v_mov_b32_e32 v133, 0
	v_mov_b32_e32 v134, 0
	v_mov_b32_e32 v135, 0
	v_mov_b32_e32 v144, 0
	v_mov_b32_e32 v145, 0
	v_mov_b32_e32 v146, 0
	v_mov_b32_e32 v147, 0
	v_mov_b32_e32 v148, 0
	v_mov_b32_e32 v149, 0
	v_mov_b32_e32 v150, 0
	v_mov_b32_e32 v151, 0
	global_load_dwordx4 v[0:3], v[152:153], off
	global_load_dwordx4 v[4:7], v[154:155], off
	global_load_dwordx4 v[8:11], v[156:157], off
	global_load_dwordx4 v[12:15], v[158:159], off
	global_load_dwordx4 v[16:19], v[152:153], off offset:64
	global_load_dwordx4 v[20:23], v[154:155], off offset:64
	global_load_dwordx4 v[24:27], v[156:157], off offset:64
	global_load_dwordx4 v[28:31], v[158:159], off offset:64
	global_load_dwordx4 v[32:35], v[152:153], off offset:128
	global_load_dwordx4 v[36:39], v[154:155], off offset:128
	global_load_dwordx4 v[40:43], v[156:157], off offset:128
	global_load_dwordx4 v[44:47], v[158:159], off offset:128
	global_load_dwordx4 v[48:51], v[152:153], off offset:192
	global_load_dwordx4 v[52:55], v[154:155], off offset:192
	global_load_dwordx4 v[56:59], v[156:157], off offset:192
	global_load_dwordx4 v[60:63], v[158:159], off offset:192
	global_load_dwordx4 v[64:67], v[152:153], off offset:256
	global_load_dwordx4 v[68:71], v[154:155], off offset:256
	global_load_dwordx4 v[72:75], v[156:157], off offset:256
	global_load_dwordx4 v[76:79], v[158:159], off offset:256
	global_load_dwordx4 v[80:83], v[152:153], off offset:320
	global_load_dwordx4 v[84:87], v[154:155], off offset:320
	global_load_dwordx4 v[88:91], v[156:157], off offset:320
	global_load_dwordx4 v[92:95], v[158:159], off offset:320
	global_load_dwordx4 v[96:99], v[152:153], off offset:384
	global_load_dwordx4 v[100:103], v[154:155], off offset:384
	global_load_dwordx4 v[104:107], v[156:157], off offset:384
	global_load_dwordx4 v[108:111], v[158:159], off offset:384
	global_load_dwordx4 v[112:115], v[152:153], off offset:448
	global_load_dwordx4 v[116:119], v[154:155], off offset:448
	global_load_dwordx4 v[120:123], v[156:157], off offset:448
	global_load_dwordx4 v[124:127], v[158:159], off offset:448
	s_waitcnt vmcnt(16)
	v_mfma_f32_16x16x32_bf16 v[128:131], v[0:3], v[8:11], v[128:131]
	v_mfma_f32_16x16x32_bf16 v[132:135], v[4:7], v[8:11], v[132:135]
	v_mfma_f32_16x16x32_bf16 v[144:147], v[0:3], v[12:15], v[144:147]
	v_mfma_f32_16x16x32_bf16 v[148:151], v[4:7], v[12:15], v[148:151]
	v_mfma_f32_16x16x32_bf16 v[128:131], v[16:19], v[24:27], v[128:131]
	v_mfma_f32_16x16x32_bf16 v[132:135], v[20:23], v[24:27], v[132:135]
	v_mfma_f32_16x16x32_bf16 v[144:147], v[16:19], v[28:31], v[144:147]
	v_mfma_f32_16x16x32_bf16 v[148:151], v[20:23], v[28:31], v[148:151]
	v_mfma_f32_16x16x32_bf16 v[128:131], v[32:35], v[40:43], v[128:131]
	v_mfma_f32_16x16x32_bf16 v[132:135], v[36:39], v[40:43], v[132:135]
	v_mfma_f32_16x16x32_bf16 v[144:147], v[32:35], v[44:47], v[144:147]
	v_mfma_f32_16x16x32_bf16 v[148:151], v[36:39], v[44:47], v[148:151]
	v_mfma_f32_16x16x32_bf16 v[128:131], v[48:51], v[56:59], v[128:131]
	v_mfma_f32_16x16x32_bf16 v[132:135], v[52:55], v[56:59], v[132:135]
	v_mfma_f32_16x16x32_bf16 v[144:147], v[48:51], v[60:63], v[144:147]
	v_mfma_f32_16x16x32_bf16 v[148:151], v[52:55], v[60:63], v[148:151]
	global_load_dwordx4 v[0:3], v[152:153], off offset:512
	global_load_dwordx4 v[4:7], v[154:155], off offset:512
	global_load_dwordx4 v[8:11], v[156:157], off offset:512
	global_load_dwordx4 v[12:15], v[158:159], off offset:512
	global_load_dwordx4 v[16:19], v[152:153], off offset:576
	global_load_dwordx4 v[20:23], v[154:155], off offset:576
	global_load_dwordx4 v[24:27], v[156:157], off offset:576
	global_load_dwordx4 v[28:31], v[158:159], off offset:576
	global_load_dwordx4 v[32:35], v[152:153], off offset:640
	global_load_dwordx4 v[36:39], v[154:155], off offset:640
	global_load_dwordx4 v[40:43], v[156:157], off offset:640
	global_load_dwordx4 v[44:47], v[158:159], off offset:640
	s_waitcnt vmcnt(12)
	v_mfma_f32_16x16x32_bf16 v[128:131], v[64:67], v[72:75], v[128:131]
	v_mfma_f32_16x16x32_bf16 v[132:135], v[68:71], v[72:75], v[132:135]
	v_mfma_f32_16x16x32_bf16 v[144:147], v[64:67], v[76:79], v[144:147]
	v_mfma_f32_16x16x32_bf16 v[148:151], v[68:71], v[76:79], v[148:151]
	v_mfma_f32_16x16x32_bf16 v[128:131], v[80:83], v[88:91], v[128:131]
	v_mfma_f32_16x16x32_bf16 v[132:135], v[84:87], v[88:91], v[132:135]
	v_mfma_f32_16x16x32_bf16 v[144:147], v[80:83], v[92:95], v[144:147]
	v_mfma_f32_16x16x32_bf16 v[148:151], v[84:87], v[92:95], v[148:151]
	v_mfma_f32_16x16x32_bf16 v[128:131], v[96:99], v[104:107], v[128:131]
	v_mfma_f32_16x16x32_bf16 v[132:135], v[100:103], v[104:107], v[132:135]
	v_mfma_f32_16x16x32_bf16 v[144:147], v[96:99], v[108:111], v[144:147]
	v_mfma_f32_16x16x32_bf16 v[148:151], v[100:103], v[108:111], v[148:151]
	v_mfma_f32_16x16x32_bf16 v[128:131], v[112:115], v[120:123], v[128:131]
	v_mfma_f32_16x16x32_bf16 v[132:135], v[116:119], v[120:123], v[132:135]
	v_mfma_f32_16x16x32_bf16 v[144:147], v[112:115], v[124:127], v[144:147]
	v_mfma_f32_16x16x32_bf16 v[148:151], v[116:119], v[124:127], v[148:151]
	s_waitcnt vmcnt(0)
	v_mfma_f32_16x16x32_bf16 v[128:131], v[0:3], v[8:11], v[128:131]
	v_mfma_f32_16x16x32_bf16 v[132:135], v[4:7], v[8:11], v[132:135]
	v_mfma_f32_16x16x32_bf16 v[144:147], v[0:3], v[12:15], v[144:147]
	v_mfma_f32_16x16x32_bf16 v[148:151], v[4:7], v[12:15], v[148:151]
	v_mfma_f32_16x16x32_bf16 v[128:131], v[16:19], v[24:27], v[128:131]
	v_mfma_f32_16x16x32_bf16 v[132:135], v[20:23], v[24:27], v[132:135]
	v_mfma_f32_16x16x32_bf16 v[144:147], v[16:19], v[28:31], v[144:147]
	v_mfma_f32_16x16x32_bf16 v[148:151], v[20:23], v[28:31], v[148:151]
	v_mfma_f32_16x16x32_bf16 v[128:131], v[32:35], v[40:43], v[128:131]
	v_mfma_f32_16x16x32_bf16 v[132:135], v[36:39], v[40:43], v[132:135]
	v_mfma_f32_16x16x32_bf16 v[144:147], v[32:35], v[44:47], v[144:147]
	v_mfma_f32_16x16x32_bf16 v[148:151], v[36:39], v[44:47], v[148:151]
	s_nop 7
	s_nop 7
	v_lshlrev_b32_e32 v170, 12, v162
	v_lshl_add_u32 v170, v136, 4, v170
	ds_write_b128 v170, v[128:131]
	ds_write_b128 v170, v[132:135] offset:1024
	ds_write_b128 v170, v[144:147] offset:2048
	ds_write_b128 v170, v[148:151] offset:3072
	s_waitcnt lgkmcnt(0)
	s_barrier
	s_cmp_ge_u32 s80, 4
	s_cbranch_scc1 .Lmg3p_end
	s_lshl_b32 s84, s80, 10
	v_lshlrev_b32_e32 v171, 4, v136
	v_add_u32_e32 v171, s84, v171
	ds_read_b128 v[0:3], v171
	ds_read_b128 v[4:7], v171 offset:4096
	ds_read_b128 v[8:11], v171 offset:8192
	ds_read_b128 v[12:15], v171 offset:12288
	ds_read_b128 v[16:19], v171 offset:16384
	ds_read_b128 v[20:23], v171 offset:20480
	ds_read_b128 v[24:27], v171 offset:24576
	ds_read_b128 v[28:31], v171 offset:28672
	s_lshr_b32 s84, s80, 1
	s_lshl_b32 s84, s84, 4
	s_lshl_b32 s85, s81, 5
	s_add_i32 s84, s84, s85
	s_addk_i32 s84, 0x4000
	s_and_b32 s85, s80, 1
	s_lshl_b32 s85, s85, 4
	s_lshl_b32 s83, s82, 5
	s_add_i32 s85, s85, s83
	v_add_u32_e32 v165, s84, v160
	v_lshl_add_u32 v164, v161, 2, s85
	v_lshlrev_b32_e32 v166, 12, v165
	v_lshl_add_u32 v166, v164, 2, v166
	v_mov_b32_e32 v167, 0
	s_add_u32 s86, s74, 0x5000000
	s_addc_u32 s87, s75, 0
	v_lshl_add_u64 v[168:169], s[86:87], 0, v[166:167]
	global_load_dwordx4 v[32:35], v[168:169], off
	v_lshrrev_b32_e32 v172, 1, v166
	v_mov_b32_e32 v173, 0
	s_add_u32 s86, s74, 0x9100000
	s_addc_u32 s87, s75, 0
	v_lshl_add_u64 v[172:173], s[86:87], 0, v[172:173]
	v_lshlrev_b32_e32 v166, 2, v165
	s_add_u32 s86, s74, 0x12ba1000
	s_addc_u32 s87, s75, 0
	v_lshl_add_u64 v[166:167], s[86:87], 0, v[166:167]
	s_waitcnt lgkmcnt(0)
	v_add_f32_e32 v0, v0, v4
	v_add_f32_e32 v1, v1, v5
	v_add_f32_e32 v2, v2, v6
	v_add_f32_e32 v3, v3, v7
	v_add_f32_e32 v0, v0, v8
	v_add_f32_e32 v1, v1, v9
	v_add_f32_e32 v2, v2, v10
	v_add_f32_e32 v3, v3, v11
	v_add_f32_e32 v0, v0, v12
	v_add_f32_e32 v1, v1, v13
	v_add_f32_e32 v2, v2, v14
	v_add_f32_e32 v3, v3, v15
	v_add_f32_e32 v0, v0, v16
	v_add_f32_e32 v1, v1, v17
	v_add_f32_e32 v2, v2, v18
	v_add_f32_e32 v3, v3, v19
	v_add_f32_e32 v0, v0, v20
	v_add_f32_e32 v1, v1, v21
	v_add_f32_e32 v2, v2, v22
	v_add_f32_e32 v3, v3, v23
	v_add_f32_e32 v0, v0, v24
	v_add_f32_e32 v1, v1, v25
	v_add_f32_e32 v2, v2, v26
	v_add_f32_e32 v3, v3, v27
	v_add_f32_e32 v0, v0, v28
	v_add_f32_e32 v1, v1, v29
	v_add_f32_e32 v2, v2, v30
	v_add_f32_e32 v3, v3, v31
	s_waitcnt vmcnt(0)
	v_fma_f32 v32, v0, 0.5, v32
	v_fma_f32 v33, v1, 0.5, v33
	v_fma_f32 v34, v2, 0.5, v34
	v_fma_f32 v35, v3, 0.5, v35
	global_store_dwordx4 v[168:169], v[32:35], off
	v_cvt_pk_bf16_f32 v36, v32, v33
	v_cvt_pk_bf16_f32 v37, v34, v35
	global_store_dwordx2 v[172:173], v[36:37], off
	v_mul_f32_e32 v38, v32, v32
	v_fmac_f32_e32 v38, v33, v33
	v_fmac_f32_e32 v38, v34, v34
	v_fmac_f32_e32 v38, v35, v35
	v_xor_b32_e32 v39, 16, v136
	v_lshlrev_b32_e32 v39, 2, v39
	ds_bpermute_b32 v40, v39, v38
	v_xor_b32_e32 v41, 32, v136
	v_lshlrev_b32_e32 v41, 2, v41
	s_waitcnt lgkmcnt(0)
	v_add_f32_e32 v38, v38, v40
	ds_bpermute_b32 v40, v41, v38
	s_waitcnt lgkmcnt(0)
	v_add_f32_e32 v38, v38, v40
	v_cmp_gt_u32_e64 s[82:83], 16, v136
	s_nop 1
	s_and_saveexec_b64 s[84:85], s[82:83]
	global_atomic_add_f32 v[166:167], v38, off
	s_mov_b64 exec, s[84:85]
.Lmg3p_end:
	s_barrier

.LBB0_1002:
	ds_read_b128 v[144:147], v151
	ds_read_b128 v[156:159], v151 offset:1024
	ds_read_b128 v[160:163], v151 offset:2048
	ds_read_b128 v[164:167], v151 offset:3072
	s_add_u32 s26, s24, 0x100
	s_addc_u32 s27, s25, 0
	s_cmp_eq_u32 s67, 40
	s_cselect_b32 s31, s13, s27
	s_cselect_b32 s30, s12, s26
	s_cselect_b32 s29, s15, s66
	s_cselect_b32 s28, s14, s65
	v_lshl_add_u64 v[172:173], s[24:25], 0, v[136:137]
	s_add_i32 m0, s34, 0xc000
	ds_read_b128 v[168:171], v152
	ds_read_b128 v[178:181], v152 offset:1024
	ds_read_b128 v[182:185], v152 offset:2048
	ds_read_b128 v[186:189], v152 offset:3072
	ds_read_b128 v[190:193], v152 offset:4096
	ds_read_b128 v[194:197], v152 offset:5120
	ds_read_b128 v[198:201], v152 offset:6144
	ds_read_b128 v[202:205], v152 offset:7168
	global_load_lds_dwordx4 v[172:173], off
	v_lshl_add_u64 v[172:173], s[24:25], 0, v[138:139]
	s_add_i32 m0, s34, 0xe000
	s_nop 0
	global_load_lds_dwordx4 v[172:173], off
	s_waitcnt lgkmcnt(8)
	s_barrier
	s_waitcnt lgkmcnt(0)
	s_setprio 1
	s_waitcnt lgkmcnt(0)
	v_mfma_f32_16x16x32_bf16 v[124:127], v[144:147], v[168:171], v[124:127]
	v_mfma_f32_16x16x32_bf16 v[120:123], v[160:163], v[168:171], v[120:123]
	v_mfma_f32_16x16x32_bf16 v[108:111], v[144:147], v[182:185], v[108:111]
	v_mfma_f32_16x16x32_bf16 v[104:107], v[160:163], v[182:185], v[104:107]
	v_mfma_f32_16x16x32_bf16 v[92:95], v[144:147], v[190:193], v[92:95]
	v_mfma_f32_16x16x32_bf16 v[88:91], v[160:163], v[190:193], v[88:91]
	v_mfma_f32_16x16x32_bf16 v[76:79], v[144:147], v[198:201], v[76:79]
	v_mfma_f32_16x16x32_bf16 v[72:75], v[160:163], v[198:201], v[72:75]
	v_mfma_f32_16x16x32_bf16 v[124:127], v[156:159], v[178:181], v[124:127]
	v_mfma_f32_16x16x32_bf16 v[120:123], v[164:167], v[178:181], v[120:123]
	v_mfma_f32_16x16x32_bf16 v[108:111], v[156:159], v[186:189], v[108:111]
	v_mfma_f32_16x16x32_bf16 v[104:107], v[164:167], v[186:189], v[104:107]
	v_mfma_f32_16x16x32_bf16 v[92:95], v[156:159], v[194:197], v[92:95]
	v_mfma_f32_16x16x32_bf16 v[88:91], v[164:167], v[194:197], v[88:91]
	v_mfma_f32_16x16x32_bf16 v[76:79], v[156:159], v[202:205], v[76:79]
	v_mfma_f32_16x16x32_bf16 v[72:75], v[164:167], v[202:205], v[72:75]
	s_setprio 0
	s_barrier
	s_add_i32 s24, s57, s7
	v_lshl_add_u64 v[172:173], s[28:29], 0, v[130:131]
	s_mov_b32 m0, s24
	ds_read_b128 v[206:209], v153
	ds_read_b128 v[210:213], v153 offset:1024
	ds_read_b128 v[214:217], v153 offset:2048
	ds_read_b128 v[218:221], v153 offset:3072
	global_load_lds_dwordx4 v[172:173], off
	v_lshl_add_u64 v[222:223], s[28:29], 0, v[134:135]
	s_add_i32 m0, s24, 0x2000
	s_nop 0
	global_load_lds_dwordx4 v[222:223], off
	s_barrier
	s_waitcnt lgkmcnt(0)
	s_setprio 1
	s_waitcnt lgkmcnt(0)
	v_mfma_f32_16x16x32_bf16 v[116:119], v[206:209], v[168:171], v[116:119]
	v_mfma_f32_16x16x32_bf16 v[112:115], v[214:217], v[168:171], v[112:115]
	v_mfma_f32_16x16x32_bf16 v[100:103], v[206:209], v[182:185], v[100:103]
	v_mfma_f32_16x16x32_bf16 v[96:99], v[214:217], v[182:185], v[96:99]
	v_mfma_f32_16x16x32_bf16 v[84:87], v[206:209], v[190:193], v[84:87]
	v_mfma_f32_16x16x32_bf16 v[80:83], v[214:217], v[190:193], v[80:83]
	v_mfma_f32_16x16x32_bf16 v[68:71], v[206:209], v[198:201], v[68:71]
	v_mfma_f32_16x16x32_bf16 v[64:67], v[214:217], v[198:201], v[64:67]
	v_mfma_f32_16x16x32_bf16 v[116:119], v[210:213], v[178:181], v[116:119]
	v_mfma_f32_16x16x32_bf16 v[112:115], v[218:221], v[178:181], v[112:115]
	v_mfma_f32_16x16x32_bf16 v[100:103], v[210:213], v[186:189], v[100:103]
	v_mfma_f32_16x16x32_bf16 v[96:99], v[218:221], v[186:189], v[96:99]
	v_mfma_f32_16x16x32_bf16 v[84:87], v[210:213], v[194:197], v[84:87]
	v_mfma_f32_16x16x32_bf16 v[80:83], v[218:221], v[194:197], v[80:83]
	v_mfma_f32_16x16x32_bf16 v[68:71], v[210:213], v[202:205], v[68:71]
	v_mfma_f32_16x16x32_bf16 v[64:67], v[218:221], v[202:205], v[64:67]
	s_setprio 0
	s_mov_b32 m0, s34
	v_lshl_add_u64 v[224:225], s[30:31], 0, v[128:129]
	s_barrier
	ds_read_b128 v[168:171], v152 offset:16384
	ds_read_b128 v[178:181], v152 offset:17408
	ds_read_b128 v[182:185], v152 offset:18432
	ds_read_b128 v[186:189], v152 offset:19456
	ds_read_b128 v[190:193], v152 offset:20480
	ds_read_b128 v[194:197], v152 offset:21504
	ds_read_b128 v[198:201], v152 offset:22528
	ds_read_b128 v[202:205], v152 offset:23552
	global_load_lds_dwordx4 v[224:225], off
	v_lshl_add_u64 v[226:227], s[30:31], 0, v[132:133]
	s_mov_b32 m0, s35
	s_nop 0
	global_load_lds_dwordx4 v[226:227], off
	s_barrier
	s_waitcnt lgkmcnt(0)
	s_setprio 1
	s_waitcnt lgkmcnt(0)
	v_mfma_f32_16x16x32_bf16 v[60:63], v[144:147], v[168:171], v[60:63]
	v_mfma_f32_16x16x32_bf16 v[56:59], v[160:163], v[168:171], v[56:59]
	v_mfma_f32_16x16x32_bf16 v[44:47], v[144:147], v[182:185], v[44:47]
	v_mfma_f32_16x16x32_bf16 v[40:43], v[160:163], v[182:185], v[40:43]
	v_mfma_f32_16x16x32_bf16 v[28:31], v[144:147], v[190:193], v[28:31]
	v_mfma_f32_16x16x32_bf16 v[24:27], v[160:163], v[190:193], v[24:27]
	v_mfma_f32_16x16x32_bf16 v[12:15], v[144:147], v[198:201], v[12:15]
	v_mfma_f32_16x16x32_bf16 v[8:11], v[160:163], v[198:201], v[8:11]
	v_mfma_f32_16x16x32_bf16 v[60:63], v[156:159], v[178:181], v[60:63]
	v_mfma_f32_16x16x32_bf16 v[56:59], v[164:167], v[178:181], v[56:59]
	v_mfma_f32_16x16x32_bf16 v[44:47], v[156:159], v[186:189], v[44:47]
	v_mfma_f32_16x16x32_bf16 v[40:43], v[164:167], v[186:189], v[40:43]
	v_mfma_f32_16x16x32_bf16 v[28:31], v[156:159], v[194:197], v[28:31]
	v_mfma_f32_16x16x32_bf16 v[24:27], v[164:167], v[194:197], v[24:27]
	v_mfma_f32_16x16x32_bf16 v[12:15], v[156:159], v[202:205], v[12:15]
	v_mfma_f32_16x16x32_bf16 v[8:11], v[164:167], v[202:205], v[8:11]
	s_setprio 0
	s_barrier
	s_add_u32 s24, s28, 0xb0000
	s_addc_u32 s25, s29, 0
	s_add_i32 s68, s58, s7
	v_lshl_add_u64 v[144:145], s[24:25], 0, v[130:131]
	s_mov_b32 m0, s68
	s_nop 0
	global_load_lds_dwordx4 v[144:145], off
	v_lshl_add_u64 v[144:145], s[24:25], 0, v[134:135]
	s_add_i32 m0, s68, 0x2000
	s_nop 0
	global_load_lds_dwordx4 v[144:145], off
	s_waitcnt vmcnt(6)
	s_barrier
	s_setprio 1
	v_mfma_f32_16x16x32_bf16 v[52:55], v[206:209], v[168:171], v[52:55]
	v_mfma_f32_16x16x32_bf16 v[48:51], v[214:217], v[168:171], v[48:51]
	v_mfma_f32_16x16x32_bf16 v[36:39], v[206:209], v[182:185], v[36:39]
	v_mfma_f32_16x16x32_bf16 v[32:35], v[214:217], v[182:185], v[32:35]
	v_mfma_f32_16x16x32_bf16 v[20:23], v[206:209], v[190:193], v[20:23]
	v_mfma_f32_16x16x32_bf16 v[16:19], v[214:217], v[190:193], v[16:19]
	v_mfma_f32_16x16x32_bf16 v[4:7], v[206:209], v[198:201], v[4:7]
	v_mfma_f32_16x16x32_bf16 v[0:3], v[214:217], v[198:201], v[0:3]
	v_mfma_f32_16x16x32_bf16 v[52:55], v[210:213], v[178:181], v[52:55]
	v_mfma_f32_16x16x32_bf16 v[48:51], v[218:221], v[178:181], v[48:51]
	v_mfma_f32_16x16x32_bf16 v[36:39], v[210:213], v[186:189], v[36:39]
	v_mfma_f32_16x16x32_bf16 v[32:35], v[218:221], v[186:189], v[32:35]
	v_mfma_f32_16x16x32_bf16 v[20:23], v[210:213], v[194:197], v[20:23]
	v_mfma_f32_16x16x32_bf16 v[16:19], v[218:221], v[194:197], v[16:19]
	v_mfma_f32_16x16x32_bf16 v[4:7], v[210:213], v[202:205], v[4:7]
	v_mfma_f32_16x16x32_bf16 v[0:3], v[218:221], v[202:205], v[0:3]
	s_setprio 0
	s_add_i32 s68, 0, 0x18000
	v_add_u32_e32 v155, s68, v149
	s_barrier
	ds_read_b128 v[144:147], v155
	ds_read_b128 v[156:159], v155 offset:1024
	ds_read_b128 v[160:163], v155 offset:2048
	ds_read_b128 v[164:167], v155 offset:3072
	s_add_u32 s24, s30, 0xb0000
	s_addc_u32 s25, s31, 0
	s_mov_b32 m0, s36
	v_lshl_add_u64 v[206:207], s[24:25], 0, v[128:129]
	ds_read_b128 v[168:171], v152 offset:32768
	ds_read_b128 v[178:181], v152 offset:33792
	ds_read_b128 v[182:185], v152 offset:34816
	ds_read_b128 v[186:189], v152 offset:35840
	ds_read_b128 v[190:193], v152 offset:36864
	ds_read_b128 v[194:197], v152 offset:37888
	ds_read_b128 v[198:201], v152 offset:38912
	ds_read_b128 v[202:205], v152 offset:39936
	global_load_lds_dwordx4 v[206:207], off
	v_lshl_add_u64 v[206:207], s[24:25], 0, v[132:133]
	s_mov_b32 m0, s37
	s_nop 0
	global_load_lds_dwordx4 v[206:207], off
	s_waitcnt lgkmcnt(8)
	s_barrier
	s_waitcnt lgkmcnt(0)
	s_setprio 1
	s_waitcnt lgkmcnt(0)
	v_mfma_f32_16x16x32_bf16 v[124:127], v[144:147], v[168:171], v[124:127]
	v_mfma_f32_16x16x32_bf16 v[120:123], v[160:163], v[168:171], v[120:123]
	v_mfma_f32_16x16x32_bf16 v[108:111], v[144:147], v[182:185], v[108:111]
	v_mfma_f32_16x16x32_bf16 v[104:107], v[160:163], v[182:185], v[104:107]
	v_mfma_f32_16x16x32_bf16 v[92:95], v[144:147], v[190:193], v[92:95]
	v_mfma_f32_16x16x32_bf16 v[88:91], v[160:163], v[190:193], v[88:91]
	v_mfma_f32_16x16x32_bf16 v[76:79], v[144:147], v[198:201], v[76:79]
	v_mfma_f32_16x16x32_bf16 v[72:75], v[160:163], v[198:201], v[72:75]
	v_mfma_f32_16x16x32_bf16 v[124:127], v[156:159], v[178:181], v[124:127]
	v_mfma_f32_16x16x32_bf16 v[120:123], v[164:167], v[178:181], v[120:123]
	v_mfma_f32_16x16x32_bf16 v[108:111], v[156:159], v[186:189], v[108:111]
	v_mfma_f32_16x16x32_bf16 v[104:107], v[164:167], v[186:189], v[104:107]
	v_mfma_f32_16x16x32_bf16 v[92:95], v[156:159], v[194:197], v[92:95]
	v_mfma_f32_16x16x32_bf16 v[88:91], v[164:167], v[194:197], v[88:91]
	v_mfma_f32_16x16x32_bf16 v[76:79], v[156:159], v[202:205], v[76:79]
	v_mfma_f32_16x16x32_bf16 v[72:75], v[164:167], v[202:205], v[72:75]
	s_setprio 0
	s_barrier
	s_add_i32 s30, 0, 0x1c000
	s_add_i32 s24, s68, s7
	v_add_u32_e32 v155, s30, v149
	v_lshl_add_u64 v[172:173], v[172:173], 0, s[16:17]
	s_mov_b32 m0, s24
	ds_read_b128 v[206:209], v155
	ds_read_b128 v[210:213], v155 offset:1024
	ds_read_b128 v[214:217], v155 offset:2048
	ds_read_b128 v[218:221], v155 offset:3072
	global_load_lds_dwordx4 v[172:173], off
	v_lshl_add_u64 v[172:173], v[222:223], 0, s[16:17]
	s_add_i32 m0, s24, 0x2000
	s_nop 0
	global_load_lds_dwordx4 v[172:173], off
	s_barrier
	s_waitcnt lgkmcnt(0)
	s_setprio 1
	s_waitcnt lgkmcnt(0)
	v_mfma_f32_16x16x32_bf16 v[116:119], v[206:209], v[168:171], v[116:119]
	v_mfma_f32_16x16x32_bf16 v[112:115], v[214:217], v[168:171], v[112:115]
	v_mfma_f32_16x16x32_bf16 v[100:103], v[206:209], v[182:185], v[100:103]
	v_mfma_f32_16x16x32_bf16 v[96:99], v[214:217], v[182:185], v[96:99]
	v_mfma_f32_16x16x32_bf16 v[84:87], v[206:209], v[190:193], v[84:87]
	v_mfma_f32_16x16x32_bf16 v[80:83], v[214:217], v[190:193], v[80:83]
	v_mfma_f32_16x16x32_bf16 v[68:71], v[206:209], v[198:201], v[68:71]
	v_mfma_f32_16x16x32_bf16 v[64:67], v[214:217], v[198:201], v[64:67]
	v_mfma_f32_16x16x32_bf16 v[116:119], v[210:213], v[178:181], v[116:119]
	v_mfma_f32_16x16x32_bf16 v[112:115], v[218:221], v[178:181], v[112:115]
	v_mfma_f32_16x16x32_bf16 v[100:103], v[210:213], v[186:189], v[100:103]
	v_mfma_f32_16x16x32_bf16 v[96:99], v[218:221], v[186:189], v[96:99]
	v_mfma_f32_16x16x32_bf16 v[84:87], v[210:213], v[194:197], v[84:87]
	v_mfma_f32_16x16x32_bf16 v[80:83], v[218:221], v[194:197], v[80:83]
	v_mfma_f32_16x16x32_bf16 v[68:71], v[210:213], v[202:205], v[68:71]
	v_mfma_f32_16x16x32_bf16 v[64:67], v[218:221], v[202:205], v[64:67]
	s_setprio 0
	s_mov_b32 m0, s47
	v_lshl_add_u64 v[172:173], v[224:225], 0, s[16:17]
	s_barrier
	ds_read_b128 v[168:171], v152 offset:49152
	ds_read_b128 v[178:181], v152 offset:50176
	ds_read_b128 v[182:185], v152 offset:51200
	ds_read_b128 v[186:189], v152 offset:52224
	ds_read_b128 v[190:193], v152 offset:53248
	ds_read_b128 v[194:197], v152 offset:54272
	ds_read_b128 v[198:201], v152 offset:55296
	ds_read_b128 v[202:205], v152 offset:56320
	global_load_lds_dwordx4 v[172:173], off
	v_lshl_add_u64 v[172:173], v[226:227], 0, s[16:17]
	s_mov_b32 m0, s54
	s_nop 0
	global_load_lds_dwordx4 v[172:173], off
	s_barrier
	s_waitcnt lgkmcnt(0)
	s_setprio 1
	s_waitcnt lgkmcnt(0)
	v_mfma_f32_16x16x32_bf16 v[60:63], v[144:147], v[168:171], v[60:63]
	v_mfma_f32_16x16x32_bf16 v[56:59], v[160:163], v[168:171], v[56:59]
	v_mfma_f32_16x16x32_bf16 v[44:47], v[144:147], v[182:185], v[44:47]
	v_mfma_f32_16x16x32_bf16 v[40:43], v[160:163], v[182:185], v[40:43]
	v_mfma_f32_16x16x32_bf16 v[28:31], v[144:147], v[190:193], v[28:31]
	v_mfma_f32_16x16x32_bf16 v[24:27], v[160:163], v[190:193], v[24:27]
	v_mfma_f32_16x16x32_bf16 v[12:15], v[144:147], v[198:201], v[12:15]
	v_mfma_f32_16x16x32_bf16 v[8:11], v[160:163], v[198:201], v[8:11]
	v_mfma_f32_16x16x32_bf16 v[60:63], v[156:159], v[178:181], v[60:63]
	v_mfma_f32_16x16x32_bf16 v[56:59], v[164:167], v[178:181], v[56:59]
	v_mfma_f32_16x16x32_bf16 v[44:47], v[156:159], v[186:189], v[44:47]
	v_mfma_f32_16x16x32_bf16 v[40:43], v[164:167], v[186:189], v[40:43]
	v_mfma_f32_16x16x32_bf16 v[28:31], v[156:159], v[194:197], v[28:31]
	v_mfma_f32_16x16x32_bf16 v[24:27], v[164:167], v[194:197], v[24:27]
	v_mfma_f32_16x16x32_bf16 v[12:15], v[156:159], v[202:205], v[12:15]
	v_mfma_f32_16x16x32_bf16 v[8:11], v[164:167], v[202:205], v[8:11]
	s_setprio 0
	s_barrier
	s_add_u32 s24, s28, 0xb0080
	s_addc_u32 s25, s29, 0
	s_add_i32 s28, s30, s7
	v_lshl_add_u64 v[144:145], s[24:25], 0, v[130:131]
	s_mov_b32 m0, s28
	s_nop 0
	global_load_lds_dwordx4 v[144:145], off
	v_lshl_add_u64 v[144:145], s[24:25], 0, v[134:135]
	s_add_i32 m0, s28, 0x2000
	s_nop 0
	global_load_lds_dwordx4 v[144:145], off
	s_waitcnt vmcnt(6)
	s_barrier
	s_setprio 1
	v_mfma_f32_16x16x32_bf16 v[52:55], v[206:209], v[168:171], v[52:55]
	v_mfma_f32_16x16x32_bf16 v[48:51], v[214:217], v[168:171], v[48:51]
	v_mfma_f32_16x16x32_bf16 v[36:39], v[206:209], v[182:185], v[36:39]
	v_mfma_f32_16x16x32_bf16 v[32:35], v[214:217], v[182:185], v[32:35]
	v_mfma_f32_16x16x32_bf16 v[20:23], v[206:209], v[190:193], v[20:23]
	v_mfma_f32_16x16x32_bf16 v[16:19], v[214:217], v[190:193], v[16:19]
	v_mfma_f32_16x16x32_bf16 v[4:7], v[206:209], v[198:201], v[4:7]
	v_mfma_f32_16x16x32_bf16 v[0:3], v[214:217], v[198:201], v[0:3]
	v_mfma_f32_16x16x32_bf16 v[52:55], v[210:213], v[178:181], v[52:55]
	v_mfma_f32_16x16x32_bf16 v[48:51], v[218:221], v[178:181], v[48:51]
	v_mfma_f32_16x16x32_bf16 v[36:39], v[210:213], v[186:189], v[36:39]
	v_mfma_f32_16x16x32_bf16 v[32:35], v[218:221], v[186:189], v[32:35]
	v_mfma_f32_16x16x32_bf16 v[20:23], v[210:213], v[194:197], v[20:23]
	v_mfma_f32_16x16x32_bf16 v[16:19], v[218:221], v[194:197], v[16:19]
	v_mfma_f32_16x16x32_bf16 v[4:7], v[210:213], v[202:205], v[4:7]
	v_mfma_f32_16x16x32_bf16 v[0:3], v[218:221], v[202:205], v[0:3]
	s_setprio 0
	s_add_i32 s67, s67, 2
	s_add_u32 s65, s65, 0x100
	s_addc_u32 s66, s66, 0
	s_cmp_gt_u32 s67, 41
	s_mov_b64 s[24:25], s[26:27]
	s_barrier
	s_cbranch_scc0 .LBB0_1002
	s_nop 7
	s_nop 7
	v_and_b32_e32 v160, 15, v174
	v_bfe_u32 v161, v174, 4, 2
	v_lshrrev_b32_e32 v162, 6, v174
	v_lshrrev_b32_e32 v163, 2, v162
	v_and_b32_e32 v164, 3, v162
	v_and_b32_e32 v170, 63, v174
	s_lshr_b32 s80, s33, 3
	s_and_b32 s81, s80, 7
	s_lshl_b32 s81, s81, 3
	s_lshr_b32 s82, s80, 3
	s_and_b32 s82, s82, 7
	s_add_i32 s81, s81, s82
	s_lshr_b32 s82, s80, 6
	v_lshl_add_u32 v165, v163, 6, v160
	s_lshl_b32 s83, s81, 8
	v_add_u32_e32 v165, s83, v165
	v_lshlrev_b32_e32 v166, 3, v161
	v_lshl_add_u32 v166, v164, 5, v166
	s_lshl_b32 s83, s82, 8
	v_add_u32_e32 v166, s83, v166
	v_lshlrev_b32_e32 v168, 12, v165
	v_lshl_add_u32 v168, v166, 2, v168
	v_mov_b32_e32 v169, 0
	s_add_u32 s84, s74, 0x5000000
	s_addc_u32 s85, s75, 0
	v_lshl_add_u64 v[210:211], s[84:85], 0, v[168:169]
	v_lshrrev_b32_e32 v168, 1, v168
	s_add_u32 s84, s74, 0x9100000
	s_addc_u32 s85, s75, 0
	v_lshl_add_u64 v[212:213], s[84:85], 0, v[168:169]
	v_lshlrev_b32_e32 v168, 2, v165
	s_add_u32 s84, s74, 0x12ba1000
	s_addc_u32 s85, s75, 0
	v_lshl_add_u64 v[214:215], s[84:85], 0, v[168:169]
	v_xor_b32_e32 v171, 16, v170
	v_lshlrev_b32_e32 v171, 2, v171
	v_xor_b32_e32 v172, 32, v170
	v_lshlrev_b32_e32 v172, 2, v172
	v_cmp_eq_u32_e64 s[86:87], 0, v161
	s_mov_b32 s85, 0
	s_mov_b32 s89, 0
	s_mov_b32 s84, 0x0
	v_lshl_add_u64 v[216:217], s[84:85], 0, v[210:211]
	global_load_dwordx4 v[128:131], v[216:217], off
	global_load_dwordx4 v[132:135], v[216:217], off offset:16
	global_load_dwordx4 v[136:139], v[216:217], off offset:512
	global_load_dwordx4 v[140:143], v[216:217], off offset:528
	s_mov_b32 s84, 0x10000
	v_lshl_add_u64 v[216:217], s[84:85], 0, v[210:211]
	global_load_dwordx4 v[144:147], v[216:217], off
	global_load_dwordx4 v[148:151], v[216:217], off offset:16
	global_load_dwordx4 v[152:155], v[216:217], off offset:512
	global_load_dwordx4 v[156:159], v[216:217], off offset:528
	s_mov_b32 s84, 0x20000
	v_lshl_add_u64 v[216:217], s[84:85], 0, v[210:211]
	global_load_dwordx4 v[178:181], v[216:217], off
	global_load_dwordx4 v[182:185], v[216:217], off offset:16
	global_load_dwordx4 v[186:189], v[216:217], off offset:512
	global_load_dwordx4 v[190:193], v[216:217], off offset:528
	s_mov_b32 s84, 0x30000
	v_lshl_add_u64 v[216:217], s[84:85], 0, v[210:211]
	global_load_dwordx4 v[194:197], v[216:217], off
	global_load_dwordx4 v[198:201], v[216:217], off offset:16
	global_load_dwordx4 v[202:205], v[216:217], off offset:512
	global_load_dwordx4 v[206:209], v[216:217], off offset:528
	s_waitcnt vmcnt(0)
	s_mov_b32 s84, 0x0
	v_lshl_add_u64 v[216:217], s[84:85], 0, v[210:211]
	s_mov_b32 s88, 0x0
	v_lshl_add_u64 v[218:219], s[88:89], 0, v[212:213]
	v_pk_fma_f32 v[128:129], v[124:125], 0.5, v[128:129] op_sel_hi:[1,0,1]
	v_pk_fma_f32 v[130:131], v[126:127], 0.5, v[130:131] op_sel_hi:[1,0,1]
	v_pk_fma_f32 v[132:133], v[120:121], 0.5, v[132:133] op_sel_hi:[1,0,1]
	v_pk_fma_f32 v[134:135], v[122:123], 0.5, v[134:135] op_sel_hi:[1,0,1]
	global_store_dwordx4 v[216:217], v[128:131], off
	global_store_dwordx4 v[216:217], v[132:135], off offset:16
	v_cvt_pk_bf16_f32 v224, v128, v129
	v_cvt_pk_bf16_f32 v225, v130, v131
	v_cvt_pk_bf16_f32 v226, v132, v133
	v_cvt_pk_bf16_f32 v227, v134, v135
	global_store_dwordx4 v[218:219], v[224:227], off
	v_mul_f32_e32 v220, v128, v128
	v_fmac_f32_e32 v220, v129, v129
	v_fmac_f32_e32 v220, v130, v130
	v_fmac_f32_e32 v220, v131, v131
	v_fmac_f32_e32 v220, v132, v132
	v_fmac_f32_e32 v220, v133, v133
	v_fmac_f32_e32 v220, v134, v134
	v_fmac_f32_e32 v220, v135, v135
	v_pk_fma_f32 v[136:137], v[116:117], 0.5, v[136:137] op_sel_hi:[1,0,1]
	v_pk_fma_f32 v[138:139], v[118:119], 0.5, v[138:139] op_sel_hi:[1,0,1]
	v_pk_fma_f32 v[140:141], v[112:113], 0.5, v[140:141] op_sel_hi:[1,0,1]
	v_pk_fma_f32 v[142:143], v[114:115], 0.5, v[142:143] op_sel_hi:[1,0,1]
	global_store_dwordx4 v[216:217], v[136:139], off offset:512
	global_store_dwordx4 v[216:217], v[140:143], off offset:528
	v_cvt_pk_bf16_f32 v228, v136, v137
	v_cvt_pk_bf16_f32 v229, v138, v139
	v_cvt_pk_bf16_f32 v230, v140, v141
	v_cvt_pk_bf16_f32 v231, v142, v143
	global_store_dwordx4 v[218:219], v[228:231], off offset:256
	v_fmac_f32_e32 v220, v136, v136
	v_fmac_f32_e32 v220, v137, v137
	v_fmac_f32_e32 v220, v138, v138
	v_fmac_f32_e32 v220, v139, v139
	v_fmac_f32_e32 v220, v140, v140
	v_fmac_f32_e32 v220, v141, v141
	v_fmac_f32_e32 v220, v142, v142
	v_fmac_f32_e32 v220, v143, v143
	s_mov_b32 s84, 0x10000
	v_lshl_add_u64 v[216:217], s[84:85], 0, v[210:211]
	s_mov_b32 s88, 0x8000
	v_lshl_add_u64 v[218:219], s[88:89], 0, v[212:213]
	v_pk_fma_f32 v[144:145], v[108:109], 0.5, v[144:145] op_sel_hi:[1,0,1]
	v_pk_fma_f32 v[146:147], v[110:111], 0.5, v[146:147] op_sel_hi:[1,0,1]
	v_pk_fma_f32 v[148:149], v[104:105], 0.5, v[148:149] op_sel_hi:[1,0,1]
	v_pk_fma_f32 v[150:151], v[106:107], 0.5, v[150:151] op_sel_hi:[1,0,1]
	global_store_dwordx4 v[216:217], v[144:147], off
	global_store_dwordx4 v[216:217], v[148:151], off offset:16
	v_cvt_pk_bf16_f32 v224, v144, v145
	v_cvt_pk_bf16_f32 v225, v146, v147
	v_cvt_pk_bf16_f32 v226, v148, v149
	v_cvt_pk_bf16_f32 v227, v150, v151
	global_store_dwordx4 v[218:219], v[224:227], off
	v_mul_f32_e32 v221, v144, v144
	v_fmac_f32_e32 v221, v145, v145
	v_fmac_f32_e32 v221, v146, v146
	v_fmac_f32_e32 v221, v147, v147
	v_fmac_f32_e32 v221, v148, v148
	v_fmac_f32_e32 v221, v149, v149
	v_fmac_f32_e32 v221, v150, v150
	v_fmac_f32_e32 v221, v151, v151
	v_pk_fma_f32 v[152:153], v[100:101], 0.5, v[152:153] op_sel_hi:[1,0,1]
	v_pk_fma_f32 v[154:155], v[102:103], 0.5, v[154:155] op_sel_hi:[1,0,1]
	v_pk_fma_f32 v[156:157], v[96:97], 0.5, v[156:157] op_sel_hi:[1,0,1]
	v_pk_fma_f32 v[158:159], v[98:99], 0.5, v[158:159] op_sel_hi:[1,0,1]
	global_store_dwordx4 v[216:217], v[152:155], off offset:512
	global_store_dwordx4 v[216:217], v[156:159], off offset:528
	v_cvt_pk_bf16_f32 v228, v152, v153
	v_cvt_pk_bf16_f32 v229, v154, v155
	v_cvt_pk_bf16_f32 v230, v156, v157
	v_cvt_pk_bf16_f32 v231, v158, v159
	global_store_dwordx4 v[218:219], v[228:231], off offset:256
	v_fmac_f32_e32 v221, v152, v152
	v_fmac_f32_e32 v221, v153, v153
	v_fmac_f32_e32 v221, v154, v154
	v_fmac_f32_e32 v221, v155, v155
	v_fmac_f32_e32 v221, v156, v156
	v_fmac_f32_e32 v221, v157, v157
	v_fmac_f32_e32 v221, v158, v158
	v_fmac_f32_e32 v221, v159, v159
	s_mov_b32 s84, 0x20000
	v_lshl_add_u64 v[216:217], s[84:85], 0, v[210:211]
	s_mov_b32 s88, 0x10000
	v_lshl_add_u64 v[218:219], s[88:89], 0, v[212:213]
	v_pk_fma_f32 v[178:179], v[92:93], 0.5, v[178:179] op_sel_hi:[1,0,1]
	v_pk_fma_f32 v[180:181], v[94:95], 0.5, v[180:181] op_sel_hi:[1,0,1]
	v_pk_fma_f32 v[182:183], v[88:89], 0.5, v[182:183] op_sel_hi:[1,0,1]
	v_pk_fma_f32 v[184:185], v[90:91], 0.5, v[184:185] op_sel_hi:[1,0,1]
	global_store_dwordx4 v[216:217], v[178:181], off
	global_store_dwordx4 v[216:217], v[182:185], off offset:16
	v_cvt_pk_bf16_f32 v224, v178, v179
	v_cvt_pk_bf16_f32 v225, v180, v181
	v_cvt_pk_bf16_f32 v226, v182, v183
	v_cvt_pk_bf16_f32 v227, v184, v185
	global_store_dwordx4 v[218:219], v[224:227], off
	v_mul_f32_e32 v222, v178, v178
	v_fmac_f32_e32 v222, v179, v179
	v_fmac_f32_e32 v222, v180, v180
	v_fmac_f32_e32 v222, v181, v181
	v_fmac_f32_e32 v222, v182, v182
	v_fmac_f32_e32 v222, v183, v183
	v_fmac_f32_e32 v222, v184, v184
	v_fmac_f32_e32 v222, v185, v185
	v_pk_fma_f32 v[186:187], v[84:85], 0.5, v[186:187] op_sel_hi:[1,0,1]
	v_pk_fma_f32 v[188:189], v[86:87], 0.5, v[188:189] op_sel_hi:[1,0,1]
	v_pk_fma_f32 v[190:191], v[80:81], 0.5, v[190:191] op_sel_hi:[1,0,1]
	v_pk_fma_f32 v[192:193], v[82:83], 0.5, v[192:193] op_sel_hi:[1,0,1]
	global_store_dwordx4 v[216:217], v[186:189], off offset:512
	global_store_dwordx4 v[216:217], v[190:193], off offset:528
	v_cvt_pk_bf16_f32 v228, v186, v187
	v_cvt_pk_bf16_f32 v229, v188, v189
	v_cvt_pk_bf16_f32 v230, v190, v191
	v_cvt_pk_bf16_f32 v231, v192, v193
	global_store_dwordx4 v[218:219], v[228:231], off offset:256
	v_fmac_f32_e32 v222, v186, v186
	v_fmac_f32_e32 v222, v187, v187
	v_fmac_f32_e32 v222, v188, v188
	v_fmac_f32_e32 v222, v189, v189
	v_fmac_f32_e32 v222, v190, v190
	v_fmac_f32_e32 v222, v191, v191
	v_fmac_f32_e32 v222, v192, v192
	v_fmac_f32_e32 v222, v193, v193
	s_mov_b32 s84, 0x30000
	v_lshl_add_u64 v[216:217], s[84:85], 0, v[210:211]
	s_mov_b32 s88, 0x18000
	v_lshl_add_u64 v[218:219], s[88:89], 0, v[212:213]
	v_pk_fma_f32 v[194:195], v[76:77], 0.5, v[194:195] op_sel_hi:[1,0,1]
	v_pk_fma_f32 v[196:197], v[78:79], 0.5, v[196:197] op_sel_hi:[1,0,1]
	v_pk_fma_f32 v[198:199], v[72:73], 0.5, v[198:199] op_sel_hi:[1,0,1]
	v_pk_fma_f32 v[200:201], v[74:75], 0.5, v[200:201] op_sel_hi:[1,0,1]
	global_store_dwordx4 v[216:217], v[194:197], off
	global_store_dwordx4 v[216:217], v[198:201], off offset:16
	v_cvt_pk_bf16_f32 v224, v194, v195
	v_cvt_pk_bf16_f32 v225, v196, v197
	v_cvt_pk_bf16_f32 v226, v198, v199
	v_cvt_pk_bf16_f32 v227, v200, v201
	global_store_dwordx4 v[218:219], v[224:227], off
	v_mul_f32_e32 v223, v194, v194
	v_fmac_f32_e32 v223, v195, v195
	v_fmac_f32_e32 v223, v196, v196
	v_fmac_f32_e32 v223, v197, v197
	v_fmac_f32_e32 v223, v198, v198
	v_fmac_f32_e32 v223, v199, v199
	v_fmac_f32_e32 v223, v200, v200
	v_fmac_f32_e32 v223, v201, v201
	v_pk_fma_f32 v[202:203], v[68:69], 0.5, v[202:203] op_sel_hi:[1,0,1]
	v_pk_fma_f32 v[204:205], v[70:71], 0.5, v[204:205] op_sel_hi:[1,0,1]
	v_pk_fma_f32 v[206:207], v[64:65], 0.5, v[206:207] op_sel_hi:[1,0,1]
	v_pk_fma_f32 v[208:209], v[66:67], 0.5, v[208:209] op_sel_hi:[1,0,1]
	global_store_dwordx4 v[216:217], v[202:205], off offset:512
	global_store_dwordx4 v[216:217], v[206:209], off offset:528
	v_cvt_pk_bf16_f32 v228, v202, v203
	v_cvt_pk_bf16_f32 v229, v204, v205
	v_cvt_pk_bf16_f32 v230, v206, v207
	v_cvt_pk_bf16_f32 v231, v208, v209
	global_store_dwordx4 v[218:219], v[228:231], off offset:256
	v_fmac_f32_e32 v223, v202, v202
	v_fmac_f32_e32 v223, v203, v203
	v_fmac_f32_e32 v223, v204, v204
	v_fmac_f32_e32 v223, v205, v205
	v_fmac_f32_e32 v223, v206, v206
	v_fmac_f32_e32 v223, v207, v207
	v_fmac_f32_e32 v223, v208, v208
	v_fmac_f32_e32 v223, v209, v209
	ds_bpermute_b32 v224, v171, v220
	ds_bpermute_b32 v225, v171, v221
	ds_bpermute_b32 v226, v171, v222
	ds_bpermute_b32 v227, v171, v223
	s_waitcnt lgkmcnt(0)
	v_add_f32_e32 v220, v220, v224
	v_add_f32_e32 v221, v221, v225
	v_add_f32_e32 v222, v222, v226
	v_add_f32_e32 v223, v223, v227
	ds_bpermute_b32 v224, v172, v220
	ds_bpermute_b32 v225, v172, v221
	ds_bpermute_b32 v226, v172, v222
	ds_bpermute_b32 v227, v172, v223
	s_waitcnt lgkmcnt(0)
	v_add_f32_e32 v220, v220, v224
	v_add_f32_e32 v221, v221, v225
	v_add_f32_e32 v222, v222, v226
	v_add_f32_e32 v223, v223, v227
	s_and_saveexec_b64 s[90:91], s[86:87]
	global_atomic_add_f32 v[214:215], v220, off
	global_atomic_add_f32 v[214:215], v221, off offset:64
	global_atomic_add_f32 v[214:215], v222, off offset:128
	global_atomic_add_f32 v[214:215], v223, off offset:192
	s_mov_b64 exec, s[90:91]
	s_mov_b32 s84, 0x80000
	v_lshl_add_u64 v[216:217], s[84:85], 0, v[210:211]
	global_load_dwordx4 v[128:131], v[216:217], off
	global_load_dwordx4 v[132:135], v[216:217], off offset:16
	global_load_dwordx4 v[136:139], v[216:217], off offset:512
	global_load_dwordx4 v[140:143], v[216:217], off offset:528
	s_mov_b32 s84, 0x90000
	v_lshl_add_u64 v[216:217], s[84:85], 0, v[210:211]
	global_load_dwordx4 v[144:147], v[216:217], off
	global_load_dwordx4 v[148:151], v[216:217], off offset:16
	global_load_dwordx4 v[152:155], v[216:217], off offset:512
	global_load_dwordx4 v[156:159], v[216:217], off offset:528
	s_mov_b32 s84, 0xa0000
	v_lshl_add_u64 v[216:217], s[84:85], 0, v[210:211]
	global_load_dwordx4 v[178:181], v[216:217], off
	global_load_dwordx4 v[182:185], v[216:217], off offset:16
	global_load_dwordx4 v[186:189], v[216:217], off offset:512
	global_load_dwordx4 v[190:193], v[216:217], off offset:528
	s_mov_b32 s84, 0xb0000
	v_lshl_add_u64 v[216:217], s[84:85], 0, v[210:211]
	global_load_dwordx4 v[194:197], v[216:217], off
	global_load_dwordx4 v[198:201], v[216:217], off offset:16
	global_load_dwordx4 v[202:205], v[216:217], off offset:512
	global_load_dwordx4 v[206:209], v[216:217], off offset:528
	s_waitcnt vmcnt(0)
	s_mov_b32 s84, 0x80000
	v_lshl_add_u64 v[216:217], s[84:85], 0, v[210:211]
	s_mov_b32 s88, 0x40000
	v_lshl_add_u64 v[218:219], s[88:89], 0, v[212:213]
	v_pk_fma_f32 v[128:129], v[60:61], 0.5, v[128:129] op_sel_hi:[1,0,1]
	v_pk_fma_f32 v[130:131], v[62:63], 0.5, v[130:131] op_sel_hi:[1,0,1]
	v_pk_fma_f32 v[132:133], v[56:57], 0.5, v[132:133] op_sel_hi:[1,0,1]
	v_pk_fma_f32 v[134:135], v[58:59], 0.5, v[134:135] op_sel_hi:[1,0,1]
	global_store_dwordx4 v[216:217], v[128:131], off
	global_store_dwordx4 v[216:217], v[132:135], off offset:16
	v_cvt_pk_bf16_f32 v224, v128, v129
	v_cvt_pk_bf16_f32 v225, v130, v131
	v_cvt_pk_bf16_f32 v226, v132, v133
	v_cvt_pk_bf16_f32 v227, v134, v135
	global_store_dwordx4 v[218:219], v[224:227], off
	v_mul_f32_e32 v220, v128, v128
	v_fmac_f32_e32 v220, v129, v129
	v_fmac_f32_e32 v220, v130, v130
	v_fmac_f32_e32 v220, v131, v131
	v_fmac_f32_e32 v220, v132, v132
	v_fmac_f32_e32 v220, v133, v133
	v_fmac_f32_e32 v220, v134, v134
	v_fmac_f32_e32 v220, v135, v135
	v_pk_fma_f32 v[136:137], v[52:53], 0.5, v[136:137] op_sel_hi:[1,0,1]
	v_pk_fma_f32 v[138:139], v[54:55], 0.5, v[138:139] op_sel_hi:[1,0,1]
	v_pk_fma_f32 v[140:141], v[48:49], 0.5, v[140:141] op_sel_hi:[1,0,1]
	v_pk_fma_f32 v[142:143], v[50:51], 0.5, v[142:143] op_sel_hi:[1,0,1]
	global_store_dwordx4 v[216:217], v[136:139], off offset:512
	global_store_dwordx4 v[216:217], v[140:143], off offset:528
	v_cvt_pk_bf16_f32 v228, v136, v137
	v_cvt_pk_bf16_f32 v229, v138, v139
	v_cvt_pk_bf16_f32 v230, v140, v141
	v_cvt_pk_bf16_f32 v231, v142, v143
	global_store_dwordx4 v[218:219], v[228:231], off offset:256
	v_fmac_f32_e32 v220, v136, v136
	v_fmac_f32_e32 v220, v137, v137
	v_fmac_f32_e32 v220, v138, v138
	v_fmac_f32_e32 v220, v139, v139
	v_fmac_f32_e32 v220, v140, v140
	v_fmac_f32_e32 v220, v141, v141
	v_fmac_f32_e32 v220, v142, v142
	v_fmac_f32_e32 v220, v143, v143
	s_mov_b32 s84, 0x90000
	v_lshl_add_u64 v[216:217], s[84:85], 0, v[210:211]
	s_mov_b32 s88, 0x48000
	v_lshl_add_u64 v[218:219], s[88:89], 0, v[212:213]
	v_pk_fma_f32 v[144:145], v[44:45], 0.5, v[144:145] op_sel_hi:[1,0,1]
	v_pk_fma_f32 v[146:147], v[46:47], 0.5, v[146:147] op_sel_hi:[1,0,1]
	v_pk_fma_f32 v[148:149], v[40:41], 0.5, v[148:149] op_sel_hi:[1,0,1]
	v_pk_fma_f32 v[150:151], v[42:43], 0.5, v[150:151] op_sel_hi:[1,0,1]
	global_store_dwordx4 v[216:217], v[144:147], off
	global_store_dwordx4 v[216:217], v[148:151], off offset:16
	v_cvt_pk_bf16_f32 v224, v144, v145
	v_cvt_pk_bf16_f32 v225, v146, v147
	v_cvt_pk_bf16_f32 v226, v148, v149
	v_cvt_pk_bf16_f32 v227, v150, v151
	global_store_dwordx4 v[218:219], v[224:227], off
	v_mul_f32_e32 v221, v144, v144
	v_fmac_f32_e32 v221, v145, v145
	v_fmac_f32_e32 v221, v146, v146
	v_fmac_f32_e32 v221, v147, v147
	v_fmac_f32_e32 v221, v148, v148
	v_fmac_f32_e32 v221, v149, v149
	v_fmac_f32_e32 v221, v150, v150
	v_fmac_f32_e32 v221, v151, v151
	v_pk_fma_f32 v[152:153], v[36:37], 0.5, v[152:153] op_sel_hi:[1,0,1]
	v_pk_fma_f32 v[154:155], v[38:39], 0.5, v[154:155] op_sel_hi:[1,0,1]
	v_pk_fma_f32 v[156:157], v[32:33], 0.5, v[156:157] op_sel_hi:[1,0,1]
	v_pk_fma_f32 v[158:159], v[34:35], 0.5, v[158:159] op_sel_hi:[1,0,1]
	global_store_dwordx4 v[216:217], v[152:155], off offset:512
	global_store_dwordx4 v[216:217], v[156:159], off offset:528
	v_cvt_pk_bf16_f32 v228, v152, v153
	v_cvt_pk_bf16_f32 v229, v154, v155
	v_cvt_pk_bf16_f32 v230, v156, v157
	v_cvt_pk_bf16_f32 v231, v158, v159
	global_store_dwordx4 v[218:219], v[228:231], off offset:256
	v_fmac_f32_e32 v221, v152, v152
	v_fmac_f32_e32 v221, v153, v153
	v_fmac_f32_e32 v221, v154, v154
	v_fmac_f32_e32 v221, v155, v155
	v_fmac_f32_e32 v221, v156, v156
	v_fmac_f32_e32 v221, v157, v157
	v_fmac_f32_e32 v221, v158, v158
	v_fmac_f32_e32 v221, v159, v159
	s_mov_b32 s84, 0xa0000
	v_lshl_add_u64 v[216:217], s[84:85], 0, v[210:211]
	s_mov_b32 s88, 0x50000
	v_lshl_add_u64 v[218:219], s[88:89], 0, v[212:213]
	v_pk_fma_f32 v[178:179], v[28:29], 0.5, v[178:179] op_sel_hi:[1,0,1]
	v_pk_fma_f32 v[180:181], v[30:31], 0.5, v[180:181] op_sel_hi:[1,0,1]
	v_pk_fma_f32 v[182:183], v[24:25], 0.5, v[182:183] op_sel_hi:[1,0,1]
	v_pk_fma_f32 v[184:185], v[26:27], 0.5, v[184:185] op_sel_hi:[1,0,1]
	global_store_dwordx4 v[216:217], v[178:181], off
	global_store_dwordx4 v[216:217], v[182:185], off offset:16
	v_cvt_pk_bf16_f32 v224, v178, v179
	v_cvt_pk_bf16_f32 v225, v180, v181
	v_cvt_pk_bf16_f32 v226, v182, v183
	v_cvt_pk_bf16_f32 v227, v184, v185
	global_store_dwordx4 v[218:219], v[224:227], off
	v_mul_f32_e32 v222, v178, v178
	v_fmac_f32_e32 v222, v179, v179
	v_fmac_f32_e32 v222, v180, v180
	v_fmac_f32_e32 v222, v181, v181
	v_fmac_f32_e32 v222, v182, v182
	v_fmac_f32_e32 v222, v183, v183
	v_fmac_f32_e32 v222, v184, v184
	v_fmac_f32_e32 v222, v185, v185
	v_pk_fma_f32 v[186:187], v[20:21], 0.5, v[186:187] op_sel_hi:[1,0,1]
	v_pk_fma_f32 v[188:189], v[22:23], 0.5, v[188:189] op_sel_hi:[1,0,1]
	v_pk_fma_f32 v[190:191], v[16:17], 0.5, v[190:191] op_sel_hi:[1,0,1]
	v_pk_fma_f32 v[192:193], v[18:19], 0.5, v[192:193] op_sel_hi:[1,0,1]
	global_store_dwordx4 v[216:217], v[186:189], off offset:512
	global_store_dwordx4 v[216:217], v[190:193], off offset:528
	v_cvt_pk_bf16_f32 v228, v186, v187
	v_cvt_pk_bf16_f32 v229, v188, v189
	v_cvt_pk_bf16_f32 v230, v190, v191
	v_cvt_pk_bf16_f32 v231, v192, v193
	global_store_dwordx4 v[218:219], v[228:231], off offset:256
	v_fmac_f32_e32 v222, v186, v186
	v_fmac_f32_e32 v222, v187, v187
	v_fmac_f32_e32 v222, v188, v188
	v_fmac_f32_e32 v222, v189, v189
	v_fmac_f32_e32 v222, v190, v190
	v_fmac_f32_e32 v222, v191, v191
	v_fmac_f32_e32 v222, v192, v192
	v_fmac_f32_e32 v222, v193, v193
	s_mov_b32 s84, 0xb0000
	v_lshl_add_u64 v[216:217], s[84:85], 0, v[210:211]
	s_mov_b32 s88, 0x58000
	v_lshl_add_u64 v[218:219], s[88:89], 0, v[212:213]
	v_pk_fma_f32 v[194:195], v[12:13], 0.5, v[194:195] op_sel_hi:[1,0,1]
	v_pk_fma_f32 v[196:197], v[14:15], 0.5, v[196:197] op_sel_hi:[1,0,1]
	v_pk_fma_f32 v[198:199], v[8:9], 0.5, v[198:199] op_sel_hi:[1,0,1]
	v_pk_fma_f32 v[200:201], v[10:11], 0.5, v[200:201] op_sel_hi:[1,0,1]
	global_store_dwordx4 v[216:217], v[194:197], off
	global_store_dwordx4 v[216:217], v[198:201], off offset:16
	v_cvt_pk_bf16_f32 v224, v194, v195
	v_cvt_pk_bf16_f32 v225, v196, v197
	v_cvt_pk_bf16_f32 v226, v198, v199
	v_cvt_pk_bf16_f32 v227, v200, v201
	global_store_dwordx4 v[218:219], v[224:227], off
	v_mul_f32_e32 v223, v194, v194
	v_fmac_f32_e32 v223, v195, v195
	v_fmac_f32_e32 v223, v196, v196
	v_fmac_f32_e32 v223, v197, v197
	v_fmac_f32_e32 v223, v198, v198
	v_fmac_f32_e32 v223, v199, v199
	v_fmac_f32_e32 v223, v200, v200
	v_fmac_f32_e32 v223, v201, v201
	v_pk_fma_f32 v[202:203], v[4:5], 0.5, v[202:203] op_sel_hi:[1,0,1]
	v_pk_fma_f32 v[204:205], v[6:7], 0.5, v[204:205] op_sel_hi:[1,0,1]
	v_pk_fma_f32 v[206:207], v[0:1], 0.5, v[206:207] op_sel_hi:[1,0,1]
	v_pk_fma_f32 v[208:209], v[2:3], 0.5, v[208:209] op_sel_hi:[1,0,1]
	global_store_dwordx4 v[216:217], v[202:205], off offset:512
	global_store_dwordx4 v[216:217], v[206:209], off offset:528
	v_cvt_pk_bf16_f32 v228, v202, v203
	v_cvt_pk_bf16_f32 v229, v204, v205
	v_cvt_pk_bf16_f32 v230, v206, v207
	v_cvt_pk_bf16_f32 v231, v208, v209
	global_store_dwordx4 v[218:219], v[228:231], off offset:256
	v_fmac_f32_e32 v223, v202, v202
	v_fmac_f32_e32 v223, v203, v203
	v_fmac_f32_e32 v223, v204, v204
	v_fmac_f32_e32 v223, v205, v205
	v_fmac_f32_e32 v223, v206, v206
	v_fmac_f32_e32 v223, v207, v207
	v_fmac_f32_e32 v223, v208, v208
	v_fmac_f32_e32 v223, v209, v209
	ds_bpermute_b32 v224, v171, v220
	ds_bpermute_b32 v225, v171, v221
	ds_bpermute_b32 v226, v171, v222
	ds_bpermute_b32 v227, v171, v223
	s_waitcnt lgkmcnt(0)
	v_add_f32_e32 v220, v220, v224
	v_add_f32_e32 v221, v221, v225
	v_add_f32_e32 v222, v222, v226
	v_add_f32_e32 v223, v223, v227
	ds_bpermute_b32 v224, v172, v220
	ds_bpermute_b32 v225, v172, v221
	ds_bpermute_b32 v226, v172, v222
	ds_bpermute_b32 v227, v172, v223
	s_waitcnt lgkmcnt(0)
	v_add_f32_e32 v220, v220, v224
	v_add_f32_e32 v221, v221, v225
	v_add_f32_e32 v222, v222, v226
	v_add_f32_e32 v223, v223, v227
	s_and_saveexec_b64 s[90:91], s[86:87]
	global_atomic_add_f32 v[214:215], v220, off offset:512
	global_atomic_add_f32 v[214:215], v221, off offset:576
	global_atomic_add_f32 v[214:215], v222, off offset:640
	global_atomic_add_f32 v[214:215], v223, off offset:704
	s_mov_b64 exec, s[90:91]

.LBB0_1022:
	s_and_b32 s80, s33, 64
	s_cmp_lg_u32 s80, 0
	s_cbranch_scc1 .Lpost3_skip
	v_and_b32_e32 v160, 15, v174
	v_bfe_u32 v161, v174, 4, 2
	v_lshrrev_b32_e32 v162, 6, v174
	v_and_b32_e32 v136, 63, v174
	v_readfirstlane_b32 s80, v162
	s_lshr_b32 s81, s33, 8
	s_lshr_b32 s82, s33, 3
	s_and_b32 s82, s82, 31
	s_mul_i32 s83, s80, 704
	v_lshlrev_b32_e32 v164, 4, v161
	v_mov_b32_e32 v167, 0
	s_lshl_b32 s84, s82, 5
	v_add_u32_e32 v165, s84, v160
	v_mul_u32_u24_e32 v166, 0x1600, v165
	v_add3_u32 v166, v166, v164, s83
	s_add_u32 s86, s74, 0x3180000
	s_addc_u32 s87, s75, 0
	s_mov_b32 s88, 0x16000
	s_mov_b32 s89, 0
	v_lshl_add_u64 v[152:153], s[86:87], 0, v[166:167]
	v_lshl_add_u64 v[154:155], v[152:153], 0, s[88:89]
	s_lshl_b32 s84, s81, 5
	v_add_u32_e32 v165, s84, v160
	v_mul_u32_u24_e32 v166, 0x1600, v165
	v_add3_u32 v166, v166, v164, s83
	s_add_u32 s90, s74, 0x10980000
	s_addc_u32 s91, s75, 0
	v_lshl_add_u64 v[156:157], s[90:91], 0, v[166:167]
	v_lshl_add_u64 v[158:159], v[156:157], 0, s[88:89]
	v_mov_b32_e32 v128, 0
	v_mov_b32_e32 v129, 0
	v_mov_b32_e32 v130, 0
	v_mov_b32_e32 v131, 0
	v_mov_b32_e32 v132, 0
	v_mov_b32_e32 v133, 0
	v_mov_b32_e32 v134, 0
	v_mov_b32_e32 v135, 0
	v_mov_b32_e32 v144, 0
	v_mov_b32_e32 v145, 0
	v_mov_b32_e32 v146, 0
	v_mov_b32_e32 v147, 0
	v_mov_b32_e32 v148, 0
	v_mov_b32_e32 v149, 0
	v_mov_b32_e32 v150, 0
	v_mov_b32_e32 v151, 0
	global_load_dwordx4 v[0:3], v[152:153], off
	global_load_dwordx4 v[4:7], v[154:155], off
	global_load_dwordx4 v[8:11], v[156:157], off
	global_load_dwordx4 v[12:15], v[158:159], off
	global_load_dwordx4 v[16:19], v[152:153], off offset:64
	global_load_dwordx4 v[20:23], v[154:155], off offset:64
	global_load_dwordx4 v[24:27], v[156:157], off offset:64
	global_load_dwordx4 v[28:31], v[158:159], off offset:64
	global_load_dwordx4 v[32:35], v[152:153], off offset:128
	global_load_dwordx4 v[36:39], v[154:155], off offset:128
	global_load_dwordx4 v[40:43], v[156:157], off offset:128
	global_load_dwordx4 v[44:47], v[158:159], off offset:128
	global_load_dwordx4 v[48:51], v[152:153], off offset:192
	global_load_dwordx4 v[52:55], v[154:155], off offset:192
	global_load_dwordx4 v[56:59], v[156:157], off offset:192
	global_load_dwordx4 v[60:63], v[158:159], off offset:192
	global_load_dwordx4 v[64:67], v[152:153], off offset:256
	global_load_dwordx4 v[68:71], v[154:155], off offset:256
	global_load_dwordx4 v[72:75], v[156:157], off offset:256
	global_load_dwordx4 v[76:79], v[158:159], off offset:256
	global_load_dwordx4 v[80:83], v[152:153], off offset:320
	global_load_dwordx4 v[84:87], v[154:155], off offset:320
	global_load_dwordx4 v[88:91], v[156:157], off offset:320
	global_load_dwordx4 v[92:95], v[158:159], off offset:320
	global_load_dwordx4 v[96:99], v[152:153], off offset:384
	global_load_dwordx4 v[100:103], v[154:155], off offset:384
	global_load_dwordx4 v[104:107], v[156:157], off offset:384
	global_load_dwordx4 v[108:111], v[158:159], off offset:384
	global_load_dwordx4 v[112:115], v[152:153], off offset:448
	global_load_dwordx4 v[116:119], v[154:155], off offset:448
	global_load_dwordx4 v[120:123], v[156:157], off offset:448
	global_load_dwordx4 v[124:127], v[158:159], off offset:448
	s_waitcnt vmcnt(16)
	v_mfma_f32_16x16x32_bf16 v[128:131], v[0:3], v[8:11], v[128:131]
	v_mfma_f32_16x16x32_bf16 v[132:135], v[4:7], v[8:11], v[132:135]
	v_mfma_f32_16x16x32_bf16 v[144:147], v[0:3], v[12:15], v[144:147]
	v_mfma_f32_16x16x32_bf16 v[148:151], v[4:7], v[12:15], v[148:151]
	v_mfma_f32_16x16x32_bf16 v[128:131], v[16:19], v[24:27], v[128:131]
	v_mfma_f32_16x16x32_bf16 v[132:135], v[20:23], v[24:27], v[132:135]
	v_mfma_f32_16x16x32_bf16 v[144:147], v[16:19], v[28:31], v[144:147]
	v_mfma_f32_16x16x32_bf16 v[148:151], v[20:23], v[28:31], v[148:151]
	v_mfma_f32_16x16x32_bf16 v[128:131], v[32:35], v[40:43], v[128:131]
	v_mfma_f32_16x16x32_bf16 v[132:135], v[36:39], v[40:43], v[132:135]
	v_mfma_f32_16x16x32_bf16 v[144:147], v[32:35], v[44:47], v[144:147]
	v_mfma_f32_16x16x32_bf16 v[148:151], v[36:39], v[44:47], v[148:151]
	v_mfma_f32_16x16x32_bf16 v[128:131], v[48:51], v[56:59], v[128:131]
	v_mfma_f32_16x16x32_bf16 v[132:135], v[52:55], v[56:59], v[132:135]
	v_mfma_f32_16x16x32_bf16 v[144:147], v[48:51], v[60:63], v[144:147]
	v_mfma_f32_16x16x32_bf16 v[148:151], v[52:55], v[60:63], v[148:151]
	global_load_dwordx4 v[0:3], v[152:153], off offset:512
	global_load_dwordx4 v[4:7], v[154:155], off offset:512
	global_load_dwordx4 v[8:11], v[156:157], off offset:512
	global_load_dwordx4 v[12:15], v[158:159], off offset:512
	global_load_dwordx4 v[16:19], v[152:153], off offset:576
	global_load_dwordx4 v[20:23], v[154:155], off offset:576
	global_load_dwordx4 v[24:27], v[156:157], off offset:576
	global_load_dwordx4 v[28:31], v[158:159], off offset:576
	global_load_dwordx4 v[32:35], v[152:153], off offset:640
	global_load_dwordx4 v[36:39], v[154:155], off offset:640
	global_load_dwordx4 v[40:43], v[156:157], off offset:640
	global_load_dwordx4 v[44:47], v[158:159], off offset:640
	s_waitcnt vmcnt(12)
	v_mfma_f32_16x16x32_bf16 v[128:131], v[64:67], v[72:75], v[128:131]
	v_mfma_f32_16x16x32_bf16 v[132:135], v[68:71], v[72:75], v[132:135]
	v_mfma_f32_16x16x32_bf16 v[144:147], v[64:67], v[76:79], v[144:147]
	v_mfma_f32_16x16x32_bf16 v[148:151], v[68:71], v[76:79], v[148:151]
	v_mfma_f32_16x16x32_bf16 v[128:131], v[80:83], v[88:91], v[128:131]
	v_mfma_f32_16x16x32_bf16 v[132:135], v[84:87], v[88:91], v[132:135]
	v_mfma_f32_16x16x32_bf16 v[144:147], v[80:83], v[92:95], v[144:147]
	v_mfma_f32_16x16x32_bf16 v[148:151], v[84:87], v[92:95], v[148:151]
	v_mfma_f32_16x16x32_bf16 v[128:131], v[96:99], v[104:107], v[128:131]
	v_mfma_f32_16x16x32_bf16 v[132:135], v[100:103], v[104:107], v[132:135]
	v_mfma_f32_16x16x32_bf16 v[144:147], v[96:99], v[108:111], v[144:147]
	v_mfma_f32_16x16x32_bf16 v[148:151], v[100:103], v[108:111], v[148:151]
	v_mfma_f32_16x16x32_bf16 v[128:131], v[112:115], v[120:123], v[128:131]
	v_mfma_f32_16x16x32_bf16 v[132:135], v[116:119], v[120:123], v[132:135]
	v_mfma_f32_16x16x32_bf16 v[144:147], v[112:115], v[124:127], v[144:147]
	v_mfma_f32_16x16x32_bf16 v[148:151], v[116:119], v[124:127], v[148:151]
	s_waitcnt vmcnt(0)
	v_mfma_f32_16x16x32_bf16 v[128:131], v[0:3], v[8:11], v[128:131]
	v_mfma_f32_16x16x32_bf16 v[132:135], v[4:7], v[8:11], v[132:135]
	v_mfma_f32_16x16x32_bf16 v[144:147], v[0:3], v[12:15], v[144:147]
	v_mfma_f32_16x16x32_bf16 v[148:151], v[4:7], v[12:15], v[148:151]
	v_mfma_f32_16x16x32_bf16 v[128:131], v[16:19], v[24:27], v[128:131]
	v_mfma_f32_16x16x32_bf16 v[132:135], v[20:23], v[24:27], v[132:135]
	v_mfma_f32_16x16x32_bf16 v[144:147], v[16:19], v[28:31], v[144:147]
	v_mfma_f32_16x16x32_bf16 v[148:151], v[20:23], v[28:31], v[148:151]
	v_mfma_f32_16x16x32_bf16 v[128:131], v[32:35], v[40:43], v[128:131]
	v_mfma_f32_16x16x32_bf16 v[132:135], v[36:39], v[40:43], v[132:135]
	v_mfma_f32_16x16x32_bf16 v[144:147], v[32:35], v[44:47], v[144:147]
	v_mfma_f32_16x16x32_bf16 v[148:151], v[36:39], v[44:47], v[148:151]
	s_nop 7
	s_nop 7
	v_lshlrev_b32_e32 v170, 12, v162
	v_lshl_add_u32 v170, v136, 4, v170
	ds_write_b128 v170, v[128:131]
	ds_write_b128 v170, v[132:135] offset:1024
	ds_write_b128 v170, v[144:147] offset:2048
	ds_write_b128 v170, v[148:151] offset:3072
	s_waitcnt lgkmcnt(0)
	s_barrier
	s_cmp_ge_u32 s80, 4
	s_cbranch_scc1 .Lmg3_end
	s_lshl_b32 s84, s80, 10
	v_lshlrev_b32_e32 v171, 4, v136
	v_add_u32_e32 v171, s84, v171
	ds_read_b128 v[0:3], v171
	ds_read_b128 v[4:7], v171 offset:4096
	ds_read_b128 v[8:11], v171 offset:8192
	ds_read_b128 v[12:15], v171 offset:12288
	ds_read_b128 v[16:19], v171 offset:16384
	ds_read_b128 v[20:23], v171 offset:20480
	ds_read_b128 v[24:27], v171 offset:24576
	ds_read_b128 v[28:31], v171 offset:28672
	s_lshr_b32 s84, s80, 1
	s_lshl_b32 s84, s84, 4
	s_lshl_b32 s85, s81, 5
	s_add_i32 s84, s84, s85
	s_addk_i32 s84, 0x4000
	s_and_b32 s85, s80, 1
	s_lshl_b32 s85, s85, 4
	s_lshl_b32 s83, s82, 5
	s_add_i32 s85, s85, s83
	v_add_u32_e32 v165, s84, v160
	v_lshl_add_u32 v164, v161, 2, s85
	v_lshlrev_b32_e32 v166, 12, v165
	v_lshl_add_u32 v166, v164, 2, v166
	v_mov_b32_e32 v167, 0
	s_add_u32 s86, s74, 0x5000000
	s_addc_u32 s87, s75, 0
	v_lshl_add_u64 v[168:169], s[86:87], 0, v[166:167]
	global_load_dwordx4 v[32:35], v[168:169], off
	v_lshrrev_b32_e32 v172, 1, v166
	v_mov_b32_e32 v173, 0
	s_add_u32 s86, s74, 0x9100000
	s_addc_u32 s87, s75, 0
	v_lshl_add_u64 v[172:173], s[86:87], 0, v[172:173]
	v_lshlrev_b32_e32 v166, 2, v165
	s_add_u32 s86, s74, 0x12ba1000
	s_addc_u32 s87, s75, 0
	v_lshl_add_u64 v[166:167], s[86:87], 0, v[166:167]
	s_waitcnt lgkmcnt(0)
	v_add_f32_e32 v0, v0, v4
	v_add_f32_e32 v1, v1, v5
	v_add_f32_e32 v2, v2, v6
	v_add_f32_e32 v3, v3, v7
	v_add_f32_e32 v0, v0, v8
	v_add_f32_e32 v1, v1, v9
	v_add_f32_e32 v2, v2, v10
	v_add_f32_e32 v3, v3, v11
	v_add_f32_e32 v0, v0, v12
	v_add_f32_e32 v1, v1, v13
	v_add_f32_e32 v2, v2, v14
	v_add_f32_e32 v3, v3, v15
	v_add_f32_e32 v0, v0, v16
	v_add_f32_e32 v1, v1, v17
	v_add_f32_e32 v2, v2, v18
	v_add_f32_e32 v3, v3, v19
	v_add_f32_e32 v0, v0, v20
	v_add_f32_e32 v1, v1, v21
	v_add_f32_e32 v2, v2, v22
	v_add_f32_e32 v3, v3, v23
	v_add_f32_e32 v0, v0, v24
	v_add_f32_e32 v1, v1, v25
	v_add_f32_e32 v2, v2, v26
	v_add_f32_e32 v3, v3, v27
	v_add_f32_e32 v0, v0, v28
	v_add_f32_e32 v1, v1, v29
	v_add_f32_e32 v2, v2, v30
	v_add_f32_e32 v3, v3, v31
	s_waitcnt vmcnt(0)
	v_fma_f32 v32, v0, 0.5, v32
	v_fma_f32 v33, v1, 0.5, v33
	v_fma_f32 v34, v2, 0.5, v34
	v_fma_f32 v35, v3, 0.5, v35
	global_store_dwordx4 v[168:169], v[32:35], off
	v_cvt_pk_bf16_f32 v36, v32, v33
	v_cvt_pk_bf16_f32 v37, v34, v35
	global_store_dwordx2 v[172:173], v[36:37], off
	v_mul_f32_e32 v38, v32, v32
	v_fmac_f32_e32 v38, v33, v33
	v_fmac_f32_e32 v38, v34, v34
	v_fmac_f32_e32 v38, v35, v35
	v_xor_b32_e32 v39, 16, v136
	v_lshlrev_b32_e32 v39, 2, v39
	ds_bpermute_b32 v40, v39, v38
	v_xor_b32_e32 v41, 32, v136
	v_lshlrev_b32_e32 v41, 2, v41
	s_waitcnt lgkmcnt(0)
	v_add_f32_e32 v38, v38, v40
	ds_bpermute_b32 v40, v41, v38
	s_waitcnt lgkmcnt(0)
	v_add_f32_e32 v38, v38, v40
	v_cmp_gt_u32_e64 s[82:83], 16, v136
	s_nop 1
	s_and_saveexec_b64 s[84:85], s[82:83]
	global_atomic_add_f32 v[166:167], v38, off
	s_mov_b64 exec, s[84:85]
.Lmg3_end:
	v_lshrrev_b32_e32 v21, 6, v174
	v_and_b32_e32 v22, 63, v174
	v_lshlrev_b32_e32 v22, 4, v22
	v_readfirstlane_b32 s80, v21
	v_add_u32_e32 v23, 0x1000, v22
	v_readfirstlane_b32 s92, v235
	v_readfirstlane_b32 s93, v236
	v_readfirstlane_b32 s94, v237
	v_readfirstlane_b32 s95, v238
	v_readfirstlane_b32 s98, v239
	v_readfirstlane_b32 s99, v240
	s_lshr_b32 s100, s33, 7
	s_lshl_b32 s100, s100, 3
	s_lshr_b32 s101, s33, 3
	s_and_b32 s101, s101, 7
	s_add_i32 s100, s100, s101
	s_lshl_b32 s100, s100, 3
	s_add_i32 s80, s80, s100
	s_add_i32 s80, s80, 0xf94c
	s_movk_i32 s100, 0x400

.Lcpy3_end:
.Lpost3_skip:
	s_waitcnt vmcnt(0)
	s_waitcnt lgkmcnt(0)
	s_barrier
	s_and_saveexec_b64 s[8:9], s[0:1]
	s_cbranch_execz .LBB0_1042
	v_rcp_iflag_f32_e32 v0, v176
	s_sub_i32 s4, 0, s78
	s_mov_b64 s[10:11], exec
	buffer_wbl2 sc1
	s_waitcnt vmcnt(0)
	v_mul_f32_e32 v0, 0x4f7ffffe, v0
	v_cvt_u32_f32_e32 v0, v0
	s_waitcnt vmcnt(0)
	v_mbcnt_lo_u32_b32 v1, s10, 0
	s_mul_i32 s5, s78, 9
	v_readfirstlane_b32 s6, v0
	s_mul_i32 s4, s4, s6
	s_mul_hi_u32 s4, s6, s4
	s_add_i32 s6, s6, s4
	v_mbcnt_hi_u32_b32 v0, s11, v1
	s_mul_hi_u32 s4, s5, s6
	v_cmp_eq_u32_e32 vcc, 0, v0
	s_and_saveexec_b64 s[12:13], vcc
	s_cbranch_execz .LBB0_1025
	s_bcnt1_i32_b64 s6, s[10:11]
	v_mov_b32_e32 v1, 0
	v_mov_b32_e32 v2, s6
	global_atomic_add v1, v1, v2, s[96:97] sc0

.LBB0_1383:
	s_or_b64 exec, exec, s[8:9]
	v_readlane_b32 s4, v234, 2
	v_mov_b32_e32 v8, v174
	v_readlane_b32 s5, v234, 3
	s_barrier
	s_and_b32 s80, s33, 64
	s_cmp_eq_u32 s80, 0
	s_cbranch_scc1 .Lpref_skip
	v_lshrrev_b32_e32 v21, 6, v174
	v_and_b32_e32 v22, 63, v174
	v_lshlrev_b32_e32 v22, 4, v22
	v_readfirstlane_b32 s80, v21
	v_add_u32_e32 v23, 0x1000, v22
	v_readfirstlane_b32 s92, v235
	v_readfirstlane_b32 s93, v236
	v_readfirstlane_b32 s94, v237
	v_readfirstlane_b32 s95, v238
	v_readfirstlane_b32 s98, v239
	v_readfirstlane_b32 s99, v240
	s_lshr_b32 s100, s33, 7
	s_lshl_b32 s100, s100, 3
	s_lshr_b32 s101, s33, 3
	s_and_b32 s101, s101, 7
	s_add_i32 s100, s100, s101
	s_lshl_b32 s100, s100, 3
	s_add_i32 s80, s80, s100
	s_add_i32 s80, s80, 0x122c8
	s_movk_i32 s100, 0x400
.Lcpyfp_loop:
	s_add_i32 s101, s80, s100
	s_cmp_lt_u32 s101, 0x1316e
	s_cbranch_scc0 .Lcpyfp_tail
	s_mul_hi_u32 s81, s80, 0x2ad5802b
	s_lshr_b32 s81, s81, 8
	s_mul_i32 s82, s81, 0x5fa
	s_sub_i32 s82, s80, s82
	s_lshl_b32 s82, s82, 13
	s_and_b32 s83, s81, 31
	s_mul_i32 s83, s83, 0xc00000
	s_add_i32 s82, s82, s83
	s_cmp_lt_u32 s81, 32
	s_cselect_b32 s84, s92, s94
	s_cselect_b32 s85, s93, s95
	s_mov_b32 s83, 0x1f210000
	s_cselect_b32 s83, 0x7210000, s83
	s_add_u32 s84, s84, s82
	s_addc_u32 s85, s85, 0
	s_add_u32 s84, s84, 0xc000
	s_addc_u32 s85, s85, 0
	s_add_u32 s83, s83, s82
	s_add_u32 s86, s98, s83
	s_addc_u32 s87, s99, 0
	s_mul_hi_u32 s81, s101, 0x2ad5802b
	s_lshr_b32 s81, s81, 8
	s_mul_i32 s82, s81, 0x5fa
	s_sub_i32 s82, s101, s82
	s_lshl_b32 s82, s82, 13
	s_and_b32 s83, s81, 31
	s_mul_i32 s83, s83, 0xc00000
	s_add_i32 s82, s82, s83
	s_cmp_lt_u32 s81, 32
	s_cselect_b32 s88, s92, s94
	s_cselect_b32 s89, s93, s95
	s_mov_b32 s83, 0x1f210000
	s_cselect_b32 s83, 0x7210000, s83
	s_add_u32 s88, s88, s82
	s_addc_u32 s89, s89, 0
	s_add_u32 s88, s88, 0xc000
	s_addc_u32 s89, s89, 0
	s_add_u32 s83, s83, s82
	s_add_u32 s90, s98, s83
	s_addc_u32 s91, s99, 0
	global_load_dwordx4 v[64:67], v22, s[84:85] nt
	global_load_dwordx4 v[68:71], v22, s[84:85] offset:1024 nt
	global_load_dwordx4 v[72:75], v22, s[84:85] offset:2048 nt
	global_load_dwordx4 v[76:79], v22, s[84:85] offset:3072 nt
	global_load_dwordx4 v[80:83], v23, s[84:85] nt
	global_load_dwordx4 v[84:87], v23, s[84:85] offset:1024 nt
	global_load_dwordx4 v[88:91], v23, s[84:85] offset:2048 nt
	global_load_dwordx4 v[92:95], v23, s[84:85] offset:3072 nt
	global_load_dwordx4 v[96:99], v22, s[88:89] nt
	global_load_dwordx4 v[100:103], v22, s[88:89] offset:1024 nt
	global_load_dwordx4 v[104:107], v22, s[88:89] offset:2048 nt
	global_load_dwordx4 v[108:111], v22, s[88:89] offset:3072 nt
	global_load_dwordx4 v[112:115], v23, s[88:89] nt
	global_load_dwordx4 v[116:119], v23, s[88:89] offset:1024 nt
	global_load_dwordx4 v[120:123], v23, s[88:89] offset:2048 nt
	global_load_dwordx4 v[124:127], v23, s[88:89] offset:3072 nt
	s_waitcnt vmcnt(15)
	global_store_dwordx4 v22, v[64:67], s[86:87] nt
	s_waitcnt vmcnt(15)
	global_store_dwordx4 v22, v[68:71], s[86:87] offset:1024 nt
	s_waitcnt vmcnt(15)
	global_store_dwordx4 v22, v[72:75], s[86:87] offset:2048 nt
	s_waitcnt vmcnt(15)
	global_store_dwordx4 v22, v[76:79], s[86:87] offset:3072 nt
	s_waitcnt vmcnt(15)
	global_store_dwordx4 v23, v[80:83], s[86:87] nt
	s_waitcnt vmcnt(15)
	global_store_dwordx4 v23, v[84:87], s[86:87] offset:1024 nt
	s_waitcnt vmcnt(15)
	global_store_dwordx4 v23, v[88:91], s[86:87] offset:2048 nt
	s_waitcnt vmcnt(15)
	global_store_dwordx4 v23, v[92:95], s[86:87] offset:3072 nt
	s_waitcnt vmcnt(15)
	global_store_dwordx4 v22, v[96:99], s[90:91] nt
	s_waitcnt vmcnt(15)
	global_store_dwordx4 v22, v[100:103], s[90:91] offset:1024 nt
	s_waitcnt vmcnt(15)
	global_store_dwordx4 v22, v[104:107], s[90:91] offset:2048 nt
	s_waitcnt vmcnt(15)
	global_store_dwordx4 v22, v[108:111], s[90:91] offset:3072 nt
	s_waitcnt vmcnt(15)
	global_store_dwordx4 v23, v[112:115], s[90:91] nt
	s_waitcnt vmcnt(15)
	global_store_dwordx4 v23, v[116:119], s[90:91] offset:1024 nt
	s_waitcnt vmcnt(15)
	global_store_dwordx4 v23, v[120:123], s[90:91] offset:2048 nt
	s_waitcnt vmcnt(15)
	global_store_dwordx4 v23, v[124:127], s[90:91] offset:3072 nt
	s_add_i32 s80, s101, s100
	s_branch .Lcpyfp_loop
.Lcpyfp_tail:
	s_cmp_lt_u32 s80, 0x1316e
	s_cbranch_scc0 .Lcpyfp_end
	s_mul_hi_u32 s81, s80, 0x2ad5802b
	s_lshr_b32 s81, s81, 8
	s_mul_i32 s82, s81, 0x5fa
	s_sub_i32 s82, s80, s82
	s_lshl_b32 s82, s82, 13
	s_and_b32 s83, s81, 31
	s_mul_i32 s83, s83, 0xc00000
	s_add_i32 s82, s82, s83
	s_cmp_lt_u32 s81, 32
	s_cselect_b32 s84, s92, s94
	s_cselect_b32 s85, s93, s95
	s_mov_b32 s83, 0x1f210000
	s_cselect_b32 s83, 0x7210000, s83
	s_add_u32 s84, s84, s82
	s_addc_u32 s85, s85, 0
	s_add_u32 s84, s84, 0xc000
	s_addc_u32 s85, s85, 0
	s_add_u32 s83, s83, s82
	s_add_u32 s86, s98, s83
	s_addc_u32 s87, s99, 0
	global_load_dwordx4 v[64:67], v22, s[84:85] nt
	global_load_dwordx4 v[68:71], v22, s[84:85] offset:1024 nt
	global_load_dwordx4 v[72:75], v22, s[84:85] offset:2048 nt
	global_load_dwordx4 v[76:79], v22, s[84:85] offset:3072 nt
	global_load_dwordx4 v[80:83], v23, s[84:85] nt
	global_load_dwordx4 v[84:87], v23, s[84:85] offset:1024 nt
	global_load_dwordx4 v[88:91], v23, s[84:85] offset:2048 nt
	global_load_dwordx4 v[92:95], v23, s[84:85] offset:3072 nt
	s_waitcnt vmcnt(7)
	global_store_dwordx4 v22, v[64:67], s[86:87] nt
	s_waitcnt vmcnt(7)
	global_store_dwordx4 v22, v[68:71], s[86:87] offset:1024 nt
	s_waitcnt vmcnt(7)
	global_store_dwordx4 v22, v[72:75], s[86:87] offset:2048 nt
	s_waitcnt vmcnt(7)
	global_store_dwordx4 v22, v[76:79], s[86:87] offset:3072 nt
	s_waitcnt vmcnt(7)
	global_store_dwordx4 v23, v[80:83], s[86:87] nt
	s_waitcnt vmcnt(7)
	global_store_dwordx4 v23, v[84:87], s[86:87] offset:1024 nt
	s_waitcnt vmcnt(7)
	global_store_dwordx4 v23, v[88:91], s[86:87] offset:2048 nt
	s_waitcnt vmcnt(7)
	global_store_dwordx4 v23, v[92:95], s[86:87] offset:3072 nt
.Lcpyfp_end:
	v_and_b32_e32 v160, 15, v174
	v_bfe_u32 v161, v174, 4, 2
	v_lshrrev_b32_e32 v162, 6, v174
	v_and_b32_e32 v136, 63, v174
	v_readfirstlane_b32 s80, v162
	s_lshr_b32 s81, s33, 8
	s_lshr_b32 s82, s33, 3
	s_and_b32 s82, s82, 31
	s_mul_i32 s83, s80, 128
	v_lshlrev_b32_e32 v164, 4, v161
	v_mov_b32_e32 v167, 0
	s_lshl_b32 s84, s82, 5
	v_add_u32_e32 v165, s84, v160
	v_mul_u32_u24_e32 v166, 0x400, v165
	v_add3_u32 v166, v166, v164, s83
	s_add_u32 s86, s74, 0x4f00000
	s_addc_u32 s87, s75, 0
	s_mov_b32 s88, 0x4000
	s_mov_b32 s89, 0
	v_lshl_add_u64 v[152:153], s[86:87], 0, v[166:167]
	v_lshl_add_u64 v[154:155], v[152:153], 0, s[88:89]
	s_lshl_b32 s84, s81, 5
	v_add_u32_e32 v165, s84, v160
	v_mul_u32_u24_e32 v166, 0x400, v165
	v_add3_u32 v166, v166, v164, s83
	s_add_u32 s90, s74, 0x3d16bc00
	s_addc_u32 s91, s75, 0
	v_lshl_add_u64 v[156:157], s[90:91], 0, v[166:167]
	v_lshl_add_u64 v[158:159], v[156:157], 0, s[88:89]
	v_mov_b32_e32 v128, 0
	v_mov_b32_e32 v129, 0
	v_mov_b32_e32 v130, 0
	v_mov_b32_e32 v131, 0
	v_mov_b32_e32 v132, 0
	v_mov_b32_e32 v133, 0
	v_mov_b32_e32 v134, 0
	v_mov_b32_e32 v135, 0
	v_mov_b32_e32 v144, 0
	v_mov_b32_e32 v145, 0
	v_mov_b32_e32 v146, 0
	v_mov_b32_e32 v147, 0
	v_mov_b32_e32 v148, 0
	v_mov_b32_e32 v149, 0
	v_mov_b32_e32 v150, 0
	v_mov_b32_e32 v151, 0
	global_load_dwordx4 v[0:3], v[152:153], off
	global_load_dwordx4 v[4:7], v[154:155], off
	global_load_dwordx4 v[8:11], v[156:157], off
	global_load_dwordx4 v[12:15], v[158:159], off
	global_load_dwordx4 v[16:19], v[152:153], off offset:64
	global_load_dwordx4 v[20:23], v[154:155], off offset:64
	global_load_dwordx4 v[24:27], v[156:157], off offset:64
	global_load_dwordx4 v[28:31], v[158:159], off offset:64
	s_waitcnt vmcnt(0)
	v_mfma_f32_16x16x32_bf16 v[128:131], v[0:3], v[8:11], v[128:131]
	v_mfma_f32_16x16x32_bf16 v[132:135], v[4:7], v[8:11], v[132:135]
	v_mfma_f32_16x16x32_bf16 v[144:147], v[0:3], v[12:15], v[144:147]
	v_mfma_f32_16x16x32_bf16 v[148:151], v[4:7], v[12:15], v[148:151]
	v_mfma_f32_16x16x32_bf16 v[128:131], v[16:19], v[24:27], v[128:131]
	v_mfma_f32_16x16x32_bf16 v[132:135], v[20:23], v[24:27], v[132:135]
	v_mfma_f32_16x16x32_bf16 v[144:147], v[16:19], v[28:31], v[144:147]
	v_mfma_f32_16x16x32_bf16 v[148:151], v[20:23], v[28:31], v[148:151]
	s_nop 7
	s_nop 7
	v_lshlrev_b32_e32 v170, 12, v162
	v_lshl_add_u32 v170, v136, 4, v170
	ds_write_b128 v170, v[128:131]
	ds_write_b128 v170, v[132:135] offset:1024
	ds_write_b128 v170, v[144:147] offset:2048
	ds_write_b128 v170, v[148:151] offset:3072
	s_waitcnt lgkmcnt(0)
	s_barrier
	s_cmp_ge_u32 s80, 4
	s_cbranch_scc1 .Lmgfp_end
	s_lshl_b32 s84, s80, 10
	v_lshlrev_b32_e32 v171, 4, v136
	v_add_u32_e32 v171, s84, v171
	ds_read_b128 v[0:3], v171
	ds_read_b128 v[4:7], v171 offset:4096
	ds_read_b128 v[8:11], v171 offset:8192
	ds_read_b128 v[12:15], v171 offset:12288
	ds_read_b128 v[16:19], v171 offset:16384
	ds_read_b128 v[20:23], v171 offset:20480
	ds_read_b128 v[24:27], v171 offset:24576
	ds_read_b128 v[28:31], v171 offset:28672
	s_lshr_b32 s84, s80, 1
	s_lshl_b32 s84, s84, 4
	s_lshl_b32 s85, s81, 5
	s_add_i32 s84, s84, s85
	s_addk_i32 s84, 0x4000
	s_and_b32 s85, s80, 1
	s_lshl_b32 s85, s85, 4
	s_lshl_b32 s83, s82, 5
	s_add_i32 s85, s85, s83
	v_add_u32_e32 v165, s84, v160
	v_lshl_add_u32 v164, v161, 2, s85
	v_lshlrev_b32_e32 v166, 12, v165
	v_lshl_add_u32 v166, v164, 2, v166
	v_mov_b32_e32 v167, 0
	s_add_u32 s86, s74, 0x5000000
	s_addc_u32 s87, s75, 0
	v_lshl_add_u64 v[168:169], s[86:87], 0, v[166:167]
	global_load_dwordx4 v[32:35], v[168:169], off
	v_lshrrev_b32_e32 v172, 1, v166
	v_mov_b32_e32 v173, 0
	s_add_u32 s86, s74, 0x9100000
	s_addc_u32 s87, s75, 0
	v_lshl_add_u64 v[172:173], s[86:87], 0, v[172:173]
	v_lshlrev_b32_e32 v166, 2, v165
	s_add_u32 s86, s74, 0x12bb1400
	s_addc_u32 s87, s75, 0
	v_lshl_add_u64 v[166:167], s[86:87], 0, v[166:167]
	s_waitcnt lgkmcnt(0)
	v_add_f32_e32 v0, v0, v4
	v_add_f32_e32 v1, v1, v5
	v_add_f32_e32 v2, v2, v6
	v_add_f32_e32 v3, v3, v7
	v_add_f32_e32 v0, v0, v8
	v_add_f32_e32 v1, v1, v9
	v_add_f32_e32 v2, v2, v10
	v_add_f32_e32 v3, v3, v11
	v_add_f32_e32 v0, v0, v12
	v_add_f32_e32 v1, v1, v13
	v_add_f32_e32 v2, v2, v14
	v_add_f32_e32 v3, v3, v15
	v_add_f32_e32 v0, v0, v16
	v_add_f32_e32 v1, v1, v17
	v_add_f32_e32 v2, v2, v18
	v_add_f32_e32 v3, v3, v19
	v_add_f32_e32 v0, v0, v20
	v_add_f32_e32 v1, v1, v21
	v_add_f32_e32 v2, v2, v22
	v_add_f32_e32 v3, v3, v23
	v_add_f32_e32 v0, v0, v24
	v_add_f32_e32 v1, v1, v25
	v_add_f32_e32 v2, v2, v26
	v_add_f32_e32 v3, v3, v27
	v_add_f32_e32 v0, v0, v28
	v_add_f32_e32 v1, v1, v29
	v_add_f32_e32 v2, v2, v30
	v_add_f32_e32 v3, v3, v31
	s_waitcnt vmcnt(0)
	v_fma_f32 v32, v0, 1.0, v32
	v_fma_f32 v33, v1, 1.0, v33
	v_fma_f32 v34, v2, 1.0, v34
	v_fma_f32 v35, v3, 1.0, v35
	global_store_dwordx4 v[168:169], v[32:35], off
	v_cvt_pk_bf16_f32 v36, v32, v33
	v_cvt_pk_bf16_f32 v37, v34, v35
	global_store_dwordx2 v[172:173], v[36:37], off
	v_mul_f32_e32 v38, v32, v32
	v_fmac_f32_e32 v38, v33, v33
	v_fmac_f32_e32 v38, v34, v34
	v_fmac_f32_e32 v38, v35, v35
	v_xor_b32_e32 v39, 16, v136
	v_lshlrev_b32_e32 v39, 2, v39
	ds_bpermute_b32 v40, v39, v38
	v_xor_b32_e32 v41, 32, v136
	v_lshlrev_b32_e32 v41, 2, v41
	s_waitcnt lgkmcnt(0)
	v_add_f32_e32 v38, v38, v40
	ds_bpermute_b32 v40, v41, v38
	s_waitcnt lgkmcnt(0)
	v_add_f32_e32 v38, v38, v40
	v_cmp_gt_u32_e64 s[82:83], 16, v136
	s_nop 1
	s_and_saveexec_b64 s[84:85], s[82:83]
	global_atomic_add_f32 v[166:167], v38, off
	s_mov_b64 exec, s[84:85]
.Lmgfp_end:
	s_barrier
.Lpref_skip:
	v_mov_b32_e32 v8, v174
	s_and_b64 vcc, exec, s[4:5]
	v_readfirstlane_b32 s3, v8
	s_cbranch_vccnz .LBB0_1389
	s_ashr_i32 s4, s2, 31
	s_lshr_b32 s4, s4, 29
	s_add_i32 s4, s2, s4
	s_and_b32 s5, s4, -8
	s_sub_i32 s5, s2, s5
	s_cmp_gt_i32 s5, -1
	s_cbranch_scc0 .LBB0_1386
	s_lshl_b32 s6, s5, 5
	s_or_b32 s6, s6, 0
	s_cbranch_execz .LBB0_1387
	s_branch .LBB0_1388

.LBB0_1401:
	ds_read_b128 v[144:147], v151
	ds_read_b128 v[156:159], v151 offset:1024
	ds_read_b128 v[160:163], v151 offset:2048
	ds_read_b128 v[164:167], v151 offset:3072
	s_add_u32 s36, s34, 0xfffe0080
	s_addc_u32 s37, s35, -1
	s_cmp_eq_u32 s57, 4
	s_cselect_b32 s43, s23, s37
	s_cselect_b32 s42, s29, s36
	s_cselect_b32 s37, s21, s56
	s_cselect_b32 s36, s54, s55
	v_lshl_add_u64 v[172:173], s[34:35], 0, v[136:137]
	s_add_i32 m0, s7, 0xc000
	ds_read_b128 v[168:171], v152
	ds_read_b128 v[178:181], v152 offset:1024
	ds_read_b128 v[182:185], v152 offset:2048
	ds_read_b128 v[186:189], v152 offset:3072
	ds_read_b128 v[190:193], v152 offset:4096
	ds_read_b128 v[194:197], v152 offset:5120
	ds_read_b128 v[198:201], v152 offset:6144
	ds_read_b128 v[202:205], v152 offset:7168
	global_load_lds_dwordx4 v[172:173], off
	v_lshl_add_u64 v[172:173], s[34:35], 0, v[138:139]
	s_add_i32 m0, s7, 0xe000
	s_nop 0
	global_load_lds_dwordx4 v[172:173], off
	s_waitcnt lgkmcnt(8)
	s_barrier
	s_waitcnt lgkmcnt(0)
	s_setprio 1
	s_waitcnt lgkmcnt(0)
	v_mfma_f32_16x16x32_bf16 v[124:127], v[144:147], v[168:171], v[124:127]
	v_mfma_f32_16x16x32_bf16 v[120:123], v[160:163], v[168:171], v[120:123]
	v_mfma_f32_16x16x32_bf16 v[108:111], v[144:147], v[182:185], v[108:111]
	v_mfma_f32_16x16x32_bf16 v[104:107], v[160:163], v[182:185], v[104:107]
	v_mfma_f32_16x16x32_bf16 v[92:95], v[144:147], v[190:193], v[92:95]
	v_mfma_f32_16x16x32_bf16 v[88:91], v[160:163], v[190:193], v[88:91]
	v_mfma_f32_16x16x32_bf16 v[76:79], v[144:147], v[198:201], v[76:79]
	v_mfma_f32_16x16x32_bf16 v[72:75], v[160:163], v[198:201], v[72:75]
	v_mfma_f32_16x16x32_bf16 v[124:127], v[156:159], v[178:181], v[124:127]
	v_mfma_f32_16x16x32_bf16 v[120:123], v[164:167], v[178:181], v[120:123]
	v_mfma_f32_16x16x32_bf16 v[108:111], v[156:159], v[186:189], v[108:111]
	v_mfma_f32_16x16x32_bf16 v[104:107], v[164:167], v[186:189], v[104:107]
	v_mfma_f32_16x16x32_bf16 v[92:95], v[156:159], v[194:197], v[92:95]
	v_mfma_f32_16x16x32_bf16 v[88:91], v[164:167], v[194:197], v[88:91]
	v_mfma_f32_16x16x32_bf16 v[76:79], v[156:159], v[202:205], v[76:79]
	v_mfma_f32_16x16x32_bf16 v[72:75], v[164:167], v[202:205], v[72:75]
	s_setprio 0
	s_barrier
	s_add_i32 s58, s52, s6
	v_lshl_add_u64 v[172:173], s[36:37], 0, v[130:131]
	s_mov_b32 m0, s58
	ds_read_b128 v[206:209], v153
	ds_read_b128 v[210:213], v153 offset:1024
	ds_read_b128 v[214:217], v153 offset:2048
	ds_read_b128 v[218:221], v153 offset:3072
	global_load_lds_dwordx4 v[172:173], off
	v_lshl_add_u64 v[222:223], s[36:37], 0, v[134:135]
	s_add_i32 m0, s58, 0x2000
	s_nop 0
	global_load_lds_dwordx4 v[222:223], off
	s_barrier
	s_waitcnt lgkmcnt(0)
	s_setprio 1
	s_waitcnt lgkmcnt(0)
	v_mfma_f32_16x16x32_bf16 v[116:119], v[206:209], v[168:171], v[116:119]
	v_mfma_f32_16x16x32_bf16 v[112:115], v[214:217], v[168:171], v[112:115]
	v_mfma_f32_16x16x32_bf16 v[100:103], v[206:209], v[182:185], v[100:103]
	v_mfma_f32_16x16x32_bf16 v[96:99], v[214:217], v[182:185], v[96:99]
	v_mfma_f32_16x16x32_bf16 v[84:87], v[206:209], v[190:193], v[84:87]
	v_mfma_f32_16x16x32_bf16 v[80:83], v[214:217], v[190:193], v[80:83]
	v_mfma_f32_16x16x32_bf16 v[68:71], v[206:209], v[198:201], v[68:71]
	v_mfma_f32_16x16x32_bf16 v[64:67], v[214:217], v[198:201], v[64:67]
	v_mfma_f32_16x16x32_bf16 v[116:119], v[210:213], v[178:181], v[116:119]
	v_mfma_f32_16x16x32_bf16 v[112:115], v[218:221], v[178:181], v[112:115]
	v_mfma_f32_16x16x32_bf16 v[100:103], v[210:213], v[186:189], v[100:103]
	v_mfma_f32_16x16x32_bf16 v[96:99], v[218:221], v[186:189], v[96:99]
	v_mfma_f32_16x16x32_bf16 v[84:87], v[210:213], v[194:197], v[84:87]
	v_mfma_f32_16x16x32_bf16 v[80:83], v[218:221], v[194:197], v[80:83]
	v_mfma_f32_16x16x32_bf16 v[68:71], v[210:213], v[202:205], v[68:71]
	v_mfma_f32_16x16x32_bf16 v[64:67], v[218:221], v[202:205], v[64:67]
	s_setprio 0
	s_mov_b32 m0, s7
	v_lshl_add_u64 v[224:225], s[42:43], 0, v[128:129]
	s_barrier
	ds_read_b128 v[168:171], v152 offset:16384
	ds_read_b128 v[178:181], v152 offset:17408
	ds_read_b128 v[182:185], v152 offset:18432
	ds_read_b128 v[186:189], v152 offset:19456
	ds_read_b128 v[190:193], v152 offset:20480
	ds_read_b128 v[194:197], v152 offset:21504
	ds_read_b128 v[198:201], v152 offset:22528
	ds_read_b128 v[202:205], v152 offset:23552
	global_load_lds_dwordx4 v[224:225], off
	v_lshl_add_u64 v[226:227], s[42:43], 0, v[132:133]
	s_mov_b32 m0, s31
	s_nop 0
	global_load_lds_dwordx4 v[226:227], off
	s_barrier
	s_waitcnt lgkmcnt(0)
	s_setprio 1
	s_waitcnt lgkmcnt(0)
	v_mfma_f32_16x16x32_bf16 v[60:63], v[144:147], v[168:171], v[60:63]
	v_mfma_f32_16x16x32_bf16 v[56:59], v[160:163], v[168:171], v[56:59]
	v_mfma_f32_16x16x32_bf16 v[44:47], v[144:147], v[182:185], v[44:47]
	v_mfma_f32_16x16x32_bf16 v[40:43], v[160:163], v[182:185], v[40:43]
	v_mfma_f32_16x16x32_bf16 v[28:31], v[144:147], v[190:193], v[28:31]
	v_mfma_f32_16x16x32_bf16 v[24:27], v[160:163], v[190:193], v[24:27]
	v_mfma_f32_16x16x32_bf16 v[12:15], v[144:147], v[198:201], v[12:15]
	v_mfma_f32_16x16x32_bf16 v[8:11], v[160:163], v[198:201], v[8:11]
	v_mfma_f32_16x16x32_bf16 v[60:63], v[156:159], v[178:181], v[60:63]
	v_mfma_f32_16x16x32_bf16 v[56:59], v[164:167], v[178:181], v[56:59]
	v_mfma_f32_16x16x32_bf16 v[44:47], v[156:159], v[186:189], v[44:47]
	v_mfma_f32_16x16x32_bf16 v[40:43], v[164:167], v[186:189], v[40:43]
	v_mfma_f32_16x16x32_bf16 v[28:31], v[156:159], v[194:197], v[28:31]
	v_mfma_f32_16x16x32_bf16 v[24:27], v[164:167], v[194:197], v[24:27]
	v_mfma_f32_16x16x32_bf16 v[12:15], v[156:159], v[202:205], v[12:15]
	v_mfma_f32_16x16x32_bf16 v[8:11], v[164:167], v[202:205], v[8:11]
	s_setprio 0
	s_barrier
	s_add_u32 s58, s36, 0x20000
	s_addc_u32 s59, s37, 0
	s_add_i32 s60, s53, s6
	v_lshl_add_u64 v[144:145], s[58:59], 0, v[130:131]
	s_mov_b32 m0, s60
	s_nop 0
	global_load_lds_dwordx4 v[144:145], off
	v_lshl_add_u64 v[144:145], s[58:59], 0, v[134:135]
	s_add_i32 m0, s60, 0x2000
	s_nop 0
	global_load_lds_dwordx4 v[144:145], off
	s_waitcnt vmcnt(6)
	s_barrier
	s_setprio 1
	v_mfma_f32_16x16x32_bf16 v[52:55], v[206:209], v[168:171], v[52:55]
	v_mfma_f32_16x16x32_bf16 v[48:51], v[214:217], v[168:171], v[48:51]
	v_mfma_f32_16x16x32_bf16 v[36:39], v[206:209], v[182:185], v[36:39]
	v_mfma_f32_16x16x32_bf16 v[32:35], v[214:217], v[182:185], v[32:35]
	v_mfma_f32_16x16x32_bf16 v[20:23], v[206:209], v[190:193], v[20:23]
	v_mfma_f32_16x16x32_bf16 v[16:19], v[214:217], v[190:193], v[16:19]
	v_mfma_f32_16x16x32_bf16 v[4:7], v[206:209], v[198:201], v[4:7]
	v_mfma_f32_16x16x32_bf16 v[0:3], v[214:217], v[198:201], v[0:3]
	v_mfma_f32_16x16x32_bf16 v[52:55], v[210:213], v[178:181], v[52:55]
	v_mfma_f32_16x16x32_bf16 v[48:51], v[218:221], v[178:181], v[48:51]
	v_mfma_f32_16x16x32_bf16 v[36:39], v[210:213], v[186:189], v[36:39]
	v_mfma_f32_16x16x32_bf16 v[32:35], v[218:221], v[186:189], v[32:35]
	v_mfma_f32_16x16x32_bf16 v[20:23], v[210:213], v[194:197], v[20:23]
	v_mfma_f32_16x16x32_bf16 v[16:19], v[218:221], v[194:197], v[16:19]
	v_mfma_f32_16x16x32_bf16 v[4:7], v[210:213], v[202:205], v[4:7]
	v_mfma_f32_16x16x32_bf16 v[0:3], v[218:221], v[202:205], v[0:3]
	s_setprio 0
	s_add_i32 s58, 0, 0x18000
	v_add_u32_e32 v155, s58, v149
	s_barrier
	ds_read_b128 v[144:147], v155
	ds_read_b128 v[156:159], v155 offset:1024
	ds_read_b128 v[160:163], v155 offset:2048
	ds_read_b128 v[164:167], v155 offset:3072
	s_add_u32 s42, s42, 0x20000
	s_addc_u32 s43, s43, 0
	s_mov_b32 m0, s46
	v_lshl_add_u64 v[206:207], s[42:43], 0, v[128:129]
	ds_read_b128 v[168:171], v152 offset:32768
	ds_read_b128 v[178:181], v152 offset:33792
	ds_read_b128 v[182:185], v152 offset:34816
	ds_read_b128 v[186:189], v152 offset:35840
	ds_read_b128 v[190:193], v152 offset:36864
	ds_read_b128 v[194:197], v152 offset:37888
	ds_read_b128 v[198:201], v152 offset:38912
	ds_read_b128 v[202:205], v152 offset:39936
	global_load_lds_dwordx4 v[206:207], off
	v_lshl_add_u64 v[206:207], s[42:43], 0, v[132:133]
	s_mov_b32 m0, s47
	s_nop 0
	global_load_lds_dwordx4 v[206:207], off
	s_waitcnt lgkmcnt(8)
	s_barrier
	s_waitcnt lgkmcnt(0)
	s_setprio 1
	s_waitcnt lgkmcnt(0)
	v_mfma_f32_16x16x32_bf16 v[124:127], v[144:147], v[168:171], v[124:127]
	v_mfma_f32_16x16x32_bf16 v[120:123], v[160:163], v[168:171], v[120:123]
	v_mfma_f32_16x16x32_bf16 v[108:111], v[144:147], v[182:185], v[108:111]
	v_mfma_f32_16x16x32_bf16 v[104:107], v[160:163], v[182:185], v[104:107]
	v_mfma_f32_16x16x32_bf16 v[92:95], v[144:147], v[190:193], v[92:95]
	v_mfma_f32_16x16x32_bf16 v[88:91], v[160:163], v[190:193], v[88:91]
	v_mfma_f32_16x16x32_bf16 v[76:79], v[144:147], v[198:201], v[76:79]
	v_mfma_f32_16x16x32_bf16 v[72:75], v[160:163], v[198:201], v[72:75]
	v_mfma_f32_16x16x32_bf16 v[124:127], v[156:159], v[178:181], v[124:127]
	v_mfma_f32_16x16x32_bf16 v[120:123], v[164:167], v[178:181], v[120:123]
	v_mfma_f32_16x16x32_bf16 v[108:111], v[156:159], v[186:189], v[108:111]
	v_mfma_f32_16x16x32_bf16 v[104:107], v[164:167], v[186:189], v[104:107]
	v_mfma_f32_16x16x32_bf16 v[92:95], v[156:159], v[194:197], v[92:95]
	v_mfma_f32_16x16x32_bf16 v[88:91], v[164:167], v[194:197], v[88:91]
	v_mfma_f32_16x16x32_bf16 v[76:79], v[156:159], v[202:205], v[76:79]
	v_mfma_f32_16x16x32_bf16 v[72:75], v[164:167], v[202:205], v[72:75]
	s_setprio 0
	s_barrier
	s_add_i32 s42, 0, 0x1c000
	s_add_i32 s43, s58, s6
	v_add_u32_e32 v155, s42, v149
	v_lshl_add_u64 v[172:173], v[172:173], 0, s[16:17]
	s_mov_b32 m0, s43
	ds_read_b128 v[206:209], v155
	ds_read_b128 v[210:213], v155 offset:1024
	ds_read_b128 v[214:217], v155 offset:2048
	ds_read_b128 v[218:221], v155 offset:3072
	global_load_lds_dwordx4 v[172:173], off
	v_lshl_add_u64 v[172:173], v[222:223], 0, s[16:17]
	s_add_i32 m0, s43, 0x2000
	s_nop 0
	global_load_lds_dwordx4 v[172:173], off
	s_barrier
	s_waitcnt lgkmcnt(0)
	s_setprio 1
	s_waitcnt lgkmcnt(0)
	v_mfma_f32_16x16x32_bf16 v[116:119], v[206:209], v[168:171], v[116:119]
	v_mfma_f32_16x16x32_bf16 v[112:115], v[214:217], v[168:171], v[112:115]
	v_mfma_f32_16x16x32_bf16 v[100:103], v[206:209], v[182:185], v[100:103]
	v_mfma_f32_16x16x32_bf16 v[96:99], v[214:217], v[182:185], v[96:99]
	v_mfma_f32_16x16x32_bf16 v[84:87], v[206:209], v[190:193], v[84:87]
	v_mfma_f32_16x16x32_bf16 v[80:83], v[214:217], v[190:193], v[80:83]
	v_mfma_f32_16x16x32_bf16 v[68:71], v[206:209], v[198:201], v[68:71]
	v_mfma_f32_16x16x32_bf16 v[64:67], v[214:217], v[198:201], v[64:67]
	v_mfma_f32_16x16x32_bf16 v[116:119], v[210:213], v[178:181], v[116:119]
	v_mfma_f32_16x16x32_bf16 v[112:115], v[218:221], v[178:181], v[112:115]
	v_mfma_f32_16x16x32_bf16 v[100:103], v[210:213], v[186:189], v[100:103]
	v_mfma_f32_16x16x32_bf16 v[96:99], v[218:221], v[186:189], v[96:99]
	v_mfma_f32_16x16x32_bf16 v[84:87], v[210:213], v[194:197], v[84:87]
	v_mfma_f32_16x16x32_bf16 v[80:83], v[218:221], v[194:197], v[80:83]
	v_mfma_f32_16x16x32_bf16 v[68:71], v[210:213], v[202:205], v[68:71]
	v_mfma_f32_16x16x32_bf16 v[64:67], v[218:221], v[202:205], v[64:67]
	s_setprio 0
	s_mov_b32 m0, s49
	v_lshl_add_u64 v[172:173], v[224:225], 0, s[16:17]
	s_barrier
	ds_read_b128 v[168:171], v152 offset:49152
	ds_read_b128 v[178:181], v152 offset:50176
	ds_read_b128 v[182:185], v152 offset:51200
	ds_read_b128 v[186:189], v152 offset:52224
	ds_read_b128 v[190:193], v152 offset:53248
	ds_read_b128 v[194:197], v152 offset:54272
	ds_read_b128 v[198:201], v152 offset:55296
	ds_read_b128 v[202:205], v152 offset:56320
	global_load_lds_dwordx4 v[172:173], off
	v_lshl_add_u64 v[172:173], v[226:227], 0, s[16:17]
	s_mov_b32 m0, s50
	s_nop 0
	global_load_lds_dwordx4 v[172:173], off
	s_barrier
	s_waitcnt lgkmcnt(0)
	s_setprio 1
	s_waitcnt lgkmcnt(0)
	v_mfma_f32_16x16x32_bf16 v[60:63], v[144:147], v[168:171], v[60:63]
	v_mfma_f32_16x16x32_bf16 v[56:59], v[160:163], v[168:171], v[56:59]
	v_mfma_f32_16x16x32_bf16 v[44:47], v[144:147], v[182:185], v[44:47]
	v_mfma_f32_16x16x32_bf16 v[40:43], v[160:163], v[182:185], v[40:43]
	v_mfma_f32_16x16x32_bf16 v[28:31], v[144:147], v[190:193], v[28:31]
	v_mfma_f32_16x16x32_bf16 v[24:27], v[160:163], v[190:193], v[24:27]
	v_mfma_f32_16x16x32_bf16 v[12:15], v[144:147], v[198:201], v[12:15]
	v_mfma_f32_16x16x32_bf16 v[8:11], v[160:163], v[198:201], v[8:11]
	v_mfma_f32_16x16x32_bf16 v[60:63], v[156:159], v[178:181], v[60:63]
	v_mfma_f32_16x16x32_bf16 v[56:59], v[164:167], v[178:181], v[56:59]
	v_mfma_f32_16x16x32_bf16 v[44:47], v[156:159], v[186:189], v[44:47]
	v_mfma_f32_16x16x32_bf16 v[40:43], v[164:167], v[186:189], v[40:43]
	v_mfma_f32_16x16x32_bf16 v[28:31], v[156:159], v[194:197], v[28:31]
	v_mfma_f32_16x16x32_bf16 v[24:27], v[164:167], v[194:197], v[24:27]
	v_mfma_f32_16x16x32_bf16 v[12:15], v[156:159], v[202:205], v[12:15]
	v_mfma_f32_16x16x32_bf16 v[8:11], v[164:167], v[202:205], v[8:11]
	s_setprio 0
	s_barrier
	s_add_u32 s36, s36, 0x20080
	s_addc_u32 s37, s37, 0
	s_add_i32 s42, s42, s6
	v_lshl_add_u64 v[144:145], s[36:37], 0, v[130:131]
	s_mov_b32 m0, s42
	s_nop 0
	global_load_lds_dwordx4 v[144:145], off
	v_lshl_add_u64 v[144:145], s[36:37], 0, v[134:135]
	s_add_i32 m0, s42, 0x2000
	s_nop 0
	global_load_lds_dwordx4 v[144:145], off
	s_waitcnt vmcnt(6)
	s_barrier
	s_setprio 1
	v_mfma_f32_16x16x32_bf16 v[52:55], v[206:209], v[168:171], v[52:55]
	v_mfma_f32_16x16x32_bf16 v[48:51], v[214:217], v[168:171], v[48:51]
	v_mfma_f32_16x16x32_bf16 v[36:39], v[206:209], v[182:185], v[36:39]
	v_mfma_f32_16x16x32_bf16 v[32:35], v[214:217], v[182:185], v[32:35]
	v_mfma_f32_16x16x32_bf16 v[20:23], v[206:209], v[190:193], v[20:23]
	v_mfma_f32_16x16x32_bf16 v[16:19], v[214:217], v[190:193], v[16:19]
	v_mfma_f32_16x16x32_bf16 v[4:7], v[206:209], v[198:201], v[4:7]
	v_mfma_f32_16x16x32_bf16 v[0:3], v[214:217], v[198:201], v[0:3]
	v_mfma_f32_16x16x32_bf16 v[52:55], v[210:213], v[178:181], v[52:55]
	v_mfma_f32_16x16x32_bf16 v[48:51], v[218:221], v[178:181], v[48:51]
	v_mfma_f32_16x16x32_bf16 v[36:39], v[210:213], v[186:189], v[36:39]
	v_mfma_f32_16x16x32_bf16 v[32:35], v[218:221], v[186:189], v[32:35]
	v_mfma_f32_16x16x32_bf16 v[20:23], v[210:213], v[194:197], v[20:23]
	v_mfma_f32_16x16x32_bf16 v[16:19], v[218:221], v[194:197], v[16:19]
	v_mfma_f32_16x16x32_bf16 v[4:7], v[210:213], v[202:205], v[4:7]
	v_mfma_f32_16x16x32_bf16 v[0:3], v[218:221], v[202:205], v[0:3]
	s_setprio 0
	s_add_i32 s57, s57, 2
	s_add_u32 s34, s34, 0x100
	s_addc_u32 s35, s35, 0
	s_add_u32 s55, s55, 0x100
	s_addc_u32 s56, s56, 0
	s_cmp_gt_u32 s57, 5
	s_barrier
	s_cbranch_scc0 .LBB0_1401
	s_nop 7
	s_nop 7
	v_and_b32_e32 v160, 15, v174
	v_bfe_u32 v161, v174, 4, 2
	v_lshrrev_b32_e32 v162, 6, v174
	v_lshrrev_b32_e32 v163, 2, v162
	v_and_b32_e32 v164, 3, v162
	v_and_b32_e32 v170, 63, v174
	s_lshr_b32 s80, s33, 3
	s_and_b32 s81, s80, 7
	s_lshl_b32 s81, s81, 3
	s_lshr_b32 s82, s80, 3
	s_and_b32 s82, s82, 7
	s_add_i32 s81, s81, s82
	s_lshr_b32 s82, s80, 6
	v_lshl_add_u32 v165, v163, 6, v160
	s_lshl_b32 s83, s81, 8
	v_add_u32_e32 v165, s83, v165
	v_lshlrev_b32_e32 v166, 3, v161
	v_lshl_add_u32 v166, v164, 5, v166
	s_lshl_b32 s83, s82, 8
	v_add_u32_e32 v166, s83, v166
	v_lshlrev_b32_e32 v168, 12, v165
	v_lshl_add_u32 v168, v166, 2, v168
	v_mov_b32_e32 v169, 0
	s_add_u32 s84, s74, 0x5000000
	s_addc_u32 s85, s75, 0
	v_lshl_add_u64 v[210:211], s[84:85], 0, v[168:169]
	v_lshrrev_b32_e32 v168, 1, v168
	s_add_u32 s84, s74, 0x9100000
	s_addc_u32 s85, s75, 0
	v_lshl_add_u64 v[212:213], s[84:85], 0, v[168:169]
	v_lshlrev_b32_e32 v168, 2, v165
	s_add_u32 s84, s74, 0x12bb1400
	s_addc_u32 s85, s75, 0
	v_lshl_add_u64 v[214:215], s[84:85], 0, v[168:169]
	v_xor_b32_e32 v171, 16, v170
	v_lshlrev_b32_e32 v171, 2, v171
	v_xor_b32_e32 v172, 32, v170
	v_lshlrev_b32_e32 v172, 2, v172
	v_cmp_eq_u32_e64 s[86:87], 0, v161
	s_mov_b32 s85, 0
	s_mov_b32 s89, 0
	s_mov_b32 s84, 0x0
	v_lshl_add_u64 v[216:217], s[84:85], 0, v[210:211]
	global_load_dwordx4 v[128:131], v[216:217], off
	global_load_dwordx4 v[132:135], v[216:217], off offset:16
	global_load_dwordx4 v[136:139], v[216:217], off offset:512
	global_load_dwordx4 v[140:143], v[216:217], off offset:528
	s_mov_b32 s84, 0x10000
	v_lshl_add_u64 v[216:217], s[84:85], 0, v[210:211]
	global_load_dwordx4 v[144:147], v[216:217], off
	global_load_dwordx4 v[148:151], v[216:217], off offset:16
	global_load_dwordx4 v[152:155], v[216:217], off offset:512
	global_load_dwordx4 v[156:159], v[216:217], off offset:528
	s_mov_b32 s84, 0x20000
	v_lshl_add_u64 v[216:217], s[84:85], 0, v[210:211]
	global_load_dwordx4 v[178:181], v[216:217], off
	global_load_dwordx4 v[182:185], v[216:217], off offset:16
	global_load_dwordx4 v[186:189], v[216:217], off offset:512
	global_load_dwordx4 v[190:193], v[216:217], off offset:528
	s_mov_b32 s84, 0x30000
	v_lshl_add_u64 v[216:217], s[84:85], 0, v[210:211]
	global_load_dwordx4 v[194:197], v[216:217], off
	global_load_dwordx4 v[198:201], v[216:217], off offset:16
	global_load_dwordx4 v[202:205], v[216:217], off offset:512
	global_load_dwordx4 v[206:209], v[216:217], off offset:528
	s_waitcnt vmcnt(0)
	s_mov_b32 s84, 0x0
	v_lshl_add_u64 v[216:217], s[84:85], 0, v[210:211]
	s_mov_b32 s88, 0x0
	v_lshl_add_u64 v[218:219], s[88:89], 0, v[212:213]
	v_pk_add_f32 v[128:129], v[124:125], v[128:129]
	v_pk_add_f32 v[130:131], v[126:127], v[130:131]
	v_pk_add_f32 v[132:133], v[120:121], v[132:133]
	v_pk_add_f32 v[134:135], v[122:123], v[134:135]
	global_store_dwordx4 v[216:217], v[128:131], off
	global_store_dwordx4 v[216:217], v[132:135], off offset:16
	v_cvt_pk_bf16_f32 v224, v128, v129
	v_cvt_pk_bf16_f32 v225, v130, v131
	v_cvt_pk_bf16_f32 v226, v132, v133
	v_cvt_pk_bf16_f32 v227, v134, v135
	global_store_dwordx4 v[218:219], v[224:227], off
	v_mul_f32_e32 v220, v128, v128
	v_fmac_f32_e32 v220, v129, v129
	v_fmac_f32_e32 v220, v130, v130
	v_fmac_f32_e32 v220, v131, v131
	v_fmac_f32_e32 v220, v132, v132
	v_fmac_f32_e32 v220, v133, v133
	v_fmac_f32_e32 v220, v134, v134
	v_fmac_f32_e32 v220, v135, v135
	v_pk_add_f32 v[136:137], v[116:117], v[136:137]
	v_pk_add_f32 v[138:139], v[118:119], v[138:139]
	v_pk_add_f32 v[140:141], v[112:113], v[140:141]
	v_pk_add_f32 v[142:143], v[114:115], v[142:143]
	global_store_dwordx4 v[216:217], v[136:139], off offset:512
	global_store_dwordx4 v[216:217], v[140:143], off offset:528
	v_cvt_pk_bf16_f32 v228, v136, v137
	v_cvt_pk_bf16_f32 v229, v138, v139
	v_cvt_pk_bf16_f32 v230, v140, v141
	v_cvt_pk_bf16_f32 v231, v142, v143
	global_store_dwordx4 v[218:219], v[228:231], off offset:256
	v_fmac_f32_e32 v220, v136, v136
	v_fmac_f32_e32 v220, v137, v137
	v_fmac_f32_e32 v220, v138, v138
	v_fmac_f32_e32 v220, v139, v139
	v_fmac_f32_e32 v220, v140, v140
	v_fmac_f32_e32 v220, v141, v141
	v_fmac_f32_e32 v220, v142, v142
	v_fmac_f32_e32 v220, v143, v143
	s_mov_b32 s84, 0x10000
	v_lshl_add_u64 v[216:217], s[84:85], 0, v[210:211]
	s_mov_b32 s88, 0x8000
	v_lshl_add_u64 v[218:219], s[88:89], 0, v[212:213]
	v_pk_add_f32 v[144:145], v[108:109], v[144:145]
	v_pk_add_f32 v[146:147], v[110:111], v[146:147]
	v_pk_add_f32 v[148:149], v[104:105], v[148:149]
	v_pk_add_f32 v[150:151], v[106:107], v[150:151]
	global_store_dwordx4 v[216:217], v[144:147], off
	global_store_dwordx4 v[216:217], v[148:151], off offset:16
	v_cvt_pk_bf16_f32 v224, v144, v145
	v_cvt_pk_bf16_f32 v225, v146, v147
	v_cvt_pk_bf16_f32 v226, v148, v149
	v_cvt_pk_bf16_f32 v227, v150, v151
	global_store_dwordx4 v[218:219], v[224:227], off
	v_mul_f32_e32 v221, v144, v144
	v_fmac_f32_e32 v221, v145, v145
	v_fmac_f32_e32 v221, v146, v146
	v_fmac_f32_e32 v221, v147, v147
	v_fmac_f32_e32 v221, v148, v148
	v_fmac_f32_e32 v221, v149, v149
	v_fmac_f32_e32 v221, v150, v150
	v_fmac_f32_e32 v221, v151, v151
	v_pk_add_f32 v[152:153], v[100:101], v[152:153]
	v_pk_add_f32 v[154:155], v[102:103], v[154:155]
	v_pk_add_f32 v[156:157], v[96:97], v[156:157]
	v_pk_add_f32 v[158:159], v[98:99], v[158:159]
	global_store_dwordx4 v[216:217], v[152:155], off offset:512
	global_store_dwordx4 v[216:217], v[156:159], off offset:528
	v_cvt_pk_bf16_f32 v228, v152, v153
	v_cvt_pk_bf16_f32 v229, v154, v155
	v_cvt_pk_bf16_f32 v230, v156, v157
	v_cvt_pk_bf16_f32 v231, v158, v159
	global_store_dwordx4 v[218:219], v[228:231], off offset:256
	v_fmac_f32_e32 v221, v152, v152
	v_fmac_f32_e32 v221, v153, v153
	v_fmac_f32_e32 v221, v154, v154
	v_fmac_f32_e32 v221, v155, v155
	v_fmac_f32_e32 v221, v156, v156
	v_fmac_f32_e32 v221, v157, v157
	v_fmac_f32_e32 v221, v158, v158
	v_fmac_f32_e32 v221, v159, v159
	s_mov_b32 s84, 0x20000
	v_lshl_add_u64 v[216:217], s[84:85], 0, v[210:211]
	s_mov_b32 s88, 0x10000
	v_lshl_add_u64 v[218:219], s[88:89], 0, v[212:213]
	v_pk_add_f32 v[178:179], v[92:93], v[178:179]
	v_pk_add_f32 v[180:181], v[94:95], v[180:181]
	v_pk_add_f32 v[182:183], v[88:89], v[182:183]
	v_pk_add_f32 v[184:185], v[90:91], v[184:185]
	global_store_dwordx4 v[216:217], v[178:181], off
	global_store_dwordx4 v[216:217], v[182:185], off offset:16
	v_cvt_pk_bf16_f32 v224, v178, v179
	v_cvt_pk_bf16_f32 v225, v180, v181
	v_cvt_pk_bf16_f32 v226, v182, v183
	v_cvt_pk_bf16_f32 v227, v184, v185
	global_store_dwordx4 v[218:219], v[224:227], off
	v_mul_f32_e32 v222, v178, v178
	v_fmac_f32_e32 v222, v179, v179
	v_fmac_f32_e32 v222, v180, v180
	v_fmac_f32_e32 v222, v181, v181
	v_fmac_f32_e32 v222, v182, v182
	v_fmac_f32_e32 v222, v183, v183
	v_fmac_f32_e32 v222, v184, v184
	v_fmac_f32_e32 v222, v185, v185
	v_pk_add_f32 v[186:187], v[84:85], v[186:187]
	v_pk_add_f32 v[188:189], v[86:87], v[188:189]
	v_pk_add_f32 v[190:191], v[80:81], v[190:191]
	v_pk_add_f32 v[192:193], v[82:83], v[192:193]
	global_store_dwordx4 v[216:217], v[186:189], off offset:512
	global_store_dwordx4 v[216:217], v[190:193], off offset:528
	v_cvt_pk_bf16_f32 v228, v186, v187
	v_cvt_pk_bf16_f32 v229, v188, v189
	v_cvt_pk_bf16_f32 v230, v190, v191
	v_cvt_pk_bf16_f32 v231, v192, v193
	global_store_dwordx4 v[218:219], v[228:231], off offset:256
	v_fmac_f32_e32 v222, v186, v186
	v_fmac_f32_e32 v222, v187, v187
	v_fmac_f32_e32 v222, v188, v188
	v_fmac_f32_e32 v222, v189, v189
	v_fmac_f32_e32 v222, v190, v190
	v_fmac_f32_e32 v222, v191, v191
	v_fmac_f32_e32 v222, v192, v192
	v_fmac_f32_e32 v222, v193, v193
	s_mov_b32 s84, 0x30000
	v_lshl_add_u64 v[216:217], s[84:85], 0, v[210:211]
	s_mov_b32 s88, 0x18000
	v_lshl_add_u64 v[218:219], s[88:89], 0, v[212:213]
	v_pk_add_f32 v[194:195], v[76:77], v[194:195]
	v_pk_add_f32 v[196:197], v[78:79], v[196:197]
	v_pk_add_f32 v[198:199], v[72:73], v[198:199]
	v_pk_add_f32 v[200:201], v[74:75], v[200:201]
	global_store_dwordx4 v[216:217], v[194:197], off
	global_store_dwordx4 v[216:217], v[198:201], off offset:16
	v_cvt_pk_bf16_f32 v224, v194, v195
	v_cvt_pk_bf16_f32 v225, v196, v197
	v_cvt_pk_bf16_f32 v226, v198, v199
	v_cvt_pk_bf16_f32 v227, v200, v201
	global_store_dwordx4 v[218:219], v[224:227], off
	v_mul_f32_e32 v223, v194, v194
	v_fmac_f32_e32 v223, v195, v195
	v_fmac_f32_e32 v223, v196, v196
	v_fmac_f32_e32 v223, v197, v197
	v_fmac_f32_e32 v223, v198, v198
	v_fmac_f32_e32 v223, v199, v199
	v_fmac_f32_e32 v223, v200, v200
	v_fmac_f32_e32 v223, v201, v201
	v_pk_add_f32 v[202:203], v[68:69], v[202:203]
	v_pk_add_f32 v[204:205], v[70:71], v[204:205]
	v_pk_add_f32 v[206:207], v[64:65], v[206:207]
	v_pk_add_f32 v[208:209], v[66:67], v[208:209]
	global_store_dwordx4 v[216:217], v[202:205], off offset:512
	global_store_dwordx4 v[216:217], v[206:209], off offset:528
	v_cvt_pk_bf16_f32 v228, v202, v203
	v_cvt_pk_bf16_f32 v229, v204, v205
	v_cvt_pk_bf16_f32 v230, v206, v207
	v_cvt_pk_bf16_f32 v231, v208, v209
	global_store_dwordx4 v[218:219], v[228:231], off offset:256
	v_fmac_f32_e32 v223, v202, v202
	v_fmac_f32_e32 v223, v203, v203
	v_fmac_f32_e32 v223, v204, v204
	v_fmac_f32_e32 v223, v205, v205
	v_fmac_f32_e32 v223, v206, v206
	v_fmac_f32_e32 v223, v207, v207
	v_fmac_f32_e32 v223, v208, v208
	v_fmac_f32_e32 v223, v209, v209
	ds_bpermute_b32 v224, v171, v220
	ds_bpermute_b32 v225, v171, v221
	ds_bpermute_b32 v226, v171, v222
	ds_bpermute_b32 v227, v171, v223
	s_waitcnt lgkmcnt(0)
	v_add_f32_e32 v220, v220, v224
	v_add_f32_e32 v221, v221, v225
	v_add_f32_e32 v222, v222, v226
	v_add_f32_e32 v223, v223, v227
	ds_bpermute_b32 v224, v172, v220
	ds_bpermute_b32 v225, v172, v221
	ds_bpermute_b32 v226, v172, v222
	ds_bpermute_b32 v227, v172, v223
	s_waitcnt lgkmcnt(0)
	v_add_f32_e32 v220, v220, v224
	v_add_f32_e32 v221, v221, v225
	v_add_f32_e32 v222, v222, v226
	v_add_f32_e32 v223, v223, v227
	s_and_saveexec_b64 s[90:91], s[86:87]
	global_atomic_add_f32 v[214:215], v220, off
	global_atomic_add_f32 v[214:215], v221, off offset:64
	global_atomic_add_f32 v[214:215], v222, off offset:128
	global_atomic_add_f32 v[214:215], v223, off offset:192
	s_mov_b64 exec, s[90:91]
	s_mov_b32 s84, 0x80000
	v_lshl_add_u64 v[216:217], s[84:85], 0, v[210:211]
	global_load_dwordx4 v[128:131], v[216:217], off
	global_load_dwordx4 v[132:135], v[216:217], off offset:16
	global_load_dwordx4 v[136:139], v[216:217], off offset:512
	global_load_dwordx4 v[140:143], v[216:217], off offset:528
	s_mov_b32 s84, 0x90000
	v_lshl_add_u64 v[216:217], s[84:85], 0, v[210:211]
	global_load_dwordx4 v[144:147], v[216:217], off
	global_load_dwordx4 v[148:151], v[216:217], off offset:16
	global_load_dwordx4 v[152:155], v[216:217], off offset:512
	global_load_dwordx4 v[156:159], v[216:217], off offset:528
	s_mov_b32 s84, 0xa0000
	v_lshl_add_u64 v[216:217], s[84:85], 0, v[210:211]
	global_load_dwordx4 v[178:181], v[216:217], off
	global_load_dwordx4 v[182:185], v[216:217], off offset:16
	global_load_dwordx4 v[186:189], v[216:217], off offset:512
	global_load_dwordx4 v[190:193], v[216:217], off offset:528
	s_mov_b32 s84, 0xb0000
	v_lshl_add_u64 v[216:217], s[84:85], 0, v[210:211]
	global_load_dwordx4 v[194:197], v[216:217], off
	global_load_dwordx4 v[198:201], v[216:217], off offset:16
	global_load_dwordx4 v[202:205], v[216:217], off offset:512
	global_load_dwordx4 v[206:209], v[216:217], off offset:528
	s_waitcnt vmcnt(0)
	s_mov_b32 s84, 0x80000
	v_lshl_add_u64 v[216:217], s[84:85], 0, v[210:211]
	s_mov_b32 s88, 0x40000
	v_lshl_add_u64 v[218:219], s[88:89], 0, v[212:213]
	v_pk_add_f32 v[128:129], v[60:61], v[128:129]
	v_pk_add_f32 v[130:131], v[62:63], v[130:131]
	v_pk_add_f32 v[132:133], v[56:57], v[132:133]
	v_pk_add_f32 v[134:135], v[58:59], v[134:135]
	global_store_dwordx4 v[216:217], v[128:131], off
	global_store_dwordx4 v[216:217], v[132:135], off offset:16
	v_cvt_pk_bf16_f32 v224, v128, v129
	v_cvt_pk_bf16_f32 v225, v130, v131
	v_cvt_pk_bf16_f32 v226, v132, v133
	v_cvt_pk_bf16_f32 v227, v134, v135
	global_store_dwordx4 v[218:219], v[224:227], off
	v_mul_f32_e32 v220, v128, v128
	v_fmac_f32_e32 v220, v129, v129
	v_fmac_f32_e32 v220, v130, v130
	v_fmac_f32_e32 v220, v131, v131
	v_fmac_f32_e32 v220, v132, v132
	v_fmac_f32_e32 v220, v133, v133
	v_fmac_f32_e32 v220, v134, v134
	v_fmac_f32_e32 v220, v135, v135
	v_pk_add_f32 v[136:137], v[52:53], v[136:137]
	v_pk_add_f32 v[138:139], v[54:55], v[138:139]
	v_pk_add_f32 v[140:141], v[48:49], v[140:141]
	v_pk_add_f32 v[142:143], v[50:51], v[142:143]
	global_store_dwordx4 v[216:217], v[136:139], off offset:512
	global_store_dwordx4 v[216:217], v[140:143], off offset:528
	v_cvt_pk_bf16_f32 v228, v136, v137
	v_cvt_pk_bf16_f32 v229, v138, v139
	v_cvt_pk_bf16_f32 v230, v140, v141
	v_cvt_pk_bf16_f32 v231, v142, v143
	global_store_dwordx4 v[218:219], v[228:231], off offset:256
	v_fmac_f32_e32 v220, v136, v136
	v_fmac_f32_e32 v220, v137, v137
	v_fmac_f32_e32 v220, v138, v138
	v_fmac_f32_e32 v220, v139, v139
	v_fmac_f32_e32 v220, v140, v140
	v_fmac_f32_e32 v220, v141, v141
	v_fmac_f32_e32 v220, v142, v142
	v_fmac_f32_e32 v220, v143, v143
	s_mov_b32 s84, 0x90000
	v_lshl_add_u64 v[216:217], s[84:85], 0, v[210:211]
	s_mov_b32 s88, 0x48000
	v_lshl_add_u64 v[218:219], s[88:89], 0, v[212:213]
	v_pk_add_f32 v[144:145], v[44:45], v[144:145]
	v_pk_add_f32 v[146:147], v[46:47], v[146:147]
	v_pk_add_f32 v[148:149], v[40:41], v[148:149]
	v_pk_add_f32 v[150:151], v[42:43], v[150:151]
	global_store_dwordx4 v[216:217], v[144:147], off
	global_store_dwordx4 v[216:217], v[148:151], off offset:16
	v_cvt_pk_bf16_f32 v224, v144, v145
	v_cvt_pk_bf16_f32 v225, v146, v147
	v_cvt_pk_bf16_f32 v226, v148, v149
	v_cvt_pk_bf16_f32 v227, v150, v151
	global_store_dwordx4 v[218:219], v[224:227], off
	v_mul_f32_e32 v221, v144, v144
	v_fmac_f32_e32 v221, v145, v145
	v_fmac_f32_e32 v221, v146, v146
	v_fmac_f32_e32 v221, v147, v147
	v_fmac_f32_e32 v221, v148, v148
	v_fmac_f32_e32 v221, v149, v149
	v_fmac_f32_e32 v221, v150, v150
	v_fmac_f32_e32 v221, v151, v151
	v_pk_add_f32 v[152:153], v[36:37], v[152:153]
	v_pk_add_f32 v[154:155], v[38:39], v[154:155]
	v_pk_add_f32 v[156:157], v[32:33], v[156:157]
	v_pk_add_f32 v[158:159], v[34:35], v[158:159]
	global_store_dwordx4 v[216:217], v[152:155], off offset:512
	global_store_dwordx4 v[216:217], v[156:159], off offset:528
	v_cvt_pk_bf16_f32 v228, v152, v153
	v_cvt_pk_bf16_f32 v229, v154, v155
	v_cvt_pk_bf16_f32 v230, v156, v157
	v_cvt_pk_bf16_f32 v231, v158, v159
	global_store_dwordx4 v[218:219], v[228:231], off offset:256
	v_fmac_f32_e32 v221, v152, v152
	v_fmac_f32_e32 v221, v153, v153
	v_fmac_f32_e32 v221, v154, v154
	v_fmac_f32_e32 v221, v155, v155
	v_fmac_f32_e32 v221, v156, v156
	v_fmac_f32_e32 v221, v157, v157
	v_fmac_f32_e32 v221, v158, v158
	v_fmac_f32_e32 v221, v159, v159
	s_mov_b32 s84, 0xa0000
	v_lshl_add_u64 v[216:217], s[84:85], 0, v[210:211]
	s_mov_b32 s88, 0x50000
	v_lshl_add_u64 v[218:219], s[88:89], 0, v[212:213]
	v_pk_add_f32 v[178:179], v[28:29], v[178:179]
	v_pk_add_f32 v[180:181], v[30:31], v[180:181]
	v_pk_add_f32 v[182:183], v[24:25], v[182:183]
	v_pk_add_f32 v[184:185], v[26:27], v[184:185]
	global_store_dwordx4 v[216:217], v[178:181], off
	global_store_dwordx4 v[216:217], v[182:185], off offset:16
	v_cvt_pk_bf16_f32 v224, v178, v179
	v_cvt_pk_bf16_f32 v225, v180, v181
	v_cvt_pk_bf16_f32 v226, v182, v183
	v_cvt_pk_bf16_f32 v227, v184, v185
	global_store_dwordx4 v[218:219], v[224:227], off
	v_mul_f32_e32 v222, v178, v178
	v_fmac_f32_e32 v222, v179, v179
	v_fmac_f32_e32 v222, v180, v180
	v_fmac_f32_e32 v222, v181, v181
	v_fmac_f32_e32 v222, v182, v182
	v_fmac_f32_e32 v222, v183, v183
	v_fmac_f32_e32 v222, v184, v184
	v_fmac_f32_e32 v222, v185, v185
	v_pk_add_f32 v[186:187], v[20:21], v[186:187]
	v_pk_add_f32 v[188:189], v[22:23], v[188:189]
	v_pk_add_f32 v[190:191], v[16:17], v[190:191]
	v_pk_add_f32 v[192:193], v[18:19], v[192:193]
	global_store_dwordx4 v[216:217], v[186:189], off offset:512
	global_store_dwordx4 v[216:217], v[190:193], off offset:528
	v_cvt_pk_bf16_f32 v228, v186, v187
	v_cvt_pk_bf16_f32 v229, v188, v189
	v_cvt_pk_bf16_f32 v230, v190, v191
	v_cvt_pk_bf16_f32 v231, v192, v193
	global_store_dwordx4 v[218:219], v[228:231], off offset:256
	v_fmac_f32_e32 v222, v186, v186
	v_fmac_f32_e32 v222, v187, v187
	v_fmac_f32_e32 v222, v188, v188
	v_fmac_f32_e32 v222, v189, v189
	v_fmac_f32_e32 v222, v190, v190
	v_fmac_f32_e32 v222, v191, v191
	v_fmac_f32_e32 v222, v192, v192
	v_fmac_f32_e32 v222, v193, v193
	s_mov_b32 s84, 0xb0000
	v_lshl_add_u64 v[216:217], s[84:85], 0, v[210:211]
	s_mov_b32 s88, 0x58000
	v_lshl_add_u64 v[218:219], s[88:89], 0, v[212:213]
	v_pk_add_f32 v[194:195], v[12:13], v[194:195]
	v_pk_add_f32 v[196:197], v[14:15], v[196:197]
	v_pk_add_f32 v[198:199], v[8:9], v[198:199]
	v_pk_add_f32 v[200:201], v[10:11], v[200:201]
	global_store_dwordx4 v[216:217], v[194:197], off
	global_store_dwordx4 v[216:217], v[198:201], off offset:16
	v_cvt_pk_bf16_f32 v224, v194, v195
	v_cvt_pk_bf16_f32 v225, v196, v197
	v_cvt_pk_bf16_f32 v226, v198, v199
	v_cvt_pk_bf16_f32 v227, v200, v201
	global_store_dwordx4 v[218:219], v[224:227], off
	v_mul_f32_e32 v223, v194, v194
	v_fmac_f32_e32 v223, v195, v195
	v_fmac_f32_e32 v223, v196, v196
	v_fmac_f32_e32 v223, v197, v197
	v_fmac_f32_e32 v223, v198, v198
	v_fmac_f32_e32 v223, v199, v199
	v_fmac_f32_e32 v223, v200, v200
	v_fmac_f32_e32 v223, v201, v201
	v_pk_add_f32 v[202:203], v[4:5], v[202:203]
	v_pk_add_f32 v[204:205], v[6:7], v[204:205]
	v_pk_add_f32 v[206:207], v[0:1], v[206:207]
	v_pk_add_f32 v[208:209], v[2:3], v[208:209]
	global_store_dwordx4 v[216:217], v[202:205], off offset:512
	global_store_dwordx4 v[216:217], v[206:209], off offset:528
	v_cvt_pk_bf16_f32 v228, v202, v203
	v_cvt_pk_bf16_f32 v229, v204, v205
	v_cvt_pk_bf16_f32 v230, v206, v207
	v_cvt_pk_bf16_f32 v231, v208, v209
	global_store_dwordx4 v[218:219], v[228:231], off offset:256
	v_fmac_f32_e32 v223, v202, v202
	v_fmac_f32_e32 v223, v203, v203
	v_fmac_f32_e32 v223, v204, v204
	v_fmac_f32_e32 v223, v205, v205
	v_fmac_f32_e32 v223, v206, v206
	v_fmac_f32_e32 v223, v207, v207
	v_fmac_f32_e32 v223, v208, v208
	v_fmac_f32_e32 v223, v209, v209
	ds_bpermute_b32 v224, v171, v220
	ds_bpermute_b32 v225, v171, v221
	ds_bpermute_b32 v226, v171, v222
	ds_bpermute_b32 v227, v171, v223
	s_waitcnt lgkmcnt(0)
	v_add_f32_e32 v220, v220, v224
	v_add_f32_e32 v221, v221, v225
	v_add_f32_e32 v222, v222, v226
	v_add_f32_e32 v223, v223, v227
	ds_bpermute_b32 v224, v172, v220
	ds_bpermute_b32 v225, v172, v221
	ds_bpermute_b32 v226, v172, v222
	ds_bpermute_b32 v227, v172, v223
	s_waitcnt lgkmcnt(0)
	v_add_f32_e32 v220, v220, v224
	v_add_f32_e32 v221, v221, v225
	v_add_f32_e32 v222, v222, v226
	v_add_f32_e32 v223, v223, v227
	s_and_saveexec_b64 s[90:91], s[86:87]
	global_atomic_add_f32 v[214:215], v220, off offset:512
	global_atomic_add_f32 v[214:215], v221, off offset:576
	global_atomic_add_f32 v[214:215], v222, off offset:640
	global_atomic_add_f32 v[214:215], v223, off offset:704
	s_mov_b64 exec, s[90:91]

.LBB0_1421:
	s_and_b32 s80, s33, 64
	s_cmp_lg_u32 s80, 0
	s_cbranch_scc1 .Lpostf_skip
	v_and_b32_e32 v160, 15, v174
	v_bfe_u32 v161, v174, 4, 2
	v_lshrrev_b32_e32 v162, 6, v174
	v_and_b32_e32 v136, 63, v174
	v_readfirstlane_b32 s80, v162
	s_lshr_b32 s81, s33, 8
	s_lshr_b32 s82, s33, 3
	s_and_b32 s82, s82, 31
	s_mul_i32 s83, s80, 128
	v_lshlrev_b32_e32 v164, 4, v161
	v_mov_b32_e32 v167, 0
	s_lshl_b32 s84, s82, 5
	v_add_u32_e32 v165, s84, v160
	v_mul_u32_u24_e32 v166, 0x400, v165
	v_add3_u32 v166, v166, v164, s83
	s_add_u32 s86, s74, 0x4f00000
	s_addc_u32 s87, s75, 0
	s_mov_b32 s88, 0x4000
	s_mov_b32 s89, 0
	v_lshl_add_u64 v[152:153], s[86:87], 0, v[166:167]
	v_lshl_add_u64 v[154:155], v[152:153], 0, s[88:89]
	s_lshl_b32 s84, s81, 5
	v_add_u32_e32 v165, s84, v160
	v_mul_u32_u24_e32 v166, 0x400, v165
	v_add3_u32 v166, v166, v164, s83
	s_add_u32 s90, s74, 0x3d16bc00
	s_addc_u32 s91, s75, 0
	v_lshl_add_u64 v[156:157], s[90:91], 0, v[166:167]
	v_lshl_add_u64 v[158:159], v[156:157], 0, s[88:89]
	v_mov_b32_e32 v128, 0
	v_mov_b32_e32 v129, 0
	v_mov_b32_e32 v130, 0
	v_mov_b32_e32 v131, 0
	v_mov_b32_e32 v132, 0
	v_mov_b32_e32 v133, 0
	v_mov_b32_e32 v134, 0
	v_mov_b32_e32 v135, 0
	v_mov_b32_e32 v144, 0
	v_mov_b32_e32 v145, 0
	v_mov_b32_e32 v146, 0
	v_mov_b32_e32 v147, 0
	v_mov_b32_e32 v148, 0
	v_mov_b32_e32 v149, 0
	v_mov_b32_e32 v150, 0
	v_mov_b32_e32 v151, 0
	global_load_dwordx4 v[0:3], v[152:153], off
	global_load_dwordx4 v[4:7], v[154:155], off
	global_load_dwordx4 v[8:11], v[156:157], off
	global_load_dwordx4 v[12:15], v[158:159], off
	global_load_dwordx4 v[16:19], v[152:153], off offset:64
	global_load_dwordx4 v[20:23], v[154:155], off offset:64
	global_load_dwordx4 v[24:27], v[156:157], off offset:64
	global_load_dwordx4 v[28:31], v[158:159], off offset:64
	s_waitcnt vmcnt(0)
	v_mfma_f32_16x16x32_bf16 v[128:131], v[0:3], v[8:11], v[128:131]
	v_mfma_f32_16x16x32_bf16 v[132:135], v[4:7], v[8:11], v[132:135]
	v_mfma_f32_16x16x32_bf16 v[144:147], v[0:3], v[12:15], v[144:147]
	v_mfma_f32_16x16x32_bf16 v[148:151], v[4:7], v[12:15], v[148:151]
	v_mfma_f32_16x16x32_bf16 v[128:131], v[16:19], v[24:27], v[128:131]
	v_mfma_f32_16x16x32_bf16 v[132:135], v[20:23], v[24:27], v[132:135]
	v_mfma_f32_16x16x32_bf16 v[144:147], v[16:19], v[28:31], v[144:147]
	v_mfma_f32_16x16x32_bf16 v[148:151], v[20:23], v[28:31], v[148:151]
	s_nop 7
	s_nop 7
	v_lshlrev_b32_e32 v170, 12, v162
	v_lshl_add_u32 v170, v136, 4, v170
	ds_write_b128 v170, v[128:131]
	ds_write_b128 v170, v[132:135] offset:1024
	ds_write_b128 v170, v[144:147] offset:2048
	ds_write_b128 v170, v[148:151] offset:3072
	s_waitcnt lgkmcnt(0)
	s_barrier
	s_cmp_ge_u32 s80, 4
	s_cbranch_scc1 .Lmgf_end
	s_lshl_b32 s84, s80, 10
	v_lshlrev_b32_e32 v171, 4, v136
	v_add_u32_e32 v171, s84, v171
	ds_read_b128 v[0:3], v171
	ds_read_b128 v[4:7], v171 offset:4096
	ds_read_b128 v[8:11], v171 offset:8192
	ds_read_b128 v[12:15], v171 offset:12288
	ds_read_b128 v[16:19], v171 offset:16384
	ds_read_b128 v[20:23], v171 offset:20480
	ds_read_b128 v[24:27], v171 offset:24576
	ds_read_b128 v[28:31], v171 offset:28672
	s_lshr_b32 s84, s80, 1
	s_lshl_b32 s84, s84, 4
	s_lshl_b32 s85, s81, 5
	s_add_i32 s84, s84, s85
	s_addk_i32 s84, 0x4000
	s_and_b32 s85, s80, 1
	s_lshl_b32 s85, s85, 4
	s_lshl_b32 s83, s82, 5
	s_add_i32 s85, s85, s83
	v_add_u32_e32 v165, s84, v160
	v_lshl_add_u32 v164, v161, 2, s85
	v_lshlrev_b32_e32 v166, 12, v165
	v_lshl_add_u32 v166, v164, 2, v166
	v_mov_b32_e32 v167, 0
	s_add_u32 s86, s74, 0x5000000
	s_addc_u32 s87, s75, 0
	v_lshl_add_u64 v[168:169], s[86:87], 0, v[166:167]
	global_load_dwordx4 v[32:35], v[168:169], off
	v_lshrrev_b32_e32 v172, 1, v166
	v_mov_b32_e32 v173, 0
	s_add_u32 s86, s74, 0x9100000
	s_addc_u32 s87, s75, 0
	v_lshl_add_u64 v[172:173], s[86:87], 0, v[172:173]
	v_lshlrev_b32_e32 v166, 2, v165
	s_add_u32 s86, s74, 0x12bb1400
	s_addc_u32 s87, s75, 0
	v_lshl_add_u64 v[166:167], s[86:87], 0, v[166:167]
	s_waitcnt lgkmcnt(0)
	v_add_f32_e32 v0, v0, v4
	v_add_f32_e32 v1, v1, v5
	v_add_f32_e32 v2, v2, v6
	v_add_f32_e32 v3, v3, v7
	v_add_f32_e32 v0, v0, v8
	v_add_f32_e32 v1, v1, v9
	v_add_f32_e32 v2, v2, v10
	v_add_f32_e32 v3, v3, v11
	v_add_f32_e32 v0, v0, v12
	v_add_f32_e32 v1, v1, v13
	v_add_f32_e32 v2, v2, v14
	v_add_f32_e32 v3, v3, v15
	v_add_f32_e32 v0, v0, v16
	v_add_f32_e32 v1, v1, v17
	v_add_f32_e32 v2, v2, v18
	v_add_f32_e32 v3, v3, v19
	v_add_f32_e32 v0, v0, v20
	v_add_f32_e32 v1, v1, v21
	v_add_f32_e32 v2, v2, v22
	v_add_f32_e32 v3, v3, v23
	v_add_f32_e32 v0, v0, v24
	v_add_f32_e32 v1, v1, v25
	v_add_f32_e32 v2, v2, v26
	v_add_f32_e32 v3, v3, v27
	v_add_f32_e32 v0, v0, v28
	v_add_f32_e32 v1, v1, v29
	v_add_f32_e32 v2, v2, v30
	v_add_f32_e32 v3, v3, v31
	s_waitcnt vmcnt(0)
	v_fma_f32 v32, v0, 1.0, v32
	v_fma_f32 v33, v1, 1.0, v33
	v_fma_f32 v34, v2, 1.0, v34
	v_fma_f32 v35, v3, 1.0, v35
	global_store_dwordx4 v[168:169], v[32:35], off
	v_cvt_pk_bf16_f32 v36, v32, v33
	v_cvt_pk_bf16_f32 v37, v34, v35
	global_store_dwordx2 v[172:173], v[36:37], off
	v_mul_f32_e32 v38, v32, v32
	v_fmac_f32_e32 v38, v33, v33
	v_fmac_f32_e32 v38, v34, v34
	v_fmac_f32_e32 v38, v35, v35
	v_xor_b32_e32 v39, 16, v136
	v_lshlrev_b32_e32 v39, 2, v39
	ds_bpermute_b32 v40, v39, v38
	v_xor_b32_e32 v41, 32, v136
	v_lshlrev_b32_e32 v41, 2, v41
	s_waitcnt lgkmcnt(0)
	v_add_f32_e32 v38, v38, v40
	ds_bpermute_b32 v40, v41, v38
	s_waitcnt lgkmcnt(0)
	v_add_f32_e32 v38, v38, v40
	v_cmp_gt_u32_e64 s[82:83], 16, v136
	s_nop 1
	s_and_saveexec_b64 s[84:85], s[82:83]
	global_atomic_add_f32 v[166:167], v38, off
	s_mov_b64 exec, s[84:85]
.Lmgf_end:
	v_lshrrev_b32_e32 v21, 6, v174
	v_and_b32_e32 v22, 63, v174
	v_lshlrev_b32_e32 v22, 4, v22
	v_readfirstlane_b32 s80, v21
	v_add_u32_e32 v23, 0x1000, v22
	v_readfirstlane_b32 s92, v235
	v_readfirstlane_b32 s93, v236
	v_readfirstlane_b32 s94, v237
	v_readfirstlane_b32 s95, v238
	v_readfirstlane_b32 s98, v239
	v_readfirstlane_b32 s99, v240
	s_lshr_b32 s100, s33, 7
	s_lshl_b32 s100, s100, 3
	s_lshr_b32 s101, s33, 3
	s_and_b32 s101, s101, 7
	s_add_i32 s100, s100, s101
	s_lshl_b32 s100, s100, 3
	s_add_i32 s80, s80, s100
	s_add_i32 s80, s80, 0x1316e
	s_movk_i32 s100, 0x400

.Lcpyf_end:
.Lpostf_skip:
	s_waitcnt vmcnt(0)
	s_waitcnt lgkmcnt(0)
	s_barrier
	s_and_saveexec_b64 s[8:9], s[0:1]
	s_cbranch_execz .LBB0_1441
	v_rcp_iflag_f32_e32 v0, v176
	s_sub_i32 s3, 0, s78
	s_mov_b64 s[10:11], exec
	buffer_wbl2 sc1
	s_waitcnt vmcnt(0)
	v_mul_f32_e32 v0, 0x4f7ffffe, v0
	v_cvt_u32_f32_e32 v0, v0
	s_waitcnt vmcnt(0)
	v_mbcnt_lo_u32_b32 v1, s10, 0
	s_mul_i32 s4, s78, 13
	v_readfirstlane_b32 s5, v0
	s_mul_i32 s3, s3, s5
	s_mul_hi_u32 s3, s5, s3
	s_add_i32 s5, s5, s3
	v_mbcnt_hi_u32_b32 v0, s11, v1
	s_mul_hi_u32 s3, s4, s5
	v_cmp_eq_u32_e32 vcc, 0, v0
	s_and_saveexec_b64 s[14:15], vcc
	s_cbranch_execz .LBB0_1424
	s_bcnt1_i32_b64 s5, s[10:11]
	v_mov_b32_e32 v1, 0
	v_mov_b32_e32 v2, s5
	global_atomic_add v1, v1, v2, s[96:97] sc0

.LBB0_1481:
	s_or_b64 exec, exec, s[6:7]
	v_readlane_b32 s4, v234, 2
	v_mov_b32_e32 v8, v174
	v_readlane_b32 s5, v234, 3
	s_barrier
	s_and_b32 s80, s33, 64
	s_cmp_eq_u32 s80, 0
	s_cbranch_scc1 .Lpre4_skip
	v_lshrrev_b32_e32 v21, 6, v174
	v_and_b32_e32 v22, 63, v174
	v_lshlrev_b32_e32 v22, 4, v22
	v_readfirstlane_b32 s80, v21
	v_add_u32_e32 v23, 0x1000, v22
	v_readfirstlane_b32 s92, v235
	v_readfirstlane_b32 s93, v236
	v_readfirstlane_b32 s94, v237
	v_readfirstlane_b32 s95, v238
	v_readfirstlane_b32 s98, v239
	v_readfirstlane_b32 s99, v240
	s_lshr_b32 s100, s33, 7
	s_lshl_b32 s100, s100, 3
	s_lshr_b32 s101, s33, 3
	s_and_b32 s101, s101, 7
	s_add_i32 s100, s100, s101
	s_lshl_b32 s100, s100, 3
	s_add_i32 s80, s80, s100
	s_add_i32 s80, s80, 0x15590
	s_movk_i32 s100, 0x400
.Lcpy4p_loop:
	s_add_i32 s101, s80, s100
	s_cmp_lt_u32 s101, 0x17444
	s_cbranch_scc0 .Lcpy4p_tail
	s_mul_hi_u32 s81, s80, 0x2ad5802b
	s_lshr_b32 s81, s81, 8
	s_mul_i32 s82, s81, 0x5fa
	s_sub_i32 s82, s80, s82
	s_lshl_b32 s82, s82, 13
	s_and_b32 s83, s81, 31
	s_mul_i32 s83, s83, 0xc00000
	s_add_i32 s82, s82, s83
	s_cmp_lt_u32 s81, 32
	s_cselect_b32 s84, s92, s94
	s_cselect_b32 s85, s93, s95
	s_mov_b32 s83, 0x1f210000
	s_cselect_b32 s83, 0x7210000, s83
	s_add_u32 s84, s84, s82
	s_addc_u32 s85, s85, 0
	s_add_u32 s84, s84, 0xc000
	s_addc_u32 s85, s85, 0
	s_add_u32 s83, s83, s82
	s_add_u32 s86, s98, s83
	s_addc_u32 s87, s99, 0
	s_mul_hi_u32 s81, s101, 0x2ad5802b
	s_lshr_b32 s81, s81, 8
	s_mul_i32 s82, s81, 0x5fa
	s_sub_i32 s82, s101, s82
	s_lshl_b32 s82, s82, 13
	s_and_b32 s83, s81, 31
	s_mul_i32 s83, s83, 0xc00000
	s_add_i32 s82, s82, s83
	s_cmp_lt_u32 s81, 32
	s_cselect_b32 s88, s92, s94
	s_cselect_b32 s89, s93, s95
	s_mov_b32 s83, 0x1f210000
	s_cselect_b32 s83, 0x7210000, s83
	s_add_u32 s88, s88, s82
	s_addc_u32 s89, s89, 0
	s_add_u32 s88, s88, 0xc000
	s_addc_u32 s89, s89, 0
	s_add_u32 s83, s83, s82
	s_add_u32 s90, s98, s83
	s_addc_u32 s91, s99, 0
	global_load_dwordx4 v[64:67], v22, s[84:85] nt
	global_load_dwordx4 v[68:71], v22, s[84:85] offset:1024 nt
	global_load_dwordx4 v[72:75], v22, s[84:85] offset:2048 nt
	global_load_dwordx4 v[76:79], v22, s[84:85] offset:3072 nt
	global_load_dwordx4 v[80:83], v23, s[84:85] nt
	global_load_dwordx4 v[84:87], v23, s[84:85] offset:1024 nt
	global_load_dwordx4 v[88:91], v23, s[84:85] offset:2048 nt
	global_load_dwordx4 v[92:95], v23, s[84:85] offset:3072 nt
	global_load_dwordx4 v[96:99], v22, s[88:89] nt
	global_load_dwordx4 v[100:103], v22, s[88:89] offset:1024 nt
	global_load_dwordx4 v[104:107], v22, s[88:89] offset:2048 nt
	global_load_dwordx4 v[108:111], v22, s[88:89] offset:3072 nt
	global_load_dwordx4 v[112:115], v23, s[88:89] nt
	global_load_dwordx4 v[116:119], v23, s[88:89] offset:1024 nt
	global_load_dwordx4 v[120:123], v23, s[88:89] offset:2048 nt
	global_load_dwordx4 v[124:127], v23, s[88:89] offset:3072 nt
	s_waitcnt vmcnt(15)
	global_store_dwordx4 v22, v[64:67], s[86:87] nt
	s_waitcnt vmcnt(15)
	global_store_dwordx4 v22, v[68:71], s[86:87] offset:1024 nt
	s_waitcnt vmcnt(15)
	global_store_dwordx4 v22, v[72:75], s[86:87] offset:2048 nt
	s_waitcnt vmcnt(15)
	global_store_dwordx4 v22, v[76:79], s[86:87] offset:3072 nt
	s_waitcnt vmcnt(15)
	global_store_dwordx4 v23, v[80:83], s[86:87] nt
	s_waitcnt vmcnt(15)
	global_store_dwordx4 v23, v[84:87], s[86:87] offset:1024 nt
	s_waitcnt vmcnt(15)
	global_store_dwordx4 v23, v[88:91], s[86:87] offset:2048 nt
	s_waitcnt vmcnt(15)
	global_store_dwordx4 v23, v[92:95], s[86:87] offset:3072 nt
	s_waitcnt vmcnt(15)
	global_store_dwordx4 v22, v[96:99], s[90:91] nt
	s_waitcnt vmcnt(15)
	global_store_dwordx4 v22, v[100:103], s[90:91] offset:1024 nt
	s_waitcnt vmcnt(15)
	global_store_dwordx4 v22, v[104:107], s[90:91] offset:2048 nt
	s_waitcnt vmcnt(15)
	global_store_dwordx4 v22, v[108:111], s[90:91] offset:3072 nt
	s_waitcnt vmcnt(15)
	global_store_dwordx4 v23, v[112:115], s[90:91] nt
	s_waitcnt vmcnt(15)
	global_store_dwordx4 v23, v[116:119], s[90:91] offset:1024 nt
	s_waitcnt vmcnt(15)
	global_store_dwordx4 v23, v[120:123], s[90:91] offset:2048 nt
	s_waitcnt vmcnt(15)
	global_store_dwordx4 v23, v[124:127], s[90:91] offset:3072 nt
	s_add_i32 s80, s101, s100
	s_branch .Lcpy4p_loop
.Lcpy4p_tail:
	s_cmp_lt_u32 s80, 0x17444
	s_cbranch_scc0 .Lcpy4p_end
	s_mul_hi_u32 s81, s80, 0x2ad5802b
	s_lshr_b32 s81, s81, 8
	s_mul_i32 s82, s81, 0x5fa
	s_sub_i32 s82, s80, s82
	s_lshl_b32 s82, s82, 13
	s_and_b32 s83, s81, 31
	s_mul_i32 s83, s83, 0xc00000
	s_add_i32 s82, s82, s83
	s_cmp_lt_u32 s81, 32
	s_cselect_b32 s84, s92, s94
	s_cselect_b32 s85, s93, s95
	s_mov_b32 s83, 0x1f210000
	s_cselect_b32 s83, 0x7210000, s83
	s_add_u32 s84, s84, s82
	s_addc_u32 s85, s85, 0
	s_add_u32 s84, s84, 0xc000
	s_addc_u32 s85, s85, 0
	s_add_u32 s83, s83, s82
	s_add_u32 s86, s98, s83
	s_addc_u32 s87, s99, 0
	global_load_dwordx4 v[64:67], v22, s[84:85] nt
	global_load_dwordx4 v[68:71], v22, s[84:85] offset:1024 nt
	global_load_dwordx4 v[72:75], v22, s[84:85] offset:2048 nt
	global_load_dwordx4 v[76:79], v22, s[84:85] offset:3072 nt
	global_load_dwordx4 v[80:83], v23, s[84:85] nt
	global_load_dwordx4 v[84:87], v23, s[84:85] offset:1024 nt
	global_load_dwordx4 v[88:91], v23, s[84:85] offset:2048 nt
	global_load_dwordx4 v[92:95], v23, s[84:85] offset:3072 nt
	s_waitcnt vmcnt(7)
	global_store_dwordx4 v22, v[64:67], s[86:87] nt
	s_waitcnt vmcnt(7)
	global_store_dwordx4 v22, v[68:71], s[86:87] offset:1024 nt
	s_waitcnt vmcnt(7)
	global_store_dwordx4 v22, v[72:75], s[86:87] offset:2048 nt
	s_waitcnt vmcnt(7)
	global_store_dwordx4 v22, v[76:79], s[86:87] offset:3072 nt
	s_waitcnt vmcnt(7)
	global_store_dwordx4 v23, v[80:83], s[86:87] nt
	s_waitcnt vmcnt(7)
	global_store_dwordx4 v23, v[84:87], s[86:87] offset:1024 nt
	s_waitcnt vmcnt(7)
	global_store_dwordx4 v23, v[88:91], s[86:87] offset:2048 nt
	s_waitcnt vmcnt(7)
	global_store_dwordx4 v23, v[92:95], s[86:87] offset:3072 nt
.Lcpy4p_end:
	v_and_b32_e32 v160, 15, v174
	v_bfe_u32 v161, v174, 4, 2
	v_lshrrev_b32_e32 v162, 6, v174
	v_and_b32_e32 v136, 63, v174
	v_readfirstlane_b32 s80, v162
	s_lshr_b32 s81, s33, 8
	s_lshr_b32 s82, s33, 3
	s_and_b32 s82, s82, 31
	s_mul_i32 s83, s80, 704
	v_lshlrev_b32_e32 v164, 4, v161
	v_mov_b32_e32 v167, 0
	s_lshl_b32 s84, s82, 5
	v_add_u32_e32 v165, s84, v160
	v_mul_u32_u24_e32 v166, 0x1600, v165
	v_add3_u32 v166, v166, v164, s83
	s_add_u32 s86, s74, 0x3c80000
	s_addc_u32 s87, s75, 0
	s_mov_b32 s88, 0x16000
	s_mov_b32 s89, 0
	v_lshl_add_u64 v[152:153], s[86:87], 0, v[166:167]
	v_lshl_add_u64 v[154:155], v[152:153], 0, s[88:89]
	s_lshl_b32 s84, s81, 5
	v_add_u32_e32 v165, s84, v160
	v_mul_u32_u24_e32 v166, 0x1600, v165
	v_add3_u32 v166, v166, v164, s83
	s_add_u32 s90, s74, 0x10980000
	s_addc_u32 s91, s75, 0
	v_lshl_add_u64 v[156:157], s[90:91], 0, v[166:167]
	v_lshl_add_u64 v[158:159], v[156:157], 0, s[88:89]
	v_mov_b32_e32 v128, 0
	v_mov_b32_e32 v129, 0
	v_mov_b32_e32 v130, 0
	v_mov_b32_e32 v131, 0
	v_mov_b32_e32 v132, 0
	v_mov_b32_e32 v133, 0
	v_mov_b32_e32 v134, 0
	v_mov_b32_e32 v135, 0
	v_mov_b32_e32 v144, 0
	v_mov_b32_e32 v145, 0
	v_mov_b32_e32 v146, 0
	v_mov_b32_e32 v147, 0
	v_mov_b32_e32 v148, 0
	v_mov_b32_e32 v149, 0
	v_mov_b32_e32 v150, 0
	v_mov_b32_e32 v151, 0
	global_load_dwordx4 v[0:3], v[152:153], off
	global_load_dwordx4 v[4:7], v[154:155], off
	global_load_dwordx4 v[8:11], v[156:157], off
	global_load_dwordx4 v[12:15], v[158:159], off
	global_load_dwordx4 v[16:19], v[152:153], off offset:64
	global_load_dwordx4 v[20:23], v[154:155], off offset:64
	global_load_dwordx4 v[24:27], v[156:157], off offset:64
	global_load_dwordx4 v[28:31], v[158:159], off offset:64
	global_load_dwordx4 v[32:35], v[152:153], off offset:128
	global_load_dwordx4 v[36:39], v[154:155], off offset:128
	global_load_dwordx4 v[40:43], v[156:157], off offset:128
	global_load_dwordx4 v[44:47], v[158:159], off offset:128
	global_load_dwordx4 v[48:51], v[152:153], off offset:192
	global_load_dwordx4 v[52:55], v[154:155], off offset:192
	global_load_dwordx4 v[56:59], v[156:157], off offset:192
	global_load_dwordx4 v[60:63], v[158:159], off offset:192
	global_load_dwordx4 v[64:67], v[152:153], off offset:256
	global_load_dwordx4 v[68:71], v[154:155], off offset:256
	global_load_dwordx4 v[72:75], v[156:157], off offset:256
	global_load_dwordx4 v[76:79], v[158:159], off offset:256
	global_load_dwordx4 v[80:83], v[152:153], off offset:320
	global_load_dwordx4 v[84:87], v[154:155], off offset:320
	global_load_dwordx4 v[88:91], v[156:157], off offset:320
	global_load_dwordx4 v[92:95], v[158:159], off offset:320
	global_load_dwordx4 v[96:99], v[152:153], off offset:384
	global_load_dwordx4 v[100:103], v[154:155], off offset:384
	global_load_dwordx4 v[104:107], v[156:157], off offset:384
	global_load_dwordx4 v[108:111], v[158:159], off offset:384
	global_load_dwordx4 v[112:115], v[152:153], off offset:448
	global_load_dwordx4 v[116:119], v[154:155], off offset:448
	global_load_dwordx4 v[120:123], v[156:157], off offset:448
	global_load_dwordx4 v[124:127], v[158:159], off offset:448
	s_waitcnt vmcnt(16)
	v_mfma_f32_16x16x32_bf16 v[128:131], v[0:3], v[8:11], v[128:131]
	v_mfma_f32_16x16x32_bf16 v[132:135], v[4:7], v[8:11], v[132:135]
	v_mfma_f32_16x16x32_bf16 v[144:147], v[0:3], v[12:15], v[144:147]
	v_mfma_f32_16x16x32_bf16 v[148:151], v[4:7], v[12:15], v[148:151]
	v_mfma_f32_16x16x32_bf16 v[128:131], v[16:19], v[24:27], v[128:131]
	v_mfma_f32_16x16x32_bf16 v[132:135], v[20:23], v[24:27], v[132:135]
	v_mfma_f32_16x16x32_bf16 v[144:147], v[16:19], v[28:31], v[144:147]
	v_mfma_f32_16x16x32_bf16 v[148:151], v[20:23], v[28:31], v[148:151]
	v_mfma_f32_16x16x32_bf16 v[128:131], v[32:35], v[40:43], v[128:131]
	v_mfma_f32_16x16x32_bf16 v[132:135], v[36:39], v[40:43], v[132:135]
	v_mfma_f32_16x16x32_bf16 v[144:147], v[32:35], v[44:47], v[144:147]
	v_mfma_f32_16x16x32_bf16 v[148:151], v[36:39], v[44:47], v[148:151]
	v_mfma_f32_16x16x32_bf16 v[128:131], v[48:51], v[56:59], v[128:131]
	v_mfma_f32_16x16x32_bf16 v[132:135], v[52:55], v[56:59], v[132:135]
	v_mfma_f32_16x16x32_bf16 v[144:147], v[48:51], v[60:63], v[144:147]
	v_mfma_f32_16x16x32_bf16 v[148:151], v[52:55], v[60:63], v[148:151]
	global_load_dwordx4 v[0:3], v[152:153], off offset:512
	global_load_dwordx4 v[4:7], v[154:155], off offset:512
	global_load_dwordx4 v[8:11], v[156:157], off offset:512
	global_load_dwordx4 v[12:15], v[158:159], off offset:512
	global_load_dwordx4 v[16:19], v[152:153], off offset:576
	global_load_dwordx4 v[20:23], v[154:155], off offset:576
	global_load_dwordx4 v[24:27], v[156:157], off offset:576
	global_load_dwordx4 v[28:31], v[158:159], off offset:576
	global_load_dwordx4 v[32:35], v[152:153], off offset:640
	global_load_dwordx4 v[36:39], v[154:155], off offset:640
	global_load_dwordx4 v[40:43], v[156:157], off offset:640
	global_load_dwordx4 v[44:47], v[158:159], off offset:640
	s_waitcnt vmcnt(12)
	v_mfma_f32_16x16x32_bf16 v[128:131], v[64:67], v[72:75], v[128:131]
	v_mfma_f32_16x16x32_bf16 v[132:135], v[68:71], v[72:75], v[132:135]
	v_mfma_f32_16x16x32_bf16 v[144:147], v[64:67], v[76:79], v[144:147]
	v_mfma_f32_16x16x32_bf16 v[148:151], v[68:71], v[76:79], v[148:151]
	v_mfma_f32_16x16x32_bf16 v[128:131], v[80:83], v[88:91], v[128:131]
	v_mfma_f32_16x16x32_bf16 v[132:135], v[84:87], v[88:91], v[132:135]
	v_mfma_f32_16x16x32_bf16 v[144:147], v[80:83], v[92:95], v[144:147]
	v_mfma_f32_16x16x32_bf16 v[148:151], v[84:87], v[92:95], v[148:151]
	v_mfma_f32_16x16x32_bf16 v[128:131], v[96:99], v[104:107], v[128:131]
	v_mfma_f32_16x16x32_bf16 v[132:135], v[100:103], v[104:107], v[132:135]
	v_mfma_f32_16x16x32_bf16 v[144:147], v[96:99], v[108:111], v[144:147]
	v_mfma_f32_16x16x32_bf16 v[148:151], v[100:103], v[108:111], v[148:151]
	v_mfma_f32_16x16x32_bf16 v[128:131], v[112:115], v[120:123], v[128:131]
	v_mfma_f32_16x16x32_bf16 v[132:135], v[116:119], v[120:123], v[132:135]
	v_mfma_f32_16x16x32_bf16 v[144:147], v[112:115], v[124:127], v[144:147]
	v_mfma_f32_16x16x32_bf16 v[148:151], v[116:119], v[124:127], v[148:151]
	s_waitcnt vmcnt(0)
	v_mfma_f32_16x16x32_bf16 v[128:131], v[0:3], v[8:11], v[128:131]
	v_mfma_f32_16x16x32_bf16 v[132:135], v[4:7], v[8:11], v[132:135]
	v_mfma_f32_16x16x32_bf16 v[144:147], v[0:3], v[12:15], v[144:147]
	v_mfma_f32_16x16x32_bf16 v[148:151], v[4:7], v[12:15], v[148:151]
	v_mfma_f32_16x16x32_bf16 v[128:131], v[16:19], v[24:27], v[128:131]
	v_mfma_f32_16x16x32_bf16 v[132:135], v[20:23], v[24:27], v[132:135]
	v_mfma_f32_16x16x32_bf16 v[144:147], v[16:19], v[28:31], v[144:147]
	v_mfma_f32_16x16x32_bf16 v[148:151], v[20:23], v[28:31], v[148:151]
	v_mfma_f32_16x16x32_bf16 v[128:131], v[32:35], v[40:43], v[128:131]
	v_mfma_f32_16x16x32_bf16 v[132:135], v[36:39], v[40:43], v[132:135]
	v_mfma_f32_16x16x32_bf16 v[144:147], v[32:35], v[44:47], v[144:147]
	v_mfma_f32_16x16x32_bf16 v[148:151], v[36:39], v[44:47], v[148:151]
	s_nop 7
	s_nop 7
	v_lshlrev_b32_e32 v170, 12, v162
	v_lshl_add_u32 v170, v136, 4, v170
	ds_write_b128 v170, v[128:131]
	ds_write_b128 v170, v[132:135] offset:1024
	ds_write_b128 v170, v[144:147] offset:2048
	ds_write_b128 v170, v[148:151] offset:3072
	s_waitcnt lgkmcnt(0)
	s_barrier
	s_cmp_ge_u32 s80, 4
	s_cbranch_scc1 .Lmg4p_end
	s_lshl_b32 s84, s80, 10
	v_lshlrev_b32_e32 v171, 4, v136
	v_add_u32_e32 v171, s84, v171
	ds_read_b128 v[0:3], v171
	ds_read_b128 v[4:7], v171 offset:4096
	ds_read_b128 v[8:11], v171 offset:8192
	ds_read_b128 v[12:15], v171 offset:12288
	ds_read_b128 v[16:19], v171 offset:16384
	ds_read_b128 v[20:23], v171 offset:20480
	ds_read_b128 v[24:27], v171 offset:24576
	ds_read_b128 v[28:31], v171 offset:28672
	s_lshr_b32 s84, s80, 1
	s_lshl_b32 s84, s84, 4
	s_lshl_b32 s85, s81, 5
	s_add_i32 s84, s84, s85
	s_addk_i32 s84, 0x4000
	s_and_b32 s85, s80, 1
	s_lshl_b32 s85, s85, 4
	s_lshl_b32 s83, s82, 5
	s_add_i32 s85, s85, s83
	v_add_u32_e32 v165, s84, v160
	v_lshl_add_u32 v164, v161, 2, s85
	v_lshlrev_b32_e32 v166, 12, v165
	v_lshl_add_u32 v166, v164, 2, v166
	v_mov_b32_e32 v167, 0
	s_add_u32 s86, s74, 0x5000000
	s_addc_u32 s87, s75, 0
	v_lshl_add_u64 v[168:169], s[86:87], 0, v[166:167]
	global_load_dwordx4 v[32:35], v[168:169], off
	v_lshrrev_b32_e32 v172, 1, v166
	v_mov_b32_e32 v173, 0
	s_add_u32 s86, s74, 0x9100000
	s_addc_u32 s87, s75, 0
	v_lshl_add_u64 v[172:173], s[86:87], 0, v[172:173]
	v_lshlrev_b32_e32 v166, 2, v165
	s_add_u32 s86, s74, 0x12bc1800
	s_addc_u32 s87, s75, 0
	v_lshl_add_u64 v[166:167], s[86:87], 0, v[166:167]
	s_waitcnt lgkmcnt(0)
	v_add_f32_e32 v0, v0, v4
	v_add_f32_e32 v1, v1, v5
	v_add_f32_e32 v2, v2, v6
	v_add_f32_e32 v3, v3, v7
	v_add_f32_e32 v0, v0, v8
	v_add_f32_e32 v1, v1, v9
	v_add_f32_e32 v2, v2, v10
	v_add_f32_e32 v3, v3, v11
	v_add_f32_e32 v0, v0, v12
	v_add_f32_e32 v1, v1, v13
	v_add_f32_e32 v2, v2, v14
	v_add_f32_e32 v3, v3, v15
	v_add_f32_e32 v0, v0, v16
	v_add_f32_e32 v1, v1, v17
	v_add_f32_e32 v2, v2, v18
	v_add_f32_e32 v3, v3, v19
	v_add_f32_e32 v0, v0, v20
	v_add_f32_e32 v1, v1, v21
	v_add_f32_e32 v2, v2, v22
	v_add_f32_e32 v3, v3, v23
	v_add_f32_e32 v0, v0, v24
	v_add_f32_e32 v1, v1, v25
	v_add_f32_e32 v2, v2, v26
	v_add_f32_e32 v3, v3, v27
	v_add_f32_e32 v0, v0, v28
	v_add_f32_e32 v1, v1, v29
	v_add_f32_e32 v2, v2, v30
	v_add_f32_e32 v3, v3, v31
	s_waitcnt vmcnt(0)
	v_fma_f32 v32, v0, 0.5, v32
	v_fma_f32 v33, v1, 0.5, v33
	v_fma_f32 v34, v2, 0.5, v34
	v_fma_f32 v35, v3, 0.5, v35
	global_store_dwordx4 v[168:169], v[32:35], off
	v_cvt_pk_bf16_f32 v36, v32, v33
	v_cvt_pk_bf16_f32 v37, v34, v35
	v_mul_f32_e32 v38, v32, v32
	v_fmac_f32_e32 v38, v33, v33
	v_fmac_f32_e32 v38, v34, v34
	v_fmac_f32_e32 v38, v35, v35
	v_xor_b32_e32 v39, 16, v136
	v_lshlrev_b32_e32 v39, 2, v39
	ds_bpermute_b32 v40, v39, v38
	v_xor_b32_e32 v41, 32, v136
	v_lshlrev_b32_e32 v41, 2, v41
	s_waitcnt lgkmcnt(0)
	v_add_f32_e32 v38, v38, v40
	ds_bpermute_b32 v40, v41, v38
	s_waitcnt lgkmcnt(0)
	v_add_f32_e32 v38, v38, v40
	v_cmp_gt_u32_e64 s[82:83], 16, v136
	s_nop 1
	s_and_saveexec_b64 s[84:85], s[82:83]
	global_atomic_add_f32 v[166:167], v38, off
	s_mov_b64 exec, s[84:85]
.Lmg4p_end:
	s_barrier
.Lpre4_skip:
	v_mov_b32_e32 v8, v174
	s_and_b64 vcc, exec, s[4:5]
	v_readfirstlane_b32 s3, v8
	s_cbranch_vccnz .LBB0_1487
	s_ashr_i32 s4, s2, 31
	s_lshr_b32 s4, s4, 29
	s_add_i32 s5, s2, s4
	s_and_b32 s4, s5, -8
	s_sub_i32 s4, s2, s4
	s_cmp_gt_i32 s4, -1
	s_cbranch_scc0 .LBB0_1484
	s_lshl_b32 s6, s4, 5
	s_or_b32 s8, s6, 0
	s_ashr_i32 s5, s5, 3
	s_cbranch_execz .LBB0_1485
	s_branch .LBB0_1486

.LBB0_1503:
	ds_read_b128 v[144:147], v151
	ds_read_b128 v[156:159], v151 offset:1024
	ds_read_b128 v[160:163], v151 offset:2048
	ds_read_b128 v[164:167], v151 offset:3072
	s_add_u32 s20, s18, 0x100
	s_addc_u32 s21, s19, 0
	s_cmp_eq_u32 s53, 40
	s_cselect_b32 s25, s9, s21
	s_cselect_b32 s24, s8, s20
	s_cselect_b32 s23, s11, s52
	s_cselect_b32 s22, s10, s51
	v_lshl_add_u64 v[172:173], s[18:19], 0, v[136:137]
	s_add_i32 m0, s29, 0xc000
	ds_read_b128 v[168:171], v152
	ds_read_b128 v[178:181], v152 offset:1024
	ds_read_b128 v[182:185], v152 offset:2048
	ds_read_b128 v[186:189], v152 offset:3072
	ds_read_b128 v[190:193], v152 offset:4096
	ds_read_b128 v[194:197], v152 offset:5120
	ds_read_b128 v[198:201], v152 offset:6144
	ds_read_b128 v[202:205], v152 offset:7168
	global_load_lds_dwordx4 v[172:173], off
	v_lshl_add_u64 v[172:173], s[18:19], 0, v[138:139]
	s_add_i32 m0, s29, 0xe000
	s_nop 0
	global_load_lds_dwordx4 v[172:173], off
	s_waitcnt lgkmcnt(8)
	s_barrier
	s_waitcnt lgkmcnt(0)
	s_setprio 1
	s_waitcnt lgkmcnt(0)
	v_mfma_f32_16x16x32_bf16 v[124:127], v[144:147], v[168:171], v[124:127]
	v_mfma_f32_16x16x32_bf16 v[120:123], v[160:163], v[168:171], v[120:123]
	v_mfma_f32_16x16x32_bf16 v[108:111], v[144:147], v[182:185], v[108:111]
	v_mfma_f32_16x16x32_bf16 v[104:107], v[160:163], v[182:185], v[104:107]
	v_mfma_f32_16x16x32_bf16 v[92:95], v[144:147], v[190:193], v[92:95]
	v_mfma_f32_16x16x32_bf16 v[88:91], v[160:163], v[190:193], v[88:91]
	v_mfma_f32_16x16x32_bf16 v[76:79], v[144:147], v[198:201], v[76:79]
	v_mfma_f32_16x16x32_bf16 v[72:75], v[160:163], v[198:201], v[72:75]
	v_mfma_f32_16x16x32_bf16 v[124:127], v[156:159], v[178:181], v[124:127]
	v_mfma_f32_16x16x32_bf16 v[120:123], v[164:167], v[178:181], v[120:123]
	v_mfma_f32_16x16x32_bf16 v[108:111], v[156:159], v[186:189], v[108:111]
	v_mfma_f32_16x16x32_bf16 v[104:107], v[164:167], v[186:189], v[104:107]
	v_mfma_f32_16x16x32_bf16 v[92:95], v[156:159], v[194:197], v[92:95]
	v_mfma_f32_16x16x32_bf16 v[88:91], v[164:167], v[194:197], v[88:91]
	v_mfma_f32_16x16x32_bf16 v[76:79], v[156:159], v[202:205], v[76:79]
	v_mfma_f32_16x16x32_bf16 v[72:75], v[164:167], v[202:205], v[72:75]
	s_setprio 0
	s_barrier
	s_add_i32 s18, s43, s28
	v_lshl_add_u64 v[172:173], s[22:23], 0, v[130:131]
	s_mov_b32 m0, s18
	ds_read_b128 v[206:209], v153
	ds_read_b128 v[210:213], v153 offset:1024
	ds_read_b128 v[214:217], v153 offset:2048
	ds_read_b128 v[218:221], v153 offset:3072
	global_load_lds_dwordx4 v[172:173], off
	v_lshl_add_u64 v[222:223], s[22:23], 0, v[134:135]
	s_add_i32 m0, s18, 0x2000
	s_nop 0
	global_load_lds_dwordx4 v[222:223], off
	s_barrier
	s_waitcnt lgkmcnt(0)
	s_setprio 1
	s_waitcnt lgkmcnt(0)
	v_mfma_f32_16x16x32_bf16 v[116:119], v[206:209], v[168:171], v[116:119]
	v_mfma_f32_16x16x32_bf16 v[112:115], v[214:217], v[168:171], v[112:115]
	v_mfma_f32_16x16x32_bf16 v[100:103], v[206:209], v[182:185], v[100:103]
	v_mfma_f32_16x16x32_bf16 v[96:99], v[214:217], v[182:185], v[96:99]
	v_mfma_f32_16x16x32_bf16 v[84:87], v[206:209], v[190:193], v[84:87]
	v_mfma_f32_16x16x32_bf16 v[80:83], v[214:217], v[190:193], v[80:83]
	v_mfma_f32_16x16x32_bf16 v[68:71], v[206:209], v[198:201], v[68:71]
	v_mfma_f32_16x16x32_bf16 v[64:67], v[214:217], v[198:201], v[64:67]
	v_mfma_f32_16x16x32_bf16 v[116:119], v[210:213], v[178:181], v[116:119]
	v_mfma_f32_16x16x32_bf16 v[112:115], v[218:221], v[178:181], v[112:115]
	v_mfma_f32_16x16x32_bf16 v[100:103], v[210:213], v[186:189], v[100:103]
	v_mfma_f32_16x16x32_bf16 v[96:99], v[218:221], v[186:189], v[96:99]
	v_mfma_f32_16x16x32_bf16 v[84:87], v[210:213], v[194:197], v[84:87]
	v_mfma_f32_16x16x32_bf16 v[80:83], v[218:221], v[194:197], v[80:83]
	v_mfma_f32_16x16x32_bf16 v[68:71], v[210:213], v[202:205], v[68:71]
	v_mfma_f32_16x16x32_bf16 v[64:67], v[218:221], v[202:205], v[64:67]
	s_setprio 0
	s_mov_b32 m0, s29
	v_lshl_add_u64 v[224:225], s[24:25], 0, v[128:129]
	s_barrier
	ds_read_b128 v[168:171], v152 offset:16384
	ds_read_b128 v[178:181], v152 offset:17408
	ds_read_b128 v[182:185], v152 offset:18432
	ds_read_b128 v[186:189], v152 offset:19456
	ds_read_b128 v[190:193], v152 offset:20480
	ds_read_b128 v[194:197], v152 offset:21504
	ds_read_b128 v[198:201], v152 offset:22528
	ds_read_b128 v[202:205], v152 offset:23552
	global_load_lds_dwordx4 v[224:225], off
	v_lshl_add_u64 v[226:227], s[24:25], 0, v[132:133]
	s_mov_b32 m0, s30
	s_nop 0
	global_load_lds_dwordx4 v[226:227], off
	s_barrier
	s_waitcnt lgkmcnt(0)
	s_setprio 1
	s_waitcnt lgkmcnt(0)
	v_mfma_f32_16x16x32_bf16 v[60:63], v[144:147], v[168:171], v[60:63]
	v_mfma_f32_16x16x32_bf16 v[56:59], v[160:163], v[168:171], v[56:59]
	v_mfma_f32_16x16x32_bf16 v[44:47], v[144:147], v[182:185], v[44:47]
	v_mfma_f32_16x16x32_bf16 v[40:43], v[160:163], v[182:185], v[40:43]
	v_mfma_f32_16x16x32_bf16 v[28:31], v[144:147], v[190:193], v[28:31]
	v_mfma_f32_16x16x32_bf16 v[24:27], v[160:163], v[190:193], v[24:27]
	v_mfma_f32_16x16x32_bf16 v[12:15], v[144:147], v[198:201], v[12:15]
	v_mfma_f32_16x16x32_bf16 v[8:11], v[160:163], v[198:201], v[8:11]
	v_mfma_f32_16x16x32_bf16 v[60:63], v[156:159], v[178:181], v[60:63]
	v_mfma_f32_16x16x32_bf16 v[56:59], v[164:167], v[178:181], v[56:59]
	v_mfma_f32_16x16x32_bf16 v[44:47], v[156:159], v[186:189], v[44:47]
	v_mfma_f32_16x16x32_bf16 v[40:43], v[164:167], v[186:189], v[40:43]
	v_mfma_f32_16x16x32_bf16 v[28:31], v[156:159], v[194:197], v[28:31]
	v_mfma_f32_16x16x32_bf16 v[24:27], v[164:167], v[194:197], v[24:27]
	v_mfma_f32_16x16x32_bf16 v[12:15], v[156:159], v[202:205], v[12:15]
	v_mfma_f32_16x16x32_bf16 v[8:11], v[164:167], v[202:205], v[8:11]
	s_setprio 0
	s_barrier
	s_add_u32 s18, s22, 0xb0000
	s_addc_u32 s19, s23, 0
	s_add_i32 s54, s46, s28
	v_lshl_add_u64 v[144:145], s[18:19], 0, v[130:131]
	s_mov_b32 m0, s54
	s_nop 0
	global_load_lds_dwordx4 v[144:145], off
	v_lshl_add_u64 v[144:145], s[18:19], 0, v[134:135]
	s_add_i32 m0, s54, 0x2000
	s_nop 0
	global_load_lds_dwordx4 v[144:145], off
	s_waitcnt vmcnt(6)
	s_barrier
	s_setprio 1
	v_mfma_f32_16x16x32_bf16 v[52:55], v[206:209], v[168:171], v[52:55]
	v_mfma_f32_16x16x32_bf16 v[48:51], v[214:217], v[168:171], v[48:51]
	v_mfma_f32_16x16x32_bf16 v[36:39], v[206:209], v[182:185], v[36:39]
	v_mfma_f32_16x16x32_bf16 v[32:35], v[214:217], v[182:185], v[32:35]
	v_mfma_f32_16x16x32_bf16 v[20:23], v[206:209], v[190:193], v[20:23]
	v_mfma_f32_16x16x32_bf16 v[16:19], v[214:217], v[190:193], v[16:19]
	v_mfma_f32_16x16x32_bf16 v[4:7], v[206:209], v[198:201], v[4:7]
	v_mfma_f32_16x16x32_bf16 v[0:3], v[214:217], v[198:201], v[0:3]
	v_mfma_f32_16x16x32_bf16 v[52:55], v[210:213], v[178:181], v[52:55]
	v_mfma_f32_16x16x32_bf16 v[48:51], v[218:221], v[178:181], v[48:51]
	v_mfma_f32_16x16x32_bf16 v[36:39], v[210:213], v[186:189], v[36:39]
	v_mfma_f32_16x16x32_bf16 v[32:35], v[218:221], v[186:189], v[32:35]
	v_mfma_f32_16x16x32_bf16 v[20:23], v[210:213], v[194:197], v[20:23]
	v_mfma_f32_16x16x32_bf16 v[16:19], v[218:221], v[194:197], v[16:19]
	v_mfma_f32_16x16x32_bf16 v[4:7], v[210:213], v[202:205], v[4:7]
	v_mfma_f32_16x16x32_bf16 v[0:3], v[218:221], v[202:205], v[0:3]
	s_setprio 0
	s_add_i32 s54, 0, 0x18000
	v_add_u32_e32 v155, s54, v149
	s_barrier
	ds_read_b128 v[144:147], v155
	ds_read_b128 v[156:159], v155 offset:1024
	ds_read_b128 v[160:163], v155 offset:2048
	ds_read_b128 v[164:167], v155 offset:3072
	s_add_u32 s18, s24, 0xb0000
	s_addc_u32 s19, s25, 0
	s_mov_b32 m0, s31
	v_lshl_add_u64 v[206:207], s[18:19], 0, v[128:129]
	ds_read_b128 v[168:171], v152 offset:32768
	ds_read_b128 v[178:181], v152 offset:33792
	ds_read_b128 v[182:185], v152 offset:34816
	ds_read_b128 v[186:189], v152 offset:35840
	ds_read_b128 v[190:193], v152 offset:36864
	ds_read_b128 v[194:197], v152 offset:37888
	ds_read_b128 v[198:201], v152 offset:38912
	ds_read_b128 v[202:205], v152 offset:39936
	global_load_lds_dwordx4 v[206:207], off
	v_lshl_add_u64 v[206:207], s[18:19], 0, v[132:133]
	s_mov_b32 m0, s34
	s_nop 0
	global_load_lds_dwordx4 v[206:207], off
	s_waitcnt lgkmcnt(8)
	s_barrier
	s_waitcnt lgkmcnt(0)
	s_setprio 1
	s_waitcnt lgkmcnt(0)
	v_mfma_f32_16x16x32_bf16 v[124:127], v[144:147], v[168:171], v[124:127]
	v_mfma_f32_16x16x32_bf16 v[120:123], v[160:163], v[168:171], v[120:123]
	v_mfma_f32_16x16x32_bf16 v[108:111], v[144:147], v[182:185], v[108:111]
	v_mfma_f32_16x16x32_bf16 v[104:107], v[160:163], v[182:185], v[104:107]
	v_mfma_f32_16x16x32_bf16 v[92:95], v[144:147], v[190:193], v[92:95]
	v_mfma_f32_16x16x32_bf16 v[88:91], v[160:163], v[190:193], v[88:91]
	v_mfma_f32_16x16x32_bf16 v[76:79], v[144:147], v[198:201], v[76:79]
	v_mfma_f32_16x16x32_bf16 v[72:75], v[160:163], v[198:201], v[72:75]
	v_mfma_f32_16x16x32_bf16 v[124:127], v[156:159], v[178:181], v[124:127]
	v_mfma_f32_16x16x32_bf16 v[120:123], v[164:167], v[178:181], v[120:123]
	v_mfma_f32_16x16x32_bf16 v[108:111], v[156:159], v[186:189], v[108:111]
	v_mfma_f32_16x16x32_bf16 v[104:107], v[164:167], v[186:189], v[104:107]
	v_mfma_f32_16x16x32_bf16 v[92:95], v[156:159], v[194:197], v[92:95]
	v_mfma_f32_16x16x32_bf16 v[88:91], v[164:167], v[194:197], v[88:91]
	v_mfma_f32_16x16x32_bf16 v[76:79], v[156:159], v[202:205], v[76:79]
	v_mfma_f32_16x16x32_bf16 v[72:75], v[164:167], v[202:205], v[72:75]
	s_setprio 0
	s_barrier
	s_add_i32 s24, 0, 0x1c000
	s_add_i32 s18, s54, s28
	v_add_u32_e32 v155, s24, v149
	v_lshl_add_u64 v[172:173], v[172:173], 0, s[14:15]
	s_mov_b32 m0, s18
	ds_read_b128 v[206:209], v155
	ds_read_b128 v[210:213], v155 offset:1024
	ds_read_b128 v[214:217], v155 offset:2048
	ds_read_b128 v[218:221], v155 offset:3072
	global_load_lds_dwordx4 v[172:173], off
	v_lshl_add_u64 v[172:173], v[222:223], 0, s[14:15]
	s_add_i32 m0, s18, 0x2000
	s_nop 0
	global_load_lds_dwordx4 v[172:173], off
	s_barrier
	s_waitcnt lgkmcnt(0)
	s_setprio 1
	s_waitcnt lgkmcnt(0)
	v_mfma_f32_16x16x32_bf16 v[116:119], v[206:209], v[168:171], v[116:119]
	v_mfma_f32_16x16x32_bf16 v[112:115], v[214:217], v[168:171], v[112:115]
	v_mfma_f32_16x16x32_bf16 v[100:103], v[206:209], v[182:185], v[100:103]
	v_mfma_f32_16x16x32_bf16 v[96:99], v[214:217], v[182:185], v[96:99]
	v_mfma_f32_16x16x32_bf16 v[84:87], v[206:209], v[190:193], v[84:87]
	v_mfma_f32_16x16x32_bf16 v[80:83], v[214:217], v[190:193], v[80:83]
	v_mfma_f32_16x16x32_bf16 v[68:71], v[206:209], v[198:201], v[68:71]
	v_mfma_f32_16x16x32_bf16 v[64:67], v[214:217], v[198:201], v[64:67]
	v_mfma_f32_16x16x32_bf16 v[116:119], v[210:213], v[178:181], v[116:119]
	v_mfma_f32_16x16x32_bf16 v[112:115], v[218:221], v[178:181], v[112:115]
	v_mfma_f32_16x16x32_bf16 v[100:103], v[210:213], v[186:189], v[100:103]
	v_mfma_f32_16x16x32_bf16 v[96:99], v[218:221], v[186:189], v[96:99]
	v_mfma_f32_16x16x32_bf16 v[84:87], v[210:213], v[194:197], v[84:87]
	v_mfma_f32_16x16x32_bf16 v[80:83], v[218:221], v[194:197], v[80:83]
	v_mfma_f32_16x16x32_bf16 v[68:71], v[210:213], v[202:205], v[68:71]
	v_mfma_f32_16x16x32_bf16 v[64:67], v[218:221], v[202:205], v[64:67]
	s_setprio 0
	s_mov_b32 m0, s36
	v_lshl_add_u64 v[172:173], v[224:225], 0, s[14:15]
	s_barrier
	ds_read_b128 v[168:171], v152 offset:49152
	ds_read_b128 v[178:181], v152 offset:50176
	ds_read_b128 v[182:185], v152 offset:51200
	ds_read_b128 v[186:189], v152 offset:52224
	ds_read_b128 v[190:193], v152 offset:53248
	ds_read_b128 v[194:197], v152 offset:54272
	ds_read_b128 v[198:201], v152 offset:55296
	ds_read_b128 v[202:205], v152 offset:56320
	global_load_lds_dwordx4 v[172:173], off
	v_lshl_add_u64 v[172:173], v[226:227], 0, s[14:15]
	s_mov_b32 m0, s37
	s_nop 0
	global_load_lds_dwordx4 v[172:173], off
	s_barrier
	s_waitcnt lgkmcnt(0)
	s_setprio 1
	s_waitcnt lgkmcnt(0)
	v_mfma_f32_16x16x32_bf16 v[60:63], v[144:147], v[168:171], v[60:63]
	v_mfma_f32_16x16x32_bf16 v[56:59], v[160:163], v[168:171], v[56:59]
	v_mfma_f32_16x16x32_bf16 v[44:47], v[144:147], v[182:185], v[44:47]
	v_mfma_f32_16x16x32_bf16 v[40:43], v[160:163], v[182:185], v[40:43]
	v_mfma_f32_16x16x32_bf16 v[28:31], v[144:147], v[190:193], v[28:31]
	v_mfma_f32_16x16x32_bf16 v[24:27], v[160:163], v[190:193], v[24:27]
	v_mfma_f32_16x16x32_bf16 v[12:15], v[144:147], v[198:201], v[12:15]
	v_mfma_f32_16x16x32_bf16 v[8:11], v[160:163], v[198:201], v[8:11]
	v_mfma_f32_16x16x32_bf16 v[60:63], v[156:159], v[178:181], v[60:63]
	v_mfma_f32_16x16x32_bf16 v[56:59], v[164:167], v[178:181], v[56:59]
	v_mfma_f32_16x16x32_bf16 v[44:47], v[156:159], v[186:189], v[44:47]
	v_mfma_f32_16x16x32_bf16 v[40:43], v[164:167], v[186:189], v[40:43]
	v_mfma_f32_16x16x32_bf16 v[28:31], v[156:159], v[194:197], v[28:31]
	v_mfma_f32_16x16x32_bf16 v[24:27], v[164:167], v[194:197], v[24:27]
	v_mfma_f32_16x16x32_bf16 v[12:15], v[156:159], v[202:205], v[12:15]
	v_mfma_f32_16x16x32_bf16 v[8:11], v[164:167], v[202:205], v[8:11]
	s_setprio 0
	s_barrier
	s_add_u32 s18, s22, 0xb0080
	s_addc_u32 s19, s23, 0
	s_add_i32 s22, s24, s28
	v_lshl_add_u64 v[144:145], s[18:19], 0, v[130:131]
	s_mov_b32 m0, s22
	s_nop 0
	global_load_lds_dwordx4 v[144:145], off
	v_lshl_add_u64 v[144:145], s[18:19], 0, v[134:135]
	s_add_i32 m0, s22, 0x2000
	s_nop 0
	global_load_lds_dwordx4 v[144:145], off
	s_waitcnt vmcnt(6)
	s_barrier
	s_setprio 1
	v_mfma_f32_16x16x32_bf16 v[52:55], v[206:209], v[168:171], v[52:55]
	v_mfma_f32_16x16x32_bf16 v[48:51], v[214:217], v[168:171], v[48:51]
	v_mfma_f32_16x16x32_bf16 v[36:39], v[206:209], v[182:185], v[36:39]
	v_mfma_f32_16x16x32_bf16 v[32:35], v[214:217], v[182:185], v[32:35]
	v_mfma_f32_16x16x32_bf16 v[20:23], v[206:209], v[190:193], v[20:23]
	v_mfma_f32_16x16x32_bf16 v[16:19], v[214:217], v[190:193], v[16:19]
	v_mfma_f32_16x16x32_bf16 v[4:7], v[206:209], v[198:201], v[4:7]
	v_mfma_f32_16x16x32_bf16 v[0:3], v[214:217], v[198:201], v[0:3]
	v_mfma_f32_16x16x32_bf16 v[52:55], v[210:213], v[178:181], v[52:55]
	v_mfma_f32_16x16x32_bf16 v[48:51], v[218:221], v[178:181], v[48:51]
	v_mfma_f32_16x16x32_bf16 v[36:39], v[210:213], v[186:189], v[36:39]
	v_mfma_f32_16x16x32_bf16 v[32:35], v[218:221], v[186:189], v[32:35]
	v_mfma_f32_16x16x32_bf16 v[20:23], v[210:213], v[194:197], v[20:23]
	v_mfma_f32_16x16x32_bf16 v[16:19], v[218:221], v[194:197], v[16:19]
	v_mfma_f32_16x16x32_bf16 v[4:7], v[210:213], v[202:205], v[4:7]
	v_mfma_f32_16x16x32_bf16 v[0:3], v[218:221], v[202:205], v[0:3]
	s_setprio 0
	s_add_i32 s53, s53, 2
	s_add_u32 s51, s51, 0x100
	s_addc_u32 s52, s52, 0
	s_cmp_gt_u32 s53, 41
	s_mov_b64 s[18:19], s[20:21]
	s_barrier
	s_cbranch_scc0 .LBB0_1503
	s_nop 7
	s_nop 7
	v_and_b32_e32 v160, 15, v174
	v_bfe_u32 v161, v174, 4, 2
	v_lshrrev_b32_e32 v162, 6, v174
	v_lshrrev_b32_e32 v163, 2, v162
	v_and_b32_e32 v164, 3, v162
	v_and_b32_e32 v170, 63, v174
	s_lshr_b32 s80, s33, 3
	s_and_b32 s81, s80, 7
	s_lshl_b32 s81, s81, 3
	s_lshr_b32 s82, s80, 3
	s_and_b32 s82, s82, 7
	s_add_i32 s81, s81, s82
	s_lshr_b32 s82, s80, 6
	v_lshl_add_u32 v165, v163, 6, v160
	s_lshl_b32 s83, s81, 8
	v_add_u32_e32 v165, s83, v165
	v_lshlrev_b32_e32 v166, 3, v161
	v_lshl_add_u32 v166, v164, 5, v166
	s_lshl_b32 s83, s82, 8
	v_add_u32_e32 v166, s83, v166
	v_lshlrev_b32_e32 v168, 12, v165
	v_lshl_add_u32 v168, v166, 2, v168
	v_mov_b32_e32 v169, 0
	s_add_u32 s84, s74, 0x5000000
	s_addc_u32 s85, s75, 0
	v_lshl_add_u64 v[210:211], s[84:85], 0, v[168:169]
	v_lshrrev_b32_e32 v168, 1, v168
	s_add_u32 s84, s74, 0x9100000
	s_addc_u32 s85, s75, 0
	v_lshl_add_u64 v[212:213], s[84:85], 0, v[168:169]
	v_lshlrev_b32_e32 v168, 2, v165
	s_add_u32 s84, s74, 0x12bc1800
	s_addc_u32 s85, s75, 0
	v_lshl_add_u64 v[214:215], s[84:85], 0, v[168:169]
	v_xor_b32_e32 v171, 16, v170
	v_lshlrev_b32_e32 v171, 2, v171
	v_xor_b32_e32 v172, 32, v170
	v_lshlrev_b32_e32 v172, 2, v172
	v_cmp_eq_u32_e64 s[86:87], 0, v161
	s_mov_b32 s85, 0
	s_mov_b32 s89, 0
	s_mov_b32 s84, 0x0
	v_lshl_add_u64 v[216:217], s[84:85], 0, v[210:211]
	global_load_dwordx4 v[128:131], v[216:217], off
	global_load_dwordx4 v[132:135], v[216:217], off offset:16
	global_load_dwordx4 v[136:139], v[216:217], off offset:512
	global_load_dwordx4 v[140:143], v[216:217], off offset:528
	s_mov_b32 s84, 0x10000
	v_lshl_add_u64 v[216:217], s[84:85], 0, v[210:211]
	global_load_dwordx4 v[144:147], v[216:217], off
	global_load_dwordx4 v[148:151], v[216:217], off offset:16
	global_load_dwordx4 v[152:155], v[216:217], off offset:512
	global_load_dwordx4 v[156:159], v[216:217], off offset:528
	s_mov_b32 s84, 0x20000
	v_lshl_add_u64 v[216:217], s[84:85], 0, v[210:211]
	global_load_dwordx4 v[178:181], v[216:217], off
	global_load_dwordx4 v[182:185], v[216:217], off offset:16
	global_load_dwordx4 v[186:189], v[216:217], off offset:512
	global_load_dwordx4 v[190:193], v[216:217], off offset:528
	s_mov_b32 s84, 0x30000
	v_lshl_add_u64 v[216:217], s[84:85], 0, v[210:211]
	global_load_dwordx4 v[194:197], v[216:217], off
	global_load_dwordx4 v[198:201], v[216:217], off offset:16
	global_load_dwordx4 v[202:205], v[216:217], off offset:512
	global_load_dwordx4 v[206:209], v[216:217], off offset:528
	s_waitcnt vmcnt(0)
	s_mov_b32 s84, 0x0
	v_lshl_add_u64 v[216:217], s[84:85], 0, v[210:211]
	v_pk_fma_f32 v[128:129], v[124:125], 0.5, v[128:129] op_sel_hi:[1,0,1]
	v_pk_fma_f32 v[130:131], v[126:127], 0.5, v[130:131] op_sel_hi:[1,0,1]
	v_pk_fma_f32 v[132:133], v[120:121], 0.5, v[132:133] op_sel_hi:[1,0,1]
	v_pk_fma_f32 v[134:135], v[122:123], 0.5, v[134:135] op_sel_hi:[1,0,1]
	global_store_dwordx4 v[216:217], v[128:131], off
	global_store_dwordx4 v[216:217], v[132:135], off offset:16
	v_mul_f32_e32 v220, v128, v128
	v_fmac_f32_e32 v220, v129, v129
	v_fmac_f32_e32 v220, v130, v130
	v_fmac_f32_e32 v220, v131, v131
	v_fmac_f32_e32 v220, v132, v132
	v_fmac_f32_e32 v220, v133, v133
	v_fmac_f32_e32 v220, v134, v134
	v_fmac_f32_e32 v220, v135, v135
	v_pk_fma_f32 v[136:137], v[116:117], 0.5, v[136:137] op_sel_hi:[1,0,1]
	v_pk_fma_f32 v[138:139], v[118:119], 0.5, v[138:139] op_sel_hi:[1,0,1]
	v_pk_fma_f32 v[140:141], v[112:113], 0.5, v[140:141] op_sel_hi:[1,0,1]
	v_pk_fma_f32 v[142:143], v[114:115], 0.5, v[142:143] op_sel_hi:[1,0,1]
	global_store_dwordx4 v[216:217], v[136:139], off offset:512
	global_store_dwordx4 v[216:217], v[140:143], off offset:528
	v_fmac_f32_e32 v220, v136, v136
	v_fmac_f32_e32 v220, v137, v137
	v_fmac_f32_e32 v220, v138, v138
	v_fmac_f32_e32 v220, v139, v139
	v_fmac_f32_e32 v220, v140, v140
	v_fmac_f32_e32 v220, v141, v141
	v_fmac_f32_e32 v220, v142, v142
	v_fmac_f32_e32 v220, v143, v143
	s_mov_b32 s84, 0x10000
	v_lshl_add_u64 v[216:217], s[84:85], 0, v[210:211]
	v_pk_fma_f32 v[144:145], v[108:109], 0.5, v[144:145] op_sel_hi:[1,0,1]
	v_pk_fma_f32 v[146:147], v[110:111], 0.5, v[146:147] op_sel_hi:[1,0,1]
	v_pk_fma_f32 v[148:149], v[104:105], 0.5, v[148:149] op_sel_hi:[1,0,1]
	v_pk_fma_f32 v[150:151], v[106:107], 0.5, v[150:151] op_sel_hi:[1,0,1]
	global_store_dwordx4 v[216:217], v[144:147], off
	global_store_dwordx4 v[216:217], v[148:151], off offset:16
	v_mul_f32_e32 v221, v144, v144
	v_fmac_f32_e32 v221, v145, v145
	v_fmac_f32_e32 v221, v146, v146
	v_fmac_f32_e32 v221, v147, v147
	v_fmac_f32_e32 v221, v148, v148
	v_fmac_f32_e32 v221, v149, v149
	v_fmac_f32_e32 v221, v150, v150
	v_fmac_f32_e32 v221, v151, v151
	v_pk_fma_f32 v[152:153], v[100:101], 0.5, v[152:153] op_sel_hi:[1,0,1]
	v_pk_fma_f32 v[154:155], v[102:103], 0.5, v[154:155] op_sel_hi:[1,0,1]
	v_pk_fma_f32 v[156:157], v[96:97], 0.5, v[156:157] op_sel_hi:[1,0,1]
	v_pk_fma_f32 v[158:159], v[98:99], 0.5, v[158:159] op_sel_hi:[1,0,1]
	global_store_dwordx4 v[216:217], v[152:155], off offset:512
	global_store_dwordx4 v[216:217], v[156:159], off offset:528
	v_fmac_f32_e32 v221, v152, v152
	v_fmac_f32_e32 v221, v153, v153
	v_fmac_f32_e32 v221, v154, v154
	v_fmac_f32_e32 v221, v155, v155
	v_fmac_f32_e32 v221, v156, v156
	v_fmac_f32_e32 v221, v157, v157
	v_fmac_f32_e32 v221, v158, v158
	v_fmac_f32_e32 v221, v159, v159
	s_mov_b32 s84, 0x20000
	v_lshl_add_u64 v[216:217], s[84:85], 0, v[210:211]
	v_pk_fma_f32 v[178:179], v[92:93], 0.5, v[178:179] op_sel_hi:[1,0,1]
	v_pk_fma_f32 v[180:181], v[94:95], 0.5, v[180:181] op_sel_hi:[1,0,1]
	v_pk_fma_f32 v[182:183], v[88:89], 0.5, v[182:183] op_sel_hi:[1,0,1]
	v_pk_fma_f32 v[184:185], v[90:91], 0.5, v[184:185] op_sel_hi:[1,0,1]
	global_store_dwordx4 v[216:217], v[178:181], off
	global_store_dwordx4 v[216:217], v[182:185], off offset:16
	v_mul_f32_e32 v222, v178, v178
	v_fmac_f32_e32 v222, v179, v179
	v_fmac_f32_e32 v222, v180, v180
	v_fmac_f32_e32 v222, v181, v181
	v_fmac_f32_e32 v222, v182, v182
	v_fmac_f32_e32 v222, v183, v183
	v_fmac_f32_e32 v222, v184, v184
	v_fmac_f32_e32 v222, v185, v185
	v_pk_fma_f32 v[186:187], v[84:85], 0.5, v[186:187] op_sel_hi:[1,0,1]
	v_pk_fma_f32 v[188:189], v[86:87], 0.5, v[188:189] op_sel_hi:[1,0,1]
	v_pk_fma_f32 v[190:191], v[80:81], 0.5, v[190:191] op_sel_hi:[1,0,1]
	v_pk_fma_f32 v[192:193], v[82:83], 0.5, v[192:193] op_sel_hi:[1,0,1]
	global_store_dwordx4 v[216:217], v[186:189], off offset:512
	global_store_dwordx4 v[216:217], v[190:193], off offset:528
	v_fmac_f32_e32 v222, v186, v186
	v_fmac_f32_e32 v222, v187, v187
	v_fmac_f32_e32 v222, v188, v188
	v_fmac_f32_e32 v222, v189, v189
	v_fmac_f32_e32 v222, v190, v190
	v_fmac_f32_e32 v222, v191, v191
	v_fmac_f32_e32 v222, v192, v192
	v_fmac_f32_e32 v222, v193, v193
	s_mov_b32 s84, 0x30000
	v_lshl_add_u64 v[216:217], s[84:85], 0, v[210:211]
	v_pk_fma_f32 v[194:195], v[76:77], 0.5, v[194:195] op_sel_hi:[1,0,1]
	v_pk_fma_f32 v[196:197], v[78:79], 0.5, v[196:197] op_sel_hi:[1,0,1]
	v_pk_fma_f32 v[198:199], v[72:73], 0.5, v[198:199] op_sel_hi:[1,0,1]
	v_pk_fma_f32 v[200:201], v[74:75], 0.5, v[200:201] op_sel_hi:[1,0,1]
	global_store_dwordx4 v[216:217], v[194:197], off
	global_store_dwordx4 v[216:217], v[198:201], off offset:16
	v_mul_f32_e32 v223, v194, v194
	v_fmac_f32_e32 v223, v195, v195
	v_fmac_f32_e32 v223, v196, v196
	v_fmac_f32_e32 v223, v197, v197
	v_fmac_f32_e32 v223, v198, v198
	v_fmac_f32_e32 v223, v199, v199
	v_fmac_f32_e32 v223, v200, v200
	v_fmac_f32_e32 v223, v201, v201
	v_pk_fma_f32 v[202:203], v[68:69], 0.5, v[202:203] op_sel_hi:[1,0,1]
	v_pk_fma_f32 v[204:205], v[70:71], 0.5, v[204:205] op_sel_hi:[1,0,1]
	v_pk_fma_f32 v[206:207], v[64:65], 0.5, v[206:207] op_sel_hi:[1,0,1]
	v_pk_fma_f32 v[208:209], v[66:67], 0.5, v[208:209] op_sel_hi:[1,0,1]
	global_store_dwordx4 v[216:217], v[202:205], off offset:512
	global_store_dwordx4 v[216:217], v[206:209], off offset:528
	v_fmac_f32_e32 v223, v202, v202
	v_fmac_f32_e32 v223, v203, v203
	v_fmac_f32_e32 v223, v204, v204
	v_fmac_f32_e32 v223, v205, v205
	v_fmac_f32_e32 v223, v206, v206
	v_fmac_f32_e32 v223, v207, v207
	v_fmac_f32_e32 v223, v208, v208
	v_fmac_f32_e32 v223, v209, v209
	ds_bpermute_b32 v224, v171, v220
	ds_bpermute_b32 v225, v171, v221
	ds_bpermute_b32 v226, v171, v222
	ds_bpermute_b32 v227, v171, v223
	s_waitcnt lgkmcnt(0)
	v_add_f32_e32 v220, v220, v224
	v_add_f32_e32 v221, v221, v225
	v_add_f32_e32 v222, v222, v226
	v_add_f32_e32 v223, v223, v227
	ds_bpermute_b32 v224, v172, v220
	ds_bpermute_b32 v225, v172, v221
	ds_bpermute_b32 v226, v172, v222
	ds_bpermute_b32 v227, v172, v223
	s_waitcnt lgkmcnt(0)
	v_add_f32_e32 v220, v220, v224
	v_add_f32_e32 v221, v221, v225
	v_add_f32_e32 v222, v222, v226
	v_add_f32_e32 v223, v223, v227
	s_and_saveexec_b64 s[90:91], s[86:87]
	global_atomic_add_f32 v[214:215], v220, off
	global_atomic_add_f32 v[214:215], v221, off offset:64
	global_atomic_add_f32 v[214:215], v222, off offset:128
	global_atomic_add_f32 v[214:215], v223, off offset:192
	s_mov_b64 exec, s[90:91]
	s_mov_b32 s84, 0x80000
	v_lshl_add_u64 v[216:217], s[84:85], 0, v[210:211]
	global_load_dwordx4 v[128:131], v[216:217], off
	global_load_dwordx4 v[132:135], v[216:217], off offset:16
	global_load_dwordx4 v[136:139], v[216:217], off offset:512
	global_load_dwordx4 v[140:143], v[216:217], off offset:528
	s_mov_b32 s84, 0x90000
	v_lshl_add_u64 v[216:217], s[84:85], 0, v[210:211]
	global_load_dwordx4 v[144:147], v[216:217], off
	global_load_dwordx4 v[148:151], v[216:217], off offset:16
	global_load_dwordx4 v[152:155], v[216:217], off offset:512
	global_load_dwordx4 v[156:159], v[216:217], off offset:528
	s_mov_b32 s84, 0xa0000
	v_lshl_add_u64 v[216:217], s[84:85], 0, v[210:211]
	global_load_dwordx4 v[178:181], v[216:217], off
	global_load_dwordx4 v[182:185], v[216:217], off offset:16
	global_load_dwordx4 v[186:189], v[216:217], off offset:512
	global_load_dwordx4 v[190:193], v[216:217], off offset:528
	s_mov_b32 s84, 0xb0000
	v_lshl_add_u64 v[216:217], s[84:85], 0, v[210:211]
	global_load_dwordx4 v[194:197], v[216:217], off
	global_load_dwordx4 v[198:201], v[216:217], off offset:16
	global_load_dwordx4 v[202:205], v[216:217], off offset:512
	global_load_dwordx4 v[206:209], v[216:217], off offset:528
	s_waitcnt vmcnt(0)
	s_mov_b32 s84, 0x80000
	v_lshl_add_u64 v[216:217], s[84:85], 0, v[210:211]
	v_pk_fma_f32 v[128:129], v[60:61], 0.5, v[128:129] op_sel_hi:[1,0,1]
	v_pk_fma_f32 v[130:131], v[62:63], 0.5, v[130:131] op_sel_hi:[1,0,1]
	v_pk_fma_f32 v[132:133], v[56:57], 0.5, v[132:133] op_sel_hi:[1,0,1]
	v_pk_fma_f32 v[134:135], v[58:59], 0.5, v[134:135] op_sel_hi:[1,0,1]
	global_store_dwordx4 v[216:217], v[128:131], off
	global_store_dwordx4 v[216:217], v[132:135], off offset:16
	v_mul_f32_e32 v220, v128, v128
	v_fmac_f32_e32 v220, v129, v129
	v_fmac_f32_e32 v220, v130, v130
	v_fmac_f32_e32 v220, v131, v131
	v_fmac_f32_e32 v220, v132, v132
	v_fmac_f32_e32 v220, v133, v133
	v_fmac_f32_e32 v220, v134, v134
	v_fmac_f32_e32 v220, v135, v135
	v_pk_fma_f32 v[136:137], v[52:53], 0.5, v[136:137] op_sel_hi:[1,0,1]
	v_pk_fma_f32 v[138:139], v[54:55], 0.5, v[138:139] op_sel_hi:[1,0,1]
	v_pk_fma_f32 v[140:141], v[48:49], 0.5, v[140:141] op_sel_hi:[1,0,1]
	v_pk_fma_f32 v[142:143], v[50:51], 0.5, v[142:143] op_sel_hi:[1,0,1]
	global_store_dwordx4 v[216:217], v[136:139], off offset:512
	global_store_dwordx4 v[216:217], v[140:143], off offset:528
	v_fmac_f32_e32 v220, v136, v136
	v_fmac_f32_e32 v220, v137, v137
	v_fmac_f32_e32 v220, v138, v138
	v_fmac_f32_e32 v220, v139, v139
	v_fmac_f32_e32 v220, v140, v140
	v_fmac_f32_e32 v220, v141, v141
	v_fmac_f32_e32 v220, v142, v142
	v_fmac_f32_e32 v220, v143, v143
	s_mov_b32 s84, 0x90000
	v_lshl_add_u64 v[216:217], s[84:85], 0, v[210:211]
	v_pk_fma_f32 v[144:145], v[44:45], 0.5, v[144:145] op_sel_hi:[1,0,1]
	v_pk_fma_f32 v[146:147], v[46:47], 0.5, v[146:147] op_sel_hi:[1,0,1]
	v_pk_fma_f32 v[148:149], v[40:41], 0.5, v[148:149] op_sel_hi:[1,0,1]
	v_pk_fma_f32 v[150:151], v[42:43], 0.5, v[150:151] op_sel_hi:[1,0,1]
	global_store_dwordx4 v[216:217], v[144:147], off
	global_store_dwordx4 v[216:217], v[148:151], off offset:16
	v_mul_f32_e32 v221, v144, v144
	v_fmac_f32_e32 v221, v145, v145
	v_fmac_f32_e32 v221, v146, v146
	v_fmac_f32_e32 v221, v147, v147
	v_fmac_f32_e32 v221, v148, v148
	v_fmac_f32_e32 v221, v149, v149
	v_fmac_f32_e32 v221, v150, v150
	v_fmac_f32_e32 v221, v151, v151
	v_pk_fma_f32 v[152:153], v[36:37], 0.5, v[152:153] op_sel_hi:[1,0,1]
	v_pk_fma_f32 v[154:155], v[38:39], 0.5, v[154:155] op_sel_hi:[1,0,1]
	v_pk_fma_f32 v[156:157], v[32:33], 0.5, v[156:157] op_sel_hi:[1,0,1]
	v_pk_fma_f32 v[158:159], v[34:35], 0.5, v[158:159] op_sel_hi:[1,0,1]
	global_store_dwordx4 v[216:217], v[152:155], off offset:512
	global_store_dwordx4 v[216:217], v[156:159], off offset:528
	v_fmac_f32_e32 v221, v152, v152
	v_fmac_f32_e32 v221, v153, v153
	v_fmac_f32_e32 v221, v154, v154
	v_fmac_f32_e32 v221, v155, v155
	v_fmac_f32_e32 v221, v156, v156
	v_fmac_f32_e32 v221, v157, v157
	v_fmac_f32_e32 v221, v158, v158
	v_fmac_f32_e32 v221, v159, v159
	s_mov_b32 s84, 0xa0000
	v_lshl_add_u64 v[216:217], s[84:85], 0, v[210:211]
	v_pk_fma_f32 v[178:179], v[28:29], 0.5, v[178:179] op_sel_hi:[1,0,1]
	v_pk_fma_f32 v[180:181], v[30:31], 0.5, v[180:181] op_sel_hi:[1,0,1]
	v_pk_fma_f32 v[182:183], v[24:25], 0.5, v[182:183] op_sel_hi:[1,0,1]
	v_pk_fma_f32 v[184:185], v[26:27], 0.5, v[184:185] op_sel_hi:[1,0,1]
	global_store_dwordx4 v[216:217], v[178:181], off
	global_store_dwordx4 v[216:217], v[182:185], off offset:16
	v_mul_f32_e32 v222, v178, v178
	v_fmac_f32_e32 v222, v179, v179
	v_fmac_f32_e32 v222, v180, v180
	v_fmac_f32_e32 v222, v181, v181
	v_fmac_f32_e32 v222, v182, v182
	v_fmac_f32_e32 v222, v183, v183
	v_fmac_f32_e32 v222, v184, v184
	v_fmac_f32_e32 v222, v185, v185
	v_pk_fma_f32 v[186:187], v[20:21], 0.5, v[186:187] op_sel_hi:[1,0,1]
	v_pk_fma_f32 v[188:189], v[22:23], 0.5, v[188:189] op_sel_hi:[1,0,1]
	v_pk_fma_f32 v[190:191], v[16:17], 0.5, v[190:191] op_sel_hi:[1,0,1]
	v_pk_fma_f32 v[192:193], v[18:19], 0.5, v[192:193] op_sel_hi:[1,0,1]
	global_store_dwordx4 v[216:217], v[186:189], off offset:512
	global_store_dwordx4 v[216:217], v[190:193], off offset:528
	v_fmac_f32_e32 v222, v186, v186
	v_fmac_f32_e32 v222, v187, v187
	v_fmac_f32_e32 v222, v188, v188
	v_fmac_f32_e32 v222, v189, v189
	v_fmac_f32_e32 v222, v190, v190
	v_fmac_f32_e32 v222, v191, v191
	v_fmac_f32_e32 v222, v192, v192
	v_fmac_f32_e32 v222, v193, v193
	s_mov_b32 s84, 0xb0000
	v_lshl_add_u64 v[216:217], s[84:85], 0, v[210:211]
	v_pk_fma_f32 v[194:195], v[12:13], 0.5, v[194:195] op_sel_hi:[1,0,1]
	v_pk_fma_f32 v[196:197], v[14:15], 0.5, v[196:197] op_sel_hi:[1,0,1]
	v_pk_fma_f32 v[198:199], v[8:9], 0.5, v[198:199] op_sel_hi:[1,0,1]
	v_pk_fma_f32 v[200:201], v[10:11], 0.5, v[200:201] op_sel_hi:[1,0,1]
	global_store_dwordx4 v[216:217], v[194:197], off
	global_store_dwordx4 v[216:217], v[198:201], off offset:16
	v_mul_f32_e32 v223, v194, v194
	v_fmac_f32_e32 v223, v195, v195
	v_fmac_f32_e32 v223, v196, v196
	v_fmac_f32_e32 v223, v197, v197
	v_fmac_f32_e32 v223, v198, v198
	v_fmac_f32_e32 v223, v199, v199
	v_fmac_f32_e32 v223, v200, v200
	v_fmac_f32_e32 v223, v201, v201
	v_pk_fma_f32 v[202:203], v[4:5], 0.5, v[202:203] op_sel_hi:[1,0,1]
	v_pk_fma_f32 v[204:205], v[6:7], 0.5, v[204:205] op_sel_hi:[1,0,1]
	v_pk_fma_f32 v[206:207], v[0:1], 0.5, v[206:207] op_sel_hi:[1,0,1]
	v_pk_fma_f32 v[208:209], v[2:3], 0.5, v[208:209] op_sel_hi:[1,0,1]
	global_store_dwordx4 v[216:217], v[202:205], off offset:512
	global_store_dwordx4 v[216:217], v[206:209], off offset:528
	v_fmac_f32_e32 v223, v202, v202
	v_fmac_f32_e32 v223, v203, v203
	v_fmac_f32_e32 v223, v204, v204
	v_fmac_f32_e32 v223, v205, v205
	v_fmac_f32_e32 v223, v206, v206
	v_fmac_f32_e32 v223, v207, v207
	v_fmac_f32_e32 v223, v208, v208
	v_fmac_f32_e32 v223, v209, v209
	ds_bpermute_b32 v224, v171, v220
	ds_bpermute_b32 v225, v171, v221
	ds_bpermute_b32 v226, v171, v222
	ds_bpermute_b32 v227, v171, v223
	s_waitcnt lgkmcnt(0)
	v_add_f32_e32 v220, v220, v224
	v_add_f32_e32 v221, v221, v225
	v_add_f32_e32 v222, v222, v226
	v_add_f32_e32 v223, v223, v227
	ds_bpermute_b32 v224, v172, v220
	ds_bpermute_b32 v225, v172, v221
	ds_bpermute_b32 v226, v172, v222
	ds_bpermute_b32 v227, v172, v223
	s_waitcnt lgkmcnt(0)
	v_add_f32_e32 v220, v220, v224
	v_add_f32_e32 v221, v221, v225
	v_add_f32_e32 v222, v222, v226
	v_add_f32_e32 v223, v223, v227
	s_and_saveexec_b64 s[90:91], s[86:87]
	global_atomic_add_f32 v[214:215], v220, off offset:512
	global_atomic_add_f32 v[214:215], v221, off offset:576
	global_atomic_add_f32 v[214:215], v222, off offset:640
	global_atomic_add_f32 v[214:215], v223, off offset:704
	s_mov_b64 exec, s[90:91]

.LBB0_1523:
	s_and_b32 s80, s33, 64
	s_cmp_lg_u32 s80, 0
	s_cbranch_scc1 .Lpost4_skip
	v_and_b32_e32 v160, 15, v174
	v_bfe_u32 v161, v174, 4, 2
	v_lshrrev_b32_e32 v162, 6, v174
	v_and_b32_e32 v136, 63, v174
	v_readfirstlane_b32 s80, v162
	s_lshr_b32 s81, s33, 8
	s_lshr_b32 s82, s33, 3
	s_and_b32 s82, s82, 31
	s_mul_i32 s83, s80, 704
	v_lshlrev_b32_e32 v164, 4, v161
	v_mov_b32_e32 v167, 0
	s_lshl_b32 s84, s82, 5
	v_add_u32_e32 v165, s84, v160
	v_mul_u32_u24_e32 v166, 0x1600, v165
	v_add3_u32 v166, v166, v164, s83
	s_add_u32 s86, s74, 0x3c80000
	s_addc_u32 s87, s75, 0
	s_mov_b32 s88, 0x16000
	s_mov_b32 s89, 0
	v_lshl_add_u64 v[152:153], s[86:87], 0, v[166:167]
	v_lshl_add_u64 v[154:155], v[152:153], 0, s[88:89]
	s_lshl_b32 s84, s81, 5
	v_add_u32_e32 v165, s84, v160
	v_mul_u32_u24_e32 v166, 0x1600, v165
	v_add3_u32 v166, v166, v164, s83
	s_add_u32 s90, s74, 0x10980000
	s_addc_u32 s91, s75, 0
	v_lshl_add_u64 v[156:157], s[90:91], 0, v[166:167]
	v_lshl_add_u64 v[158:159], v[156:157], 0, s[88:89]
	v_mov_b32_e32 v128, 0
	v_mov_b32_e32 v129, 0
	v_mov_b32_e32 v130, 0
	v_mov_b32_e32 v131, 0
	v_mov_b32_e32 v132, 0
	v_mov_b32_e32 v133, 0
	v_mov_b32_e32 v134, 0
	v_mov_b32_e32 v135, 0
	v_mov_b32_e32 v144, 0
	v_mov_b32_e32 v145, 0
	v_mov_b32_e32 v146, 0
	v_mov_b32_e32 v147, 0
	v_mov_b32_e32 v148, 0
	v_mov_b32_e32 v149, 0
	v_mov_b32_e32 v150, 0
	v_mov_b32_e32 v151, 0
	global_load_dwordx4 v[0:3], v[152:153], off
	global_load_dwordx4 v[4:7], v[154:155], off
	global_load_dwordx4 v[8:11], v[156:157], off
	global_load_dwordx4 v[12:15], v[158:159], off
	global_load_dwordx4 v[16:19], v[152:153], off offset:64
	global_load_dwordx4 v[20:23], v[154:155], off offset:64
	global_load_dwordx4 v[24:27], v[156:157], off offset:64
	global_load_dwordx4 v[28:31], v[158:159], off offset:64
	global_load_dwordx4 v[32:35], v[152:153], off offset:128
	global_load_dwordx4 v[36:39], v[154:155], off offset:128
	global_load_dwordx4 v[40:43], v[156:157], off offset:128
	global_load_dwordx4 v[44:47], v[158:159], off offset:128
	global_load_dwordx4 v[48:51], v[152:153], off offset:192
	global_load_dwordx4 v[52:55], v[154:155], off offset:192
	global_load_dwordx4 v[56:59], v[156:157], off offset:192
	global_load_dwordx4 v[60:63], v[158:159], off offset:192
	global_load_dwordx4 v[64:67], v[152:153], off offset:256
	global_load_dwordx4 v[68:71], v[154:155], off offset:256
	global_load_dwordx4 v[72:75], v[156:157], off offset:256
	global_load_dwordx4 v[76:79], v[158:159], off offset:256
	global_load_dwordx4 v[80:83], v[152:153], off offset:320
	global_load_dwordx4 v[84:87], v[154:155], off offset:320
	global_load_dwordx4 v[88:91], v[156:157], off offset:320
	global_load_dwordx4 v[92:95], v[158:159], off offset:320
	global_load_dwordx4 v[96:99], v[152:153], off offset:384
	global_load_dwordx4 v[100:103], v[154:155], off offset:384
	global_load_dwordx4 v[104:107], v[156:157], off offset:384
	global_load_dwordx4 v[108:111], v[158:159], off offset:384
	global_load_dwordx4 v[112:115], v[152:153], off offset:448
	global_load_dwordx4 v[116:119], v[154:155], off offset:448
	global_load_dwordx4 v[120:123], v[156:157], off offset:448
	global_load_dwordx4 v[124:127], v[158:159], off offset:448
	s_waitcnt vmcnt(16)
	v_mfma_f32_16x16x32_bf16 v[128:131], v[0:3], v[8:11], v[128:131]
	v_mfma_f32_16x16x32_bf16 v[132:135], v[4:7], v[8:11], v[132:135]
	v_mfma_f32_16x16x32_bf16 v[144:147], v[0:3], v[12:15], v[144:147]
	v_mfma_f32_16x16x32_bf16 v[148:151], v[4:7], v[12:15], v[148:151]
	v_mfma_f32_16x16x32_bf16 v[128:131], v[16:19], v[24:27], v[128:131]
	v_mfma_f32_16x16x32_bf16 v[132:135], v[20:23], v[24:27], v[132:135]
	v_mfma_f32_16x16x32_bf16 v[144:147], v[16:19], v[28:31], v[144:147]
	v_mfma_f32_16x16x32_bf16 v[148:151], v[20:23], v[28:31], v[148:151]
	v_mfma_f32_16x16x32_bf16 v[128:131], v[32:35], v[40:43], v[128:131]
	v_mfma_f32_16x16x32_bf16 v[132:135], v[36:39], v[40:43], v[132:135]
	v_mfma_f32_16x16x32_bf16 v[144:147], v[32:35], v[44:47], v[144:147]
	v_mfma_f32_16x16x32_bf16 v[148:151], v[36:39], v[44:47], v[148:151]
	v_mfma_f32_16x16x32_bf16 v[128:131], v[48:51], v[56:59], v[128:131]
	v_mfma_f32_16x16x32_bf16 v[132:135], v[52:55], v[56:59], v[132:135]
	v_mfma_f32_16x16x32_bf16 v[144:147], v[48:51], v[60:63], v[144:147]
	v_mfma_f32_16x16x32_bf16 v[148:151], v[52:55], v[60:63], v[148:151]
	global_load_dwordx4 v[0:3], v[152:153], off offset:512
	global_load_dwordx4 v[4:7], v[154:155], off offset:512
	global_load_dwordx4 v[8:11], v[156:157], off offset:512
	global_load_dwordx4 v[12:15], v[158:159], off offset:512
	global_load_dwordx4 v[16:19], v[152:153], off offset:576
	global_load_dwordx4 v[20:23], v[154:155], off offset:576
	global_load_dwordx4 v[24:27], v[156:157], off offset:576
	global_load_dwordx4 v[28:31], v[158:159], off offset:576
	global_load_dwordx4 v[32:35], v[152:153], off offset:640
	global_load_dwordx4 v[36:39], v[154:155], off offset:640
	global_load_dwordx4 v[40:43], v[156:157], off offset:640
	global_load_dwordx4 v[44:47], v[158:159], off offset:640
	s_waitcnt vmcnt(12)
	v_mfma_f32_16x16x32_bf16 v[128:131], v[64:67], v[72:75], v[128:131]
	v_mfma_f32_16x16x32_bf16 v[132:135], v[68:71], v[72:75], v[132:135]
	v_mfma_f32_16x16x32_bf16 v[144:147], v[64:67], v[76:79], v[144:147]
	v_mfma_f32_16x16x32_bf16 v[148:151], v[68:71], v[76:79], v[148:151]
	v_mfma_f32_16x16x32_bf16 v[128:131], v[80:83], v[88:91], v[128:131]
	v_mfma_f32_16x16x32_bf16 v[132:135], v[84:87], v[88:91], v[132:135]
	v_mfma_f32_16x16x32_bf16 v[144:147], v[80:83], v[92:95], v[144:147]
	v_mfma_f32_16x16x32_bf16 v[148:151], v[84:87], v[92:95], v[148:151]
	v_mfma_f32_16x16x32_bf16 v[128:131], v[96:99], v[104:107], v[128:131]
	v_mfma_f32_16x16x32_bf16 v[132:135], v[100:103], v[104:107], v[132:135]
	v_mfma_f32_16x16x32_bf16 v[144:147], v[96:99], v[108:111], v[144:147]
	v_mfma_f32_16x16x32_bf16 v[148:151], v[100:103], v[108:111], v[148:151]
	v_mfma_f32_16x16x32_bf16 v[128:131], v[112:115], v[120:123], v[128:131]
	v_mfma_f32_16x16x32_bf16 v[132:135], v[116:119], v[120:123], v[132:135]
	v_mfma_f32_16x16x32_bf16 v[144:147], v[112:115], v[124:127], v[144:147]
	v_mfma_f32_16x16x32_bf16 v[148:151], v[116:119], v[124:127], v[148:151]
	s_waitcnt vmcnt(0)
	v_mfma_f32_16x16x32_bf16 v[128:131], v[0:3], v[8:11], v[128:131]
	v_mfma_f32_16x16x32_bf16 v[132:135], v[4:7], v[8:11], v[132:135]
	v_mfma_f32_16x16x32_bf16 v[144:147], v[0:3], v[12:15], v[144:147]
	v_mfma_f32_16x16x32_bf16 v[148:151], v[4:7], v[12:15], v[148:151]
	v_mfma_f32_16x16x32_bf16 v[128:131], v[16:19], v[24:27], v[128:131]
	v_mfma_f32_16x16x32_bf16 v[132:135], v[20:23], v[24:27], v[132:135]
	v_mfma_f32_16x16x32_bf16 v[144:147], v[16:19], v[28:31], v[144:147]
	v_mfma_f32_16x16x32_bf16 v[148:151], v[20:23], v[28:31], v[148:151]
	v_mfma_f32_16x16x32_bf16 v[128:131], v[32:35], v[40:43], v[128:131]
	v_mfma_f32_16x16x32_bf16 v[132:135], v[36:39], v[40:43], v[132:135]
	v_mfma_f32_16x16x32_bf16 v[144:147], v[32:35], v[44:47], v[144:147]
	v_mfma_f32_16x16x32_bf16 v[148:151], v[36:39], v[44:47], v[148:151]
	s_nop 7
	s_nop 7
	v_lshlrev_b32_e32 v170, 12, v162
	v_lshl_add_u32 v170, v136, 4, v170
	ds_write_b128 v170, v[128:131]
	ds_write_b128 v170, v[132:135] offset:1024
	ds_write_b128 v170, v[144:147] offset:2048
	ds_write_b128 v170, v[148:151] offset:3072
	s_waitcnt lgkmcnt(0)
	s_barrier
	s_cmp_ge_u32 s80, 4
	s_cbranch_scc1 .Lmg4_end
	s_lshl_b32 s84, s80, 10
	v_lshlrev_b32_e32 v171, 4, v136
	v_add_u32_e32 v171, s84, v171
	ds_read_b128 v[0:3], v171
	ds_read_b128 v[4:7], v171 offset:4096
	ds_read_b128 v[8:11], v171 offset:8192
	ds_read_b128 v[12:15], v171 offset:12288
	ds_read_b128 v[16:19], v171 offset:16384
	ds_read_b128 v[20:23], v171 offset:20480
	ds_read_b128 v[24:27], v171 offset:24576
	ds_read_b128 v[28:31], v171 offset:28672
	s_lshr_b32 s84, s80, 1
	s_lshl_b32 s84, s84, 4
	s_lshl_b32 s85, s81, 5
	s_add_i32 s84, s84, s85
	s_addk_i32 s84, 0x4000
	s_and_b32 s85, s80, 1
	s_lshl_b32 s85, s85, 4
	s_lshl_b32 s83, s82, 5
	s_add_i32 s85, s85, s83
	v_add_u32_e32 v165, s84, v160
	v_lshl_add_u32 v164, v161, 2, s85
	v_lshlrev_b32_e32 v166, 12, v165
	v_lshl_add_u32 v166, v164, 2, v166
	v_mov_b32_e32 v167, 0
	s_add_u32 s86, s74, 0x5000000
	s_addc_u32 s87, s75, 0
	v_lshl_add_u64 v[168:169], s[86:87], 0, v[166:167]
	global_load_dwordx4 v[32:35], v[168:169], off
	v_lshrrev_b32_e32 v172, 1, v166
	v_mov_b32_e32 v173, 0
	s_add_u32 s86, s74, 0x9100000
	s_addc_u32 s87, s75, 0
	v_lshl_add_u64 v[172:173], s[86:87], 0, v[172:173]
	v_lshlrev_b32_e32 v166, 2, v165
	s_add_u32 s86, s74, 0x12bc1800
	s_addc_u32 s87, s75, 0
	v_lshl_add_u64 v[166:167], s[86:87], 0, v[166:167]
	s_waitcnt lgkmcnt(0)
	v_add_f32_e32 v0, v0, v4
	v_add_f32_e32 v1, v1, v5
	v_add_f32_e32 v2, v2, v6
	v_add_f32_e32 v3, v3, v7
	v_add_f32_e32 v0, v0, v8
	v_add_f32_e32 v1, v1, v9
	v_add_f32_e32 v2, v2, v10
	v_add_f32_e32 v3, v3, v11
	v_add_f32_e32 v0, v0, v12
	v_add_f32_e32 v1, v1, v13
	v_add_f32_e32 v2, v2, v14
	v_add_f32_e32 v3, v3, v15
	v_add_f32_e32 v0, v0, v16
	v_add_f32_e32 v1, v1, v17
	v_add_f32_e32 v2, v2, v18
	v_add_f32_e32 v3, v3, v19
	v_add_f32_e32 v0, v0, v20
	v_add_f32_e32 v1, v1, v21
	v_add_f32_e32 v2, v2, v22
	v_add_f32_e32 v3, v3, v23
	v_add_f32_e32 v0, v0, v24
	v_add_f32_e32 v1, v1, v25
	v_add_f32_e32 v2, v2, v26
	v_add_f32_e32 v3, v3, v27
	v_add_f32_e32 v0, v0, v28
	v_add_f32_e32 v1, v1, v29
	v_add_f32_e32 v2, v2, v30
	v_add_f32_e32 v3, v3, v31
	s_waitcnt vmcnt(0)
	v_fma_f32 v32, v0, 0.5, v32
	v_fma_f32 v33, v1, 0.5, v33
	v_fma_f32 v34, v2, 0.5, v34
	v_fma_f32 v35, v3, 0.5, v35
	global_store_dwordx4 v[168:169], v[32:35], off
	v_cvt_pk_bf16_f32 v36, v32, v33
	v_cvt_pk_bf16_f32 v37, v34, v35
	v_mul_f32_e32 v38, v32, v32
	v_fmac_f32_e32 v38, v33, v33
	v_fmac_f32_e32 v38, v34, v34
	v_fmac_f32_e32 v38, v35, v35
	v_xor_b32_e32 v39, 16, v136
	v_lshlrev_b32_e32 v39, 2, v39
	ds_bpermute_b32 v40, v39, v38
	v_xor_b32_e32 v41, 32, v136
	v_lshlrev_b32_e32 v41, 2, v41
	s_waitcnt lgkmcnt(0)
	v_add_f32_e32 v38, v38, v40
	ds_bpermute_b32 v40, v41, v38
	s_waitcnt lgkmcnt(0)
	v_add_f32_e32 v38, v38, v40
	v_cmp_gt_u32_e64 s[82:83], 16, v136
	s_nop 1
	s_and_saveexec_b64 s[84:85], s[82:83]
	global_atomic_add_f32 v[166:167], v38, off
	s_mov_b64 exec, s[84:85]
.Lmg4_end:
	v_lshrrev_b32_e32 v21, 6, v174
	v_and_b32_e32 v22, 63, v174
	v_lshlrev_b32_e32 v22, 4, v22
	v_readfirstlane_b32 s80, v21
	v_add_u32_e32 v23, 0x1000, v22
	v_readfirstlane_b32 s92, v235
	v_readfirstlane_b32 s93, v236
	v_readfirstlane_b32 s94, v237
	v_readfirstlane_b32 s95, v238
	v_readfirstlane_b32 s98, v239
	v_readfirstlane_b32 s99, v240
	s_lshr_b32 s100, s33, 7
	s_lshl_b32 s100, s100, 3
	s_lshr_b32 s101, s33, 3
	s_and_b32 s101, s101, 7
	s_add_i32 s100, s100, s101
	s_lshl_b32 s100, s100, 3
	s_add_i32 s80, s80, s100
	s_add_i32 s80, s80, 0x17444
	s_movk_i32 s100, 0x400

.Lcpy4_end:
.Lpost4_skip:
	s_waitcnt vmcnt(0)
	s_waitcnt lgkmcnt(0)
	s_barrier
	s_and_saveexec_b64 s[2:3], s[0:1]
	s_cbranch_execz .LBB0_1543
	v_rcp_iflag_f32_e32 v0, v176
	s_sub_i32 s4, 0, s78
	s_mov_b64 s[0:1], exec
	buffer_wbl2 sc1
	s_waitcnt vmcnt(0)
	v_mul_f32_e32 v0, 0x4f7ffffe, v0
	v_cvt_u32_f32_e32 v0, v0
	s_waitcnt vmcnt(0)
	v_mbcnt_lo_u32_b32 v1, s0, 0
	s_mul_i32 s6, s78, 15
	v_readfirstlane_b32 s5, v0
	s_mul_i32 s4, s4, s5
	s_mul_hi_u32 s4, s5, s4
	s_add_i32 s5, s5, s4
	v_mbcnt_hi_u32_b32 v0, s1, v1
	s_mul_hi_u32 s7, s6, s5
	v_cmp_eq_u32_e32 vcc, 0, v0
	s_and_saveexec_b64 s[4:5], vcc
	s_cbranch_execz .LBB0_1526
	s_bcnt1_i32_b64 s0, s[0:1]
	v_mov_b32_e32 v1, 0
	v_mov_b32_e32 v2, s0
	global_atomic_add v1, v1, v2, s[96:97] sc0
